# v27 + priority 2 for the DMA-issuing part of each k-step (1 for the LDS-read part, 0 after MFMA 23)
# baseline (speedup 1.0000x reference)
;     ...
;   for (int kt = 0; kt < nk; kt++) {
;     if (kt + 1 < nk) asm volatile("s_waitcnt vmcnt(6)" ::: "memory");
;     else asm volatile("s_waitcnt vmcnt(0)" ::: "memory");
;     __builtin_amdgcn_s_barrier();
;     asm volatile("" ::: "memory");
;     if (kt + 2 < nk) G2_STAGE(kt + 2);
;     const char* cS = smem + (kt % 3) * 24576;
;     bf16x8 xa[8], wb[4];
; #pragma unroll
;     for (int f = 0; f < 8; f++) xa[f] = *(const bf16x8*)(cS + aoff + f * 1024);
; #pragma unroll
;     for (int f = 0; f < 4; f++) wb[f] = *(const bf16x8*)(cS + boff + f * 1024);
; #pragma unroll
;     for (int nf = 0; nf < 4; nf++)
; #pragma unroll
;       for (int mf = 0; mf < 8; mf++)
;         acc[nf][mf] = __builtin_amdgcn_mfma_f32_16x16x32_bf16(wb[nf], xa[mf], acc[nf][mf], 0, 0, 0);
;   }
.Lta11_loop:
	.p2align 3
	s_waitcnt vmcnt(6) lgkmcnt(0)
	s_barrier
	s_setprio 1
	v_add_u32_e32 v144, s40, v136
	v_mfma_f32_16x16x32_bf16 v[126:129], v[184:187], v[146:149], v[126:129]
	ds_read_b128 v[200:203], v144 offset:0
	v_mfma_f32_16x16x32_bf16 v[122:125], v[184:187], v[152:155], v[122:125]
	ds_read_b128 v[204:207], v144 offset:1024
	v_mfma_f32_16x16x32_bf16 v[118:121], v[184:187], v[156:159], v[118:121]
	ds_read_b128 v[208:211], v144 offset:2048
	v_mfma_f32_16x16x32_bf16 v[114:117], v[184:187], v[162:165], v[114:117]
	ds_read_b128 v[212:215], v144 offset:3072
	v_mfma_f32_16x16x32_bf16 v[110:113], v[184:187], v[166:169], v[110:113]
	ds_read_b128 v[216:219], v144 offset:4096
	v_mfma_f32_16x16x32_bf16 v[106:109], v[184:187], v[170:173], v[106:109]
	ds_read_b128 v[220:223], v144 offset:5120
	v_mfma_f32_16x16x32_bf16 v[102:105], v[184:187], v[176:179], v[102:105]
	ds_read_b128 v[224:227], v144 offset:6144
	v_mfma_f32_16x16x32_bf16 v[98:101], v[184:187], v[180:183], v[98:101]
	ds_read_b128 v[228:231], v144 offset:7168
	v_mfma_f32_16x16x32_bf16 v[94:97], v[188:191], v[146:149], v[94:97]
	v_add_u32_e64 v144, s40, v137
	v_mfma_f32_16x16x32_bf16 v[90:93], v[188:191], v[152:155], v[90:93]
	v_mfma_f32_16x16x32_bf16 v[86:89], v[188:191], v[156:159], v[86:89]
	ds_read_b128 v[232:235], v144 offset:16384
	v_mfma_f32_16x16x32_bf16 v[82:85], v[188:191], v[162:165], v[82:85]
	ds_read_b128 v[236:239], v144 offset:17408
	v_mfma_f32_16x16x32_bf16 v[78:81], v[188:191], v[166:169], v[78:81]
	ds_read_b128 v[240:243], v144 offset:18432
	s_setprio 2
	s_nop 0
	v_mfma_f32_16x16x32_bf16 v[74:77], v[188:191], v[170:173], v[74:77]
	ds_read_b128 v[244:247], v144 offset:19456
	v_mfma_f32_16x16x32_bf16 v[70:73], v[188:191], v[176:179], v[70:73]
	s_add_i32 s42, s46, s41
	s_mov_b32 m0, s42
	v_lshl_add_u64 v[142:143], v[132:133], 0, s[2:3]
	v_mfma_f32_16x16x32_bf16 v[66:69], v[188:191], v[180:183], v[66:69]
	global_load_lds_dwordx4 v[132:133], off
	s_add_i32 m0, m0, 0x1000
	v_mfma_f32_16x16x32_bf16 v[62:65], v[192:195], v[146:149], v[62:65]
	v_mfma_f32_16x16x32_bf16 v[58:61], v[192:195], v[152:155], v[58:61]
	v_mfma_f32_16x16x32_bf16 v[54:57], v[192:195], v[156:159], v[54:57]
	global_load_lds_dwordx4 v[142:143], off
	v_lshl_add_u64 v[142:143], v[142:143], 0, s[2:3]
	s_add_i32 m0, m0, 0x1000
	v_mfma_f32_16x16x32_bf16 v[50:53], v[192:195], v[162:165], v[50:53]
	v_mfma_f32_16x16x32_bf16 v[46:49], v[192:195], v[166:169], v[46:49]
	v_mfma_f32_16x16x32_bf16 v[42:45], v[192:195], v[170:173], v[42:45]
	global_load_lds_dwordx4 v[142:143], off
	v_lshl_add_u64 v[142:143], v[142:143], 0, s[2:3]
	s_add_i32 m0, m0, 0x1000
	v_mfma_f32_16x16x32_bf16 v[38:41], v[192:195], v[176:179], v[38:41]
	v_mfma_f32_16x16x32_bf16 v[34:37], v[192:195], v[180:183], v[34:37]
	s_setprio 0
	s_nop 0
	v_mfma_f32_16x16x32_bf16 v[30:33], v[196:199], v[146:149], v[30:33]
	global_load_lds_dwordx4 v[142:143], off
	s_add_i32 m0, m0, 0x1000
	v_lshl_add_u64 v[142:143], v[134:135], 0, s[2:3]
	v_mfma_f32_16x16x32_bf16 v[26:29], v[196:199], v[152:155], v[26:29]
	v_mfma_f32_16x16x32_bf16 v[22:25], v[196:199], v[156:159], v[22:25]
	v_mfma_f32_16x16x32_bf16 v[18:21], v[196:199], v[162:165], v[18:21]
	global_load_lds_dwordx4 v[134:135], off
	s_add_i32 m0, m0, 0x1000
	v_lshl_add_u64 v[132:133], v[132:133], 0, s[12:13]
	v_mfma_f32_16x16x32_bf16 v[14:17], v[196:199], v[166:169], v[14:17]
	v_mfma_f32_16x16x32_bf16 v[10:13], v[196:199], v[170:173], v[10:13]
	v_mfma_f32_16x16x32_bf16 v[6:9], v[196:199], v[176:179], v[6:9]
	global_load_lds_dwordx4 v[142:143], off
	v_lshl_add_u64 v[134:135], v[134:135], 0, s[4:5]
	v_mfma_f32_16x16x32_bf16 v[2:5], v[196:199], v[180:183], v[2:5]
	s_mov_b32 s41, s40
	s_nop 0
	s_add_i32 s40, s40, 0x6000
	s_cmp_eq_u32 s40, 0x12000
	s_cselect_b32 s40, 0, s40
	s_nop 0
	.p2align 3
	s_waitcnt vmcnt(6) lgkmcnt(0)
	s_barrier
	s_setprio 1
	v_add_u32_e32 v144, s40, v136
	v_mfma_f32_16x16x32_bf16 v[126:129], v[232:235], v[200:203], v[126:129]
	ds_read_b128 v[146:149], v144 offset:0
	v_mfma_f32_16x16x32_bf16 v[122:125], v[232:235], v[204:207], v[122:125]
	ds_read_b128 v[152:155], v144 offset:1024
	v_mfma_f32_16x16x32_bf16 v[118:121], v[232:235], v[208:211], v[118:121]
	ds_read_b128 v[156:159], v144 offset:2048
	v_mfma_f32_16x16x32_bf16 v[114:117], v[232:235], v[212:215], v[114:117]
	ds_read_b128 v[162:165], v144 offset:3072
	v_mfma_f32_16x16x32_bf16 v[110:113], v[232:235], v[216:219], v[110:113]
	ds_read_b128 v[166:169], v144 offset:4096
	v_mfma_f32_16x16x32_bf16 v[106:109], v[232:235], v[220:223], v[106:109]
	ds_read_b128 v[170:173], v144 offset:5120
	v_mfma_f32_16x16x32_bf16 v[102:105], v[232:235], v[224:227], v[102:105]
	ds_read_b128 v[176:179], v144 offset:6144
	v_mfma_f32_16x16x32_bf16 v[98:101], v[232:235], v[228:231], v[98:101]
	ds_read_b128 v[180:183], v144 offset:7168
	v_mfma_f32_16x16x32_bf16 v[94:97], v[236:239], v[200:203], v[94:97]
	v_add_u32_e64 v144, s40, v137
	v_mfma_f32_16x16x32_bf16 v[90:93], v[236:239], v[204:207], v[90:93]
	v_mfma_f32_16x16x32_bf16 v[86:89], v[236:239], v[208:211], v[86:89]
	ds_read_b128 v[184:187], v144 offset:16384
	v_mfma_f32_16x16x32_bf16 v[82:85], v[236:239], v[212:215], v[82:85]
	ds_read_b128 v[188:191], v144 offset:17408
	v_mfma_f32_16x16x32_bf16 v[78:81], v[236:239], v[216:219], v[78:81]
	ds_read_b128 v[192:195], v144 offset:18432
	s_setprio 2
	s_nop 0
	v_mfma_f32_16x16x32_bf16 v[74:77], v[236:239], v[220:223], v[74:77]
	ds_read_b128 v[196:199], v144 offset:19456
	v_mfma_f32_16x16x32_bf16 v[70:73], v[236:239], v[224:227], v[70:73]
	s_add_i32 s42, s46, s41
	s_mov_b32 m0, s42
	v_lshl_add_u64 v[142:143], v[132:133], 0, s[2:3]
	v_mfma_f32_16x16x32_bf16 v[66:69], v[236:239], v[228:231], v[66:69]
;     ...
;   for (int kt = 0; kt < nk; kt++) {
;     if (kt + 1 < nk) asm volatile("s_waitcnt vmcnt(6)" ::: "memory");
;     else asm volatile("s_waitcnt vmcnt(0)" ::: "memory");
;     __builtin_amdgcn_s_barrier();
;     asm volatile("" ::: "memory");
;     if (kt + 2 < nk) G2_STAGE(kt + 2);
;     const char* cS = smem + (kt % 3) * 24576;
;     bf16x8 xa[8], wb[4];
; #pragma unroll
;     for (int f = 0; f < 8; f++) xa[f] = *(const bf16x8*)(cS + aoff + f * 1024);
; #pragma unroll
;     for (int f = 0; f < 4; f++) wb[f] = *(const bf16x8*)(cS + boff + f * 1024);
; #pragma unroll
;     for (int nf = 0; nf < 4; nf++)
; #pragma unroll
;       for (int mf = 0; mf < 8; mf++)
;         acc[nf][mf] = __builtin_amdgcn_mfma_f32_16x16x32_bf16(wb[nf], xa[mf], acc[nf][mf], 0, 0, 0);
;   }
	global_load_lds_dwordx4 v[132:133], off
	s_add_i32 m0, m0, 0x1000
	v_mfma_f32_16x16x32_bf16 v[62:65], v[240:243], v[200:203], v[62:65]
	v_mfma_f32_16x16x32_bf16 v[58:61], v[240:243], v[204:207], v[58:61]
	v_mfma_f32_16x16x32_bf16 v[54:57], v[240:243], v[208:211], v[54:57]
	global_load_lds_dwordx4 v[142:143], off
	v_lshl_add_u64 v[142:143], v[142:143], 0, s[2:3]
	s_add_i32 m0, m0, 0x1000
	v_mfma_f32_16x16x32_bf16 v[50:53], v[240:243], v[212:215], v[50:53]
	v_mfma_f32_16x16x32_bf16 v[46:49], v[240:243], v[216:219], v[46:49]
	v_mfma_f32_16x16x32_bf16 v[42:45], v[240:243], v[220:223], v[42:45]
	global_load_lds_dwordx4 v[142:143], off
	v_lshl_add_u64 v[142:143], v[142:143], 0, s[2:3]
	s_add_i32 m0, m0, 0x1000
	v_mfma_f32_16x16x32_bf16 v[38:41], v[240:243], v[224:227], v[38:41]
	v_mfma_f32_16x16x32_bf16 v[34:37], v[240:243], v[228:231], v[34:37]
	s_setprio 0
	s_nop 0
	v_mfma_f32_16x16x32_bf16 v[30:33], v[244:247], v[200:203], v[30:33]
	global_load_lds_dwordx4 v[142:143], off
	s_add_i32 m0, m0, 0x1000
	v_lshl_add_u64 v[142:143], v[134:135], 0, s[2:3]
	v_mfma_f32_16x16x32_bf16 v[26:29], v[244:247], v[204:207], v[26:29]
	v_mfma_f32_16x16x32_bf16 v[22:25], v[244:247], v[208:211], v[22:25]
	v_mfma_f32_16x16x32_bf16 v[18:21], v[244:247], v[212:215], v[18:21]
	global_load_lds_dwordx4 v[134:135], off
	s_add_i32 m0, m0, 0x1000
	v_lshl_add_u64 v[132:133], v[132:133], 0, s[12:13]
	v_mfma_f32_16x16x32_bf16 v[14:17], v[244:247], v[216:219], v[14:17]
	v_mfma_f32_16x16x32_bf16 v[10:13], v[244:247], v[220:223], v[10:13]
	v_mfma_f32_16x16x32_bf16 v[6:9], v[244:247], v[224:227], v[6:9]
	global_load_lds_dwordx4 v[142:143], off
	v_lshl_add_u64 v[134:135], v[134:135], 0, s[4:5]
	v_mfma_f32_16x16x32_bf16 v[2:5], v[244:247], v[228:231], v[2:5]
	s_mov_b32 s41, s40
	s_nop 0
	s_add_i32 s40, s40, 0x6000
	s_cmp_eq_u32 s40, 0x12000
	s_cselect_b32 s40, 0, s40
	s_nop 0
	s_sub_i32 s39, s39, 1
	s_cmp_lg_u32 s39, 0
	s_cbranch_scc1 .Lta11_loop
	.p2align 3
	s_waitcnt vmcnt(6) lgkmcnt(0)
	s_barrier
	s_setprio 1
	v_add_u32_e32 v144, s40, v136
	v_mfma_f32_16x16x32_bf16 v[126:129], v[184:187], v[146:149], v[126:129]
	ds_read_b128 v[200:203], v144 offset:0
	v_mfma_f32_16x16x32_bf16 v[122:125], v[184:187], v[152:155], v[122:125]
	ds_read_b128 v[204:207], v144 offset:1024
	v_mfma_f32_16x16x32_bf16 v[118:121], v[184:187], v[156:159], v[118:121]
	ds_read_b128 v[208:211], v144 offset:2048
	v_mfma_f32_16x16x32_bf16 v[114:117], v[184:187], v[162:165], v[114:117]
	ds_read_b128 v[212:215], v144 offset:3072
	v_mfma_f32_16x16x32_bf16 v[110:113], v[184:187], v[166:169], v[110:113]
	ds_read_b128 v[216:219], v144 offset:4096
	v_mfma_f32_16x16x32_bf16 v[106:109], v[184:187], v[170:173], v[106:109]
	ds_read_b128 v[220:223], v144 offset:5120
	v_mfma_f32_16x16x32_bf16 v[102:105], v[184:187], v[176:179], v[102:105]
	ds_read_b128 v[224:227], v144 offset:6144
	v_mfma_f32_16x16x32_bf16 v[98:101], v[184:187], v[180:183], v[98:101]
	ds_read_b128 v[228:231], v144 offset:7168
	v_mfma_f32_16x16x32_bf16 v[94:97], v[188:191], v[146:149], v[94:97]
	v_add_u32_e64 v144, s40, v137
	v_mfma_f32_16x16x32_bf16 v[90:93], v[188:191], v[152:155], v[90:93]
	v_mfma_f32_16x16x32_bf16 v[86:89], v[188:191], v[156:159], v[86:89]
	ds_read_b128 v[232:235], v144 offset:16384
	v_mfma_f32_16x16x32_bf16 v[82:85], v[188:191], v[162:165], v[82:85]
	ds_read_b128 v[236:239], v144 offset:17408
	v_mfma_f32_16x16x32_bf16 v[78:81], v[188:191], v[166:169], v[78:81]
	ds_read_b128 v[240:243], v144 offset:18432
	s_setprio 2
	s_nop 0
	v_mfma_f32_16x16x32_bf16 v[74:77], v[188:191], v[170:173], v[74:77]
	ds_read_b128 v[244:247], v144 offset:19456
	v_mfma_f32_16x16x32_bf16 v[70:73], v[188:191], v[176:179], v[70:73]
	s_add_i32 s42, s46, s41
	s_mov_b32 m0, s42
	v_lshl_add_u64 v[142:143], v[132:133], 0, s[2:3]
	v_mfma_f32_16x16x32_bf16 v[66:69], v[188:191], v[180:183], v[66:69]
	global_load_lds_dwordx4 v[132:133], off
	s_add_i32 m0, m0, 0x1000
	v_mfma_f32_16x16x32_bf16 v[62:65], v[192:195], v[146:149], v[62:65]
	v_mfma_f32_16x16x32_bf16 v[58:61], v[192:195], v[152:155], v[58:61]
	v_mfma_f32_16x16x32_bf16 v[54:57], v[192:195], v[156:159], v[54:57]
	global_load_lds_dwordx4 v[142:143], off
	v_lshl_add_u64 v[142:143], v[142:143], 0, s[2:3]
	s_add_i32 m0, m0, 0x1000
	v_mfma_f32_16x16x32_bf16 v[50:53], v[192:195], v[162:165], v[50:53]
	v_mfma_f32_16x16x32_bf16 v[46:49], v[192:195], v[166:169], v[46:49]
	v_mfma_f32_16x16x32_bf16 v[42:45], v[192:195], v[170:173], v[42:45]
	global_load_lds_dwordx4 v[142:143], off
	v_lshl_add_u64 v[142:143], v[142:143], 0, s[2:3]
	s_add_i32 m0, m0, 0x1000
	v_mfma_f32_16x16x32_bf16 v[38:41], v[192:195], v[176:179], v[38:41]
	v_mfma_f32_16x16x32_bf16 v[34:37], v[192:195], v[180:183], v[34:37]
	s_setprio 0
	s_nop 0
	v_mfma_f32_16x16x32_bf16 v[30:33], v[196:199], v[146:149], v[30:33]
	global_load_lds_dwordx4 v[142:143], off
	s_add_i32 m0, m0, 0x1000
	v_lshl_add_u64 v[142:143], v[134:135], 0, s[2:3]
	v_mfma_f32_16x16x32_bf16 v[26:29], v[196:199], v[152:155], v[26:29]
	v_mfma_f32_16x16x32_bf16 v[22:25], v[196:199], v[156:159], v[22:25]
	v_mfma_f32_16x16x32_bf16 v[18:21], v[196:199], v[162:165], v[18:21]
	global_load_lds_dwordx4 v[134:135], off
	s_add_i32 m0, m0, 0x1000
	v_lshl_add_u64 v[132:133], v[132:133], 0, s[12:13]
	v_mfma_f32_16x16x32_bf16 v[14:17], v[196:199], v[166:169], v[14:17]
	v_mfma_f32_16x16x32_bf16 v[10:13], v[196:199], v[170:173], v[10:13]
	v_mfma_f32_16x16x32_bf16 v[6:9], v[196:199], v[176:179], v[6:9]
	global_load_lds_dwordx4 v[142:143], off
	v_lshl_add_u64 v[134:135], v[134:135], 0, s[4:5]
	v_mfma_f32_16x16x32_bf16 v[2:5], v[196:199], v[180:183], v[2:5]
	s_mov_b32 s41, s40
	s_nop 0
	s_add_i32 s40, s40, 0x6000
	s_cmp_eq_u32 s40, 0x12000
	s_cselect_b32 s40, 0, s40
	s_nop 0
	.p2align 3
	s_waitcnt vmcnt(6) lgkmcnt(0)
	s_barrier
;     ...
;   for (int kt = 0; kt < nk; kt++) {
;     if (kt + 1 < nk) asm volatile("s_waitcnt vmcnt(6)" ::: "memory");
;     else asm volatile("s_waitcnt vmcnt(0)" ::: "memory");
;     __builtin_amdgcn_s_barrier();
;     asm volatile("" ::: "memory");
;     if (kt + 2 < nk) G2_STAGE(kt + 2);
;     const char* cS = smem + (kt % 3) * 24576;
;     bf16x8 xa[8], wb[4];
; #pragma unroll
;     for (int f = 0; f < 8; f++) xa[f] = *(const bf16x8*)(cS + aoff + f * 1024);
; #pragma unroll
;     for (int f = 0; f < 4; f++) wb[f] = *(const bf16x8*)(cS + boff + f * 1024);
; #pragma unroll
;     for (int nf = 0; nf < 4; nf++)
; #pragma unroll
;       for (int mf = 0; mf < 8; mf++)
;         acc[nf][mf] = __builtin_amdgcn_mfma_f32_16x16x32_bf16(wb[nf], xa[mf], acc[nf][mf], 0, 0, 0);
	s_setprio 1
	v_add_u32_e32 v144, s40, v136
	v_mfma_f32_16x16x32_bf16 v[126:129], v[232:235], v[200:203], v[126:129]
	ds_read_b128 v[146:149], v144 offset:0
	v_mfma_f32_16x16x32_bf16 v[122:125], v[232:235], v[204:207], v[122:125]
	ds_read_b128 v[152:155], v144 offset:1024
	v_mfma_f32_16x16x32_bf16 v[118:121], v[232:235], v[208:211], v[118:121]
	ds_read_b128 v[156:159], v144 offset:2048
	v_mfma_f32_16x16x32_bf16 v[114:117], v[232:235], v[212:215], v[114:117]
	ds_read_b128 v[162:165], v144 offset:3072
	v_mfma_f32_16x16x32_bf16 v[110:113], v[232:235], v[216:219], v[110:113]
	ds_read_b128 v[166:169], v144 offset:4096
	v_mfma_f32_16x16x32_bf16 v[106:109], v[232:235], v[220:223], v[106:109]
	ds_read_b128 v[170:173], v144 offset:5120
	v_mfma_f32_16x16x32_bf16 v[102:105], v[232:235], v[224:227], v[102:105]
	ds_read_b128 v[176:179], v144 offset:6144
	v_mfma_f32_16x16x32_bf16 v[98:101], v[232:235], v[228:231], v[98:101]
	ds_read_b128 v[180:183], v144 offset:7168
	v_mfma_f32_16x16x32_bf16 v[94:97], v[236:239], v[200:203], v[94:97]
	v_add_u32_e64 v144, s40, v137
	v_mfma_f32_16x16x32_bf16 v[90:93], v[236:239], v[204:207], v[90:93]
	v_mfma_f32_16x16x32_bf16 v[86:89], v[236:239], v[208:211], v[86:89]
	ds_read_b128 v[184:187], v144 offset:16384
	v_mfma_f32_16x16x32_bf16 v[82:85], v[236:239], v[212:215], v[82:85]
	ds_read_b128 v[188:191], v144 offset:17408
	v_mfma_f32_16x16x32_bf16 v[78:81], v[236:239], v[216:219], v[78:81]
	ds_read_b128 v[192:195], v144 offset:18432
	v_mfma_f32_16x16x32_bf16 v[74:77], v[236:239], v[220:223], v[74:77]
	ds_read_b128 v[196:199], v144 offset:19456
	v_mfma_f32_16x16x32_bf16 v[70:73], v[236:239], v[224:227], v[70:73]
	v_mfma_f32_16x16x32_bf16 v[66:69], v[236:239], v[228:231], v[66:69]
	v_mfma_f32_16x16x32_bf16 v[62:65], v[240:243], v[200:203], v[62:65]
	v_mfma_f32_16x16x32_bf16 v[58:61], v[240:243], v[204:207], v[58:61]
	v_mfma_f32_16x16x32_bf16 v[54:57], v[240:243], v[208:211], v[54:57]
	v_mfma_f32_16x16x32_bf16 v[50:53], v[240:243], v[212:215], v[50:53]
	v_mfma_f32_16x16x32_bf16 v[46:49], v[240:243], v[216:219], v[46:49]
	v_mfma_f32_16x16x32_bf16 v[42:45], v[240:243], v[220:223], v[42:45]
	v_mfma_f32_16x16x32_bf16 v[38:41], v[240:243], v[224:227], v[38:41]
	v_mfma_f32_16x16x32_bf16 v[34:37], v[240:243], v[228:231], v[34:37]
	s_setprio 0
	s_nop 0
	v_mfma_f32_16x16x32_bf16 v[30:33], v[244:247], v[200:203], v[30:33]
	v_mfma_f32_16x16x32_bf16 v[26:29], v[244:247], v[204:207], v[26:29]
	v_mfma_f32_16x16x32_bf16 v[22:25], v[244:247], v[208:211], v[22:25]
	v_mfma_f32_16x16x32_bf16 v[18:21], v[244:247], v[212:215], v[18:21]
	v_mfma_f32_16x16x32_bf16 v[14:17], v[244:247], v[216:219], v[14:17]
	v_mfma_f32_16x16x32_bf16 v[10:13], v[244:247], v[220:223], v[10:13]
	v_mfma_f32_16x16x32_bf16 v[6:9], v[244:247], v[224:227], v[6:9]
	v_mfma_f32_16x16x32_bf16 v[2:5], v[244:247], v[228:231], v[2:5]
	s_mov_b32 s41, s40
	s_nop 0
	s_add_i32 s40, s40, 0x6000
	s_cmp_eq_u32 s40, 0x12000
	s_cselect_b32 s40, 0, s40
	s_nop 0
	.p2align 3
	s_waitcnt vmcnt(0) lgkmcnt(0)
	s_barrier
	s_setprio 1
	v_add_u32_e32 v144, s40, v136
	v_mfma_f32_16x16x32_bf16 v[126:129], v[184:187], v[146:149], v[126:129]
	ds_read_b128 v[200:203], v144 offset:0
	v_mfma_f32_16x16x32_bf16 v[122:125], v[184:187], v[152:155], v[122:125]
	ds_read_b128 v[204:207], v144 offset:1024
	v_mfma_f32_16x16x32_bf16 v[118:121], v[184:187], v[156:159], v[118:121]
	ds_read_b128 v[208:211], v144 offset:2048
	v_mfma_f32_16x16x32_bf16 v[114:117], v[184:187], v[162:165], v[114:117]
	ds_read_b128 v[212:215], v144 offset:3072
	v_mfma_f32_16x16x32_bf16 v[110:113], v[184:187], v[166:169], v[110:113]
	ds_read_b128 v[216:219], v144 offset:4096
	v_mfma_f32_16x16x32_bf16 v[106:109], v[184:187], v[170:173], v[106:109]
	ds_read_b128 v[220:223], v144 offset:5120
	v_mfma_f32_16x16x32_bf16 v[102:105], v[184:187], v[176:179], v[102:105]
	ds_read_b128 v[224:227], v144 offset:6144
	v_mfma_f32_16x16x32_bf16 v[98:101], v[184:187], v[180:183], v[98:101]
	ds_read_b128 v[228:231], v144 offset:7168
	v_mfma_f32_16x16x32_bf16 v[94:97], v[188:191], v[146:149], v[94:97]
	v_add_u32_e64 v144, s40, v137
	v_mfma_f32_16x16x32_bf16 v[90:93], v[188:191], v[152:155], v[90:93]
	v_mfma_f32_16x16x32_bf16 v[86:89], v[188:191], v[156:159], v[86:89]
	ds_read_b128 v[232:235], v144 offset:16384
	v_mfma_f32_16x16x32_bf16 v[82:85], v[188:191], v[162:165], v[82:85]
	ds_read_b128 v[236:239], v144 offset:17408
	v_mfma_f32_16x16x32_bf16 v[78:81], v[188:191], v[166:169], v[78:81]
	ds_read_b128 v[240:243], v144 offset:18432
	v_mfma_f32_16x16x32_bf16 v[74:77], v[188:191], v[170:173], v[74:77]
	ds_read_b128 v[244:247], v144 offset:19456
	v_mfma_f32_16x16x32_bf16 v[70:73], v[188:191], v[176:179], v[70:73]
	v_mfma_f32_16x16x32_bf16 v[66:69], v[188:191], v[180:183], v[66:69]
	v_mfma_f32_16x16x32_bf16 v[62:65], v[192:195], v[146:149], v[62:65]
	v_mfma_f32_16x16x32_bf16 v[58:61], v[192:195], v[152:155], v[58:61]
	v_mfma_f32_16x16x32_bf16 v[54:57], v[192:195], v[156:159], v[54:57]
	v_mfma_f32_16x16x32_bf16 v[50:53], v[192:195], v[162:165], v[50:53]
	v_mfma_f32_16x16x32_bf16 v[46:49], v[192:195], v[166:169], v[46:49]
	v_mfma_f32_16x16x32_bf16 v[42:45], v[192:195], v[170:173], v[42:45]
	v_mfma_f32_16x16x32_bf16 v[38:41], v[192:195], v[176:179], v[38:41]
	v_mfma_f32_16x16x32_bf16 v[34:37], v[192:195], v[180:183], v[34:37]
	s_setprio 0
	s_nop 0
	v_mfma_f32_16x16x32_bf16 v[30:33], v[196:199], v[146:149], v[30:33]
	v_mfma_f32_16x16x32_bf16 v[26:29], v[196:199], v[152:155], v[26:29]
	v_mfma_f32_16x16x32_bf16 v[22:25], v[196:199], v[156:159], v[22:25]
	v_mfma_f32_16x16x32_bf16 v[18:21], v[196:199], v[162:165], v[18:21]
	v_mfma_f32_16x16x32_bf16 v[14:17], v[196:199], v[166:169], v[14:17]
	v_mfma_f32_16x16x32_bf16 v[10:13], v[196:199], v[170:173], v[10:13]
	v_mfma_f32_16x16x32_bf16 v[6:9], v[196:199], v[176:179], v[6:9]
	v_mfma_f32_16x16x32_bf16 v[2:5], v[196:199], v[180:183], v[2:5]
	s_mov_b32 s41, s40
	s_nop 0
	s_add_i32 s40, s40, 0x6000
	s_cmp_eq_u32 s40, 0x12000
	s_cselect_b32 s40, 0, s40
	s_nop 0
	s_mov_b32 s4, 0x8000
	s_mov_b32 s5, 0
	s_mov_b32 s10, 0x10000
	s_mov_b32 s11, 0
	s_mov_b32 s44, 0x3fd744fd
	.p2align 3
	s_waitcnt lgkmcnt(0)
; DEVI unsigned pack2(float a, float b) { return __builtin_bit_cast(unsigned, __builtin_convertvector((f32x2_t){a, b}, bf16x2_t)); }
; DEVI float blo(unsigned u) { return __uint_as_float(u << 16); }
; DEVI float bhi(unsigned u) { return __uint_as_float(u & 0xffff0000u); }
; DEVI float siluf_(float x) { return x * __builtin_amdgcn_rcpf(1.f + __expf(-x)); }
;     ...
; #pragma unroll
;     for (int nf = 0; nf < 4; nf++)
; #pragma unroll
;       for (int mf = 0; mf < 8; mf++)
;         acc[nf][mf] = __builtin_amdgcn_mfma_f32_16x16x32_bf16(wb[nf], xa[mf], acc[nf][mf], 0, 0, 0);
;   }
;     ...
; #pragma unroll
;   for (int mf = 0; mf < 8; mf++) {
;     const int row = m0 + wm * 128 + mf * 16 + r16;
;     if (EPI == EPI_SWIGLU) {
; #pragma unroll
;       for (int nf = 0; nf < 2; nf++) {
;         const int hcol = (n0 >> 1) + wn * 32 + nf * 16 + quad * 4;
;         f32x4 g = acc[nf][mf], u = acc[nf + 2][mf];
;         u32x2 pk;
;         pk[0] = pack2(siluf_(g[0]) * u[0], siluf_(g[1]) * u[1]);
;         pk[1] = pack2(siluf_(g[2]) * u[2], siluf_(g[3]) * u[3]);
;         *(u32x2*)(outb + (size_t)row * DFF + hcol) = pk;
;       }
;     } else {
; #pragma unroll
;       for (int nf = 0; nf < 4; nf++) {
;         const int col = n0 + wn * 64 + nf * 16 + quad * 4;
;         f32x4 a = acc[nf][mf];
;         if (EPI == EPI_RESID || EPI == EPI_RESID_ATOMIC) {
;           f32x4 x = a;
;           if (EPI == EPI_RESID || kpart == 0) {
;             const u32x2 xr = *(const u32x2*)((const u16*)(p.ws + WS_XB) + (size_t)row * 1024 + col);
;             x[0] += ALPHA * blo(xr[0]); x[1] += ALPHA * bhi(xr[0]); x[2] += ALPHA * blo(xr[1]); x[3] += ALPHA * bhi(xr[1]);
;           }
;           if (EPI == EPI_RESID) *(f32x4*)((float*)(p.ws + WS_XF) + (size_t)row * 1024 + col) = x;
;           else *(f32x4*)((float*)(p.ws + WS_SLAB) + ((size_t)kpart * 512 + (row - T_P)) * 1024 + col) = x;
	s_nop 0
	v_mfma_f32_16x16x32_bf16 v[126:129], v[232:235], v[200:203], v[126:129]
	v_mfma_f32_16x16x32_bf16 v[122:125], v[232:235], v[204:207], v[122:125]
	v_mfma_f32_16x16x32_bf16 v[118:121], v[232:235], v[208:211], v[118:121]
	v_mfma_f32_16x16x32_bf16 v[114:117], v[232:235], v[212:215], v[114:117]
	v_mfma_f32_16x16x32_bf16 v[110:113], v[232:235], v[216:219], v[110:113]
	v_mfma_f32_16x16x32_bf16 v[106:109], v[232:235], v[220:223], v[106:109]
	v_mfma_f32_16x16x32_bf16 v[102:105], v[232:235], v[224:227], v[102:105]
	v_mfma_f32_16x16x32_bf16 v[98:101], v[232:235], v[228:231], v[98:101]
	v_mfma_f32_16x16x32_bf16 v[94:97], v[236:239], v[200:203], v[94:97]
	v_mfma_f32_16x16x32_bf16 v[90:93], v[236:239], v[204:207], v[90:93]
	v_mfma_f32_16x16x32_bf16 v[86:89], v[236:239], v[208:211], v[86:89]
	v_mfma_f32_16x16x32_bf16 v[82:85], v[236:239], v[212:215], v[82:85]
	v_mfma_f32_16x16x32_bf16 v[78:81], v[236:239], v[216:219], v[78:81]
	v_mfma_f32_16x16x32_bf16 v[74:77], v[236:239], v[220:223], v[74:77]
	v_mfma_f32_16x16x32_bf16 v[70:73], v[236:239], v[224:227], v[70:73]
	v_mfma_f32_16x16x32_bf16 v[66:69], v[236:239], v[228:231], v[66:69]
	v_mfma_f32_16x16x32_bf16 v[62:65], v[240:243], v[200:203], v[62:65]
	v_mfma_f32_16x16x32_bf16 v[58:61], v[240:243], v[204:207], v[58:61]
	v_mfma_f32_16x16x32_bf16 v[54:57], v[240:243], v[208:211], v[54:57]
	v_mfma_f32_16x16x32_bf16 v[50:53], v[240:243], v[212:215], v[50:53]
	v_mfma_f32_16x16x32_bf16 v[46:49], v[240:243], v[216:219], v[46:49]
	v_mfma_f32_16x16x32_bf16 v[42:45], v[240:243], v[220:223], v[42:45]
	v_mfma_f32_16x16x32_bf16 v[38:41], v[240:243], v[224:227], v[38:41]
	v_mfma_f32_16x16x32_bf16 v[34:37], v[240:243], v[228:231], v[34:37]
	v_mfma_f32_16x16x32_bf16 v[30:33], v[244:247], v[200:203], v[30:33]
	v_mfma_f32_16x16x32_bf16 v[26:29], v[244:247], v[204:207], v[26:29]
	v_mfma_f32_16x16x32_bf16 v[22:25], v[244:247], v[208:211], v[22:25]
	v_mfma_f32_16x16x32_bf16 v[18:21], v[244:247], v[212:215], v[18:21]
	v_mfma_f32_16x16x32_bf16 v[14:17], v[244:247], v[216:219], v[14:17]
	v_mfma_f32_16x16x32_bf16 v[10:13], v[244:247], v[220:223], v[10:13]
	v_mfma_f32_16x16x32_bf16 v[6:9], v[244:247], v[224:227], v[6:9]
	v_mfma_f32_16x16x32_bf16 v[2:5], v[244:247], v[228:231], v[2:5]
	s_mov_b32 m0, s43
	s_cmp_eq_u32 s47, 0
	s_cbranch_scc1 .Lta11_first
	s_nop 7
	global_store_dwordx4 v[140:141], v[126:129], off offset:0
	global_store_dwordx4 v[140:141], v[94:97], off offset:64
	global_store_dwordx4 v[140:141], v[62:65], off offset:128
	global_store_dwordx4 v[140:141], v[30:33], off offset:192
	v_lshl_add_u64 v[140:141], v[140:141], 0, s[10:11]
	global_store_dwordx4 v[140:141], v[122:125], off offset:0
	global_store_dwordx4 v[140:141], v[90:93], off offset:64
	global_store_dwordx4 v[140:141], v[58:61], off offset:128
	global_store_dwordx4 v[140:141], v[26:29], off offset:192
	v_lshl_add_u64 v[140:141], v[140:141], 0, s[10:11]
	global_store_dwordx4 v[140:141], v[118:121], off offset:0
	global_store_dwordx4 v[140:141], v[86:89], off offset:64
	global_store_dwordx4 v[140:141], v[54:57], off offset:128
	global_store_dwordx4 v[140:141], v[22:25], off offset:192
	v_lshl_add_u64 v[140:141], v[140:141], 0, s[10:11]
	global_store_dwordx4 v[140:141], v[114:117], off offset:0
	global_store_dwordx4 v[140:141], v[82:85], off offset:64
	global_store_dwordx4 v[140:141], v[50:53], off offset:128
	global_store_dwordx4 v[140:141], v[18:21], off offset:192
	v_lshl_add_u64 v[140:141], v[140:141], 0, s[10:11]
	global_store_dwordx4 v[140:141], v[110:113], off offset:0
	global_store_dwordx4 v[140:141], v[78:81], off offset:64
	global_store_dwordx4 v[140:141], v[46:49], off offset:128
	global_store_dwordx4 v[140:141], v[14:17], off offset:192
	v_lshl_add_u64 v[140:141], v[140:141], 0, s[10:11]
	global_store_dwordx4 v[140:141], v[106:109], off offset:0
	global_store_dwordx4 v[140:141], v[74:77], off offset:64
	global_store_dwordx4 v[140:141], v[42:45], off offset:128
	global_store_dwordx4 v[140:141], v[10:13], off offset:192
	v_lshl_add_u64 v[140:141], v[140:141], 0, s[10:11]
	global_store_dwordx4 v[140:141], v[102:105], off offset:0
	global_store_dwordx4 v[140:141], v[70:73], off offset:64
	global_store_dwordx4 v[140:141], v[38:41], off offset:128
	global_store_dwordx4 v[140:141], v[6:9], off offset:192
	v_lshl_add_u64 v[140:141], v[140:141], 0, s[10:11]
	global_store_dwordx4 v[140:141], v[98:101], off offset:0
	global_store_dwordx4 v[140:141], v[66:69], off offset:64
	global_store_dwordx4 v[140:141], v[34:37], off offset:128
	global_store_dwordx4 v[140:141], v[2:5], off offset:192
	v_readlane_b32 s39, v250, 7
	s_cmpk_lg_u32 s39, 0x200
	s_cbranch_scc1 .Lta11_ar1
	s_mov_b32 s39, 1
	v_writelane_b32 v255, s39, 41
	v_readlane_b32 s40, v250, 0
	s_lshr_b32 s41, s40, 3
	s_and_b32 s40, s40, 7
	s_lshl_b32 s40, s40, 6
	s_add_i32 s40, s40, s41
	s_sub_i32 s38, s40, 0x200

;     ...
;   for (int kt = 0; kt < nk; kt++) {
;     if (kt + 1 < nk) asm volatile("s_waitcnt vmcnt(6)" ::: "memory");
;     else asm volatile("s_waitcnt vmcnt(0)" ::: "memory");
;     __builtin_amdgcn_s_barrier();
;     asm volatile("" ::: "memory");
;     if (kt + 2 < nk) G2_STAGE(kt + 2);
;     const char* cS = smem + (kt % 3) * 24576;
;     bf16x8 xa[8], wb[4];
; #pragma unroll
;     for (int f = 0; f < 8; f++) xa[f] = *(const bf16x8*)(cS + aoff + f * 1024);
; #pragma unroll
;     for (int f = 0; f < 4; f++) wb[f] = *(const bf16x8*)(cS + boff + f * 1024);
; #pragma unroll
;     for (int nf = 0; nf < 4; nf++)
; #pragma unroll
;       for (int mf = 0; mf < 8; mf++)
;         acc[nf][mf] = __builtin_amdgcn_mfma_f32_16x16x32_bf16(wb[nf], xa[mf], acc[nf][mf], 0, 0, 0);
;   }
.Lt11_loop:
	.p2align 3
	s_waitcnt vmcnt(6) lgkmcnt(0)
	s_barrier
	s_setprio 1
	v_add_u32_e32 v144, s40, v136
	v_mfma_f32_16x16x32_bf16 v[126:129], v[184:187], v[146:149], v[126:129]
	ds_read_b128 v[200:203], v144 offset:0
	v_mfma_f32_16x16x32_bf16 v[122:125], v[184:187], v[152:155], v[122:125]
	ds_read_b128 v[204:207], v144 offset:1024
	v_mfma_f32_16x16x32_bf16 v[118:121], v[184:187], v[156:159], v[118:121]
	ds_read_b128 v[208:211], v144 offset:2048
	v_mfma_f32_16x16x32_bf16 v[114:117], v[184:187], v[162:165], v[114:117]
	ds_read_b128 v[212:215], v144 offset:3072
	v_mfma_f32_16x16x32_bf16 v[110:113], v[184:187], v[166:169], v[110:113]
	ds_read_b128 v[216:219], v144 offset:4096
	v_mfma_f32_16x16x32_bf16 v[106:109], v[184:187], v[170:173], v[106:109]
	ds_read_b128 v[220:223], v144 offset:5120
	v_mfma_f32_16x16x32_bf16 v[102:105], v[184:187], v[176:179], v[102:105]
	ds_read_b128 v[224:227], v144 offset:6144
	v_mfma_f32_16x16x32_bf16 v[98:101], v[184:187], v[180:183], v[98:101]
	ds_read_b128 v[228:231], v144 offset:7168
	v_mfma_f32_16x16x32_bf16 v[94:97], v[188:191], v[146:149], v[94:97]
	v_add_u32_e64 v144, s40, v137
	v_mfma_f32_16x16x32_bf16 v[90:93], v[188:191], v[152:155], v[90:93]
	v_mfma_f32_16x16x32_bf16 v[86:89], v[188:191], v[156:159], v[86:89]
	ds_read_b128 v[232:235], v144 offset:16384
	v_mfma_f32_16x16x32_bf16 v[82:85], v[188:191], v[162:165], v[82:85]
	ds_read_b128 v[236:239], v144 offset:17408
	v_mfma_f32_16x16x32_bf16 v[78:81], v[188:191], v[166:169], v[78:81]
	ds_read_b128 v[240:243], v144 offset:18432
	s_setprio 2
	s_nop 0
	v_mfma_f32_16x16x32_bf16 v[74:77], v[188:191], v[170:173], v[74:77]
	ds_read_b128 v[244:247], v144 offset:19456
	v_mfma_f32_16x16x32_bf16 v[70:73], v[188:191], v[176:179], v[70:73]
	s_add_i32 s42, s46, s41
	s_mov_b32 m0, s42
	v_lshl_add_u64 v[142:143], v[132:133], 0, s[2:3]
	v_mfma_f32_16x16x32_bf16 v[66:69], v[188:191], v[180:183], v[66:69]
	global_load_lds_dwordx4 v[132:133], off
	s_add_i32 m0, m0, 0x1000
	v_mfma_f32_16x16x32_bf16 v[62:65], v[192:195], v[146:149], v[62:65]
	v_mfma_f32_16x16x32_bf16 v[58:61], v[192:195], v[152:155], v[58:61]
	v_mfma_f32_16x16x32_bf16 v[54:57], v[192:195], v[156:159], v[54:57]
	global_load_lds_dwordx4 v[142:143], off
	v_lshl_add_u64 v[142:143], v[142:143], 0, s[2:3]
	s_add_i32 m0, m0, 0x1000
	v_mfma_f32_16x16x32_bf16 v[50:53], v[192:195], v[162:165], v[50:53]
	v_mfma_f32_16x16x32_bf16 v[46:49], v[192:195], v[166:169], v[46:49]
	v_mfma_f32_16x16x32_bf16 v[42:45], v[192:195], v[170:173], v[42:45]
	global_load_lds_dwordx4 v[142:143], off
	v_lshl_add_u64 v[142:143], v[142:143], 0, s[2:3]
	s_add_i32 m0, m0, 0x1000
	v_mfma_f32_16x16x32_bf16 v[38:41], v[192:195], v[176:179], v[38:41]
	v_mfma_f32_16x16x32_bf16 v[34:37], v[192:195], v[180:183], v[34:37]
	s_setprio 0
	s_nop 0
	v_mfma_f32_16x16x32_bf16 v[30:33], v[196:199], v[146:149], v[30:33]
	global_load_lds_dwordx4 v[142:143], off
	s_add_i32 m0, m0, 0x1000
	v_lshl_add_u64 v[142:143], v[134:135], 0, s[2:3]
	v_mfma_f32_16x16x32_bf16 v[26:29], v[196:199], v[152:155], v[26:29]
	v_mfma_f32_16x16x32_bf16 v[22:25], v[196:199], v[156:159], v[22:25]
	v_mfma_f32_16x16x32_bf16 v[18:21], v[196:199], v[162:165], v[18:21]
	global_load_lds_dwordx4 v[134:135], off
	s_add_i32 m0, m0, 0x1000
	v_lshl_add_u64 v[132:133], v[132:133], 0, s[12:13]
	v_mfma_f32_16x16x32_bf16 v[14:17], v[196:199], v[166:169], v[14:17]
	v_mfma_f32_16x16x32_bf16 v[10:13], v[196:199], v[170:173], v[10:13]
	v_mfma_f32_16x16x32_bf16 v[6:9], v[196:199], v[176:179], v[6:9]
	global_load_lds_dwordx4 v[142:143], off
	v_lshl_add_u64 v[134:135], v[134:135], 0, s[4:5]
	v_mfma_f32_16x16x32_bf16 v[2:5], v[196:199], v[180:183], v[2:5]
	s_mov_b32 s41, s40
	s_nop 0
	s_add_i32 s40, s40, 0x6000
	s_cmp_eq_u32 s40, 0x12000
	s_cselect_b32 s40, 0, s40
	s_nop 0
	.p2align 3
	s_waitcnt vmcnt(6) lgkmcnt(0)
	s_barrier
	s_setprio 1
	v_add_u32_e32 v144, s40, v136
	v_mfma_f32_16x16x32_bf16 v[126:129], v[232:235], v[200:203], v[126:129]
	ds_read_b128 v[146:149], v144 offset:0
	v_mfma_f32_16x16x32_bf16 v[122:125], v[232:235], v[204:207], v[122:125]
	ds_read_b128 v[152:155], v144 offset:1024
	v_mfma_f32_16x16x32_bf16 v[118:121], v[232:235], v[208:211], v[118:121]
	ds_read_b128 v[156:159], v144 offset:2048
	v_mfma_f32_16x16x32_bf16 v[114:117], v[232:235], v[212:215], v[114:117]
	ds_read_b128 v[162:165], v144 offset:3072
	v_mfma_f32_16x16x32_bf16 v[110:113], v[232:235], v[216:219], v[110:113]
	ds_read_b128 v[166:169], v144 offset:4096
	v_mfma_f32_16x16x32_bf16 v[106:109], v[232:235], v[220:223], v[106:109]
	ds_read_b128 v[170:173], v144 offset:5120
	v_mfma_f32_16x16x32_bf16 v[102:105], v[232:235], v[224:227], v[102:105]
	ds_read_b128 v[176:179], v144 offset:6144
	v_mfma_f32_16x16x32_bf16 v[98:101], v[232:235], v[228:231], v[98:101]
	ds_read_b128 v[180:183], v144 offset:7168
	v_mfma_f32_16x16x32_bf16 v[94:97], v[236:239], v[200:203], v[94:97]
	v_add_u32_e64 v144, s40, v137
	v_mfma_f32_16x16x32_bf16 v[90:93], v[236:239], v[204:207], v[90:93]
	v_mfma_f32_16x16x32_bf16 v[86:89], v[236:239], v[208:211], v[86:89]
	ds_read_b128 v[184:187], v144 offset:16384
	v_mfma_f32_16x16x32_bf16 v[82:85], v[236:239], v[212:215], v[82:85]
	ds_read_b128 v[188:191], v144 offset:17408
	v_mfma_f32_16x16x32_bf16 v[78:81], v[236:239], v[216:219], v[78:81]
	ds_read_b128 v[192:195], v144 offset:18432
	s_setprio 2
	s_nop 0
	v_mfma_f32_16x16x32_bf16 v[74:77], v[236:239], v[220:223], v[74:77]
	ds_read_b128 v[196:199], v144 offset:19456
	v_mfma_f32_16x16x32_bf16 v[70:73], v[236:239], v[224:227], v[70:73]
	s_add_i32 s42, s46, s41
	s_mov_b32 m0, s42
	v_lshl_add_u64 v[142:143], v[132:133], 0, s[2:3]
	v_mfma_f32_16x16x32_bf16 v[66:69], v[236:239], v[228:231], v[66:69]
;     ...
;   for (int kt = 0; kt < nk; kt++) {
;     if (kt + 1 < nk) asm volatile("s_waitcnt vmcnt(6)" ::: "memory");
;     else asm volatile("s_waitcnt vmcnt(0)" ::: "memory");
;     __builtin_amdgcn_s_barrier();
;     asm volatile("" ::: "memory");
;     if (kt + 2 < nk) G2_STAGE(kt + 2);
;     const char* cS = smem + (kt % 3) * 24576;
;     bf16x8 xa[8], wb[4];
; #pragma unroll
;     for (int f = 0; f < 8; f++) xa[f] = *(const bf16x8*)(cS + aoff + f * 1024);
; #pragma unroll
;     for (int f = 0; f < 4; f++) wb[f] = *(const bf16x8*)(cS + boff + f * 1024);
; #pragma unroll
;     for (int nf = 0; nf < 4; nf++)
; #pragma unroll
;       for (int mf = 0; mf < 8; mf++)
;         acc[nf][mf] = __builtin_amdgcn_mfma_f32_16x16x32_bf16(wb[nf], xa[mf], acc[nf][mf], 0, 0, 0);
;   }
	global_load_lds_dwordx4 v[132:133], off
	s_add_i32 m0, m0, 0x1000
	v_mfma_f32_16x16x32_bf16 v[62:65], v[240:243], v[200:203], v[62:65]
	v_mfma_f32_16x16x32_bf16 v[58:61], v[240:243], v[204:207], v[58:61]
	v_mfma_f32_16x16x32_bf16 v[54:57], v[240:243], v[208:211], v[54:57]
	global_load_lds_dwordx4 v[142:143], off
	v_lshl_add_u64 v[142:143], v[142:143], 0, s[2:3]
	s_add_i32 m0, m0, 0x1000
	v_mfma_f32_16x16x32_bf16 v[50:53], v[240:243], v[212:215], v[50:53]
	v_mfma_f32_16x16x32_bf16 v[46:49], v[240:243], v[216:219], v[46:49]
	v_mfma_f32_16x16x32_bf16 v[42:45], v[240:243], v[220:223], v[42:45]
	global_load_lds_dwordx4 v[142:143], off
	v_lshl_add_u64 v[142:143], v[142:143], 0, s[2:3]
	s_add_i32 m0, m0, 0x1000
	v_mfma_f32_16x16x32_bf16 v[38:41], v[240:243], v[224:227], v[38:41]
	v_mfma_f32_16x16x32_bf16 v[34:37], v[240:243], v[228:231], v[34:37]
	s_setprio 0
	s_nop 0
	v_mfma_f32_16x16x32_bf16 v[30:33], v[244:247], v[200:203], v[30:33]
	global_load_lds_dwordx4 v[142:143], off
	s_add_i32 m0, m0, 0x1000
	v_lshl_add_u64 v[142:143], v[134:135], 0, s[2:3]
	v_mfma_f32_16x16x32_bf16 v[26:29], v[244:247], v[204:207], v[26:29]
	v_mfma_f32_16x16x32_bf16 v[22:25], v[244:247], v[208:211], v[22:25]
	v_mfma_f32_16x16x32_bf16 v[18:21], v[244:247], v[212:215], v[18:21]
	global_load_lds_dwordx4 v[134:135], off
	s_add_i32 m0, m0, 0x1000
	v_lshl_add_u64 v[132:133], v[132:133], 0, s[12:13]
	v_mfma_f32_16x16x32_bf16 v[14:17], v[244:247], v[216:219], v[14:17]
	v_mfma_f32_16x16x32_bf16 v[10:13], v[244:247], v[220:223], v[10:13]
	v_mfma_f32_16x16x32_bf16 v[6:9], v[244:247], v[224:227], v[6:9]
	global_load_lds_dwordx4 v[142:143], off
	v_lshl_add_u64 v[134:135], v[134:135], 0, s[4:5]
	v_mfma_f32_16x16x32_bf16 v[2:5], v[244:247], v[228:231], v[2:5]
	s_mov_b32 s41, s40
	s_nop 0
	s_add_i32 s40, s40, 0x6000
	s_cmp_eq_u32 s40, 0x12000
	s_cselect_b32 s40, 0, s40
	s_nop 0
	s_sub_i32 s39, s39, 1
	s_cmp_lg_u32 s39, 0
	s_cbranch_scc1 .Lt11_loop
	.p2align 3
	s_waitcnt vmcnt(6) lgkmcnt(0)
	s_barrier
	s_setprio 1
	v_add_u32_e32 v144, s40, v136
	v_mfma_f32_16x16x32_bf16 v[126:129], v[184:187], v[146:149], v[126:129]
	ds_read_b128 v[200:203], v144 offset:0
	v_mfma_f32_16x16x32_bf16 v[122:125], v[184:187], v[152:155], v[122:125]
	ds_read_b128 v[204:207], v144 offset:1024
	v_mfma_f32_16x16x32_bf16 v[118:121], v[184:187], v[156:159], v[118:121]
	ds_read_b128 v[208:211], v144 offset:2048
	v_mfma_f32_16x16x32_bf16 v[114:117], v[184:187], v[162:165], v[114:117]
	ds_read_b128 v[212:215], v144 offset:3072
	v_mfma_f32_16x16x32_bf16 v[110:113], v[184:187], v[166:169], v[110:113]
	ds_read_b128 v[216:219], v144 offset:4096
	v_mfma_f32_16x16x32_bf16 v[106:109], v[184:187], v[170:173], v[106:109]
	ds_read_b128 v[220:223], v144 offset:5120
	v_mfma_f32_16x16x32_bf16 v[102:105], v[184:187], v[176:179], v[102:105]
	ds_read_b128 v[224:227], v144 offset:6144
	v_mfma_f32_16x16x32_bf16 v[98:101], v[184:187], v[180:183], v[98:101]
	ds_read_b128 v[228:231], v144 offset:7168
	v_mfma_f32_16x16x32_bf16 v[94:97], v[188:191], v[146:149], v[94:97]
	v_add_u32_e64 v144, s40, v137
	v_mfma_f32_16x16x32_bf16 v[90:93], v[188:191], v[152:155], v[90:93]
	v_mfma_f32_16x16x32_bf16 v[86:89], v[188:191], v[156:159], v[86:89]
	ds_read_b128 v[232:235], v144 offset:16384
	v_mfma_f32_16x16x32_bf16 v[82:85], v[188:191], v[162:165], v[82:85]
	ds_read_b128 v[236:239], v144 offset:17408
	v_mfma_f32_16x16x32_bf16 v[78:81], v[188:191], v[166:169], v[78:81]
	ds_read_b128 v[240:243], v144 offset:18432
	s_setprio 2
	s_nop 0
	v_mfma_f32_16x16x32_bf16 v[74:77], v[188:191], v[170:173], v[74:77]
	ds_read_b128 v[244:247], v144 offset:19456
	v_mfma_f32_16x16x32_bf16 v[70:73], v[188:191], v[176:179], v[70:73]
	s_add_i32 s42, s46, s41
	s_mov_b32 m0, s42
	v_lshl_add_u64 v[142:143], v[132:133], 0, s[2:3]
	v_mfma_f32_16x16x32_bf16 v[66:69], v[188:191], v[180:183], v[66:69]
	global_load_lds_dwordx4 v[132:133], off
	s_add_i32 m0, m0, 0x1000
	v_mfma_f32_16x16x32_bf16 v[62:65], v[192:195], v[146:149], v[62:65]
	v_mfma_f32_16x16x32_bf16 v[58:61], v[192:195], v[152:155], v[58:61]
	v_mfma_f32_16x16x32_bf16 v[54:57], v[192:195], v[156:159], v[54:57]
	global_load_lds_dwordx4 v[142:143], off
	v_lshl_add_u64 v[142:143], v[142:143], 0, s[2:3]
	s_add_i32 m0, m0, 0x1000
	v_mfma_f32_16x16x32_bf16 v[50:53], v[192:195], v[162:165], v[50:53]
	v_mfma_f32_16x16x32_bf16 v[46:49], v[192:195], v[166:169], v[46:49]
	v_mfma_f32_16x16x32_bf16 v[42:45], v[192:195], v[170:173], v[42:45]
	global_load_lds_dwordx4 v[142:143], off
	v_lshl_add_u64 v[142:143], v[142:143], 0, s[2:3]
	s_add_i32 m0, m0, 0x1000
	v_mfma_f32_16x16x32_bf16 v[38:41], v[192:195], v[176:179], v[38:41]
	v_mfma_f32_16x16x32_bf16 v[34:37], v[192:195], v[180:183], v[34:37]
	s_setprio 0
	s_nop 0
	v_mfma_f32_16x16x32_bf16 v[30:33], v[196:199], v[146:149], v[30:33]
	global_load_lds_dwordx4 v[142:143], off
	s_add_i32 m0, m0, 0x1000
	v_lshl_add_u64 v[142:143], v[134:135], 0, s[2:3]
	v_mfma_f32_16x16x32_bf16 v[26:29], v[196:199], v[152:155], v[26:29]
	v_mfma_f32_16x16x32_bf16 v[22:25], v[196:199], v[156:159], v[22:25]
	v_mfma_f32_16x16x32_bf16 v[18:21], v[196:199], v[162:165], v[18:21]
	global_load_lds_dwordx4 v[134:135], off
	s_add_i32 m0, m0, 0x1000
	v_lshl_add_u64 v[132:133], v[132:133], 0, s[12:13]
	v_mfma_f32_16x16x32_bf16 v[14:17], v[196:199], v[166:169], v[14:17]
	v_mfma_f32_16x16x32_bf16 v[10:13], v[196:199], v[170:173], v[10:13]
	v_mfma_f32_16x16x32_bf16 v[6:9], v[196:199], v[176:179], v[6:9]
	global_load_lds_dwordx4 v[142:143], off
	v_lshl_add_u64 v[134:135], v[134:135], 0, s[4:5]
	v_mfma_f32_16x16x32_bf16 v[2:5], v[196:199], v[180:183], v[2:5]
	s_mov_b32 s41, s40
	s_nop 0
	s_add_i32 s40, s40, 0x6000
	s_cmp_eq_u32 s40, 0x12000
	s_cselect_b32 s40, 0, s40
	s_nop 0
	.p2align 3
	s_waitcnt vmcnt(6) lgkmcnt(0)
	s_barrier
;     ...
;   for (int kt = 0; kt < nk; kt++) {
;     if (kt + 1 < nk) asm volatile("s_waitcnt vmcnt(6)" ::: "memory");
;     else asm volatile("s_waitcnt vmcnt(0)" ::: "memory");
;     __builtin_amdgcn_s_barrier();
;     asm volatile("" ::: "memory");
;     if (kt + 2 < nk) G2_STAGE(kt + 2);
;     const char* cS = smem + (kt % 3) * 24576;
;     bf16x8 xa[8], wb[4];
; #pragma unroll
;     for (int f = 0; f < 8; f++) xa[f] = *(const bf16x8*)(cS + aoff + f * 1024);
; #pragma unroll
;     for (int f = 0; f < 4; f++) wb[f] = *(const bf16x8*)(cS + boff + f * 1024);
; #pragma unroll
;     for (int nf = 0; nf < 4; nf++)
; #pragma unroll
;       for (int mf = 0; mf < 8; mf++)
;         acc[nf][mf] = __builtin_amdgcn_mfma_f32_16x16x32_bf16(wb[nf], xa[mf], acc[nf][mf], 0, 0, 0);
	s_setprio 1
	v_add_u32_e32 v144, s40, v136
	v_mfma_f32_16x16x32_bf16 v[126:129], v[232:235], v[200:203], v[126:129]
	ds_read_b128 v[146:149], v144 offset:0
	v_mfma_f32_16x16x32_bf16 v[122:125], v[232:235], v[204:207], v[122:125]
	ds_read_b128 v[152:155], v144 offset:1024
	v_mfma_f32_16x16x32_bf16 v[118:121], v[232:235], v[208:211], v[118:121]
	ds_read_b128 v[156:159], v144 offset:2048
	v_mfma_f32_16x16x32_bf16 v[114:117], v[232:235], v[212:215], v[114:117]
	ds_read_b128 v[162:165], v144 offset:3072
	v_mfma_f32_16x16x32_bf16 v[110:113], v[232:235], v[216:219], v[110:113]
	ds_read_b128 v[166:169], v144 offset:4096
	v_mfma_f32_16x16x32_bf16 v[106:109], v[232:235], v[220:223], v[106:109]
	ds_read_b128 v[170:173], v144 offset:5120
	v_mfma_f32_16x16x32_bf16 v[102:105], v[232:235], v[224:227], v[102:105]
	ds_read_b128 v[176:179], v144 offset:6144
	v_mfma_f32_16x16x32_bf16 v[98:101], v[232:235], v[228:231], v[98:101]
	ds_read_b128 v[180:183], v144 offset:7168
	v_mfma_f32_16x16x32_bf16 v[94:97], v[236:239], v[200:203], v[94:97]
	v_add_u32_e64 v144, s40, v137
	v_mfma_f32_16x16x32_bf16 v[90:93], v[236:239], v[204:207], v[90:93]
	v_mfma_f32_16x16x32_bf16 v[86:89], v[236:239], v[208:211], v[86:89]
	ds_read_b128 v[184:187], v144 offset:16384
	v_mfma_f32_16x16x32_bf16 v[82:85], v[236:239], v[212:215], v[82:85]
	ds_read_b128 v[188:191], v144 offset:17408
	v_mfma_f32_16x16x32_bf16 v[78:81], v[236:239], v[216:219], v[78:81]
	ds_read_b128 v[192:195], v144 offset:18432
	v_mfma_f32_16x16x32_bf16 v[74:77], v[236:239], v[220:223], v[74:77]
	ds_read_b128 v[196:199], v144 offset:19456
	v_mfma_f32_16x16x32_bf16 v[70:73], v[236:239], v[224:227], v[70:73]
	v_mfma_f32_16x16x32_bf16 v[66:69], v[236:239], v[228:231], v[66:69]
	v_mfma_f32_16x16x32_bf16 v[62:65], v[240:243], v[200:203], v[62:65]
	v_mfma_f32_16x16x32_bf16 v[58:61], v[240:243], v[204:207], v[58:61]
	v_mfma_f32_16x16x32_bf16 v[54:57], v[240:243], v[208:211], v[54:57]
	v_mfma_f32_16x16x32_bf16 v[50:53], v[240:243], v[212:215], v[50:53]
	v_mfma_f32_16x16x32_bf16 v[46:49], v[240:243], v[216:219], v[46:49]
	v_mfma_f32_16x16x32_bf16 v[42:45], v[240:243], v[220:223], v[42:45]
	v_mfma_f32_16x16x32_bf16 v[38:41], v[240:243], v[224:227], v[38:41]
	v_mfma_f32_16x16x32_bf16 v[34:37], v[240:243], v[228:231], v[34:37]
	s_setprio 0
	s_nop 0
	v_mfma_f32_16x16x32_bf16 v[30:33], v[244:247], v[200:203], v[30:33]
	v_mfma_f32_16x16x32_bf16 v[26:29], v[244:247], v[204:207], v[26:29]
	v_mfma_f32_16x16x32_bf16 v[22:25], v[244:247], v[208:211], v[22:25]
	v_mfma_f32_16x16x32_bf16 v[18:21], v[244:247], v[212:215], v[18:21]
	v_mfma_f32_16x16x32_bf16 v[14:17], v[244:247], v[216:219], v[14:17]
	v_mfma_f32_16x16x32_bf16 v[10:13], v[244:247], v[220:223], v[10:13]
	v_mfma_f32_16x16x32_bf16 v[6:9], v[244:247], v[224:227], v[6:9]
	v_mfma_f32_16x16x32_bf16 v[2:5], v[244:247], v[228:231], v[2:5]
	s_mov_b32 s41, s40
	s_nop 0
	s_add_i32 s40, s40, 0x6000
	s_cmp_eq_u32 s40, 0x12000
	s_cselect_b32 s40, 0, s40
	s_nop 0
	.p2align 3
	s_waitcnt vmcnt(0) lgkmcnt(0)
	s_barrier
	s_setprio 1
	v_add_u32_e32 v144, s40, v136
	v_mfma_f32_16x16x32_bf16 v[126:129], v[184:187], v[146:149], v[126:129]
	ds_read_b128 v[200:203], v144 offset:0
	v_mfma_f32_16x16x32_bf16 v[122:125], v[184:187], v[152:155], v[122:125]
	ds_read_b128 v[204:207], v144 offset:1024
	v_mfma_f32_16x16x32_bf16 v[118:121], v[184:187], v[156:159], v[118:121]
	ds_read_b128 v[208:211], v144 offset:2048
	v_mfma_f32_16x16x32_bf16 v[114:117], v[184:187], v[162:165], v[114:117]
	ds_read_b128 v[212:215], v144 offset:3072
	v_mfma_f32_16x16x32_bf16 v[110:113], v[184:187], v[166:169], v[110:113]
	ds_read_b128 v[216:219], v144 offset:4096
	v_mfma_f32_16x16x32_bf16 v[106:109], v[184:187], v[170:173], v[106:109]
	ds_read_b128 v[220:223], v144 offset:5120
	v_mfma_f32_16x16x32_bf16 v[102:105], v[184:187], v[176:179], v[102:105]
	ds_read_b128 v[224:227], v144 offset:6144
	v_mfma_f32_16x16x32_bf16 v[98:101], v[184:187], v[180:183], v[98:101]
	ds_read_b128 v[228:231], v144 offset:7168
	v_mfma_f32_16x16x32_bf16 v[94:97], v[188:191], v[146:149], v[94:97]
	v_add_u32_e64 v144, s40, v137
	v_mfma_f32_16x16x32_bf16 v[90:93], v[188:191], v[152:155], v[90:93]
	v_mfma_f32_16x16x32_bf16 v[86:89], v[188:191], v[156:159], v[86:89]
	ds_read_b128 v[232:235], v144 offset:16384
	v_mfma_f32_16x16x32_bf16 v[82:85], v[188:191], v[162:165], v[82:85]
	ds_read_b128 v[236:239], v144 offset:17408
	v_mfma_f32_16x16x32_bf16 v[78:81], v[188:191], v[166:169], v[78:81]
	ds_read_b128 v[240:243], v144 offset:18432
	v_mfma_f32_16x16x32_bf16 v[74:77], v[188:191], v[170:173], v[74:77]
	ds_read_b128 v[244:247], v144 offset:19456
	v_mfma_f32_16x16x32_bf16 v[70:73], v[188:191], v[176:179], v[70:73]
	v_mfma_f32_16x16x32_bf16 v[66:69], v[188:191], v[180:183], v[66:69]
	v_mfma_f32_16x16x32_bf16 v[62:65], v[192:195], v[146:149], v[62:65]
	v_mfma_f32_16x16x32_bf16 v[58:61], v[192:195], v[152:155], v[58:61]
	v_mfma_f32_16x16x32_bf16 v[54:57], v[192:195], v[156:159], v[54:57]
	v_mfma_f32_16x16x32_bf16 v[50:53], v[192:195], v[162:165], v[50:53]
	v_mfma_f32_16x16x32_bf16 v[46:49], v[192:195], v[166:169], v[46:49]
	v_mfma_f32_16x16x32_bf16 v[42:45], v[192:195], v[170:173], v[42:45]
	v_mfma_f32_16x16x32_bf16 v[38:41], v[192:195], v[176:179], v[38:41]
	v_mfma_f32_16x16x32_bf16 v[34:37], v[192:195], v[180:183], v[34:37]
	s_setprio 0
	s_nop 0
	v_mfma_f32_16x16x32_bf16 v[30:33], v[196:199], v[146:149], v[30:33]
	v_mfma_f32_16x16x32_bf16 v[26:29], v[196:199], v[152:155], v[26:29]
	v_mfma_f32_16x16x32_bf16 v[22:25], v[196:199], v[156:159], v[22:25]
	v_mfma_f32_16x16x32_bf16 v[18:21], v[196:199], v[162:165], v[18:21]
	v_mfma_f32_16x16x32_bf16 v[14:17], v[196:199], v[166:169], v[14:17]
	v_mfma_f32_16x16x32_bf16 v[10:13], v[196:199], v[170:173], v[10:13]
	v_mfma_f32_16x16x32_bf16 v[6:9], v[196:199], v[176:179], v[6:9]
	v_mfma_f32_16x16x32_bf16 v[2:5], v[196:199], v[180:183], v[2:5]
	s_mov_b32 s41, s40
	s_nop 0
	s_add_i32 s40, s40, 0x6000
	s_cmp_eq_u32 s40, 0x12000
	s_cselect_b32 s40, 0, s40
	s_nop 0
	s_mov_b32 s4, 0x8000
	s_mov_b32 s5, 0
	s_mov_b32 s10, 0x10000
	s_mov_b32 s11, 0
	s_mov_b32 s44, 0x3fd744fd
	.p2align 3
	s_waitcnt lgkmcnt(0)
; DEVI float blo(unsigned u) { return __uint_as_float(u << 16); }
; DEVI float bhi(unsigned u) { return __uint_as_float(u & 0xffff0000u); }
;     ...
;       for (int nf = 0; nf < 4; nf++) {
;         const int col = n0 + wn * 64 + nf * 16 + quad * 4;
;         f32x4 a = acc[nf][mf];
;         if (EPI == EPI_RESID || EPI == EPI_RESID_ATOMIC) {
;           f32x4 x = a;
;           if (EPI == EPI_RESID || kpart == 0) {
;             const u32x2 xr = *(const u32x2*)((const u16*)(p.ws + WS_XB) + (size_t)row * 1024 + col);
;             x[0] += ALPHA * blo(xr[0]); x[1] += ALPHA * bhi(xr[0]); x[2] += ALPHA * blo(xr[1]); x[3] += ALPHA * bhi(xr[1]);
;           }
;           if (EPI == EPI_RESID) *(f32x4*)((float*)(p.ws + WS_XF) + (size_t)row * 1024 + col) = x;
;           else *(f32x4*)((float*)(p.ws + WS_SLAB) + ((size_t)kpart * 512 + (row - T_P)) * 1024 + col) = x;
	s_nop 0
	v_mfma_f32_16x16x32_bf16 v[126:129], v[232:235], v[200:203], v[126:129]
	v_mfma_f32_16x16x32_bf16 v[122:125], v[232:235], v[204:207], v[122:125]
	v_mfma_f32_16x16x32_bf16 v[118:121], v[232:235], v[208:211], v[118:121]
	v_mfma_f32_16x16x32_bf16 v[114:117], v[232:235], v[212:215], v[114:117]
	v_mfma_f32_16x16x32_bf16 v[110:113], v[232:235], v[216:219], v[110:113]
	global_load_dwordx4 v[146:149], v[138:139], off offset:0
	v_mfma_f32_16x16x32_bf16 v[106:109], v[232:235], v[220:223], v[106:109]
	v_mfma_f32_16x16x32_bf16 v[102:105], v[232:235], v[224:227], v[102:105]
	global_load_dwordx4 v[152:155], v[138:139], off offset:128
	v_mfma_f32_16x16x32_bf16 v[98:101], v[232:235], v[228:231], v[98:101]
	v_lshl_add_u64 v[138:139], v[138:139], 0, s[4:5]
	v_mfma_f32_16x16x32_bf16 v[94:97], v[236:239], v[200:203], v[94:97]
	global_load_dwordx4 v[156:159], v[138:139], off offset:0
	v_mfma_f32_16x16x32_bf16 v[90:93], v[236:239], v[204:207], v[90:93]
	v_mfma_f32_16x16x32_bf16 v[86:89], v[236:239], v[208:211], v[86:89]
	global_load_dwordx4 v[162:165], v[138:139], off offset:128
	v_mfma_f32_16x16x32_bf16 v[82:85], v[236:239], v[212:215], v[82:85]
	v_lshl_add_u64 v[138:139], v[138:139], 0, s[4:5]
	v_mfma_f32_16x16x32_bf16 v[78:81], v[236:239], v[216:219], v[78:81]
	global_load_dwordx4 v[166:169], v[138:139], off offset:0
	v_mfma_f32_16x16x32_bf16 v[74:77], v[236:239], v[220:223], v[74:77]
	v_mfma_f32_16x16x32_bf16 v[70:73], v[236:239], v[224:227], v[70:73]
	global_load_dwordx4 v[170:173], v[138:139], off offset:128
	v_mfma_f32_16x16x32_bf16 v[66:69], v[236:239], v[228:231], v[66:69]
	v_lshl_add_u64 v[138:139], v[138:139], 0, s[4:5]
	v_mfma_f32_16x16x32_bf16 v[62:65], v[240:243], v[200:203], v[62:65]
	global_load_dwordx4 v[176:179], v[138:139], off offset:0
	v_mfma_f32_16x16x32_bf16 v[58:61], v[240:243], v[204:207], v[58:61]
	v_mfma_f32_16x16x32_bf16 v[54:57], v[240:243], v[208:211], v[54:57]
	global_load_dwordx4 v[180:183], v[138:139], off offset:128
	v_mfma_f32_16x16x32_bf16 v[50:53], v[240:243], v[212:215], v[50:53]
	v_lshl_add_u64 v[138:139], v[138:139], 0, s[4:5]
	v_mfma_f32_16x16x32_bf16 v[46:49], v[240:243], v[216:219], v[46:49]
	global_load_dwordx4 v[184:187], v[138:139], off offset:0
	v_mfma_f32_16x16x32_bf16 v[42:45], v[240:243], v[220:223], v[42:45]
	v_mfma_f32_16x16x32_bf16 v[38:41], v[240:243], v[224:227], v[38:41]
	global_load_dwordx4 v[188:191], v[138:139], off offset:128
	v_mfma_f32_16x16x32_bf16 v[34:37], v[240:243], v[228:231], v[34:37]
	v_lshl_add_u64 v[138:139], v[138:139], 0, s[4:5]
	v_mfma_f32_16x16x32_bf16 v[30:33], v[244:247], v[200:203], v[30:33]
	global_load_dwordx4 v[192:195], v[138:139], off offset:0
	v_mfma_f32_16x16x32_bf16 v[26:29], v[244:247], v[204:207], v[26:29]
	v_mfma_f32_16x16x32_bf16 v[22:25], v[244:247], v[208:211], v[22:25]
	global_load_dwordx4 v[196:199], v[138:139], off offset:128
	v_mfma_f32_16x16x32_bf16 v[18:21], v[244:247], v[212:215], v[18:21]
	v_lshl_add_u64 v[138:139], v[138:139], 0, s[4:5]
	v_mfma_f32_16x16x32_bf16 v[14:17], v[244:247], v[216:219], v[14:17]
	v_mfma_f32_16x16x32_bf16 v[10:13], v[244:247], v[220:223], v[10:13]
	v_mfma_f32_16x16x32_bf16 v[6:9], v[244:247], v[224:227], v[6:9]
	v_mfma_f32_16x16x32_bf16 v[2:5], v[244:247], v[228:231], v[2:5]
	s_mov_b32 m0, s43
	global_load_dwordx4 v[200:203], v[138:139], off offset:0
	global_load_dwordx4 v[204:207], v[138:139], off offset:128
	v_lshl_add_u64 v[138:139], v[138:139], 0, s[4:5]
	global_load_dwordx4 v[208:211], v[138:139], off offset:0
	global_load_dwordx4 v[212:215], v[138:139], off offset:128
	v_lshl_add_u64 v[138:139], v[138:139], 0, s[4:5]
	s_nop 7
	v_and_b32_e32 v228, 1, v145
	v_cmp_ne_u32_e32 vcc, 0, v228
	v_mov_b32_e32 v229, 0xfffff040
	v_cndmask_b32_e32 v230, 0, v229, vcc
	v_ashrrev_i32_e32 v231, 31, v230
	v_lshl_add_u64 v[140:141], v[140:141], 0, v[230:231]
	v_add_co_u32_e32 v142, vcc, 0x1000, v140
	s_nop 0
	v_addc_co_u32_e32 v143, vcc, 0, v141, vcc
	v_cmp_ne_u32_e32 vcc, 0, v228
	s_waitcnt vmcnt(15)
	v_permlane16_swap_b32_e32 v146, v148
	v_permlane16_swap_b32_e32 v147, v149
	v_lshlrev_b32_e32 v216, 16, v146
	v_and_b32_e32 v146, 0xffff0000, v146
	v_lshlrev_b32_e32 v217, 16, v147
	v_and_b32_e32 v147, 0xffff0000, v147
	v_fmac_f32_e32 v126, s44, v216
	v_fmac_f32_e32 v127, s44, v146
	v_fmac_f32_e32 v128, s44, v217
	v_fmac_f32_e32 v129, s44, v147
	v_lshlrev_b32_e32 v216, 16, v148
	v_and_b32_e32 v148, 0xffff0000, v148
	v_lshlrev_b32_e32 v217, 16, v149
	v_and_b32_e32 v149, 0xffff0000, v149
	v_fmac_f32_e32 v94, s44, v216
	v_fmac_f32_e32 v95, s44, v148
	v_fmac_f32_e32 v96, s44, v217
	v_fmac_f32_e32 v97, s44, v149
	v_mov_b32_dpp v220, v94 quad_perm:[1,0,3,2] row_mask:0xf bank_mask:0xf
	v_mov_b32_dpp v221, v95 quad_perm:[1,0,3,2] row_mask:0xf bank_mask:0xf
	v_mov_b32_dpp v222, v96 quad_perm:[1,0,3,2] row_mask:0xf bank_mask:0xf
	v_mov_b32_dpp v223, v97 quad_perm:[1,0,3,2] row_mask:0xf bank_mask:0xf
	v_mov_b32_dpp v224, v126 quad_perm:[1,0,3,2] row_mask:0xf bank_mask:0xf
	v_mov_b32_dpp v225, v127 quad_perm:[1,0,3,2] row_mask:0xf bank_mask:0xf
	v_mov_b32_dpp v226, v128 quad_perm:[1,0,3,2] row_mask:0xf bank_mask:0xf
	v_mov_b32_dpp v227, v129 quad_perm:[1,0,3,2] row_mask:0xf bank_mask:0xf
	v_cndmask_b32_e32 v94, v224, v94, vcc
	v_cndmask_b32_e32 v95, v225, v95, vcc
	v_cndmask_b32_e32 v96, v226, v96, vcc
	v_cndmask_b32_e32 v97, v227, v97, vcc
	v_cndmask_b32_e32 v126, v126, v220, vcc
	v_cndmask_b32_e32 v127, v127, v221, vcc
	v_cndmask_b32_e32 v128, v128, v222, vcc
	v_cndmask_b32_e32 v129, v129, v223, vcc
	global_store_dwordx4 v[140:141], v[126:129], off
	global_store_dwordx4 v[142:143], v[94:97], off
	s_waitcnt vmcnt(16)
; DEVI float blo(unsigned u) { return __uint_as_float(u << 16); }
; DEVI float bhi(unsigned u) { return __uint_as_float(u & 0xffff0000u); }
;     ...
;       for (int nf = 0; nf < 4; nf++) {
;         const int col = n0 + wn * 64 + nf * 16 + quad * 4;
;         f32x4 a = acc[nf][mf];
;         if (EPI == EPI_RESID || EPI == EPI_RESID_ATOMIC) {
;           f32x4 x = a;
;           if (EPI == EPI_RESID || kpart == 0) {
;             const u32x2 xr = *(const u32x2*)((const u16*)(p.ws + WS_XB) + (size_t)row * 1024 + col);
;             x[0] += ALPHA * blo(xr[0]); x[1] += ALPHA * bhi(xr[0]); x[2] += ALPHA * blo(xr[1]); x[3] += ALPHA * bhi(xr[1]);
;           }
;           if (EPI == EPI_RESID) *(f32x4*)((float*)(p.ws + WS_XF) + (size_t)row * 1024 + col) = x;
;           else *(f32x4*)((float*)(p.ws + WS_SLAB) + ((size_t)kpart * 512 + (row - T_P)) * 1024 + col) = x;
	v_permlane16_swap_b32_e32 v152, v154
	v_permlane16_swap_b32_e32 v153, v155
	v_lshlrev_b32_e32 v216, 16, v152
	v_and_b32_e32 v152, 0xffff0000, v152
	v_lshlrev_b32_e32 v217, 16, v153
	v_and_b32_e32 v153, 0xffff0000, v153
	v_fmac_f32_e32 v62, s44, v216
	v_fmac_f32_e32 v63, s44, v152
	v_fmac_f32_e32 v64, s44, v217
	v_fmac_f32_e32 v65, s44, v153
	v_lshlrev_b32_e32 v216, 16, v154
	v_and_b32_e32 v154, 0xffff0000, v154
	v_lshlrev_b32_e32 v217, 16, v155
	v_and_b32_e32 v155, 0xffff0000, v155
	v_fmac_f32_e32 v30, s44, v216
	v_fmac_f32_e32 v31, s44, v154
	v_fmac_f32_e32 v32, s44, v217
	v_fmac_f32_e32 v33, s44, v155
	v_mov_b32_dpp v220, v30 quad_perm:[1,0,3,2] row_mask:0xf bank_mask:0xf
	v_mov_b32_dpp v221, v31 quad_perm:[1,0,3,2] row_mask:0xf bank_mask:0xf
	v_mov_b32_dpp v222, v32 quad_perm:[1,0,3,2] row_mask:0xf bank_mask:0xf
	v_mov_b32_dpp v223, v33 quad_perm:[1,0,3,2] row_mask:0xf bank_mask:0xf
	v_mov_b32_dpp v224, v62 quad_perm:[1,0,3,2] row_mask:0xf bank_mask:0xf
	v_mov_b32_dpp v225, v63 quad_perm:[1,0,3,2] row_mask:0xf bank_mask:0xf
	v_mov_b32_dpp v226, v64 quad_perm:[1,0,3,2] row_mask:0xf bank_mask:0xf
	v_mov_b32_dpp v227, v65 quad_perm:[1,0,3,2] row_mask:0xf bank_mask:0xf
	v_cndmask_b32_e32 v30, v224, v30, vcc
	v_cndmask_b32_e32 v31, v225, v31, vcc
	v_cndmask_b32_e32 v32, v226, v32, vcc
	v_cndmask_b32_e32 v33, v227, v33, vcc
	v_cndmask_b32_e32 v62, v62, v220, vcc
	v_cndmask_b32_e32 v63, v63, v221, vcc
	v_cndmask_b32_e32 v64, v64, v222, vcc
	v_cndmask_b32_e32 v65, v65, v223, vcc
	global_store_dwordx4 v[140:141], v[62:65], off offset:128
	global_store_dwordx4 v[142:143], v[30:33], off offset:128
	v_lshl_add_u64 v[140:141], v[140:141], 0, s[10:11]
	v_lshl_add_u64 v[142:143], v[142:143], 0, s[10:11]
	s_waitcnt vmcnt(17)
	v_permlane16_swap_b32_e32 v156, v158
	v_permlane16_swap_b32_e32 v157, v159
	v_lshlrev_b32_e32 v216, 16, v156
	v_and_b32_e32 v156, 0xffff0000, v156
	v_lshlrev_b32_e32 v217, 16, v157
	v_and_b32_e32 v157, 0xffff0000, v157
	v_fmac_f32_e32 v122, s44, v216
	v_fmac_f32_e32 v123, s44, v156
	v_fmac_f32_e32 v124, s44, v217
	v_fmac_f32_e32 v125, s44, v157
	v_lshlrev_b32_e32 v216, 16, v158
	v_and_b32_e32 v158, 0xffff0000, v158
	v_lshlrev_b32_e32 v217, 16, v159
	v_and_b32_e32 v159, 0xffff0000, v159
	v_fmac_f32_e32 v90, s44, v216
	v_fmac_f32_e32 v91, s44, v158
	v_fmac_f32_e32 v92, s44, v217
	v_fmac_f32_e32 v93, s44, v159
	v_mov_b32_dpp v220, v90 quad_perm:[1,0,3,2] row_mask:0xf bank_mask:0xf
	v_mov_b32_dpp v221, v91 quad_perm:[1,0,3,2] row_mask:0xf bank_mask:0xf
	v_mov_b32_dpp v222, v92 quad_perm:[1,0,3,2] row_mask:0xf bank_mask:0xf
	v_mov_b32_dpp v223, v93 quad_perm:[1,0,3,2] row_mask:0xf bank_mask:0xf
	v_mov_b32_dpp v224, v122 quad_perm:[1,0,3,2] row_mask:0xf bank_mask:0xf
	v_mov_b32_dpp v225, v123 quad_perm:[1,0,3,2] row_mask:0xf bank_mask:0xf
	v_mov_b32_dpp v226, v124 quad_perm:[1,0,3,2] row_mask:0xf bank_mask:0xf
	v_mov_b32_dpp v227, v125 quad_perm:[1,0,3,2] row_mask:0xf bank_mask:0xf
	v_cndmask_b32_e32 v90, v224, v90, vcc
	v_cndmask_b32_e32 v91, v225, v91, vcc
	v_cndmask_b32_e32 v92, v226, v92, vcc
	v_cndmask_b32_e32 v93, v227, v93, vcc
	v_cndmask_b32_e32 v122, v122, v220, vcc
	v_cndmask_b32_e32 v123, v123, v221, vcc
	v_cndmask_b32_e32 v124, v124, v222, vcc
	v_cndmask_b32_e32 v125, v125, v223, vcc
	global_store_dwordx4 v[140:141], v[122:125], off
	global_store_dwordx4 v[142:143], v[90:93], off
	s_waitcnt vmcnt(18)
	v_permlane16_swap_b32_e32 v162, v164
	v_permlane16_swap_b32_e32 v163, v165
	v_lshlrev_b32_e32 v216, 16, v162
	v_and_b32_e32 v162, 0xffff0000, v162
	v_lshlrev_b32_e32 v217, 16, v163
	v_and_b32_e32 v163, 0xffff0000, v163
	v_fmac_f32_e32 v58, s44, v216
	v_fmac_f32_e32 v59, s44, v162
	v_fmac_f32_e32 v60, s44, v217
	v_fmac_f32_e32 v61, s44, v163
	v_lshlrev_b32_e32 v216, 16, v164
	v_and_b32_e32 v164, 0xffff0000, v164
	v_lshlrev_b32_e32 v217, 16, v165
	v_and_b32_e32 v165, 0xffff0000, v165
	v_fmac_f32_e32 v26, s44, v216
	v_fmac_f32_e32 v27, s44, v164
	v_fmac_f32_e32 v28, s44, v217
	v_fmac_f32_e32 v29, s44, v165
	v_mov_b32_dpp v220, v26 quad_perm:[1,0,3,2] row_mask:0xf bank_mask:0xf
	v_mov_b32_dpp v221, v27 quad_perm:[1,0,3,2] row_mask:0xf bank_mask:0xf
	v_mov_b32_dpp v222, v28 quad_perm:[1,0,3,2] row_mask:0xf bank_mask:0xf
	v_mov_b32_dpp v223, v29 quad_perm:[1,0,3,2] row_mask:0xf bank_mask:0xf
	v_mov_b32_dpp v224, v58 quad_perm:[1,0,3,2] row_mask:0xf bank_mask:0xf
	v_mov_b32_dpp v225, v59 quad_perm:[1,0,3,2] row_mask:0xf bank_mask:0xf
	v_mov_b32_dpp v226, v60 quad_perm:[1,0,3,2] row_mask:0xf bank_mask:0xf
	v_mov_b32_dpp v227, v61 quad_perm:[1,0,3,2] row_mask:0xf bank_mask:0xf
	v_cndmask_b32_e32 v26, v224, v26, vcc
	v_cndmask_b32_e32 v27, v225, v27, vcc
	v_cndmask_b32_e32 v28, v226, v28, vcc
	v_cndmask_b32_e32 v29, v227, v29, vcc
	v_cndmask_b32_e32 v58, v58, v220, vcc
	v_cndmask_b32_e32 v59, v59, v221, vcc
	v_cndmask_b32_e32 v60, v60, v222, vcc
	v_cndmask_b32_e32 v61, v61, v223, vcc
	global_store_dwordx4 v[140:141], v[58:61], off offset:128
	global_store_dwordx4 v[142:143], v[26:29], off offset:128
	v_lshl_add_u64 v[140:141], v[140:141], 0, s[10:11]
	v_lshl_add_u64 v[142:143], v[142:143], 0, s[10:11]
	s_waitcnt vmcnt(19)
; DEVI float blo(unsigned u) { return __uint_as_float(u << 16); }
; DEVI float bhi(unsigned u) { return __uint_as_float(u & 0xffff0000u); }
;     ...
;       for (int nf = 0; nf < 4; nf++) {
;         const int col = n0 + wn * 64 + nf * 16 + quad * 4;
;         f32x4 a = acc[nf][mf];
;         if (EPI == EPI_RESID || EPI == EPI_RESID_ATOMIC) {
;           f32x4 x = a;
;           if (EPI == EPI_RESID || kpart == 0) {
;             const u32x2 xr = *(const u32x2*)((const u16*)(p.ws + WS_XB) + (size_t)row * 1024 + col);
;             x[0] += ALPHA * blo(xr[0]); x[1] += ALPHA * bhi(xr[0]); x[2] += ALPHA * blo(xr[1]); x[3] += ALPHA * bhi(xr[1]);
;           }
;           if (EPI == EPI_RESID) *(f32x4*)((float*)(p.ws + WS_XF) + (size_t)row * 1024 + col) = x;
;           else *(f32x4*)((float*)(p.ws + WS_SLAB) + ((size_t)kpart * 512 + (row - T_P)) * 1024 + col) = x;
	v_permlane16_swap_b32_e32 v166, v168
	v_permlane16_swap_b32_e32 v167, v169
	v_lshlrev_b32_e32 v216, 16, v166
	v_and_b32_e32 v166, 0xffff0000, v166
	v_lshlrev_b32_e32 v217, 16, v167
	v_and_b32_e32 v167, 0xffff0000, v167
	v_fmac_f32_e32 v118, s44, v216
	v_fmac_f32_e32 v119, s44, v166
	v_fmac_f32_e32 v120, s44, v217
	v_fmac_f32_e32 v121, s44, v167
	v_lshlrev_b32_e32 v216, 16, v168
	v_and_b32_e32 v168, 0xffff0000, v168
	v_lshlrev_b32_e32 v217, 16, v169
	v_and_b32_e32 v169, 0xffff0000, v169
	v_fmac_f32_e32 v86, s44, v216
	v_fmac_f32_e32 v87, s44, v168
	v_fmac_f32_e32 v88, s44, v217
	v_fmac_f32_e32 v89, s44, v169
	v_mov_b32_dpp v220, v86 quad_perm:[1,0,3,2] row_mask:0xf bank_mask:0xf
	v_mov_b32_dpp v221, v87 quad_perm:[1,0,3,2] row_mask:0xf bank_mask:0xf
	v_mov_b32_dpp v222, v88 quad_perm:[1,0,3,2] row_mask:0xf bank_mask:0xf
	v_mov_b32_dpp v223, v89 quad_perm:[1,0,3,2] row_mask:0xf bank_mask:0xf
	v_mov_b32_dpp v224, v118 quad_perm:[1,0,3,2] row_mask:0xf bank_mask:0xf
	v_mov_b32_dpp v225, v119 quad_perm:[1,0,3,2] row_mask:0xf bank_mask:0xf
	v_mov_b32_dpp v226, v120 quad_perm:[1,0,3,2] row_mask:0xf bank_mask:0xf
	v_mov_b32_dpp v227, v121 quad_perm:[1,0,3,2] row_mask:0xf bank_mask:0xf
	v_cndmask_b32_e32 v86, v224, v86, vcc
	v_cndmask_b32_e32 v87, v225, v87, vcc
	v_cndmask_b32_e32 v88, v226, v88, vcc
	v_cndmask_b32_e32 v89, v227, v89, vcc
	v_cndmask_b32_e32 v118, v118, v220, vcc
	v_cndmask_b32_e32 v119, v119, v221, vcc
	v_cndmask_b32_e32 v120, v120, v222, vcc
	v_cndmask_b32_e32 v121, v121, v223, vcc
	global_store_dwordx4 v[140:141], v[118:121], off
	global_store_dwordx4 v[142:143], v[86:89], off
	s_waitcnt vmcnt(20)
	v_permlane16_swap_b32_e32 v170, v172
	v_permlane16_swap_b32_e32 v171, v173
	v_lshlrev_b32_e32 v216, 16, v170
	v_and_b32_e32 v170, 0xffff0000, v170
	v_lshlrev_b32_e32 v217, 16, v171
	v_and_b32_e32 v171, 0xffff0000, v171
	v_fmac_f32_e32 v54, s44, v216
	v_fmac_f32_e32 v55, s44, v170
	v_fmac_f32_e32 v56, s44, v217
	v_fmac_f32_e32 v57, s44, v171
	v_lshlrev_b32_e32 v216, 16, v172
	v_and_b32_e32 v172, 0xffff0000, v172
	v_lshlrev_b32_e32 v217, 16, v173
	v_and_b32_e32 v173, 0xffff0000, v173
	v_fmac_f32_e32 v22, s44, v216
	v_fmac_f32_e32 v23, s44, v172
	v_fmac_f32_e32 v24, s44, v217
	v_fmac_f32_e32 v25, s44, v173
	v_mov_b32_dpp v220, v22 quad_perm:[1,0,3,2] row_mask:0xf bank_mask:0xf
	v_mov_b32_dpp v221, v23 quad_perm:[1,0,3,2] row_mask:0xf bank_mask:0xf
	v_mov_b32_dpp v222, v24 quad_perm:[1,0,3,2] row_mask:0xf bank_mask:0xf
	v_mov_b32_dpp v223, v25 quad_perm:[1,0,3,2] row_mask:0xf bank_mask:0xf
	v_mov_b32_dpp v224, v54 quad_perm:[1,0,3,2] row_mask:0xf bank_mask:0xf
	v_mov_b32_dpp v225, v55 quad_perm:[1,0,3,2] row_mask:0xf bank_mask:0xf
	v_mov_b32_dpp v226, v56 quad_perm:[1,0,3,2] row_mask:0xf bank_mask:0xf
	v_mov_b32_dpp v227, v57 quad_perm:[1,0,3,2] row_mask:0xf bank_mask:0xf
	v_cndmask_b32_e32 v22, v224, v22, vcc
	v_cndmask_b32_e32 v23, v225, v23, vcc
	v_cndmask_b32_e32 v24, v226, v24, vcc
	v_cndmask_b32_e32 v25, v227, v25, vcc
	v_cndmask_b32_e32 v54, v54, v220, vcc
	v_cndmask_b32_e32 v55, v55, v221, vcc
	v_cndmask_b32_e32 v56, v56, v222, vcc
	v_cndmask_b32_e32 v57, v57, v223, vcc
	global_store_dwordx4 v[140:141], v[54:57], off offset:128
	global_store_dwordx4 v[142:143], v[22:25], off offset:128
	v_lshl_add_u64 v[140:141], v[140:141], 0, s[10:11]
	v_lshl_add_u64 v[142:143], v[142:143], 0, s[10:11]
	s_waitcnt vmcnt(21)
	v_permlane16_swap_b32_e32 v176, v178
	v_permlane16_swap_b32_e32 v177, v179
	v_lshlrev_b32_e32 v216, 16, v176
	v_and_b32_e32 v176, 0xffff0000, v176
	v_lshlrev_b32_e32 v217, 16, v177
	v_and_b32_e32 v177, 0xffff0000, v177
	v_fmac_f32_e32 v114, s44, v216
	v_fmac_f32_e32 v115, s44, v176
	v_fmac_f32_e32 v116, s44, v217
	v_fmac_f32_e32 v117, s44, v177
	v_lshlrev_b32_e32 v216, 16, v178
	v_and_b32_e32 v178, 0xffff0000, v178
	v_lshlrev_b32_e32 v217, 16, v179
	v_and_b32_e32 v179, 0xffff0000, v179
	v_fmac_f32_e32 v82, s44, v216
	v_fmac_f32_e32 v83, s44, v178
	v_fmac_f32_e32 v84, s44, v217
	v_fmac_f32_e32 v85, s44, v179
	v_mov_b32_dpp v220, v82 quad_perm:[1,0,3,2] row_mask:0xf bank_mask:0xf
	v_mov_b32_dpp v221, v83 quad_perm:[1,0,3,2] row_mask:0xf bank_mask:0xf
	v_mov_b32_dpp v222, v84 quad_perm:[1,0,3,2] row_mask:0xf bank_mask:0xf
	v_mov_b32_dpp v223, v85 quad_perm:[1,0,3,2] row_mask:0xf bank_mask:0xf
	v_mov_b32_dpp v224, v114 quad_perm:[1,0,3,2] row_mask:0xf bank_mask:0xf
	v_mov_b32_dpp v225, v115 quad_perm:[1,0,3,2] row_mask:0xf bank_mask:0xf
	v_mov_b32_dpp v226, v116 quad_perm:[1,0,3,2] row_mask:0xf bank_mask:0xf
	v_mov_b32_dpp v227, v117 quad_perm:[1,0,3,2] row_mask:0xf bank_mask:0xf
	v_cndmask_b32_e32 v82, v224, v82, vcc
	v_cndmask_b32_e32 v83, v225, v83, vcc
	v_cndmask_b32_e32 v84, v226, v84, vcc
	v_cndmask_b32_e32 v85, v227, v85, vcc
	v_cndmask_b32_e32 v114, v114, v220, vcc
	v_cndmask_b32_e32 v115, v115, v221, vcc
	v_cndmask_b32_e32 v116, v116, v222, vcc
	v_cndmask_b32_e32 v117, v117, v223, vcc
	global_store_dwordx4 v[140:141], v[114:117], off
	global_store_dwordx4 v[142:143], v[82:85], off
	s_waitcnt vmcnt(22)
; DEVI float blo(unsigned u) { return __uint_as_float(u << 16); }
; DEVI float bhi(unsigned u) { return __uint_as_float(u & 0xffff0000u); }
;     ...
;       for (int nf = 0; nf < 4; nf++) {
;         const int col = n0 + wn * 64 + nf * 16 + quad * 4;
;         f32x4 a = acc[nf][mf];
;         if (EPI == EPI_RESID || EPI == EPI_RESID_ATOMIC) {
;           f32x4 x = a;
;           if (EPI == EPI_RESID || kpart == 0) {
;             const u32x2 xr = *(const u32x2*)((const u16*)(p.ws + WS_XB) + (size_t)row * 1024 + col);
;             x[0] += ALPHA * blo(xr[0]); x[1] += ALPHA * bhi(xr[0]); x[2] += ALPHA * blo(xr[1]); x[3] += ALPHA * bhi(xr[1]);
;           }
;           if (EPI == EPI_RESID) *(f32x4*)((float*)(p.ws + WS_XF) + (size_t)row * 1024 + col) = x;
;           else *(f32x4*)((float*)(p.ws + WS_SLAB) + ((size_t)kpart * 512 + (row - T_P)) * 1024 + col) = x;
	v_permlane16_swap_b32_e32 v180, v182
	v_permlane16_swap_b32_e32 v181, v183
	v_lshlrev_b32_e32 v216, 16, v180
	v_and_b32_e32 v180, 0xffff0000, v180
	v_lshlrev_b32_e32 v217, 16, v181
	v_and_b32_e32 v181, 0xffff0000, v181
	v_fmac_f32_e32 v50, s44, v216
	v_fmac_f32_e32 v51, s44, v180
	v_fmac_f32_e32 v52, s44, v217
	v_fmac_f32_e32 v53, s44, v181
	v_lshlrev_b32_e32 v216, 16, v182
	v_and_b32_e32 v182, 0xffff0000, v182
	v_lshlrev_b32_e32 v217, 16, v183
	v_and_b32_e32 v183, 0xffff0000, v183
	v_fmac_f32_e32 v18, s44, v216
	v_fmac_f32_e32 v19, s44, v182
	v_fmac_f32_e32 v20, s44, v217
	v_fmac_f32_e32 v21, s44, v183
	v_mov_b32_dpp v220, v18 quad_perm:[1,0,3,2] row_mask:0xf bank_mask:0xf
	v_mov_b32_dpp v221, v19 quad_perm:[1,0,3,2] row_mask:0xf bank_mask:0xf
	v_mov_b32_dpp v222, v20 quad_perm:[1,0,3,2] row_mask:0xf bank_mask:0xf
	v_mov_b32_dpp v223, v21 quad_perm:[1,0,3,2] row_mask:0xf bank_mask:0xf
	v_mov_b32_dpp v224, v50 quad_perm:[1,0,3,2] row_mask:0xf bank_mask:0xf
	v_mov_b32_dpp v225, v51 quad_perm:[1,0,3,2] row_mask:0xf bank_mask:0xf
	v_mov_b32_dpp v226, v52 quad_perm:[1,0,3,2] row_mask:0xf bank_mask:0xf
	v_mov_b32_dpp v227, v53 quad_perm:[1,0,3,2] row_mask:0xf bank_mask:0xf
	v_cndmask_b32_e32 v18, v224, v18, vcc
	v_cndmask_b32_e32 v19, v225, v19, vcc
	v_cndmask_b32_e32 v20, v226, v20, vcc
	v_cndmask_b32_e32 v21, v227, v21, vcc
	v_cndmask_b32_e32 v50, v50, v220, vcc
	v_cndmask_b32_e32 v51, v51, v221, vcc
	v_cndmask_b32_e32 v52, v52, v222, vcc
	v_cndmask_b32_e32 v53, v53, v223, vcc
	global_store_dwordx4 v[140:141], v[50:53], off offset:128
	global_store_dwordx4 v[142:143], v[18:21], off offset:128
	v_lshl_add_u64 v[140:141], v[140:141], 0, s[10:11]
	v_lshl_add_u64 v[142:143], v[142:143], 0, s[10:11]
	s_waitcnt vmcnt(23)
	v_permlane16_swap_b32_e32 v184, v186
	v_permlane16_swap_b32_e32 v185, v187
	v_lshlrev_b32_e32 v216, 16, v184
	v_and_b32_e32 v184, 0xffff0000, v184
	v_lshlrev_b32_e32 v217, 16, v185
	v_and_b32_e32 v185, 0xffff0000, v185
	v_fmac_f32_e32 v110, s44, v216
	v_fmac_f32_e32 v111, s44, v184
	v_fmac_f32_e32 v112, s44, v217
	v_fmac_f32_e32 v113, s44, v185
	v_lshlrev_b32_e32 v216, 16, v186
	v_and_b32_e32 v186, 0xffff0000, v186
	v_lshlrev_b32_e32 v217, 16, v187
	v_and_b32_e32 v187, 0xffff0000, v187
	v_fmac_f32_e32 v78, s44, v216
	v_fmac_f32_e32 v79, s44, v186
	v_fmac_f32_e32 v80, s44, v217
	v_fmac_f32_e32 v81, s44, v187
	v_mov_b32_dpp v220, v78 quad_perm:[1,0,3,2] row_mask:0xf bank_mask:0xf
	v_mov_b32_dpp v221, v79 quad_perm:[1,0,3,2] row_mask:0xf bank_mask:0xf
	v_mov_b32_dpp v222, v80 quad_perm:[1,0,3,2] row_mask:0xf bank_mask:0xf
	v_mov_b32_dpp v223, v81 quad_perm:[1,0,3,2] row_mask:0xf bank_mask:0xf
	v_mov_b32_dpp v224, v110 quad_perm:[1,0,3,2] row_mask:0xf bank_mask:0xf
	v_mov_b32_dpp v225, v111 quad_perm:[1,0,3,2] row_mask:0xf bank_mask:0xf
	v_mov_b32_dpp v226, v112 quad_perm:[1,0,3,2] row_mask:0xf bank_mask:0xf
	v_mov_b32_dpp v227, v113 quad_perm:[1,0,3,2] row_mask:0xf bank_mask:0xf
	v_cndmask_b32_e32 v78, v224, v78, vcc
	v_cndmask_b32_e32 v79, v225, v79, vcc
	v_cndmask_b32_e32 v80, v226, v80, vcc
	v_cndmask_b32_e32 v81, v227, v81, vcc
	v_cndmask_b32_e32 v110, v110, v220, vcc
	v_cndmask_b32_e32 v111, v111, v221, vcc
	v_cndmask_b32_e32 v112, v112, v222, vcc
	v_cndmask_b32_e32 v113, v113, v223, vcc
	global_store_dwordx4 v[140:141], v[110:113], off
	global_store_dwordx4 v[142:143], v[78:81], off
	s_waitcnt vmcnt(24)
	v_permlane16_swap_b32_e32 v188, v190
	v_permlane16_swap_b32_e32 v189, v191
	v_lshlrev_b32_e32 v216, 16, v188
	v_and_b32_e32 v188, 0xffff0000, v188
	v_lshlrev_b32_e32 v217, 16, v189
	v_and_b32_e32 v189, 0xffff0000, v189
	v_fmac_f32_e32 v46, s44, v216
	v_fmac_f32_e32 v47, s44, v188
	v_fmac_f32_e32 v48, s44, v217
	v_fmac_f32_e32 v49, s44, v189
	v_lshlrev_b32_e32 v216, 16, v190
	v_and_b32_e32 v190, 0xffff0000, v190
	v_lshlrev_b32_e32 v217, 16, v191
	v_and_b32_e32 v191, 0xffff0000, v191
	v_fmac_f32_e32 v14, s44, v216
	v_fmac_f32_e32 v15, s44, v190
	v_fmac_f32_e32 v16, s44, v217
	v_fmac_f32_e32 v17, s44, v191
	v_mov_b32_dpp v220, v14 quad_perm:[1,0,3,2] row_mask:0xf bank_mask:0xf
	v_mov_b32_dpp v221, v15 quad_perm:[1,0,3,2] row_mask:0xf bank_mask:0xf
	v_mov_b32_dpp v222, v16 quad_perm:[1,0,3,2] row_mask:0xf bank_mask:0xf
	v_mov_b32_dpp v223, v17 quad_perm:[1,0,3,2] row_mask:0xf bank_mask:0xf
	v_mov_b32_dpp v224, v46 quad_perm:[1,0,3,2] row_mask:0xf bank_mask:0xf
	v_mov_b32_dpp v225, v47 quad_perm:[1,0,3,2] row_mask:0xf bank_mask:0xf
	v_mov_b32_dpp v226, v48 quad_perm:[1,0,3,2] row_mask:0xf bank_mask:0xf
	v_mov_b32_dpp v227, v49 quad_perm:[1,0,3,2] row_mask:0xf bank_mask:0xf
	v_cndmask_b32_e32 v14, v224, v14, vcc
	v_cndmask_b32_e32 v15, v225, v15, vcc
	v_cndmask_b32_e32 v16, v226, v16, vcc
	v_cndmask_b32_e32 v17, v227, v17, vcc
	v_cndmask_b32_e32 v46, v46, v220, vcc
	v_cndmask_b32_e32 v47, v47, v221, vcc
	v_cndmask_b32_e32 v48, v48, v222, vcc
	v_cndmask_b32_e32 v49, v49, v223, vcc
	global_store_dwordx4 v[140:141], v[46:49], off offset:128
	global_store_dwordx4 v[142:143], v[14:17], off offset:128
	v_lshl_add_u64 v[140:141], v[140:141], 0, s[10:11]
	v_lshl_add_u64 v[142:143], v[142:143], 0, s[10:11]
	s_waitcnt vmcnt(25)
; DEVI float blo(unsigned u) { return __uint_as_float(u << 16); }
; DEVI float bhi(unsigned u) { return __uint_as_float(u & 0xffff0000u); }
;     ...
;       for (int nf = 0; nf < 4; nf++) {
;         const int col = n0 + wn * 64 + nf * 16 + quad * 4;
;         f32x4 a = acc[nf][mf];
;         if (EPI == EPI_RESID || EPI == EPI_RESID_ATOMIC) {
;           f32x4 x = a;
;           if (EPI == EPI_RESID || kpart == 0) {
;             const u32x2 xr = *(const u32x2*)((const u16*)(p.ws + WS_XB) + (size_t)row * 1024 + col);
;             x[0] += ALPHA * blo(xr[0]); x[1] += ALPHA * bhi(xr[0]); x[2] += ALPHA * blo(xr[1]); x[3] += ALPHA * bhi(xr[1]);
;           }
;           if (EPI == EPI_RESID) *(f32x4*)((float*)(p.ws + WS_XF) + (size_t)row * 1024 + col) = x;
;           else *(f32x4*)((float*)(p.ws + WS_SLAB) + ((size_t)kpart * 512 + (row - T_P)) * 1024 + col) = x;
	v_permlane16_swap_b32_e32 v192, v194
	v_permlane16_swap_b32_e32 v193, v195
	v_lshlrev_b32_e32 v216, 16, v192
	v_and_b32_e32 v192, 0xffff0000, v192
	v_lshlrev_b32_e32 v217, 16, v193
	v_and_b32_e32 v193, 0xffff0000, v193
	v_fmac_f32_e32 v106, s44, v216
	v_fmac_f32_e32 v107, s44, v192
	v_fmac_f32_e32 v108, s44, v217
	v_fmac_f32_e32 v109, s44, v193
	v_lshlrev_b32_e32 v216, 16, v194
	v_and_b32_e32 v194, 0xffff0000, v194
	v_lshlrev_b32_e32 v217, 16, v195
	v_and_b32_e32 v195, 0xffff0000, v195
	v_fmac_f32_e32 v74, s44, v216
	v_fmac_f32_e32 v75, s44, v194
	v_fmac_f32_e32 v76, s44, v217
	v_fmac_f32_e32 v77, s44, v195
	v_mov_b32_dpp v220, v74 quad_perm:[1,0,3,2] row_mask:0xf bank_mask:0xf
	v_mov_b32_dpp v221, v75 quad_perm:[1,0,3,2] row_mask:0xf bank_mask:0xf
	v_mov_b32_dpp v222, v76 quad_perm:[1,0,3,2] row_mask:0xf bank_mask:0xf
	v_mov_b32_dpp v223, v77 quad_perm:[1,0,3,2] row_mask:0xf bank_mask:0xf
	v_mov_b32_dpp v224, v106 quad_perm:[1,0,3,2] row_mask:0xf bank_mask:0xf
	v_mov_b32_dpp v225, v107 quad_perm:[1,0,3,2] row_mask:0xf bank_mask:0xf
	v_mov_b32_dpp v226, v108 quad_perm:[1,0,3,2] row_mask:0xf bank_mask:0xf
	v_mov_b32_dpp v227, v109 quad_perm:[1,0,3,2] row_mask:0xf bank_mask:0xf
	v_cndmask_b32_e32 v74, v224, v74, vcc
	v_cndmask_b32_e32 v75, v225, v75, vcc
	v_cndmask_b32_e32 v76, v226, v76, vcc
	v_cndmask_b32_e32 v77, v227, v77, vcc
	v_cndmask_b32_e32 v106, v106, v220, vcc
	v_cndmask_b32_e32 v107, v107, v221, vcc
	v_cndmask_b32_e32 v108, v108, v222, vcc
	v_cndmask_b32_e32 v109, v109, v223, vcc
	global_store_dwordx4 v[140:141], v[106:109], off
	global_store_dwordx4 v[142:143], v[74:77], off
	s_waitcnt vmcnt(26)
	v_permlane16_swap_b32_e32 v196, v198
	v_permlane16_swap_b32_e32 v197, v199
	v_lshlrev_b32_e32 v216, 16, v196
	v_and_b32_e32 v196, 0xffff0000, v196
	v_lshlrev_b32_e32 v217, 16, v197
	v_and_b32_e32 v197, 0xffff0000, v197
	v_fmac_f32_e32 v42, s44, v216
	v_fmac_f32_e32 v43, s44, v196
	v_fmac_f32_e32 v44, s44, v217
	v_fmac_f32_e32 v45, s44, v197
	v_lshlrev_b32_e32 v216, 16, v198
	v_and_b32_e32 v198, 0xffff0000, v198
	v_lshlrev_b32_e32 v217, 16, v199
	v_and_b32_e32 v199, 0xffff0000, v199
	v_fmac_f32_e32 v10, s44, v216
	v_fmac_f32_e32 v11, s44, v198
	v_fmac_f32_e32 v12, s44, v217
	v_fmac_f32_e32 v13, s44, v199
	v_mov_b32_dpp v220, v10 quad_perm:[1,0,3,2] row_mask:0xf bank_mask:0xf
	v_mov_b32_dpp v221, v11 quad_perm:[1,0,3,2] row_mask:0xf bank_mask:0xf
	v_mov_b32_dpp v222, v12 quad_perm:[1,0,3,2] row_mask:0xf bank_mask:0xf
	v_mov_b32_dpp v223, v13 quad_perm:[1,0,3,2] row_mask:0xf bank_mask:0xf
	v_mov_b32_dpp v224, v42 quad_perm:[1,0,3,2] row_mask:0xf bank_mask:0xf
	v_mov_b32_dpp v225, v43 quad_perm:[1,0,3,2] row_mask:0xf bank_mask:0xf
	v_mov_b32_dpp v226, v44 quad_perm:[1,0,3,2] row_mask:0xf bank_mask:0xf
	v_mov_b32_dpp v227, v45 quad_perm:[1,0,3,2] row_mask:0xf bank_mask:0xf
	v_cndmask_b32_e32 v10, v224, v10, vcc
	v_cndmask_b32_e32 v11, v225, v11, vcc
	v_cndmask_b32_e32 v12, v226, v12, vcc
	v_cndmask_b32_e32 v13, v227, v13, vcc
	v_cndmask_b32_e32 v42, v42, v220, vcc
	v_cndmask_b32_e32 v43, v43, v221, vcc
	v_cndmask_b32_e32 v44, v44, v222, vcc
	v_cndmask_b32_e32 v45, v45, v223, vcc
	global_store_dwordx4 v[140:141], v[42:45], off offset:128
	global_store_dwordx4 v[142:143], v[10:13], off offset:128
	v_lshl_add_u64 v[140:141], v[140:141], 0, s[10:11]
	v_lshl_add_u64 v[142:143], v[142:143], 0, s[10:11]
	s_waitcnt vmcnt(27)
	v_permlane16_swap_b32_e32 v200, v202
	v_permlane16_swap_b32_e32 v201, v203
	v_lshlrev_b32_e32 v216, 16, v200
	v_and_b32_e32 v200, 0xffff0000, v200
	v_lshlrev_b32_e32 v217, 16, v201
	v_and_b32_e32 v201, 0xffff0000, v201
	v_fmac_f32_e32 v102, s44, v216
	v_fmac_f32_e32 v103, s44, v200
	v_fmac_f32_e32 v104, s44, v217
	v_fmac_f32_e32 v105, s44, v201
	v_lshlrev_b32_e32 v216, 16, v202
	v_and_b32_e32 v202, 0xffff0000, v202
	v_lshlrev_b32_e32 v217, 16, v203
	v_and_b32_e32 v203, 0xffff0000, v203
	v_fmac_f32_e32 v70, s44, v216
	v_fmac_f32_e32 v71, s44, v202
	v_fmac_f32_e32 v72, s44, v217
	v_fmac_f32_e32 v73, s44, v203
	v_mov_b32_dpp v220, v70 quad_perm:[1,0,3,2] row_mask:0xf bank_mask:0xf
	v_mov_b32_dpp v221, v71 quad_perm:[1,0,3,2] row_mask:0xf bank_mask:0xf
	v_mov_b32_dpp v222, v72 quad_perm:[1,0,3,2] row_mask:0xf bank_mask:0xf
	v_mov_b32_dpp v223, v73 quad_perm:[1,0,3,2] row_mask:0xf bank_mask:0xf
	v_mov_b32_dpp v224, v102 quad_perm:[1,0,3,2] row_mask:0xf bank_mask:0xf
	v_mov_b32_dpp v225, v103 quad_perm:[1,0,3,2] row_mask:0xf bank_mask:0xf
	v_mov_b32_dpp v226, v104 quad_perm:[1,0,3,2] row_mask:0xf bank_mask:0xf
	v_mov_b32_dpp v227, v105 quad_perm:[1,0,3,2] row_mask:0xf bank_mask:0xf
	v_cndmask_b32_e32 v70, v224, v70, vcc
	v_cndmask_b32_e32 v71, v225, v71, vcc
	v_cndmask_b32_e32 v72, v226, v72, vcc
	v_cndmask_b32_e32 v73, v227, v73, vcc
	v_cndmask_b32_e32 v102, v102, v220, vcc
	v_cndmask_b32_e32 v103, v103, v221, vcc
	v_cndmask_b32_e32 v104, v104, v222, vcc
	v_cndmask_b32_e32 v105, v105, v223, vcc
	global_store_dwordx4 v[140:141], v[102:105], off
	global_store_dwordx4 v[142:143], v[70:73], off
	s_waitcnt vmcnt(28)
; DEVI float blo(unsigned u) { return __uint_as_float(u << 16); }
; DEVI float bhi(unsigned u) { return __uint_as_float(u & 0xffff0000u); }
; DEVI int xcd_first_tile() { return (blockIdx.x & 7) * (gridDim.x >> 3) + (blockIdx.x >> 3); }
;     ...
;       for (int nf = 0; nf < 4; nf++) {
;         const int col = n0 + wn * 64 + nf * 16 + quad * 4;
;         f32x4 a = acc[nf][mf];
;         if (EPI == EPI_RESID || EPI == EPI_RESID_ATOMIC) {
;           f32x4 x = a;
;           if (EPI == EPI_RESID || kpart == 0) {
;             const u32x2 xr = *(const u32x2*)((const u16*)(p.ws + WS_XB) + (size_t)row * 1024 + col);
;             x[0] += ALPHA * blo(xr[0]); x[1] += ALPHA * bhi(xr[0]); x[2] += ALPHA * blo(xr[1]); x[3] += ALPHA * bhi(xr[1]);
;           }
;           if (EPI == EPI_RESID) *(f32x4*)((float*)(p.ws + WS_XF) + (size_t)row * 1024 + col) = x;
;           else *(f32x4*)((float*)(p.ws + WS_SLAB) + ((size_t)kpart * 512 + (row - T_P)) * 1024 + col) = x;
; DEVI void run_phase(const Params& p, int ph, char* smem) {
;     ...
;       for (int t = xcd_first_tile(); t < 512 + 16 * 11; t += xcd_tile_step()) {
;         if (t < 512) {
;           int mt_, nt_; tile_coords(t, 64, 8, mt_, nt_);
;           gemm_tile256<EPI_RESID>(p, hb, DFF, Bt, DFF, mt_ * 256, nt_ * 128, nullptr, 0, smem);
;         } else {
;           const int u_ = t - 512, tl_ = u_ / 11, q_ = u_ - tl_ * 11;
;           gemm_tile256<EPI_RESID_ATOMIC>(p, hb, DFF, Bt, DFF, (64 + (tl_ & 1)) * 256, (tl_ >> 1) * 128, nullptr, 0, smem, q_ * 256, 8, q_);
	v_permlane16_swap_b32_e32 v204, v206
	v_permlane16_swap_b32_e32 v205, v207
	v_lshlrev_b32_e32 v216, 16, v204
	v_and_b32_e32 v204, 0xffff0000, v204
	v_lshlrev_b32_e32 v217, 16, v205
	v_and_b32_e32 v205, 0xffff0000, v205
	v_fmac_f32_e32 v38, s44, v216
	v_fmac_f32_e32 v39, s44, v204
	v_fmac_f32_e32 v40, s44, v217
	v_fmac_f32_e32 v41, s44, v205
	v_lshlrev_b32_e32 v216, 16, v206
	v_and_b32_e32 v206, 0xffff0000, v206
	v_lshlrev_b32_e32 v217, 16, v207
	v_and_b32_e32 v207, 0xffff0000, v207
	v_fmac_f32_e32 v6, s44, v216
	v_fmac_f32_e32 v7, s44, v206
	v_fmac_f32_e32 v8, s44, v217
	v_fmac_f32_e32 v9, s44, v207
	v_mov_b32_dpp v220, v6 quad_perm:[1,0,3,2] row_mask:0xf bank_mask:0xf
	v_mov_b32_dpp v221, v7 quad_perm:[1,0,3,2] row_mask:0xf bank_mask:0xf
	v_mov_b32_dpp v222, v8 quad_perm:[1,0,3,2] row_mask:0xf bank_mask:0xf
	v_mov_b32_dpp v223, v9 quad_perm:[1,0,3,2] row_mask:0xf bank_mask:0xf
	v_mov_b32_dpp v224, v38 quad_perm:[1,0,3,2] row_mask:0xf bank_mask:0xf
	v_mov_b32_dpp v225, v39 quad_perm:[1,0,3,2] row_mask:0xf bank_mask:0xf
	v_mov_b32_dpp v226, v40 quad_perm:[1,0,3,2] row_mask:0xf bank_mask:0xf
	v_mov_b32_dpp v227, v41 quad_perm:[1,0,3,2] row_mask:0xf bank_mask:0xf
	v_cndmask_b32_e32 v6, v224, v6, vcc
	v_cndmask_b32_e32 v7, v225, v7, vcc
	v_cndmask_b32_e32 v8, v226, v8, vcc
	v_cndmask_b32_e32 v9, v227, v9, vcc
	v_cndmask_b32_e32 v38, v38, v220, vcc
	v_cndmask_b32_e32 v39, v39, v221, vcc
	v_cndmask_b32_e32 v40, v40, v222, vcc
	v_cndmask_b32_e32 v41, v41, v223, vcc
	global_store_dwordx4 v[140:141], v[38:41], off offset:128
	global_store_dwordx4 v[142:143], v[6:9], off offset:128
	v_lshl_add_u64 v[140:141], v[140:141], 0, s[10:11]
	v_lshl_add_u64 v[142:143], v[142:143], 0, s[10:11]
	s_waitcnt vmcnt(29)
	v_permlane16_swap_b32_e32 v208, v210
	v_permlane16_swap_b32_e32 v209, v211
	v_lshlrev_b32_e32 v216, 16, v208
	v_and_b32_e32 v208, 0xffff0000, v208
	v_lshlrev_b32_e32 v217, 16, v209
	v_and_b32_e32 v209, 0xffff0000, v209
	v_fmac_f32_e32 v98, s44, v216
	v_fmac_f32_e32 v99, s44, v208
	v_fmac_f32_e32 v100, s44, v217
	v_fmac_f32_e32 v101, s44, v209
	v_lshlrev_b32_e32 v216, 16, v210
	v_and_b32_e32 v210, 0xffff0000, v210
	v_lshlrev_b32_e32 v217, 16, v211
	v_and_b32_e32 v211, 0xffff0000, v211
	v_fmac_f32_e32 v66, s44, v216
	v_fmac_f32_e32 v67, s44, v210
	v_fmac_f32_e32 v68, s44, v217
	v_fmac_f32_e32 v69, s44, v211
	v_mov_b32_dpp v220, v66 quad_perm:[1,0,3,2] row_mask:0xf bank_mask:0xf
	v_mov_b32_dpp v221, v67 quad_perm:[1,0,3,2] row_mask:0xf bank_mask:0xf
	v_mov_b32_dpp v222, v68 quad_perm:[1,0,3,2] row_mask:0xf bank_mask:0xf
	v_mov_b32_dpp v223, v69 quad_perm:[1,0,3,2] row_mask:0xf bank_mask:0xf
	v_mov_b32_dpp v224, v98 quad_perm:[1,0,3,2] row_mask:0xf bank_mask:0xf
	v_mov_b32_dpp v225, v99 quad_perm:[1,0,3,2] row_mask:0xf bank_mask:0xf
	v_mov_b32_dpp v226, v100 quad_perm:[1,0,3,2] row_mask:0xf bank_mask:0xf
	v_mov_b32_dpp v227, v101 quad_perm:[1,0,3,2] row_mask:0xf bank_mask:0xf
	v_cndmask_b32_e32 v66, v224, v66, vcc
	v_cndmask_b32_e32 v67, v225, v67, vcc
	v_cndmask_b32_e32 v68, v226, v68, vcc
	v_cndmask_b32_e32 v69, v227, v69, vcc
	v_cndmask_b32_e32 v98, v98, v220, vcc
	v_cndmask_b32_e32 v99, v99, v221, vcc
	v_cndmask_b32_e32 v100, v100, v222, vcc
	v_cndmask_b32_e32 v101, v101, v223, vcc
	global_store_dwordx4 v[140:141], v[98:101], off
	global_store_dwordx4 v[142:143], v[66:69], off
	s_waitcnt vmcnt(30)
	v_permlane16_swap_b32_e32 v212, v214
	v_permlane16_swap_b32_e32 v213, v215
	v_lshlrev_b32_e32 v216, 16, v212
	v_and_b32_e32 v212, 0xffff0000, v212
	v_lshlrev_b32_e32 v217, 16, v213
	v_and_b32_e32 v213, 0xffff0000, v213
	v_fmac_f32_e32 v34, s44, v216
	v_fmac_f32_e32 v35, s44, v212
	v_fmac_f32_e32 v36, s44, v217
	v_fmac_f32_e32 v37, s44, v213
	v_lshlrev_b32_e32 v216, 16, v214
	v_and_b32_e32 v214, 0xffff0000, v214
	v_lshlrev_b32_e32 v217, 16, v215
	v_and_b32_e32 v215, 0xffff0000, v215
	v_fmac_f32_e32 v2, s44, v216
	v_fmac_f32_e32 v3, s44, v214
	v_fmac_f32_e32 v4, s44, v217
	v_fmac_f32_e32 v5, s44, v215
	v_mov_b32_dpp v220, v2 quad_perm:[1,0,3,2] row_mask:0xf bank_mask:0xf
	v_mov_b32_dpp v221, v3 quad_perm:[1,0,3,2] row_mask:0xf bank_mask:0xf
	v_mov_b32_dpp v222, v4 quad_perm:[1,0,3,2] row_mask:0xf bank_mask:0xf
	v_mov_b32_dpp v223, v5 quad_perm:[1,0,3,2] row_mask:0xf bank_mask:0xf
	v_mov_b32_dpp v224, v34 quad_perm:[1,0,3,2] row_mask:0xf bank_mask:0xf
	v_mov_b32_dpp v225, v35 quad_perm:[1,0,3,2] row_mask:0xf bank_mask:0xf
	v_mov_b32_dpp v226, v36 quad_perm:[1,0,3,2] row_mask:0xf bank_mask:0xf
	v_mov_b32_dpp v227, v37 quad_perm:[1,0,3,2] row_mask:0xf bank_mask:0xf
	v_cndmask_b32_e32 v2, v224, v2, vcc
	v_cndmask_b32_e32 v3, v225, v3, vcc
	v_cndmask_b32_e32 v4, v226, v4, vcc
	v_cndmask_b32_e32 v5, v227, v5, vcc
	v_cndmask_b32_e32 v34, v34, v220, vcc
	v_cndmask_b32_e32 v35, v35, v221, vcc
	v_cndmask_b32_e32 v36, v36, v222, vcc
	v_cndmask_b32_e32 v37, v37, v223, vcc
	global_store_dwordx4 v[140:141], v[34:37], off offset:128
	global_store_dwordx4 v[142:143], v[2:5], off offset:128
	v_readlane_b32 s39, v250, 7
	s_cmpk_lg_u32 s39, 0x200
	s_cbranch_scc1 .LBB0_41
	v_readlane_b32 s40, v250, 0
	s_lshr_b32 s41, s40, 3
	s_and_b32 s40, s40, 7
	s_mul_i32 s40, s40, 22
	s_add_i32 s40, s40, s41
	s_cmp_lt_u32 s41, 22
	s_movk_i32 s38, 0x4000
	s_branch .LBB0_41

;     ...
;   for (int kt = 0; kt < nk; kt++) {
;     if (kt + 1 < nk) asm volatile("s_waitcnt vmcnt(6)" ::: "memory");
;     else asm volatile("s_waitcnt vmcnt(0)" ::: "memory");
;     __builtin_amdgcn_s_barrier();
;     asm volatile("" ::: "memory");
;     if (kt + 2 < nk) G2_STAGE(kt + 2);
;     const char* cS = smem + (kt % 3) * 24576;
;     bf16x8 xa[8], wb[4];
; #pragma unroll
;     for (int f = 0; f < 8; f++) xa[f] = *(const bf16x8*)(cS + aoff + f * 1024);
; #pragma unroll
;     for (int f = 0; f < 4; f++) wb[f] = *(const bf16x8*)(cS + boff + f * 1024);
; #pragma unroll
;     for (int nf = 0; nf < 4; nf++)
; #pragma unroll
;       for (int mf = 0; mf < 8; mf++)
;         acc[nf][mf] = __builtin_amdgcn_mfma_f32_16x16x32_bf16(wb[nf], xa[mf], acc[nf][mf], 0, 0, 0);
;   }
.Lt10_loop:
	.p2align 3
	s_waitcnt vmcnt(6) lgkmcnt(0)
	s_barrier
	s_setprio 1
	v_add_u32_e32 v144, s36, v136
	v_mfma_f32_16x16x32_bf16 v[126:129], v[184:187], v[146:149], v[126:129]
	ds_read_b128 v[200:203], v144 offset:0
	v_mfma_f32_16x16x32_bf16 v[122:125], v[184:187], v[152:155], v[122:125]
	ds_read_b128 v[204:207], v144 offset:1024
	v_mfma_f32_16x16x32_bf16 v[118:121], v[184:187], v[156:159], v[118:121]
	ds_read_b128 v[208:211], v144 offset:2048
	v_mfma_f32_16x16x32_bf16 v[114:117], v[184:187], v[162:165], v[114:117]
	ds_read_b128 v[212:215], v144 offset:3072
	v_mfma_f32_16x16x32_bf16 v[110:113], v[184:187], v[166:169], v[110:113]
	ds_read_b128 v[216:219], v144 offset:4096
	v_mfma_f32_16x16x32_bf16 v[106:109], v[184:187], v[170:173], v[106:109]
	ds_read_b128 v[220:223], v144 offset:5120
	v_mfma_f32_16x16x32_bf16 v[102:105], v[184:187], v[176:179], v[102:105]
	ds_read_b128 v[224:227], v144 offset:6144
	v_mfma_f32_16x16x32_bf16 v[98:101], v[184:187], v[180:183], v[98:101]
	ds_read_b128 v[228:231], v144 offset:7168
	v_mfma_f32_16x16x32_bf16 v[94:97], v[188:191], v[146:149], v[94:97]
	v_add_u32_e64 v144, s36, v137
	v_mfma_f32_16x16x32_bf16 v[90:93], v[188:191], v[152:155], v[90:93]
	v_mfma_f32_16x16x32_bf16 v[86:89], v[188:191], v[156:159], v[86:89]
	ds_read_b128 v[232:235], v144 offset:16384
	v_mfma_f32_16x16x32_bf16 v[82:85], v[188:191], v[162:165], v[82:85]
	ds_read_b128 v[236:239], v144 offset:17408
	v_mfma_f32_16x16x32_bf16 v[78:81], v[188:191], v[166:169], v[78:81]
	ds_read_b128 v[240:243], v144 offset:18432
	s_setprio 2
	s_nop 0
	v_mfma_f32_16x16x32_bf16 v[74:77], v[188:191], v[170:173], v[74:77]
	ds_read_b128 v[244:247], v144 offset:19456
	v_mfma_f32_16x16x32_bf16 v[70:73], v[188:191], v[176:179], v[70:73]
	s_add_i32 s38, s43, s37
	s_mov_b32 m0, s38
	v_lshl_add_u64 v[142:143], v[132:133], 0, s[2:3]
	v_mfma_f32_16x16x32_bf16 v[66:69], v[188:191], v[180:183], v[66:69]
	global_load_lds_dwordx4 v[132:133], off
	s_add_i32 m0, m0, 0x1000
	v_mfma_f32_16x16x32_bf16 v[62:65], v[192:195], v[146:149], v[62:65]
	v_mfma_f32_16x16x32_bf16 v[58:61], v[192:195], v[152:155], v[58:61]
	v_mfma_f32_16x16x32_bf16 v[54:57], v[192:195], v[156:159], v[54:57]
	global_load_lds_dwordx4 v[142:143], off
	v_lshl_add_u64 v[142:143], v[142:143], 0, s[2:3]
	s_add_i32 m0, m0, 0x1000
	v_mfma_f32_16x16x32_bf16 v[50:53], v[192:195], v[162:165], v[50:53]
	v_mfma_f32_16x16x32_bf16 v[46:49], v[192:195], v[166:169], v[46:49]
	v_mfma_f32_16x16x32_bf16 v[42:45], v[192:195], v[170:173], v[42:45]
	global_load_lds_dwordx4 v[142:143], off
	v_lshl_add_u64 v[142:143], v[142:143], 0, s[2:3]
	s_add_i32 m0, m0, 0x1000
	v_mfma_f32_16x16x32_bf16 v[38:41], v[192:195], v[176:179], v[38:41]
	v_mfma_f32_16x16x32_bf16 v[34:37], v[192:195], v[180:183], v[34:37]
	s_setprio 0
	s_nop 0
	v_mfma_f32_16x16x32_bf16 v[30:33], v[196:199], v[146:149], v[30:33]
	global_load_lds_dwordx4 v[142:143], off
	s_add_i32 m0, m0, 0x1000
	v_lshl_add_u64 v[142:143], v[134:135], 0, s[2:3]
	v_mfma_f32_16x16x32_bf16 v[26:29], v[196:199], v[152:155], v[26:29]
	v_mfma_f32_16x16x32_bf16 v[22:25], v[196:199], v[156:159], v[22:25]
	v_mfma_f32_16x16x32_bf16 v[18:21], v[196:199], v[162:165], v[18:21]
	global_load_lds_dwordx4 v[134:135], off
	s_add_i32 m0, m0, 0x1000
	v_lshl_add_u64 v[132:133], v[132:133], 0, s[14:15]
	v_mfma_f32_16x16x32_bf16 v[14:17], v[196:199], v[166:169], v[14:17]
	v_mfma_f32_16x16x32_bf16 v[10:13], v[196:199], v[170:173], v[10:13]
	v_mfma_f32_16x16x32_bf16 v[6:9], v[196:199], v[176:179], v[6:9]
	global_load_lds_dwordx4 v[142:143], off
	v_lshl_add_u64 v[134:135], v[134:135], 0, s[10:11]
	v_mfma_f32_16x16x32_bf16 v[2:5], v[196:199], v[180:183], v[2:5]
	s_mov_b32 s37, s36
	s_nop 0
	s_add_i32 s36, s36, 0x6000
	s_cmp_eq_u32 s36, 0x12000
	s_cselect_b32 s36, 0, s36
	s_nop 0
	.p2align 3
	s_waitcnt vmcnt(6) lgkmcnt(0)
	s_barrier
	s_setprio 1
	v_add_u32_e32 v144, s36, v136
	v_mfma_f32_16x16x32_bf16 v[126:129], v[232:235], v[200:203], v[126:129]
	ds_read_b128 v[146:149], v144 offset:0
	v_mfma_f32_16x16x32_bf16 v[122:125], v[232:235], v[204:207], v[122:125]
	ds_read_b128 v[152:155], v144 offset:1024
	v_mfma_f32_16x16x32_bf16 v[118:121], v[232:235], v[208:211], v[118:121]
	ds_read_b128 v[156:159], v144 offset:2048
	v_mfma_f32_16x16x32_bf16 v[114:117], v[232:235], v[212:215], v[114:117]
	ds_read_b128 v[162:165], v144 offset:3072
	v_mfma_f32_16x16x32_bf16 v[110:113], v[232:235], v[216:219], v[110:113]
	ds_read_b128 v[166:169], v144 offset:4096
	v_mfma_f32_16x16x32_bf16 v[106:109], v[232:235], v[220:223], v[106:109]
	ds_read_b128 v[170:173], v144 offset:5120
	v_mfma_f32_16x16x32_bf16 v[102:105], v[232:235], v[224:227], v[102:105]
	ds_read_b128 v[176:179], v144 offset:6144
	v_mfma_f32_16x16x32_bf16 v[98:101], v[232:235], v[228:231], v[98:101]
	ds_read_b128 v[180:183], v144 offset:7168
	v_mfma_f32_16x16x32_bf16 v[94:97], v[236:239], v[200:203], v[94:97]
	v_add_u32_e64 v144, s36, v137
	v_mfma_f32_16x16x32_bf16 v[90:93], v[236:239], v[204:207], v[90:93]
	v_mfma_f32_16x16x32_bf16 v[86:89], v[236:239], v[208:211], v[86:89]
	ds_read_b128 v[184:187], v144 offset:16384
	v_mfma_f32_16x16x32_bf16 v[82:85], v[236:239], v[212:215], v[82:85]
	ds_read_b128 v[188:191], v144 offset:17408
	v_mfma_f32_16x16x32_bf16 v[78:81], v[236:239], v[216:219], v[78:81]
	ds_read_b128 v[192:195], v144 offset:18432
	s_setprio 2
	s_nop 0
	v_mfma_f32_16x16x32_bf16 v[74:77], v[236:239], v[220:223], v[74:77]
	ds_read_b128 v[196:199], v144 offset:19456
	v_mfma_f32_16x16x32_bf16 v[70:73], v[236:239], v[224:227], v[70:73]
	s_add_i32 s38, s43, s37
	s_mov_b32 m0, s38
	v_lshl_add_u64 v[142:143], v[132:133], 0, s[2:3]
	v_mfma_f32_16x16x32_bf16 v[66:69], v[236:239], v[228:231], v[66:69]
;     ...
;   for (int kt = 0; kt < nk; kt++) {
;     if (kt + 1 < nk) asm volatile("s_waitcnt vmcnt(6)" ::: "memory");
;     else asm volatile("s_waitcnt vmcnt(0)" ::: "memory");
;     __builtin_amdgcn_s_barrier();
;     asm volatile("" ::: "memory");
;     if (kt + 2 < nk) G2_STAGE(kt + 2);
;     const char* cS = smem + (kt % 3) * 24576;
;     bf16x8 xa[8], wb[4];
; #pragma unroll
;     for (int f = 0; f < 8; f++) xa[f] = *(const bf16x8*)(cS + aoff + f * 1024);
; #pragma unroll
;     for (int f = 0; f < 4; f++) wb[f] = *(const bf16x8*)(cS + boff + f * 1024);
; #pragma unroll
;     for (int nf = 0; nf < 4; nf++)
; #pragma unroll
;       for (int mf = 0; mf < 8; mf++)
;         acc[nf][mf] = __builtin_amdgcn_mfma_f32_16x16x32_bf16(wb[nf], xa[mf], acc[nf][mf], 0, 0, 0);
;   }
	global_load_lds_dwordx4 v[132:133], off
	s_add_i32 m0, m0, 0x1000
	v_mfma_f32_16x16x32_bf16 v[62:65], v[240:243], v[200:203], v[62:65]
	v_mfma_f32_16x16x32_bf16 v[58:61], v[240:243], v[204:207], v[58:61]
	v_mfma_f32_16x16x32_bf16 v[54:57], v[240:243], v[208:211], v[54:57]
	global_load_lds_dwordx4 v[142:143], off
	v_lshl_add_u64 v[142:143], v[142:143], 0, s[2:3]
	s_add_i32 m0, m0, 0x1000
	v_mfma_f32_16x16x32_bf16 v[50:53], v[240:243], v[212:215], v[50:53]
	v_mfma_f32_16x16x32_bf16 v[46:49], v[240:243], v[216:219], v[46:49]
	v_mfma_f32_16x16x32_bf16 v[42:45], v[240:243], v[220:223], v[42:45]
	global_load_lds_dwordx4 v[142:143], off
	v_lshl_add_u64 v[142:143], v[142:143], 0, s[2:3]
	s_add_i32 m0, m0, 0x1000
	v_mfma_f32_16x16x32_bf16 v[38:41], v[240:243], v[224:227], v[38:41]
	v_mfma_f32_16x16x32_bf16 v[34:37], v[240:243], v[228:231], v[34:37]
	s_setprio 0
	s_nop 0
	v_mfma_f32_16x16x32_bf16 v[30:33], v[244:247], v[200:203], v[30:33]
	global_load_lds_dwordx4 v[142:143], off
	s_add_i32 m0, m0, 0x1000
	v_lshl_add_u64 v[142:143], v[134:135], 0, s[2:3]
	v_mfma_f32_16x16x32_bf16 v[26:29], v[244:247], v[204:207], v[26:29]
	v_mfma_f32_16x16x32_bf16 v[22:25], v[244:247], v[208:211], v[22:25]
	v_mfma_f32_16x16x32_bf16 v[18:21], v[244:247], v[212:215], v[18:21]
	global_load_lds_dwordx4 v[134:135], off
	s_add_i32 m0, m0, 0x1000
	v_lshl_add_u64 v[132:133], v[132:133], 0, s[14:15]
	v_mfma_f32_16x16x32_bf16 v[14:17], v[244:247], v[216:219], v[14:17]
	v_mfma_f32_16x16x32_bf16 v[10:13], v[244:247], v[220:223], v[10:13]
	v_mfma_f32_16x16x32_bf16 v[6:9], v[244:247], v[224:227], v[6:9]
	global_load_lds_dwordx4 v[142:143], off
	v_lshl_add_u64 v[134:135], v[134:135], 0, s[10:11]
	v_mfma_f32_16x16x32_bf16 v[2:5], v[244:247], v[228:231], v[2:5]
	s_mov_b32 s37, s36
	s_nop 0
	s_add_i32 s36, s36, 0x6000
	s_cmp_eq_u32 s36, 0x12000
	s_cselect_b32 s36, 0, s36
	s_nop 0
	s_sub_i32 s9, s9, 1
	s_cmp_lg_u32 s9, 0
	s_cbranch_scc1 .Lt10_loop
	.p2align 3
	s_waitcnt vmcnt(6) lgkmcnt(0)
	s_barrier
	s_setprio 1
	v_add_u32_e32 v144, s36, v136
	v_mfma_f32_16x16x32_bf16 v[126:129], v[184:187], v[146:149], v[126:129]
	ds_read_b128 v[200:203], v144 offset:0
	v_mfma_f32_16x16x32_bf16 v[122:125], v[184:187], v[152:155], v[122:125]
	ds_read_b128 v[204:207], v144 offset:1024
	v_mfma_f32_16x16x32_bf16 v[118:121], v[184:187], v[156:159], v[118:121]
	ds_read_b128 v[208:211], v144 offset:2048
	v_mfma_f32_16x16x32_bf16 v[114:117], v[184:187], v[162:165], v[114:117]
	ds_read_b128 v[212:215], v144 offset:3072
	v_mfma_f32_16x16x32_bf16 v[110:113], v[184:187], v[166:169], v[110:113]
	ds_read_b128 v[216:219], v144 offset:4096
	v_mfma_f32_16x16x32_bf16 v[106:109], v[184:187], v[170:173], v[106:109]
	ds_read_b128 v[220:223], v144 offset:5120
	v_mfma_f32_16x16x32_bf16 v[102:105], v[184:187], v[176:179], v[102:105]
	ds_read_b128 v[224:227], v144 offset:6144
	v_mfma_f32_16x16x32_bf16 v[98:101], v[184:187], v[180:183], v[98:101]
	ds_read_b128 v[228:231], v144 offset:7168
	v_mfma_f32_16x16x32_bf16 v[94:97], v[188:191], v[146:149], v[94:97]
	v_add_u32_e64 v144, s36, v137
	v_mfma_f32_16x16x32_bf16 v[90:93], v[188:191], v[152:155], v[90:93]
	v_mfma_f32_16x16x32_bf16 v[86:89], v[188:191], v[156:159], v[86:89]
	ds_read_b128 v[232:235], v144 offset:16384
	v_mfma_f32_16x16x32_bf16 v[82:85], v[188:191], v[162:165], v[82:85]
	ds_read_b128 v[236:239], v144 offset:17408
	v_mfma_f32_16x16x32_bf16 v[78:81], v[188:191], v[166:169], v[78:81]
	ds_read_b128 v[240:243], v144 offset:18432
	s_setprio 2
	s_nop 0
	v_mfma_f32_16x16x32_bf16 v[74:77], v[188:191], v[170:173], v[74:77]
	ds_read_b128 v[244:247], v144 offset:19456
	v_mfma_f32_16x16x32_bf16 v[70:73], v[188:191], v[176:179], v[70:73]
	s_add_i32 s38, s43, s37
	s_mov_b32 m0, s38
	v_lshl_add_u64 v[142:143], v[132:133], 0, s[2:3]
	v_mfma_f32_16x16x32_bf16 v[66:69], v[188:191], v[180:183], v[66:69]
	global_load_lds_dwordx4 v[132:133], off
	s_add_i32 m0, m0, 0x1000
	v_mfma_f32_16x16x32_bf16 v[62:65], v[192:195], v[146:149], v[62:65]
	v_mfma_f32_16x16x32_bf16 v[58:61], v[192:195], v[152:155], v[58:61]
	v_mfma_f32_16x16x32_bf16 v[54:57], v[192:195], v[156:159], v[54:57]
	global_load_lds_dwordx4 v[142:143], off
	v_lshl_add_u64 v[142:143], v[142:143], 0, s[2:3]
	s_add_i32 m0, m0, 0x1000
	v_mfma_f32_16x16x32_bf16 v[50:53], v[192:195], v[162:165], v[50:53]
	v_mfma_f32_16x16x32_bf16 v[46:49], v[192:195], v[166:169], v[46:49]
	v_mfma_f32_16x16x32_bf16 v[42:45], v[192:195], v[170:173], v[42:45]
	global_load_lds_dwordx4 v[142:143], off
	v_lshl_add_u64 v[142:143], v[142:143], 0, s[2:3]
	s_add_i32 m0, m0, 0x1000
	v_mfma_f32_16x16x32_bf16 v[38:41], v[192:195], v[176:179], v[38:41]
	v_mfma_f32_16x16x32_bf16 v[34:37], v[192:195], v[180:183], v[34:37]
	s_setprio 0
	s_nop 0
	v_mfma_f32_16x16x32_bf16 v[30:33], v[196:199], v[146:149], v[30:33]
	global_load_lds_dwordx4 v[142:143], off
	s_add_i32 m0, m0, 0x1000
	v_lshl_add_u64 v[142:143], v[134:135], 0, s[2:3]
	v_mfma_f32_16x16x32_bf16 v[26:29], v[196:199], v[152:155], v[26:29]
	v_mfma_f32_16x16x32_bf16 v[22:25], v[196:199], v[156:159], v[22:25]
	v_mfma_f32_16x16x32_bf16 v[18:21], v[196:199], v[162:165], v[18:21]
	global_load_lds_dwordx4 v[134:135], off
	s_add_i32 m0, m0, 0x1000
	v_lshl_add_u64 v[132:133], v[132:133], 0, s[14:15]
	v_mfma_f32_16x16x32_bf16 v[14:17], v[196:199], v[166:169], v[14:17]
	v_mfma_f32_16x16x32_bf16 v[10:13], v[196:199], v[170:173], v[10:13]
	v_mfma_f32_16x16x32_bf16 v[6:9], v[196:199], v[176:179], v[6:9]
	global_load_lds_dwordx4 v[142:143], off
	v_lshl_add_u64 v[134:135], v[134:135], 0, s[10:11]
	v_mfma_f32_16x16x32_bf16 v[2:5], v[196:199], v[180:183], v[2:5]
	s_mov_b32 s37, s36
	s_nop 0
	s_add_i32 s36, s36, 0x6000
	s_cmp_eq_u32 s36, 0x12000
	s_cselect_b32 s36, 0, s36
	s_nop 0
	.p2align 3
	s_waitcnt vmcnt(6) lgkmcnt(0)
	s_barrier
;     ...
;   for (int kt = 0; kt < nk; kt++) {
;     if (kt + 1 < nk) asm volatile("s_waitcnt vmcnt(6)" ::: "memory");
;     else asm volatile("s_waitcnt vmcnt(0)" ::: "memory");
;     __builtin_amdgcn_s_barrier();
;     asm volatile("" ::: "memory");
;     if (kt + 2 < nk) G2_STAGE(kt + 2);
;     const char* cS = smem + (kt % 3) * 24576;
;     bf16x8 xa[8], wb[4];
; #pragma unroll
;     for (int f = 0; f < 8; f++) xa[f] = *(const bf16x8*)(cS + aoff + f * 1024);
; #pragma unroll
;     for (int f = 0; f < 4; f++) wb[f] = *(const bf16x8*)(cS + boff + f * 1024);
; #pragma unroll
;     for (int nf = 0; nf < 4; nf++)
; #pragma unroll
;       for (int mf = 0; mf < 8; mf++)
;         acc[nf][mf] = __builtin_amdgcn_mfma_f32_16x16x32_bf16(wb[nf], xa[mf], acc[nf][mf], 0, 0, 0);
	s_setprio 1
	v_add_u32_e32 v144, s36, v136
	v_mfma_f32_16x16x32_bf16 v[126:129], v[232:235], v[200:203], v[126:129]
	ds_read_b128 v[146:149], v144 offset:0
	v_mfma_f32_16x16x32_bf16 v[122:125], v[232:235], v[204:207], v[122:125]
	ds_read_b128 v[152:155], v144 offset:1024
	v_mfma_f32_16x16x32_bf16 v[118:121], v[232:235], v[208:211], v[118:121]
	ds_read_b128 v[156:159], v144 offset:2048
	v_mfma_f32_16x16x32_bf16 v[114:117], v[232:235], v[212:215], v[114:117]
	ds_read_b128 v[162:165], v144 offset:3072
	v_mfma_f32_16x16x32_bf16 v[110:113], v[232:235], v[216:219], v[110:113]
	ds_read_b128 v[166:169], v144 offset:4096
	v_mfma_f32_16x16x32_bf16 v[106:109], v[232:235], v[220:223], v[106:109]
	ds_read_b128 v[170:173], v144 offset:5120
	v_mfma_f32_16x16x32_bf16 v[102:105], v[232:235], v[224:227], v[102:105]
	ds_read_b128 v[176:179], v144 offset:6144
	v_mfma_f32_16x16x32_bf16 v[98:101], v[232:235], v[228:231], v[98:101]
	ds_read_b128 v[180:183], v144 offset:7168
	v_mfma_f32_16x16x32_bf16 v[94:97], v[236:239], v[200:203], v[94:97]
	v_add_u32_e64 v144, s36, v137
	v_mfma_f32_16x16x32_bf16 v[90:93], v[236:239], v[204:207], v[90:93]
	v_mfma_f32_16x16x32_bf16 v[86:89], v[236:239], v[208:211], v[86:89]
	ds_read_b128 v[184:187], v144 offset:16384
	v_mfma_f32_16x16x32_bf16 v[82:85], v[236:239], v[212:215], v[82:85]
	ds_read_b128 v[188:191], v144 offset:17408
	v_mfma_f32_16x16x32_bf16 v[78:81], v[236:239], v[216:219], v[78:81]
	ds_read_b128 v[192:195], v144 offset:18432
	v_mfma_f32_16x16x32_bf16 v[74:77], v[236:239], v[220:223], v[74:77]
	ds_read_b128 v[196:199], v144 offset:19456
	v_mfma_f32_16x16x32_bf16 v[70:73], v[236:239], v[224:227], v[70:73]
	v_mfma_f32_16x16x32_bf16 v[66:69], v[236:239], v[228:231], v[66:69]
	v_mfma_f32_16x16x32_bf16 v[62:65], v[240:243], v[200:203], v[62:65]
	v_mfma_f32_16x16x32_bf16 v[58:61], v[240:243], v[204:207], v[58:61]
	v_mfma_f32_16x16x32_bf16 v[54:57], v[240:243], v[208:211], v[54:57]
	v_mfma_f32_16x16x32_bf16 v[50:53], v[240:243], v[212:215], v[50:53]
	v_mfma_f32_16x16x32_bf16 v[46:49], v[240:243], v[216:219], v[46:49]
	v_mfma_f32_16x16x32_bf16 v[42:45], v[240:243], v[220:223], v[42:45]
	v_mfma_f32_16x16x32_bf16 v[38:41], v[240:243], v[224:227], v[38:41]
	v_mfma_f32_16x16x32_bf16 v[34:37], v[240:243], v[228:231], v[34:37]
	s_setprio 0
	s_nop 0
	v_mfma_f32_16x16x32_bf16 v[30:33], v[244:247], v[200:203], v[30:33]
	v_mfma_f32_16x16x32_bf16 v[26:29], v[244:247], v[204:207], v[26:29]
	v_mfma_f32_16x16x32_bf16 v[22:25], v[244:247], v[208:211], v[22:25]
	v_mfma_f32_16x16x32_bf16 v[18:21], v[244:247], v[212:215], v[18:21]
	v_mfma_f32_16x16x32_bf16 v[14:17], v[244:247], v[216:219], v[14:17]
	v_mfma_f32_16x16x32_bf16 v[10:13], v[244:247], v[220:223], v[10:13]
	v_mfma_f32_16x16x32_bf16 v[6:9], v[244:247], v[224:227], v[6:9]
	v_mfma_f32_16x16x32_bf16 v[2:5], v[244:247], v[228:231], v[2:5]
	s_mov_b32 s37, s36
	s_nop 0
	s_add_i32 s36, s36, 0x6000
	s_cmp_eq_u32 s36, 0x12000
	s_cselect_b32 s36, 0, s36
	s_nop 0
	.p2align 3
	s_waitcnt vmcnt(0) lgkmcnt(0)
	s_barrier
	s_setprio 1
	v_add_u32_e32 v144, s36, v136
	v_mfma_f32_16x16x32_bf16 v[126:129], v[184:187], v[146:149], v[126:129]
	ds_read_b128 v[200:203], v144 offset:0
	v_mfma_f32_16x16x32_bf16 v[122:125], v[184:187], v[152:155], v[122:125]
	ds_read_b128 v[204:207], v144 offset:1024
	v_mfma_f32_16x16x32_bf16 v[118:121], v[184:187], v[156:159], v[118:121]
	ds_read_b128 v[208:211], v144 offset:2048
	v_mfma_f32_16x16x32_bf16 v[114:117], v[184:187], v[162:165], v[114:117]
	ds_read_b128 v[212:215], v144 offset:3072
	v_mfma_f32_16x16x32_bf16 v[110:113], v[184:187], v[166:169], v[110:113]
	ds_read_b128 v[216:219], v144 offset:4096
	v_mfma_f32_16x16x32_bf16 v[106:109], v[184:187], v[170:173], v[106:109]
	ds_read_b128 v[220:223], v144 offset:5120
	v_mfma_f32_16x16x32_bf16 v[102:105], v[184:187], v[176:179], v[102:105]
	ds_read_b128 v[224:227], v144 offset:6144
	v_mfma_f32_16x16x32_bf16 v[98:101], v[184:187], v[180:183], v[98:101]
	ds_read_b128 v[228:231], v144 offset:7168
	v_mfma_f32_16x16x32_bf16 v[94:97], v[188:191], v[146:149], v[94:97]
	v_add_u32_e64 v144, s36, v137
	v_mfma_f32_16x16x32_bf16 v[90:93], v[188:191], v[152:155], v[90:93]
	v_mfma_f32_16x16x32_bf16 v[86:89], v[188:191], v[156:159], v[86:89]
	ds_read_b128 v[232:235], v144 offset:16384
	v_mfma_f32_16x16x32_bf16 v[82:85], v[188:191], v[162:165], v[82:85]
	ds_read_b128 v[236:239], v144 offset:17408
	v_mfma_f32_16x16x32_bf16 v[78:81], v[188:191], v[166:169], v[78:81]
	ds_read_b128 v[240:243], v144 offset:18432
	v_mfma_f32_16x16x32_bf16 v[74:77], v[188:191], v[170:173], v[74:77]
	ds_read_b128 v[244:247], v144 offset:19456
	v_mfma_f32_16x16x32_bf16 v[70:73], v[188:191], v[176:179], v[70:73]
	v_mfma_f32_16x16x32_bf16 v[66:69], v[188:191], v[180:183], v[66:69]
	v_mfma_f32_16x16x32_bf16 v[62:65], v[192:195], v[146:149], v[62:65]
	v_mfma_f32_16x16x32_bf16 v[58:61], v[192:195], v[152:155], v[58:61]
	v_mfma_f32_16x16x32_bf16 v[54:57], v[192:195], v[156:159], v[54:57]
	v_mfma_f32_16x16x32_bf16 v[50:53], v[192:195], v[162:165], v[50:53]
	v_mfma_f32_16x16x32_bf16 v[46:49], v[192:195], v[166:169], v[46:49]
	v_mfma_f32_16x16x32_bf16 v[42:45], v[192:195], v[170:173], v[42:45]
	v_mfma_f32_16x16x32_bf16 v[38:41], v[192:195], v[176:179], v[38:41]
	v_mfma_f32_16x16x32_bf16 v[34:37], v[192:195], v[180:183], v[34:37]
	s_setprio 0
	s_nop 0
	v_mfma_f32_16x16x32_bf16 v[30:33], v[196:199], v[146:149], v[30:33]
	v_mfma_f32_16x16x32_bf16 v[26:29], v[196:199], v[152:155], v[26:29]
	v_mfma_f32_16x16x32_bf16 v[22:25], v[196:199], v[156:159], v[22:25]
	v_mfma_f32_16x16x32_bf16 v[18:21], v[196:199], v[162:165], v[18:21]
	v_mfma_f32_16x16x32_bf16 v[14:17], v[196:199], v[166:169], v[14:17]
	v_mfma_f32_16x16x32_bf16 v[10:13], v[196:199], v[170:173], v[10:13]
	v_mfma_f32_16x16x32_bf16 v[6:9], v[196:199], v[176:179], v[6:9]
	v_mfma_f32_16x16x32_bf16 v[2:5], v[196:199], v[180:183], v[2:5]
	s_mov_b32 s37, s36
	s_nop 0
	s_add_i32 s36, s36, 0x6000
	s_cmp_eq_u32 s36, 0x12000
	s_cselect_b32 s36, 0, s36
	s_nop 0
	.p2align 3
	s_waitcnt lgkmcnt(0)
; DEVI unsigned pack2(float a, float b) { return __builtin_bit_cast(unsigned, __builtin_convertvector((f32x2_t){a, b}, bf16x2_t)); }
; DEVI float siluf_(float x) { return x * __builtin_amdgcn_rcpf(1.f + __expf(-x)); }
;     ...
;     if (EPI == EPI_SWIGLU) {
; #pragma unroll
;       for (int nf = 0; nf < 2; nf++) {
;         const int hcol = (n0 >> 1) + wn * 32 + nf * 16 + quad * 4;
;         f32x4 g = acc[nf][mf], u = acc[nf + 2][mf];
;         u32x2 pk;
;         pk[0] = pack2(siluf_(g[0]) * u[0], siluf_(g[1]) * u[1]);
;         pk[1] = pack2(siluf_(g[2]) * u[2], siluf_(g[3]) * u[3]);
;         *(u32x2*)(outb + (size_t)row * DFF + hcol) = pk;
;       }
	s_nop 0
	v_mfma_f32_16x16x32_bf16 v[126:129], v[232:235], v[200:203], v[126:129]
	v_mfma_f32_16x16x32_bf16 v[122:125], v[232:235], v[204:207], v[122:125]
	v_mfma_f32_16x16x32_bf16 v[118:121], v[232:235], v[208:211], v[118:121]
	v_mfma_f32_16x16x32_bf16 v[114:117], v[232:235], v[212:215], v[114:117]
	v_mfma_f32_16x16x32_bf16 v[110:113], v[232:235], v[216:219], v[110:113]
	v_mfma_f32_16x16x32_bf16 v[106:109], v[232:235], v[220:223], v[106:109]
	v_mfma_f32_16x16x32_bf16 v[102:105], v[232:235], v[224:227], v[102:105]
	v_mfma_f32_16x16x32_bf16 v[98:101], v[232:235], v[228:231], v[98:101]
	v_mfma_f32_16x16x32_bf16 v[94:97], v[236:239], v[200:203], v[94:97]
	v_mfma_f32_16x16x32_bf16 v[90:93], v[236:239], v[204:207], v[90:93]
	v_mfma_f32_16x16x32_bf16 v[86:89], v[236:239], v[208:211], v[86:89]
	v_mfma_f32_16x16x32_bf16 v[82:85], v[236:239], v[212:215], v[82:85]
	v_mfma_f32_16x16x32_bf16 v[78:81], v[236:239], v[216:219], v[78:81]
	v_mfma_f32_16x16x32_bf16 v[74:77], v[236:239], v[220:223], v[74:77]
	v_mfma_f32_16x16x32_bf16 v[70:73], v[236:239], v[224:227], v[70:73]
	v_mfma_f32_16x16x32_bf16 v[66:69], v[236:239], v[228:231], v[66:69]
	v_mfma_f32_16x16x32_bf16 v[62:65], v[240:243], v[200:203], v[62:65]
	v_mfma_f32_16x16x32_bf16 v[58:61], v[240:243], v[204:207], v[58:61]
	v_mfma_f32_16x16x32_bf16 v[54:57], v[240:243], v[208:211], v[54:57]
	v_mfma_f32_16x16x32_bf16 v[50:53], v[240:243], v[212:215], v[50:53]
	v_mfma_f32_16x16x32_bf16 v[46:49], v[240:243], v[216:219], v[46:49]
	v_mfma_f32_16x16x32_bf16 v[42:45], v[240:243], v[220:223], v[42:45]
	v_mfma_f32_16x16x32_bf16 v[38:41], v[240:243], v[224:227], v[38:41]
	v_mfma_f32_16x16x32_bf16 v[34:37], v[240:243], v[228:231], v[34:37]
	v_mfma_f32_16x16x32_bf16 v[30:33], v[244:247], v[200:203], v[30:33]
	v_mfma_f32_16x16x32_bf16 v[26:29], v[244:247], v[204:207], v[26:29]
	v_mfma_f32_16x16x32_bf16 v[22:25], v[244:247], v[208:211], v[22:25]
	v_mfma_f32_16x16x32_bf16 v[18:21], v[244:247], v[212:215], v[18:21]
	v_mfma_f32_16x16x32_bf16 v[14:17], v[244:247], v[216:219], v[14:17]
	v_mfma_f32_16x16x32_bf16 v[10:13], v[244:247], v[220:223], v[10:13]
	v_mfma_f32_16x16x32_bf16 v[6:9], v[244:247], v[224:227], v[6:9]
	v_mfma_f32_16x16x32_bf16 v[2:5], v[244:247], v[228:231], v[2:5]
	s_mov_b32 m0, s39
	s_mov_b32 s10, 0x16000
	s_mov_b32 s11, 0
	s_mov_b32 s40, 0xbfb8aa3b
	s_nop 7
	v_mov_b32_e32 v224, s40
	v_mov_b32_e32 v225, s40
	v_mov_b32_e32 v226, 1.0
	v_mov_b32_e32 v227, 1.0
	v_pk_mul_f32 v[216:217], v[126:127], v[224:225]
	v_pk_mul_f32 v[218:219], v[128:129], v[224:225]
	v_exp_f32_e32 v216, v216
	v_exp_f32_e32 v217, v217
	v_exp_f32_e32 v218, v218
	v_exp_f32_e32 v219, v219
	v_pk_add_f32 v[216:217], v[216:217], v[226:227]
	v_pk_add_f32 v[218:219], v[218:219], v[226:227]
	v_rcp_f32_e32 v216, v216
	v_rcp_f32_e32 v217, v217
	v_rcp_f32_e32 v218, v218
	v_rcp_f32_e32 v219, v219
	v_pk_mul_f32 v[126:127], v[126:127], v[216:217]
	v_pk_mul_f32 v[128:129], v[128:129], v[218:219]
	v_pk_mul_f32 v[126:127], v[126:127], v[62:63]
	v_pk_mul_f32 v[128:129], v[128:129], v[64:65]
	v_pk_mul_f32 v[220:221], v[94:95], v[224:225]
	v_pk_mul_f32 v[222:223], v[96:97], v[224:225]
	v_exp_f32_e32 v220, v220
	v_exp_f32_e32 v221, v221
	v_exp_f32_e32 v222, v222
	v_exp_f32_e32 v223, v223
	v_pk_add_f32 v[220:221], v[220:221], v[226:227]
	v_pk_add_f32 v[222:223], v[222:223], v[226:227]
	v_rcp_f32_e32 v220, v220
	v_rcp_f32_e32 v221, v221
	v_rcp_f32_e32 v222, v222
	v_rcp_f32_e32 v223, v223
	v_pk_mul_f32 v[94:95], v[94:95], v[220:221]
	v_pk_mul_f32 v[96:97], v[96:97], v[222:223]
	v_pk_mul_f32 v[94:95], v[94:95], v[30:31]
	v_pk_mul_f32 v[96:97], v[96:97], v[32:33]
	v_cvt_pk_bf16_f32 v126, v126, v127
	v_cvt_pk_bf16_f32 v127, v128, v129
	v_cvt_pk_bf16_f32 v128, v94, v95
	v_cvt_pk_bf16_f32 v129, v96, v97
	s_nop 1
	v_permlane16_swap_b32_e32 v126, v128
	v_permlane16_swap_b32_e32 v127, v129
	global_store_dwordx4 v[140:141], v[126:129], off
	v_lshl_add_u64 v[140:141], v[140:141], 0, s[10:11]
	v_pk_mul_f32 v[216:217], v[122:123], v[224:225]
	v_pk_mul_f32 v[218:219], v[124:125], v[224:225]
	v_exp_f32_e32 v216, v216
	v_exp_f32_e32 v217, v217
	v_exp_f32_e32 v218, v218
	v_exp_f32_e32 v219, v219
	v_pk_add_f32 v[216:217], v[216:217], v[226:227]
	v_pk_add_f32 v[218:219], v[218:219], v[226:227]
	v_rcp_f32_e32 v216, v216
	v_rcp_f32_e32 v217, v217
	v_rcp_f32_e32 v218, v218
	v_rcp_f32_e32 v219, v219
	v_pk_mul_f32 v[122:123], v[122:123], v[216:217]
	v_pk_mul_f32 v[124:125], v[124:125], v[218:219]
	v_pk_mul_f32 v[122:123], v[122:123], v[58:59]
	v_pk_mul_f32 v[124:125], v[124:125], v[60:61]
	v_pk_mul_f32 v[220:221], v[90:91], v[224:225]
	v_pk_mul_f32 v[222:223], v[92:93], v[224:225]
	v_exp_f32_e32 v220, v220
	v_exp_f32_e32 v221, v221
	v_exp_f32_e32 v222, v222
	v_exp_f32_e32 v223, v223
	v_pk_add_f32 v[220:221], v[220:221], v[226:227]
	v_pk_add_f32 v[222:223], v[222:223], v[226:227]
	v_rcp_f32_e32 v220, v220
	v_rcp_f32_e32 v221, v221
	v_rcp_f32_e32 v222, v222
	v_rcp_f32_e32 v223, v223
	v_pk_mul_f32 v[90:91], v[90:91], v[220:221]
	v_pk_mul_f32 v[92:93], v[92:93], v[222:223]
	v_pk_mul_f32 v[90:91], v[90:91], v[26:27]
	v_pk_mul_f32 v[92:93], v[92:93], v[28:29]
	v_cvt_pk_bf16_f32 v122, v122, v123
	v_cvt_pk_bf16_f32 v123, v124, v125
	v_cvt_pk_bf16_f32 v124, v90, v91
	v_cvt_pk_bf16_f32 v125, v92, v93
	s_nop 1
	v_permlane16_swap_b32_e32 v122, v124
	v_permlane16_swap_b32_e32 v123, v125
	global_store_dwordx4 v[140:141], v[122:125], off
	v_lshl_add_u64 v[140:141], v[140:141], 0, s[10:11]
	v_pk_mul_f32 v[216:217], v[118:119], v[224:225]
	v_pk_mul_f32 v[218:219], v[120:121], v[224:225]
	v_exp_f32_e32 v216, v216
	v_exp_f32_e32 v217, v217
	v_exp_f32_e32 v218, v218
	v_exp_f32_e32 v219, v219
; DEVI unsigned pack2(float a, float b) { return __builtin_bit_cast(unsigned, __builtin_convertvector((f32x2_t){a, b}, bf16x2_t)); }
; DEVI float siluf_(float x) { return x * __builtin_amdgcn_rcpf(1.f + __expf(-x)); }
;     ...
;     if (EPI == EPI_SWIGLU) {
; #pragma unroll
;       for (int nf = 0; nf < 2; nf++) {
;         const int hcol = (n0 >> 1) + wn * 32 + nf * 16 + quad * 4;
;         f32x4 g = acc[nf][mf], u = acc[nf + 2][mf];
;         u32x2 pk;
;         pk[0] = pack2(siluf_(g[0]) * u[0], siluf_(g[1]) * u[1]);
;         pk[1] = pack2(siluf_(g[2]) * u[2], siluf_(g[3]) * u[3]);
;         *(u32x2*)(outb + (size_t)row * DFF + hcol) = pk;
;       }
	v_pk_add_f32 v[216:217], v[216:217], v[226:227]
	v_pk_add_f32 v[218:219], v[218:219], v[226:227]
	v_rcp_f32_e32 v216, v216
	v_rcp_f32_e32 v217, v217
	v_rcp_f32_e32 v218, v218
	v_rcp_f32_e32 v219, v219
	v_pk_mul_f32 v[118:119], v[118:119], v[216:217]
	v_pk_mul_f32 v[120:121], v[120:121], v[218:219]
	v_pk_mul_f32 v[118:119], v[118:119], v[54:55]
	v_pk_mul_f32 v[120:121], v[120:121], v[56:57]
	v_pk_mul_f32 v[220:221], v[86:87], v[224:225]
	v_pk_mul_f32 v[222:223], v[88:89], v[224:225]
	v_exp_f32_e32 v220, v220
	v_exp_f32_e32 v221, v221
	v_exp_f32_e32 v222, v222
	v_exp_f32_e32 v223, v223
	v_pk_add_f32 v[220:221], v[220:221], v[226:227]
	v_pk_add_f32 v[222:223], v[222:223], v[226:227]
	v_rcp_f32_e32 v220, v220
	v_rcp_f32_e32 v221, v221
	v_rcp_f32_e32 v222, v222
	v_rcp_f32_e32 v223, v223
	v_pk_mul_f32 v[86:87], v[86:87], v[220:221]
	v_pk_mul_f32 v[88:89], v[88:89], v[222:223]
	v_pk_mul_f32 v[86:87], v[86:87], v[22:23]
	v_pk_mul_f32 v[88:89], v[88:89], v[24:25]
	v_cvt_pk_bf16_f32 v118, v118, v119
	v_cvt_pk_bf16_f32 v119, v120, v121
	v_cvt_pk_bf16_f32 v120, v86, v87
	v_cvt_pk_bf16_f32 v121, v88, v89
	s_nop 1
	v_permlane16_swap_b32_e32 v118, v120
	v_permlane16_swap_b32_e32 v119, v121
	global_store_dwordx4 v[140:141], v[118:121], off
	v_lshl_add_u64 v[140:141], v[140:141], 0, s[10:11]
	v_pk_mul_f32 v[216:217], v[114:115], v[224:225]
	v_pk_mul_f32 v[218:219], v[116:117], v[224:225]
	v_exp_f32_e32 v216, v216
	v_exp_f32_e32 v217, v217
	v_exp_f32_e32 v218, v218
	v_exp_f32_e32 v219, v219
	v_pk_add_f32 v[216:217], v[216:217], v[226:227]
	v_pk_add_f32 v[218:219], v[218:219], v[226:227]
	v_rcp_f32_e32 v216, v216
	v_rcp_f32_e32 v217, v217
	v_rcp_f32_e32 v218, v218
	v_rcp_f32_e32 v219, v219
	v_pk_mul_f32 v[114:115], v[114:115], v[216:217]
	v_pk_mul_f32 v[116:117], v[116:117], v[218:219]
	v_pk_mul_f32 v[114:115], v[114:115], v[50:51]
	v_pk_mul_f32 v[116:117], v[116:117], v[52:53]
	v_pk_mul_f32 v[220:221], v[82:83], v[224:225]
	v_pk_mul_f32 v[222:223], v[84:85], v[224:225]
	v_exp_f32_e32 v220, v220
	v_exp_f32_e32 v221, v221
	v_exp_f32_e32 v222, v222
	v_exp_f32_e32 v223, v223
	v_pk_add_f32 v[220:221], v[220:221], v[226:227]
	v_pk_add_f32 v[222:223], v[222:223], v[226:227]
	v_rcp_f32_e32 v220, v220
	v_rcp_f32_e32 v221, v221
	v_rcp_f32_e32 v222, v222
	v_rcp_f32_e32 v223, v223
	v_pk_mul_f32 v[82:83], v[82:83], v[220:221]
	v_pk_mul_f32 v[84:85], v[84:85], v[222:223]
	v_pk_mul_f32 v[82:83], v[82:83], v[18:19]
	v_pk_mul_f32 v[84:85], v[84:85], v[20:21]
	v_cvt_pk_bf16_f32 v114, v114, v115
	v_cvt_pk_bf16_f32 v115, v116, v117
	v_cvt_pk_bf16_f32 v116, v82, v83
	v_cvt_pk_bf16_f32 v117, v84, v85
	s_nop 1
	v_permlane16_swap_b32_e32 v114, v116
	v_permlane16_swap_b32_e32 v115, v117
	global_store_dwordx4 v[140:141], v[114:117], off
	v_lshl_add_u64 v[140:141], v[140:141], 0, s[10:11]
	v_pk_mul_f32 v[216:217], v[110:111], v[224:225]
	v_pk_mul_f32 v[218:219], v[112:113], v[224:225]
	v_exp_f32_e32 v216, v216
	v_exp_f32_e32 v217, v217
	v_exp_f32_e32 v218, v218
	v_exp_f32_e32 v219, v219
	v_pk_add_f32 v[216:217], v[216:217], v[226:227]
	v_pk_add_f32 v[218:219], v[218:219], v[226:227]
	v_rcp_f32_e32 v216, v216
	v_rcp_f32_e32 v217, v217
	v_rcp_f32_e32 v218, v218
	v_rcp_f32_e32 v219, v219
	v_pk_mul_f32 v[110:111], v[110:111], v[216:217]
	v_pk_mul_f32 v[112:113], v[112:113], v[218:219]
	v_pk_mul_f32 v[110:111], v[110:111], v[46:47]
	v_pk_mul_f32 v[112:113], v[112:113], v[48:49]
	v_pk_mul_f32 v[220:221], v[78:79], v[224:225]
	v_pk_mul_f32 v[222:223], v[80:81], v[224:225]
	v_exp_f32_e32 v220, v220
	v_exp_f32_e32 v221, v221
	v_exp_f32_e32 v222, v222
	v_exp_f32_e32 v223, v223
	v_pk_add_f32 v[220:221], v[220:221], v[226:227]
	v_pk_add_f32 v[222:223], v[222:223], v[226:227]
	v_rcp_f32_e32 v220, v220
	v_rcp_f32_e32 v221, v221
	v_rcp_f32_e32 v222, v222
	v_rcp_f32_e32 v223, v223
	v_pk_mul_f32 v[78:79], v[78:79], v[220:221]
	v_pk_mul_f32 v[80:81], v[80:81], v[222:223]
	v_pk_mul_f32 v[78:79], v[78:79], v[14:15]
	v_pk_mul_f32 v[80:81], v[80:81], v[16:17]
	v_cvt_pk_bf16_f32 v110, v110, v111
	v_cvt_pk_bf16_f32 v111, v112, v113
	v_cvt_pk_bf16_f32 v112, v78, v79
	v_cvt_pk_bf16_f32 v113, v80, v81
	s_nop 1
	v_permlane16_swap_b32_e32 v110, v112
	v_permlane16_swap_b32_e32 v111, v113
	global_store_dwordx4 v[140:141], v[110:113], off
	v_lshl_add_u64 v[140:141], v[140:141], 0, s[10:11]
	v_pk_mul_f32 v[216:217], v[106:107], v[224:225]
	v_pk_mul_f32 v[218:219], v[108:109], v[224:225]
	v_exp_f32_e32 v216, v216
; DEVI unsigned pack2(float a, float b) { return __builtin_bit_cast(unsigned, __builtin_convertvector((f32x2_t){a, b}, bf16x2_t)); }
; DEVI float siluf_(float x) { return x * __builtin_amdgcn_rcpf(1.f + __expf(-x)); }
; DEVI int xcd_first_tile() { return (blockIdx.x & 7) * (gridDim.x >> 3) + (blockIdx.x >> 3); }
;     ...
;     if (EPI == EPI_SWIGLU) {
; #pragma unroll
;       for (int nf = 0; nf < 2; nf++) {
;         const int hcol = (n0 >> 1) + wn * 32 + nf * 16 + quad * 4;
;         f32x4 g = acc[nf][mf], u = acc[nf + 2][mf];
;         u32x2 pk;
;         pk[0] = pack2(siluf_(g[0]) * u[0], siluf_(g[1]) * u[1]);
;         pk[1] = pack2(siluf_(g[2]) * u[2], siluf_(g[3]) * u[3]);
;         *(u32x2*)(outb + (size_t)row * DFF + hcol) = pk;
;       }
; DEVI void run_phase(const Params& p, int ph, char* smem) {
;     ...
;       for (int t = xcd_first_tile(); t < 66 * 44; t += xcd_tile_step()) {
;         int mt_, nt_; tile_coords(t, 66, 44, mt_, nt_);
;         gemm_tile256<EPI_SWIGLU>(p, xb, 1024, Bt, 1024, mt_ * 256, nt_ * 128, hb, DFF, smem);
;       }
	v_exp_f32_e32 v217, v217
	v_exp_f32_e32 v218, v218
	v_exp_f32_e32 v219, v219
	v_pk_add_f32 v[216:217], v[216:217], v[226:227]
	v_pk_add_f32 v[218:219], v[218:219], v[226:227]
	v_rcp_f32_e32 v216, v216
	v_rcp_f32_e32 v217, v217
	v_rcp_f32_e32 v218, v218
	v_rcp_f32_e32 v219, v219
	v_pk_mul_f32 v[106:107], v[106:107], v[216:217]
	v_pk_mul_f32 v[108:109], v[108:109], v[218:219]
	v_pk_mul_f32 v[106:107], v[106:107], v[42:43]
	v_pk_mul_f32 v[108:109], v[108:109], v[44:45]
	v_pk_mul_f32 v[220:221], v[74:75], v[224:225]
	v_pk_mul_f32 v[222:223], v[76:77], v[224:225]
	v_exp_f32_e32 v220, v220
	v_exp_f32_e32 v221, v221
	v_exp_f32_e32 v222, v222
	v_exp_f32_e32 v223, v223
	v_pk_add_f32 v[220:221], v[220:221], v[226:227]
	v_pk_add_f32 v[222:223], v[222:223], v[226:227]
	v_rcp_f32_e32 v220, v220
	v_rcp_f32_e32 v221, v221
	v_rcp_f32_e32 v222, v222
	v_rcp_f32_e32 v223, v223
	v_pk_mul_f32 v[74:75], v[74:75], v[220:221]
	v_pk_mul_f32 v[76:77], v[76:77], v[222:223]
	v_pk_mul_f32 v[74:75], v[74:75], v[10:11]
	v_pk_mul_f32 v[76:77], v[76:77], v[12:13]
	v_cvt_pk_bf16_f32 v106, v106, v107
	v_cvt_pk_bf16_f32 v107, v108, v109
	v_cvt_pk_bf16_f32 v108, v74, v75
	v_cvt_pk_bf16_f32 v109, v76, v77
	s_nop 1
	v_permlane16_swap_b32_e32 v106, v108
	v_permlane16_swap_b32_e32 v107, v109
	global_store_dwordx4 v[140:141], v[106:109], off
	v_lshl_add_u64 v[140:141], v[140:141], 0, s[10:11]
	v_pk_mul_f32 v[216:217], v[102:103], v[224:225]
	v_pk_mul_f32 v[218:219], v[104:105], v[224:225]
	v_exp_f32_e32 v216, v216
	v_exp_f32_e32 v217, v217
	v_exp_f32_e32 v218, v218
	v_exp_f32_e32 v219, v219
	v_pk_add_f32 v[216:217], v[216:217], v[226:227]
	v_pk_add_f32 v[218:219], v[218:219], v[226:227]
	v_rcp_f32_e32 v216, v216
	v_rcp_f32_e32 v217, v217
	v_rcp_f32_e32 v218, v218
	v_rcp_f32_e32 v219, v219
	v_pk_mul_f32 v[102:103], v[102:103], v[216:217]
	v_pk_mul_f32 v[104:105], v[104:105], v[218:219]
	v_pk_mul_f32 v[102:103], v[102:103], v[38:39]
	v_pk_mul_f32 v[104:105], v[104:105], v[40:41]
	v_pk_mul_f32 v[220:221], v[70:71], v[224:225]
	v_pk_mul_f32 v[222:223], v[72:73], v[224:225]
	v_exp_f32_e32 v220, v220
	v_exp_f32_e32 v221, v221
	v_exp_f32_e32 v222, v222
	v_exp_f32_e32 v223, v223
	v_pk_add_f32 v[220:221], v[220:221], v[226:227]
	v_pk_add_f32 v[222:223], v[222:223], v[226:227]
	v_rcp_f32_e32 v220, v220
	v_rcp_f32_e32 v221, v221
	v_rcp_f32_e32 v222, v222
	v_rcp_f32_e32 v223, v223
	v_pk_mul_f32 v[70:71], v[70:71], v[220:221]
	v_pk_mul_f32 v[72:73], v[72:73], v[222:223]
	v_pk_mul_f32 v[70:71], v[70:71], v[6:7]
	v_pk_mul_f32 v[72:73], v[72:73], v[8:9]
	v_cvt_pk_bf16_f32 v102, v102, v103
	v_cvt_pk_bf16_f32 v103, v104, v105
	v_cvt_pk_bf16_f32 v104, v70, v71
	v_cvt_pk_bf16_f32 v105, v72, v73
	s_nop 1
	v_permlane16_swap_b32_e32 v102, v104
	v_permlane16_swap_b32_e32 v103, v105
	global_store_dwordx4 v[140:141], v[102:105], off
	v_lshl_add_u64 v[140:141], v[140:141], 0, s[10:11]
	v_pk_mul_f32 v[216:217], v[98:99], v[224:225]
	v_pk_mul_f32 v[218:219], v[100:101], v[224:225]
	v_exp_f32_e32 v216, v216
	v_exp_f32_e32 v217, v217
	v_exp_f32_e32 v218, v218
	v_exp_f32_e32 v219, v219
	v_pk_add_f32 v[216:217], v[216:217], v[226:227]
	v_pk_add_f32 v[218:219], v[218:219], v[226:227]
	v_rcp_f32_e32 v216, v216
	v_rcp_f32_e32 v217, v217
	v_rcp_f32_e32 v218, v218
	v_rcp_f32_e32 v219, v219
	v_pk_mul_f32 v[98:99], v[98:99], v[216:217]
	v_pk_mul_f32 v[100:101], v[100:101], v[218:219]
	v_pk_mul_f32 v[98:99], v[98:99], v[34:35]
	v_pk_mul_f32 v[100:101], v[100:101], v[36:37]
	v_pk_mul_f32 v[220:221], v[66:67], v[224:225]
	v_pk_mul_f32 v[222:223], v[68:69], v[224:225]
	v_exp_f32_e32 v220, v220
	v_exp_f32_e32 v221, v221
	v_exp_f32_e32 v222, v222
	v_exp_f32_e32 v223, v223
	v_pk_add_f32 v[220:221], v[220:221], v[226:227]
	v_pk_add_f32 v[222:223], v[222:223], v[226:227]
	v_rcp_f32_e32 v220, v220
	v_rcp_f32_e32 v221, v221
	v_rcp_f32_e32 v222, v222
	v_rcp_f32_e32 v223, v223
	v_pk_mul_f32 v[66:67], v[66:67], v[220:221]
	v_pk_mul_f32 v[68:69], v[68:69], v[222:223]
	v_pk_mul_f32 v[66:67], v[66:67], v[2:3]
	v_pk_mul_f32 v[68:69], v[68:69], v[4:5]
	v_cvt_pk_bf16_f32 v98, v98, v99
	v_cvt_pk_bf16_f32 v99, v100, v101
	v_cvt_pk_bf16_f32 v100, v66, v67
	v_cvt_pk_bf16_f32 v101, v68, v69
	s_nop 1
	v_permlane16_swap_b32_e32 v98, v100
	v_permlane16_swap_b32_e32 v99, v101
	global_store_dwordx4 v[140:141], v[98:101], off
	v_readlane_b32 s42, v250, 7
	s_add_i32 s8, s8, s42
	s_cmpk_gt_i32 s8, 0xb57
	s_cbranch_scc0 .LBB0_124
	s_branch .LBB0_131

; #define LAS __attribute__((address_space(3)))
;     ...
;   const int nk = (nk_part < 0) ? (K >> 5) : nk_part;
;   const int lrow = tid >> 2, lpc = tid & 3;
;   const int lch = lpc ^ ((0x78 >> (((lrow >> 2) & 3) * 2)) & 3);
;   const u16* ga = A + (size_t)(m0 + lrow) * lda + kbeg + lch * 8;
;   const u16* gb = Bt + (size_t)(n0 + lrow) * K + kbeg + lch * 8;
;   const size_t ga1 = (size_t)64 * lda, gb1 = (size_t)64 * K;
;   const unsigned lds0 = (unsigned)(uintptr_t)(LAS char*)smem + (unsigned)__builtin_amdgcn_readfirstlane(wid) * 1024u;
;     ...
;   __syncthreads();
;   G2_STAGE(0); G2_STAGE(1);
; DEVI void run_phase(const Params& p, int ph, char* smem) {
;     ...
;           const int u_ = t - 512, tl_ = u_ / 2, q_ = u_ - tl_ * 2;
;           gemm_tile256<EPI_RESID_ATOMIC>(p, ox, 256, Bt, 256, (64 + (tl_ & 1)) * 256, (tl_ >> 1) * 128, nullptr, 0, smem, q_ * 128, 4, q_);
.LBB0_147:
	s_cmpk_gt_i32 s38, 0x1ff
	s_mov_b64 s[2:3], -1
	s_cbranch_scc0 .LBB0_208
	s_setprio 2
	s_sub_i32 s98, s38, 512
	s_lshr_b32 s41, s98, 1
	s_and_b32 s99, s98, 1
	s_lshr_b32 s13, s41, 1
	s_and_b32 s41, s41, 1
	s_add_i32 s41, s41, 64
	v_readlane_b32 s2, v250, 5
	v_readlane_b32 s3, v250, 6
	v_readlane_b32 s98, v254, 62
	s_mul_i32 s1, s41, 0x20000
	s_add_u32 s4, s2, s1
	s_addc_u32 s5, s3, 0
	s_add_u32 s4, s4, 0xe700000
	s_addc_u32 s5, s5, 0
	s_mul_i32 s1, s98, 0x80000
	s_mul_i32 s12, s13, 0x10000
	s_add_i32 s1, s1, s12
	s_add_u32 s8, s2, s1
	s_addc_u32 s9, s3, 0
	s_add_u32 s8, s8, 0x16c00000
	s_addc_u32 s9, s9, 0
	s_mul_i32 s1, s99, 256
	s_add_u32 s4, s4, s1
	s_addc_u32 s5, s5, 0
	s_mul_i32 s1, s99, 512
	s_add_u32 s8, s8, s1
	s_addc_u32 s9, s9, 0
	s_movk_i32 s0, 0x78
	v_lshrrev_b32_e32 v0, 2, v145
	v_and_b32_e32 v131, 3, v145
	v_bfe_u32 v136, v145, 4, 2
	v_lshlrev_b32_e32 v136, 1, v136
	v_lshrrev_b32_e64 v136, v136, s0
	v_and_b32_e32 v136, 3, v136
	v_xor_b32_e32 v131, v131, v136
	v_lshlrev_b32_e32 v131, 4, v131
	s_movk_i32 s12, 0x200
	v_mad_u32_u24 v0, v0, s12, v131
	v_bfe_u32 v137, v145, 2, 1
	s_movk_i32 s12, 0x1c0
	v_mul_u32_u24_e32 v136, s12, v137
	v_sub_u32_e32 v136, v0, v136
	v_mov_b32_e32 v137, 0
	v_lshl_add_u64 v[134:135], s[8:9], 0, v[136:137]
	v_bfe_u32 v137, v145, 2, 1
	s_mov_b32 s10, 64
	s_mov_b32 s11, 0
	v_lshl_add_u64 v[132:133], s[4:5], 0, v[0:1]
	v_bfe_u32 v136, v145, 2, 2
	v_lshlrev_b32_e32 v136, 1, v136
	v_lshrrev_b32_e64 v136, v136, s0
	v_and_b32_e32 v136, 3, v136
	v_bfe_u32 v137, v145, 4, 2
	v_xor_b32_e32 v136, v136, v137
	v_lshlrev_b32_e32 v136, 4, v136
	v_and_b32_e32 v131, 15, v145
	v_lshl_or_b32 v136, v131, 6, v136
	v_bfe_u32 v137, v145, 6, 1
	v_lshl_or_b32 v137, v137, 12, v136
	v_lshrrev_b32_e32 v0, 7, v145
	v_lshl_or_b32 v136, v0, 13, v136
	v_and_b32_e32 v140, 1, v131
	v_lshl_or_b32 v131, v0, 7, v131
	v_bfe_u32 v0, v145, 4, 2
	v_lshlrev_b32_e32 v0, 3, v0
	v_bfe_u32 v141, v145, 6, 1
	s_lshl_b32 s1, s41, 19
	s_lshl_b32 s12, s13, 8
	s_add_i32 s1, s1, s12
	s_add_u32 s4, s2, s1
	s_addc_u32 s5, s3, 0
	s_add_u32 s4, s4, 0x4200000
	s_addc_u32 s5, s5, 0
	v_lshlrev_b32_e32 v138, 11, v131
	v_lshl_add_u32 v138, v141, 7, v138
	v_bfe_u32 v139, v145, 4, 1
	v_lshl_add_u32 v138, v139, 5, v138
	v_bfe_u32 v139, v145, 5, 1
	v_lshl_add_u32 v138, v139, 4, v138
	v_mov_b32_e32 v139, 0
	v_lshl_add_u64 v[138:139], s[4:5], 0, v[138:139]
	s_and_b32 s1, s41, 1
	s_lshl_b32 s1, s1, 20
	s_lshl_b32 s12, s99, 21
	s_add_i32 s1, s1, s12
	s_lshl_b32 s12, s13, 9
	s_add_i32 s1, s1, s12
	s_add_u32 s8, s2, s1
	s_addc_u32 s9, s3, 0
	s_add_u32 s8, s8, 0x1dcc0000
	s_addc_u32 s9, s9, 0
	v_lshlrev_b32_e32 v140, 12, v131
	v_lshl_add_u32 v140, v141, 8, v140
	v_lshl_add_u32 v140, v0, 1, v140
	v_mov_b32_e32 v141, 0
	v_lshl_add_u64 v[140:141], s[8:9], 0, v[140:141]
	s_mov_b32 s2, 0x8000
	s_mov_b32 s3, 0
	v_lshrrev_b32_e32 v0, 6, v145
	v_lshlrev_b32_e32 v0, 10, v0
	s_nop 0
	v_readfirstlane_b32 s98, v0
	s_mov_b32 s39, m0
	s_mov_b32 s4, 128
	s_mov_b32 s5, 0
	s_barrier
	s_add_i32 s13, s98, 0x0
	s_mov_b32 m0, s13
	v_lshl_add_u64 v[142:143], v[132:133], 0, s[2:3]
	global_load_lds_dwordx4 v[132:133], off
	s_add_i32 m0, m0, 0x1000
	s_nop 0
	global_load_lds_dwordx4 v[142:143], off
	v_lshl_add_u64 v[142:143], v[142:143], 0, s[2:3]
	s_add_i32 m0, m0, 0x1000
	s_nop 0
	global_load_lds_dwordx4 v[142:143], off
	v_lshl_add_u64 v[142:143], v[142:143], 0, s[2:3]
	s_add_i32 m0, m0, 0x1000
	s_nop 0
	global_load_lds_dwordx4 v[142:143], off
	s_add_i32 m0, m0, 0x1000
	v_lshl_add_u64 v[142:143], v[134:135], 0, s[2:3]
	s_nop 0
	global_load_lds_dwordx4 v[134:135], off
	s_add_i32 m0, m0, 0x1000
	v_lshl_add_u64 v[132:133], v[132:133], 0, s[10:11]
	s_nop 0
	global_load_lds_dwordx4 v[142:143], off
	v_lshl_add_u64 v[134:135], v[134:135], 0, s[4:5]
	s_nop 0
	s_add_i32 s13, s98, 0x6000
	s_mov_b32 m0, s13
	v_lshl_add_u64 v[142:143], v[132:133], 0, s[2:3]
	global_load_lds_dwordx4 v[132:133], off
	s_add_i32 m0, m0, 0x1000
	s_nop 0
	global_load_lds_dwordx4 v[142:143], off
	v_lshl_add_u64 v[142:143], v[142:143], 0, s[2:3]
	s_add_i32 m0, m0, 0x1000
	s_nop 0
	global_load_lds_dwordx4 v[142:143], off
	v_lshl_add_u64 v[142:143], v[142:143], 0, s[2:3]
	s_add_i32 m0, m0, 0x1000
	s_nop 0
	global_load_lds_dwordx4 v[142:143], off
	s_add_i32 m0, m0, 0x1000
	v_lshl_add_u64 v[142:143], v[134:135], 0, s[2:3]
	s_nop 0
	global_load_lds_dwordx4 v[134:135], off
	s_add_i32 m0, m0, 0x1000
	v_lshl_add_u64 v[132:133], v[132:133], 0, s[10:11]
	s_nop 0
	global_load_lds_dwordx4 v[142:143], off
	v_lshl_add_u64 v[134:135], v[134:135], 0, s[4:5]
	s_nop 0
	s_add_i32 s13, s98, 0xc000
	s_mov_b32 m0, s13
	v_lshl_add_u64 v[142:143], v[132:133], 0, s[2:3]
	global_load_lds_dwordx4 v[132:133], off
	s_add_i32 m0, m0, 0x1000
	s_nop 0
	global_load_lds_dwordx4 v[142:143], off
	v_lshl_add_u64 v[142:143], v[142:143], 0, s[2:3]
	s_add_i32 m0, m0, 0x1000
	s_nop 0
	global_load_lds_dwordx4 v[142:143], off
	v_lshl_add_u64 v[142:143], v[142:143], 0, s[2:3]
	s_add_i32 m0, m0, 0x1000
	s_nop 0
	global_load_lds_dwordx4 v[142:143], off
	s_add_i32 m0, m0, 0x1000
	v_lshl_add_u64 v[142:143], v[134:135], 0, s[2:3]
	s_nop 0
	global_load_lds_dwordx4 v[134:135], off
	s_add_i32 m0, m0, 0x1000
	v_lshl_add_u64 v[132:133], v[132:133], 0, s[10:11]
	s_nop 0
	global_load_lds_dwordx4 v[142:143], off
	v_lshl_add_u64 v[134:135], v[134:135], 0, s[4:5]
	s_nop 0
	v_mov_b32_e32 v2, 0
	v_mov_b32_e32 v3, 0
	v_mov_b32_e32 v4, 0
	v_mov_b32_e32 v5, 0
	v_mov_b32_e32 v6, 0
	v_mov_b32_e32 v7, 0
	v_mov_b32_e32 v8, 0
	v_mov_b32_e32 v9, 0
	v_mov_b32_e32 v10, 0
	v_mov_b32_e32 v11, 0
	v_mov_b32_e32 v12, 0
	v_mov_b32_e32 v13, 0
	v_mov_b32_e32 v14, 0
	v_mov_b32_e32 v15, 0
; #define LAS __attribute__((address_space(3)))
;     ...
;   f32x4 acc[4][8];
; #pragma unroll
;   for (int i = 0; i < 4; i++)
; #pragma unroll
;     for (int j = 0; j < 8; j++) acc[i][j] = (f32x4){0.f, 0.f, 0.f, 0.f};
;   const int nk = (nk_part < 0) ? (K >> 5) : nk_part;
;   const int lrow = tid >> 2, lpc = tid & 3;
;   const int lch = lpc ^ ((0x78 >> (((lrow >> 2) & 3) * 2)) & 3);
;   const u16* ga = A + (size_t)(m0 + lrow) * lda + kbeg + lch * 8;
;   const u16* gb = Bt + (size_t)(n0 + lrow) * K + kbeg + lch * 8;
;   const size_t ga1 = (size_t)64 * lda, gb1 = (size_t)64 * K;
;   const unsigned lds0 = (unsigned)(uintptr_t)(LAS char*)smem + (unsigned)__builtin_amdgcn_readfirstlane(wid) * 1024u;
;     ...
;   __syncthreads();
;   G2_STAGE(0); G2_STAGE(1);
;   const int fsw = (0x78 >> (((r16 >> 2) & 3) * 2)) & 3;
;   const int aoff = (wm * 128 + r16) * 64 + ((quad ^ fsw) << 4);
;   const int boff = 16384 + (wn * 64 + r16) * 64 + ((quad ^ fsw) << 4);
;   for (int kt = 0; kt < nk; kt++) {
;     if (kt + 1 < nk) asm volatile("s_waitcnt vmcnt(6)" ::: "memory");
;     else asm volatile("s_waitcnt vmcnt(0)" ::: "memory");
;     __builtin_amdgcn_s_barrier();
;     asm volatile("" ::: "memory");
;     if (kt + 2 < nk) G2_STAGE(kt + 2);
;     const char* cS = smem + (kt % 3) * 24576;
;     bf16x8 xa[8], wb[4];
; #pragma unroll
;     for (int f = 0; f < 8; f++) xa[f] = *(const bf16x8*)(cS + aoff + f * 1024);
; #pragma unroll
;     for (int f = 0; f < 4; f++) wb[f] = *(const bf16x8*)(cS + boff + f * 1024);
	v_mov_b32_e32 v16, 0
	v_mov_b32_e32 v17, 0
	v_mov_b32_e32 v18, 0
	v_mov_b32_e32 v19, 0
	v_mov_b32_e32 v20, 0
	v_mov_b32_e32 v21, 0
	v_mov_b32_e32 v22, 0
	v_mov_b32_e32 v23, 0
	v_mov_b32_e32 v24, 0
	v_mov_b32_e32 v25, 0
	v_mov_b32_e32 v26, 0
	v_mov_b32_e32 v27, 0
	v_mov_b32_e32 v28, 0
	v_mov_b32_e32 v29, 0
	v_mov_b32_e32 v30, 0
	v_mov_b32_e32 v31, 0
	v_mov_b32_e32 v32, 0
	v_mov_b32_e32 v33, 0
	v_mov_b32_e32 v34, 0
	v_mov_b32_e32 v35, 0
	v_mov_b32_e32 v36, 0
	v_mov_b32_e32 v37, 0
	v_mov_b32_e32 v38, 0
	v_mov_b32_e32 v39, 0
	v_mov_b32_e32 v40, 0
	v_mov_b32_e32 v41, 0
	v_mov_b32_e32 v42, 0
	v_mov_b32_e32 v43, 0
	v_mov_b32_e32 v44, 0
	v_mov_b32_e32 v45, 0
	v_mov_b32_e32 v46, 0
	v_mov_b32_e32 v47, 0
	v_mov_b32_e32 v48, 0
	v_mov_b32_e32 v49, 0
	v_mov_b32_e32 v50, 0
	v_mov_b32_e32 v51, 0
	v_mov_b32_e32 v52, 0
	v_mov_b32_e32 v53, 0
	v_mov_b32_e32 v54, 0
	v_mov_b32_e32 v55, 0
	v_mov_b32_e32 v56, 0
	v_mov_b32_e32 v57, 0
	v_mov_b32_e32 v58, 0
	v_mov_b32_e32 v59, 0
	v_mov_b32_e32 v60, 0
	v_mov_b32_e32 v61, 0
	v_mov_b32_e32 v62, 0
	v_mov_b32_e32 v63, 0
	v_mov_b32_e32 v64, 0
	v_mov_b32_e32 v65, 0
	v_mov_b32_e32 v66, 0
	v_mov_b32_e32 v67, 0
	v_mov_b32_e32 v68, 0
	v_mov_b32_e32 v69, 0
	v_mov_b32_e32 v70, 0
	v_mov_b32_e32 v71, 0
	v_mov_b32_e32 v72, 0
	v_mov_b32_e32 v73, 0
	v_mov_b32_e32 v74, 0
	v_mov_b32_e32 v75, 0
	v_mov_b32_e32 v76, 0
	v_mov_b32_e32 v77, 0
	v_mov_b32_e32 v78, 0
	v_mov_b32_e32 v79, 0
	v_mov_b32_e32 v80, 0
	v_mov_b32_e32 v81, 0
	v_mov_b32_e32 v82, 0
	v_mov_b32_e32 v83, 0
	v_mov_b32_e32 v84, 0
	v_mov_b32_e32 v85, 0
	v_mov_b32_e32 v86, 0
	v_mov_b32_e32 v87, 0
	v_mov_b32_e32 v88, 0
	v_mov_b32_e32 v89, 0
	v_mov_b32_e32 v90, 0
	v_mov_b32_e32 v91, 0
	v_mov_b32_e32 v92, 0
	v_mov_b32_e32 v93, 0
	v_mov_b32_e32 v94, 0
	v_mov_b32_e32 v95, 0
	v_mov_b32_e32 v96, 0
	v_mov_b32_e32 v97, 0
	v_mov_b32_e32 v98, 0
	v_mov_b32_e32 v99, 0
	v_mov_b32_e32 v100, 0
	v_mov_b32_e32 v101, 0
	v_mov_b32_e32 v102, 0
	v_mov_b32_e32 v103, 0
	v_mov_b32_e32 v104, 0
	v_mov_b32_e32 v105, 0
	v_mov_b32_e32 v106, 0
	v_mov_b32_e32 v107, 0
	v_mov_b32_e32 v108, 0
	v_mov_b32_e32 v109, 0
	v_mov_b32_e32 v110, 0
	v_mov_b32_e32 v111, 0
	v_mov_b32_e32 v112, 0
	v_mov_b32_e32 v113, 0
	v_mov_b32_e32 v114, 0
	v_mov_b32_e32 v115, 0
	v_mov_b32_e32 v116, 0
	v_mov_b32_e32 v117, 0
	v_mov_b32_e32 v118, 0
	v_mov_b32_e32 v119, 0
	v_mov_b32_e32 v120, 0
	v_mov_b32_e32 v121, 0
	v_mov_b32_e32 v122, 0
	v_mov_b32_e32 v123, 0
	v_mov_b32_e32 v124, 0
	v_mov_b32_e32 v125, 0
	v_mov_b32_e32 v126, 0
	v_mov_b32_e32 v127, 0
	v_mov_b32_e32 v128, 0
	v_mov_b32_e32 v129, 0
	s_setprio 0
	s_waitcnt vmcnt(12)
	s_barrier
	ds_read_b128 v[146:149], v136 offset:0
	ds_read_b128 v[152:155], v136 offset:1024
	ds_read_b128 v[156:159], v136 offset:2048
	ds_read_b128 v[162:165], v136 offset:3072
	ds_read_b128 v[166:169], v136 offset:4096
	ds_read_b128 v[170:173], v136 offset:5120
	ds_read_b128 v[176:179], v136 offset:6144
	ds_read_b128 v[180:183], v136 offset:7168
	ds_read_b128 v[184:187], v137 offset:16384
	ds_read_b128 v[188:191], v137 offset:17408
	ds_read_b128 v[192:195], v137 offset:18432
	ds_read_b128 v[196:199], v137 offset:19456
	s_movk_i32 s1, 0x6000
	s_mov_b32 s12, 0
	.p2align 3
	s_waitcnt vmcnt(6) lgkmcnt(0)
	s_barrier
	s_setprio 1
	v_add_u32_e32 v144, s1, v136
	v_mfma_f32_16x16x32_bf16 v[126:129], v[184:187], v[146:149], v[126:129]
	ds_read_b128 v[200:203], v144 offset:0
	v_mfma_f32_16x16x32_bf16 v[122:125], v[184:187], v[152:155], v[122:125]
	ds_read_b128 v[204:207], v144 offset:1024
	v_mfma_f32_16x16x32_bf16 v[118:121], v[184:187], v[156:159], v[118:121]
	ds_read_b128 v[208:211], v144 offset:2048
	v_mfma_f32_16x16x32_bf16 v[114:117], v[184:187], v[162:165], v[114:117]
	ds_read_b128 v[212:215], v144 offset:3072
	v_mfma_f32_16x16x32_bf16 v[110:113], v[184:187], v[166:169], v[110:113]
	ds_read_b128 v[216:219], v144 offset:4096
	v_mfma_f32_16x16x32_bf16 v[106:109], v[184:187], v[170:173], v[106:109]
	ds_read_b128 v[220:223], v144 offset:5120
	v_mfma_f32_16x16x32_bf16 v[102:105], v[184:187], v[176:179], v[102:105]
	ds_read_b128 v[224:227], v144 offset:6144
	v_mfma_f32_16x16x32_bf16 v[98:101], v[184:187], v[180:183], v[98:101]
	ds_read_b128 v[228:231], v144 offset:7168
	v_mfma_f32_16x16x32_bf16 v[94:97], v[188:191], v[146:149], v[94:97]
	v_add_u32_e64 v144, s1, v137
	v_mfma_f32_16x16x32_bf16 v[90:93], v[188:191], v[152:155], v[90:93]
	v_mfma_f32_16x16x32_bf16 v[86:89], v[188:191], v[156:159], v[86:89]
	ds_read_b128 v[232:235], v144 offset:16384
	v_mfma_f32_16x16x32_bf16 v[82:85], v[188:191], v[162:165], v[82:85]
	ds_read_b128 v[236:239], v144 offset:17408
	v_mfma_f32_16x16x32_bf16 v[78:81], v[188:191], v[166:169], v[78:81]
	ds_read_b128 v[240:243], v144 offset:18432
	s_setprio 2
	s_nop 0
	v_mfma_f32_16x16x32_bf16 v[74:77], v[188:191], v[170:173], v[74:77]
	ds_read_b128 v[244:247], v144 offset:19456
	v_mfma_f32_16x16x32_bf16 v[70:73], v[188:191], v[176:179], v[70:73]
	s_add_i32 s13, s98, s12
	s_mov_b32 m0, s13
	v_lshl_add_u64 v[142:143], v[132:133], 0, s[2:3]
	v_mfma_f32_16x16x32_bf16 v[66:69], v[188:191], v[180:183], v[66:69]
	global_load_lds_dwordx4 v[132:133], off
	s_add_i32 m0, m0, 0x1000
	v_mfma_f32_16x16x32_bf16 v[62:65], v[192:195], v[146:149], v[62:65]
	v_mfma_f32_16x16x32_bf16 v[58:61], v[192:195], v[152:155], v[58:61]
	v_mfma_f32_16x16x32_bf16 v[54:57], v[192:195], v[156:159], v[54:57]
	global_load_lds_dwordx4 v[142:143], off
	v_lshl_add_u64 v[142:143], v[142:143], 0, s[2:3]
	s_add_i32 m0, m0, 0x1000
	v_mfma_f32_16x16x32_bf16 v[50:53], v[192:195], v[162:165], v[50:53]
	v_mfma_f32_16x16x32_bf16 v[46:49], v[192:195], v[166:169], v[46:49]
	v_mfma_f32_16x16x32_bf16 v[42:45], v[192:195], v[170:173], v[42:45]
	global_load_lds_dwordx4 v[142:143], off
	v_lshl_add_u64 v[142:143], v[142:143], 0, s[2:3]
	s_add_i32 m0, m0, 0x1000
	v_mfma_f32_16x16x32_bf16 v[38:41], v[192:195], v[176:179], v[38:41]
	v_mfma_f32_16x16x32_bf16 v[34:37], v[192:195], v[180:183], v[34:37]
	s_setprio 0
	s_nop 0
	v_mfma_f32_16x16x32_bf16 v[30:33], v[196:199], v[146:149], v[30:33]
	global_load_lds_dwordx4 v[142:143], off
	s_add_i32 m0, m0, 0x1000
	v_lshl_add_u64 v[142:143], v[134:135], 0, s[2:3]
	v_mfma_f32_16x16x32_bf16 v[26:29], v[196:199], v[152:155], v[26:29]
	v_mfma_f32_16x16x32_bf16 v[22:25], v[196:199], v[156:159], v[22:25]
	v_mfma_f32_16x16x32_bf16 v[18:21], v[196:199], v[162:165], v[18:21]
	global_load_lds_dwordx4 v[134:135], off
	s_add_i32 m0, m0, 0x1000
	v_lshl_add_u64 v[132:133], v[132:133], 0, s[10:11]
	v_mfma_f32_16x16x32_bf16 v[14:17], v[196:199], v[166:169], v[14:17]
	v_mfma_f32_16x16x32_bf16 v[10:13], v[196:199], v[170:173], v[10:13]
	v_mfma_f32_16x16x32_bf16 v[6:9], v[196:199], v[176:179], v[6:9]
	global_load_lds_dwordx4 v[142:143], off
	v_lshl_add_u64 v[134:135], v[134:135], 0, s[4:5]
	v_mfma_f32_16x16x32_bf16 v[2:5], v[196:199], v[180:183], v[2:5]
	s_mov_b32 s12, s1
	s_nop 0
	s_add_i32 s1, s1, 0x6000
	s_cmp_eq_u32 s1, 0x12000
	s_cselect_b32 s1, 0, s1
	s_nop 0
	.p2align 3
	s_waitcnt vmcnt(6) lgkmcnt(0)
	s_barrier
;     ...
;   for (int kt = 0; kt < nk; kt++) {
;     if (kt + 1 < nk) asm volatile("s_waitcnt vmcnt(6)" ::: "memory");
;     else asm volatile("s_waitcnt vmcnt(0)" ::: "memory");
;     __builtin_amdgcn_s_barrier();
;     asm volatile("" ::: "memory");
;     if (kt + 2 < nk) G2_STAGE(kt + 2);
;     const char* cS = smem + (kt % 3) * 24576;
;     bf16x8 xa[8], wb[4];
; #pragma unroll
;     for (int f = 0; f < 8; f++) xa[f] = *(const bf16x8*)(cS + aoff + f * 1024);
; #pragma unroll
;     for (int f = 0; f < 4; f++) wb[f] = *(const bf16x8*)(cS + boff + f * 1024);
; #pragma unroll
;     for (int nf = 0; nf < 4; nf++)
; #pragma unroll
;       for (int mf = 0; mf < 8; mf++)
;         acc[nf][mf] = __builtin_amdgcn_mfma_f32_16x16x32_bf16(wb[nf], xa[mf], acc[nf][mf], 0, 0, 0);
;   }
	s_setprio 1
	v_add_u32_e32 v144, s1, v136
	v_mfma_f32_16x16x32_bf16 v[126:129], v[232:235], v[200:203], v[126:129]
	ds_read_b128 v[146:149], v144 offset:0
	v_mfma_f32_16x16x32_bf16 v[122:125], v[232:235], v[204:207], v[122:125]
	ds_read_b128 v[152:155], v144 offset:1024
	v_mfma_f32_16x16x32_bf16 v[118:121], v[232:235], v[208:211], v[118:121]
	ds_read_b128 v[156:159], v144 offset:2048
	v_mfma_f32_16x16x32_bf16 v[114:117], v[232:235], v[212:215], v[114:117]
	ds_read_b128 v[162:165], v144 offset:3072
	v_mfma_f32_16x16x32_bf16 v[110:113], v[232:235], v[216:219], v[110:113]
	ds_read_b128 v[166:169], v144 offset:4096
	v_mfma_f32_16x16x32_bf16 v[106:109], v[232:235], v[220:223], v[106:109]
	ds_read_b128 v[170:173], v144 offset:5120
	v_mfma_f32_16x16x32_bf16 v[102:105], v[232:235], v[224:227], v[102:105]
	ds_read_b128 v[176:179], v144 offset:6144
	v_mfma_f32_16x16x32_bf16 v[98:101], v[232:235], v[228:231], v[98:101]
	ds_read_b128 v[180:183], v144 offset:7168
	v_mfma_f32_16x16x32_bf16 v[94:97], v[236:239], v[200:203], v[94:97]
	v_add_u32_e64 v144, s1, v137
	v_mfma_f32_16x16x32_bf16 v[90:93], v[236:239], v[204:207], v[90:93]
	v_mfma_f32_16x16x32_bf16 v[86:89], v[236:239], v[208:211], v[86:89]
	ds_read_b128 v[184:187], v144 offset:16384
	v_mfma_f32_16x16x32_bf16 v[82:85], v[236:239], v[212:215], v[82:85]
	ds_read_b128 v[188:191], v144 offset:17408
	v_mfma_f32_16x16x32_bf16 v[78:81], v[236:239], v[216:219], v[78:81]
	ds_read_b128 v[192:195], v144 offset:18432
	v_mfma_f32_16x16x32_bf16 v[74:77], v[236:239], v[220:223], v[74:77]
	ds_read_b128 v[196:199], v144 offset:19456
	v_mfma_f32_16x16x32_bf16 v[70:73], v[236:239], v[224:227], v[70:73]
	v_mfma_f32_16x16x32_bf16 v[66:69], v[236:239], v[228:231], v[66:69]
	v_mfma_f32_16x16x32_bf16 v[62:65], v[240:243], v[200:203], v[62:65]
	v_mfma_f32_16x16x32_bf16 v[58:61], v[240:243], v[204:207], v[58:61]
	v_mfma_f32_16x16x32_bf16 v[54:57], v[240:243], v[208:211], v[54:57]
	v_mfma_f32_16x16x32_bf16 v[50:53], v[240:243], v[212:215], v[50:53]
	v_mfma_f32_16x16x32_bf16 v[46:49], v[240:243], v[216:219], v[46:49]
	v_mfma_f32_16x16x32_bf16 v[42:45], v[240:243], v[220:223], v[42:45]
	v_mfma_f32_16x16x32_bf16 v[38:41], v[240:243], v[224:227], v[38:41]
	v_mfma_f32_16x16x32_bf16 v[34:37], v[240:243], v[228:231], v[34:37]
	s_setprio 0
	s_nop 0
	v_mfma_f32_16x16x32_bf16 v[30:33], v[244:247], v[200:203], v[30:33]
	v_mfma_f32_16x16x32_bf16 v[26:29], v[244:247], v[204:207], v[26:29]
	v_mfma_f32_16x16x32_bf16 v[22:25], v[244:247], v[208:211], v[22:25]
	v_mfma_f32_16x16x32_bf16 v[18:21], v[244:247], v[212:215], v[18:21]
	v_mfma_f32_16x16x32_bf16 v[14:17], v[244:247], v[216:219], v[14:17]
	v_mfma_f32_16x16x32_bf16 v[10:13], v[244:247], v[220:223], v[10:13]
	v_mfma_f32_16x16x32_bf16 v[6:9], v[244:247], v[224:227], v[6:9]
	v_mfma_f32_16x16x32_bf16 v[2:5], v[244:247], v[228:231], v[2:5]
	s_mov_b32 s12, s1
	s_nop 0
	s_add_i32 s1, s1, 0x6000
	s_cmp_eq_u32 s1, 0x12000
	s_cselect_b32 s1, 0, s1
	s_nop 0
	.p2align 3
	s_waitcnt vmcnt(0) lgkmcnt(0)
	s_barrier
	s_setprio 1
	v_add_u32_e32 v144, s1, v136
	v_mfma_f32_16x16x32_bf16 v[126:129], v[184:187], v[146:149], v[126:129]
	ds_read_b128 v[200:203], v144 offset:0
	v_mfma_f32_16x16x32_bf16 v[122:125], v[184:187], v[152:155], v[122:125]
	ds_read_b128 v[204:207], v144 offset:1024
	v_mfma_f32_16x16x32_bf16 v[118:121], v[184:187], v[156:159], v[118:121]
	ds_read_b128 v[208:211], v144 offset:2048
	v_mfma_f32_16x16x32_bf16 v[114:117], v[184:187], v[162:165], v[114:117]
	ds_read_b128 v[212:215], v144 offset:3072
	v_mfma_f32_16x16x32_bf16 v[110:113], v[184:187], v[166:169], v[110:113]
	ds_read_b128 v[216:219], v144 offset:4096
	v_mfma_f32_16x16x32_bf16 v[106:109], v[184:187], v[170:173], v[106:109]
	ds_read_b128 v[220:223], v144 offset:5120
	v_mfma_f32_16x16x32_bf16 v[102:105], v[184:187], v[176:179], v[102:105]
	ds_read_b128 v[224:227], v144 offset:6144
	v_mfma_f32_16x16x32_bf16 v[98:101], v[184:187], v[180:183], v[98:101]
	ds_read_b128 v[228:231], v144 offset:7168
	v_mfma_f32_16x16x32_bf16 v[94:97], v[188:191], v[146:149], v[94:97]
	v_add_u32_e64 v144, s1, v137
	v_mfma_f32_16x16x32_bf16 v[90:93], v[188:191], v[152:155], v[90:93]
	v_mfma_f32_16x16x32_bf16 v[86:89], v[188:191], v[156:159], v[86:89]
	ds_read_b128 v[232:235], v144 offset:16384
	v_mfma_f32_16x16x32_bf16 v[82:85], v[188:191], v[162:165], v[82:85]
	ds_read_b128 v[236:239], v144 offset:17408
	v_mfma_f32_16x16x32_bf16 v[78:81], v[188:191], v[166:169], v[78:81]
	ds_read_b128 v[240:243], v144 offset:18432
	v_mfma_f32_16x16x32_bf16 v[74:77], v[188:191], v[170:173], v[74:77]
	ds_read_b128 v[244:247], v144 offset:19456
	v_mfma_f32_16x16x32_bf16 v[70:73], v[188:191], v[176:179], v[70:73]
	v_mfma_f32_16x16x32_bf16 v[66:69], v[188:191], v[180:183], v[66:69]
	v_mfma_f32_16x16x32_bf16 v[62:65], v[192:195], v[146:149], v[62:65]
	v_mfma_f32_16x16x32_bf16 v[58:61], v[192:195], v[152:155], v[58:61]
	v_mfma_f32_16x16x32_bf16 v[54:57], v[192:195], v[156:159], v[54:57]
	v_mfma_f32_16x16x32_bf16 v[50:53], v[192:195], v[162:165], v[50:53]
	v_mfma_f32_16x16x32_bf16 v[46:49], v[192:195], v[166:169], v[46:49]
	v_mfma_f32_16x16x32_bf16 v[42:45], v[192:195], v[170:173], v[42:45]
	v_mfma_f32_16x16x32_bf16 v[38:41], v[192:195], v[176:179], v[38:41]
	v_mfma_f32_16x16x32_bf16 v[34:37], v[192:195], v[180:183], v[34:37]
	s_setprio 0
	s_nop 0
	v_mfma_f32_16x16x32_bf16 v[30:33], v[196:199], v[146:149], v[30:33]
	v_mfma_f32_16x16x32_bf16 v[26:29], v[196:199], v[152:155], v[26:29]
	v_mfma_f32_16x16x32_bf16 v[22:25], v[196:199], v[156:159], v[22:25]
	v_mfma_f32_16x16x32_bf16 v[18:21], v[196:199], v[162:165], v[18:21]
	v_mfma_f32_16x16x32_bf16 v[14:17], v[196:199], v[166:169], v[14:17]
	v_mfma_f32_16x16x32_bf16 v[10:13], v[196:199], v[170:173], v[10:13]
	v_mfma_f32_16x16x32_bf16 v[6:9], v[196:199], v[176:179], v[6:9]
	v_mfma_f32_16x16x32_bf16 v[2:5], v[196:199], v[180:183], v[2:5]
	s_mov_b32 s12, s1
	s_nop 0
	s_add_i32 s1, s1, 0x6000
	s_cmp_eq_u32 s1, 0x12000
	s_cselect_b32 s1, 0, s1
	s_nop 0
	s_mov_b32 s4, 0x8000
	s_mov_b32 s5, 0
	s_mov_b32 s8, 0x10000
	s_mov_b32 s9, 0
	s_mov_b32 s40, 0x3fd744fd
	.p2align 3
	s_waitcnt lgkmcnt(0)
; DEVI float blo(unsigned u) { return __uint_as_float(u << 16); }
; DEVI float bhi(unsigned u) { return __uint_as_float(u & 0xffff0000u); }
;     ...
;   for (int kt = 0; kt < nk; kt++) {
;     if (kt + 1 < nk) asm volatile("s_waitcnt vmcnt(6)" ::: "memory");
;     else asm volatile("s_waitcnt vmcnt(0)" ::: "memory");
;     __builtin_amdgcn_s_barrier();
;     asm volatile("" ::: "memory");
;     if (kt + 2 < nk) G2_STAGE(kt + 2);
;     const char* cS = smem + (kt % 3) * 24576;
;     bf16x8 xa[8], wb[4];
; #pragma unroll
;     for (int f = 0; f < 8; f++) xa[f] = *(const bf16x8*)(cS + aoff + f * 1024);
; #pragma unroll
;     for (int f = 0; f < 4; f++) wb[f] = *(const bf16x8*)(cS + boff + f * 1024);
; #pragma unroll
;     for (int nf = 0; nf < 4; nf++)
; #pragma unroll
;       for (int mf = 0; mf < 8; mf++)
;         acc[nf][mf] = __builtin_amdgcn_mfma_f32_16x16x32_bf16(wb[nf], xa[mf], acc[nf][mf], 0, 0, 0);
;   }
;     ...
;         if (EPI == EPI_RESID || EPI == EPI_RESID_ATOMIC) {
;           f32x4 x = a;
;           if (EPI == EPI_RESID || kpart == 0) {
;             const u32x2 xr = *(const u32x2*)((const u16*)(p.ws + WS_XB) + (size_t)row * 1024 + col);
;             x[0] += ALPHA * blo(xr[0]); x[1] += ALPHA * bhi(xr[0]); x[2] += ALPHA * blo(xr[1]); x[3] += ALPHA * bhi(xr[1]);
;           }
;           if (EPI == EPI_RESID) *(f32x4*)((float*)(p.ws + WS_XF) + (size_t)row * 1024 + col) = x;
;           else *(f32x4*)((float*)(p.ws + WS_SLAB) + ((size_t)kpart * 512 + (row - T_P)) * 1024 + col) = x;
	s_nop 0
	v_mfma_f32_16x16x32_bf16 v[126:129], v[232:235], v[200:203], v[126:129]
	v_mfma_f32_16x16x32_bf16 v[122:125], v[232:235], v[204:207], v[122:125]
	v_mfma_f32_16x16x32_bf16 v[118:121], v[232:235], v[208:211], v[118:121]
	v_mfma_f32_16x16x32_bf16 v[114:117], v[232:235], v[212:215], v[114:117]
	v_mfma_f32_16x16x32_bf16 v[110:113], v[232:235], v[216:219], v[110:113]
	v_mfma_f32_16x16x32_bf16 v[106:109], v[232:235], v[220:223], v[106:109]
	v_mfma_f32_16x16x32_bf16 v[102:105], v[232:235], v[224:227], v[102:105]
	v_mfma_f32_16x16x32_bf16 v[98:101], v[232:235], v[228:231], v[98:101]
	v_mfma_f32_16x16x32_bf16 v[94:97], v[236:239], v[200:203], v[94:97]
	v_mfma_f32_16x16x32_bf16 v[90:93], v[236:239], v[204:207], v[90:93]
	v_mfma_f32_16x16x32_bf16 v[86:89], v[236:239], v[208:211], v[86:89]
	v_mfma_f32_16x16x32_bf16 v[82:85], v[236:239], v[212:215], v[82:85]
	v_mfma_f32_16x16x32_bf16 v[78:81], v[236:239], v[216:219], v[78:81]
	v_mfma_f32_16x16x32_bf16 v[74:77], v[236:239], v[220:223], v[74:77]
	v_mfma_f32_16x16x32_bf16 v[70:73], v[236:239], v[224:227], v[70:73]
	v_mfma_f32_16x16x32_bf16 v[66:69], v[236:239], v[228:231], v[66:69]
	v_mfma_f32_16x16x32_bf16 v[62:65], v[240:243], v[200:203], v[62:65]
	v_mfma_f32_16x16x32_bf16 v[58:61], v[240:243], v[204:207], v[58:61]
	v_mfma_f32_16x16x32_bf16 v[54:57], v[240:243], v[208:211], v[54:57]
	v_mfma_f32_16x16x32_bf16 v[50:53], v[240:243], v[212:215], v[50:53]
	v_mfma_f32_16x16x32_bf16 v[46:49], v[240:243], v[216:219], v[46:49]
	v_mfma_f32_16x16x32_bf16 v[42:45], v[240:243], v[220:223], v[42:45]
	v_mfma_f32_16x16x32_bf16 v[38:41], v[240:243], v[224:227], v[38:41]
	v_mfma_f32_16x16x32_bf16 v[34:37], v[240:243], v[228:231], v[34:37]
	v_mfma_f32_16x16x32_bf16 v[30:33], v[244:247], v[200:203], v[30:33]
	v_mfma_f32_16x16x32_bf16 v[26:29], v[244:247], v[204:207], v[26:29]
	v_mfma_f32_16x16x32_bf16 v[22:25], v[244:247], v[208:211], v[22:25]
	v_mfma_f32_16x16x32_bf16 v[18:21], v[244:247], v[212:215], v[18:21]
	v_mfma_f32_16x16x32_bf16 v[14:17], v[244:247], v[216:219], v[14:17]
	v_mfma_f32_16x16x32_bf16 v[10:13], v[244:247], v[220:223], v[10:13]
	v_mfma_f32_16x16x32_bf16 v[6:9], v[244:247], v[224:227], v[6:9]
	v_mfma_f32_16x16x32_bf16 v[2:5], v[244:247], v[228:231], v[2:5]
	s_mov_b32 m0, s39
	s_cmp_eq_u32 s99, 0
	s_cbranch_scc1 .Lta8_first
	s_nop 7
	global_store_dwordx4 v[140:141], v[126:129], off offset:0
	global_store_dwordx4 v[140:141], v[94:97], off offset:64
	global_store_dwordx4 v[140:141], v[62:65], off offset:128
	global_store_dwordx4 v[140:141], v[30:33], off offset:192
	v_lshl_add_u64 v[140:141], v[140:141], 0, s[8:9]
	global_store_dwordx4 v[140:141], v[122:125], off offset:0
	global_store_dwordx4 v[140:141], v[90:93], off offset:64
	global_store_dwordx4 v[140:141], v[58:61], off offset:128
	global_store_dwordx4 v[140:141], v[26:29], off offset:192
	v_lshl_add_u64 v[140:141], v[140:141], 0, s[8:9]
	global_store_dwordx4 v[140:141], v[118:121], off offset:0
	global_store_dwordx4 v[140:141], v[86:89], off offset:64
	global_store_dwordx4 v[140:141], v[54:57], off offset:128
	global_store_dwordx4 v[140:141], v[22:25], off offset:192
	v_lshl_add_u64 v[140:141], v[140:141], 0, s[8:9]
	global_store_dwordx4 v[140:141], v[114:117], off offset:0
	global_store_dwordx4 v[140:141], v[82:85], off offset:64
	global_store_dwordx4 v[140:141], v[50:53], off offset:128
	global_store_dwordx4 v[140:141], v[18:21], off offset:192
	v_lshl_add_u64 v[140:141], v[140:141], 0, s[8:9]
	global_store_dwordx4 v[140:141], v[110:113], off offset:0
	global_store_dwordx4 v[140:141], v[78:81], off offset:64
	global_store_dwordx4 v[140:141], v[46:49], off offset:128
	global_store_dwordx4 v[140:141], v[14:17], off offset:192
	v_lshl_add_u64 v[140:141], v[140:141], 0, s[8:9]
	global_store_dwordx4 v[140:141], v[106:109], off offset:0
	global_store_dwordx4 v[140:141], v[74:77], off offset:64
	global_store_dwordx4 v[140:141], v[42:45], off offset:128
	global_store_dwordx4 v[140:141], v[10:13], off offset:192
	v_lshl_add_u64 v[140:141], v[140:141], 0, s[8:9]
	global_store_dwordx4 v[140:141], v[102:105], off offset:0
	global_store_dwordx4 v[140:141], v[70:73], off offset:64
	global_store_dwordx4 v[140:141], v[38:41], off offset:128
	global_store_dwordx4 v[140:141], v[6:9], off offset:192
	v_lshl_add_u64 v[140:141], v[140:141], 0, s[8:9]
	global_store_dwordx4 v[140:141], v[98:101], off offset:0
	global_store_dwordx4 v[140:141], v[66:69], off offset:64
	global_store_dwordx4 v[140:141], v[34:37], off offset:128
	global_store_dwordx4 v[140:141], v[2:5], off offset:192
	v_readlane_b32 s0, v250, 7
	s_cmpk_lg_u32 s0, 0x200
	s_cbranch_scc1 .Lta8_ar1
	s_mov_b32 s0, 1
	v_writelane_b32 v255, s0, 41
	v_readlane_b32 s1, v250, 0
	s_lshr_b32 s12, s1, 3
	s_and_b32 s1, s1, 7
	s_lshl_b32 s1, s1, 6
	s_add_i32 s1, s1, s12
	s_sub_i32 s38, s1, 0x200

;     ...
;   for (int kt = 0; kt < nk; kt++) {
;     if (kt + 1 < nk) asm volatile("s_waitcnt vmcnt(6)" ::: "memory");
;     else asm volatile("s_waitcnt vmcnt(0)" ::: "memory");
;     __builtin_amdgcn_s_barrier();
;     asm volatile("" ::: "memory");
;     if (kt + 2 < nk) G2_STAGE(kt + 2);
;     const char* cS = smem + (kt % 3) * 24576;
;     bf16x8 xa[8], wb[4];
; #pragma unroll
;     for (int f = 0; f < 8; f++) xa[f] = *(const bf16x8*)(cS + aoff + f * 1024);
; #pragma unroll
;     for (int f = 0; f < 4; f++) wb[f] = *(const bf16x8*)(cS + boff + f * 1024);
; #pragma unroll
;     for (int nf = 0; nf < 4; nf++)
; #pragma unroll
;       for (int mf = 0; mf < 8; mf++)
;         acc[nf][mf] = __builtin_amdgcn_mfma_f32_16x16x32_bf16(wb[nf], xa[mf], acc[nf][mf], 0, 0, 0);
;   }
.Lt8_loop:
	.p2align 3
	s_waitcnt vmcnt(6) lgkmcnt(0)
	s_barrier
	s_setprio 1
	v_add_u32_e32 v144, s40, v136
	v_mfma_f32_16x16x32_bf16 v[126:129], v[184:187], v[146:149], v[126:129]
	ds_read_b128 v[200:203], v144 offset:0
	v_mfma_f32_16x16x32_bf16 v[122:125], v[184:187], v[152:155], v[122:125]
	ds_read_b128 v[204:207], v144 offset:1024
	v_mfma_f32_16x16x32_bf16 v[118:121], v[184:187], v[156:159], v[118:121]
	ds_read_b128 v[208:211], v144 offset:2048
	v_mfma_f32_16x16x32_bf16 v[114:117], v[184:187], v[162:165], v[114:117]
	ds_read_b128 v[212:215], v144 offset:3072
	v_mfma_f32_16x16x32_bf16 v[110:113], v[184:187], v[166:169], v[110:113]
	ds_read_b128 v[216:219], v144 offset:4096
	v_mfma_f32_16x16x32_bf16 v[106:109], v[184:187], v[170:173], v[106:109]
	ds_read_b128 v[220:223], v144 offset:5120
	v_mfma_f32_16x16x32_bf16 v[102:105], v[184:187], v[176:179], v[102:105]
	ds_read_b128 v[224:227], v144 offset:6144
	v_mfma_f32_16x16x32_bf16 v[98:101], v[184:187], v[180:183], v[98:101]
	ds_read_b128 v[228:231], v144 offset:7168
	v_mfma_f32_16x16x32_bf16 v[94:97], v[188:191], v[146:149], v[94:97]
	v_add_u32_e64 v144, s40, v137
	v_mfma_f32_16x16x32_bf16 v[90:93], v[188:191], v[152:155], v[90:93]
	v_mfma_f32_16x16x32_bf16 v[86:89], v[188:191], v[156:159], v[86:89]
	ds_read_b128 v[232:235], v144 offset:16384
	v_mfma_f32_16x16x32_bf16 v[82:85], v[188:191], v[162:165], v[82:85]
	ds_read_b128 v[236:239], v144 offset:17408
	v_mfma_f32_16x16x32_bf16 v[78:81], v[188:191], v[166:169], v[78:81]
	ds_read_b128 v[240:243], v144 offset:18432
	s_setprio 2
	s_nop 0
	v_mfma_f32_16x16x32_bf16 v[74:77], v[188:191], v[170:173], v[74:77]
	ds_read_b128 v[244:247], v144 offset:19456
	v_mfma_f32_16x16x32_bf16 v[70:73], v[188:191], v[176:179], v[70:73]
	s_add_i32 s42, s46, s41
	s_mov_b32 m0, s42
	v_lshl_add_u64 v[142:143], v[132:133], 0, s[2:3]
	v_mfma_f32_16x16x32_bf16 v[66:69], v[188:191], v[180:183], v[66:69]
	global_load_lds_dwordx4 v[132:133], off
	s_add_i32 m0, m0, 0x1000
	v_mfma_f32_16x16x32_bf16 v[62:65], v[192:195], v[146:149], v[62:65]
	v_mfma_f32_16x16x32_bf16 v[58:61], v[192:195], v[152:155], v[58:61]
	v_mfma_f32_16x16x32_bf16 v[54:57], v[192:195], v[156:159], v[54:57]
	global_load_lds_dwordx4 v[142:143], off
	v_lshl_add_u64 v[142:143], v[142:143], 0, s[2:3]
	s_add_i32 m0, m0, 0x1000
	v_mfma_f32_16x16x32_bf16 v[50:53], v[192:195], v[162:165], v[50:53]
	v_mfma_f32_16x16x32_bf16 v[46:49], v[192:195], v[166:169], v[46:49]
	v_mfma_f32_16x16x32_bf16 v[42:45], v[192:195], v[170:173], v[42:45]
	global_load_lds_dwordx4 v[142:143], off
	v_lshl_add_u64 v[142:143], v[142:143], 0, s[2:3]
	s_add_i32 m0, m0, 0x1000
	v_mfma_f32_16x16x32_bf16 v[38:41], v[192:195], v[176:179], v[38:41]
	v_mfma_f32_16x16x32_bf16 v[34:37], v[192:195], v[180:183], v[34:37]
	s_setprio 0
	s_nop 0
	v_mfma_f32_16x16x32_bf16 v[30:33], v[196:199], v[146:149], v[30:33]
	global_load_lds_dwordx4 v[142:143], off
	s_add_i32 m0, m0, 0x1000
	v_lshl_add_u64 v[142:143], v[134:135], 0, s[2:3]
	v_mfma_f32_16x16x32_bf16 v[26:29], v[196:199], v[152:155], v[26:29]
	v_mfma_f32_16x16x32_bf16 v[22:25], v[196:199], v[156:159], v[22:25]
	v_mfma_f32_16x16x32_bf16 v[18:21], v[196:199], v[162:165], v[18:21]
	global_load_lds_dwordx4 v[134:135], off
	s_add_i32 m0, m0, 0x1000
	v_lshl_add_u64 v[132:133], v[132:133], 0, s[12:13]
	v_mfma_f32_16x16x32_bf16 v[14:17], v[196:199], v[166:169], v[14:17]
	v_mfma_f32_16x16x32_bf16 v[10:13], v[196:199], v[170:173], v[10:13]
	v_mfma_f32_16x16x32_bf16 v[6:9], v[196:199], v[176:179], v[6:9]
	global_load_lds_dwordx4 v[142:143], off
	v_lshl_add_u64 v[134:135], v[134:135], 0, s[4:5]
	v_mfma_f32_16x16x32_bf16 v[2:5], v[196:199], v[180:183], v[2:5]
	s_mov_b32 s41, s40
	s_nop 0
	s_add_i32 s40, s40, 0x6000
	s_cmp_eq_u32 s40, 0x12000
	s_cselect_b32 s40, 0, s40
	s_nop 0
	.p2align 3
	s_waitcnt vmcnt(6) lgkmcnt(0)
	s_barrier
	s_setprio 1
	v_add_u32_e32 v144, s40, v136
	v_mfma_f32_16x16x32_bf16 v[126:129], v[232:235], v[200:203], v[126:129]
	ds_read_b128 v[146:149], v144 offset:0
	v_mfma_f32_16x16x32_bf16 v[122:125], v[232:235], v[204:207], v[122:125]
	ds_read_b128 v[152:155], v144 offset:1024
	v_mfma_f32_16x16x32_bf16 v[118:121], v[232:235], v[208:211], v[118:121]
	ds_read_b128 v[156:159], v144 offset:2048
	v_mfma_f32_16x16x32_bf16 v[114:117], v[232:235], v[212:215], v[114:117]
	ds_read_b128 v[162:165], v144 offset:3072
	v_mfma_f32_16x16x32_bf16 v[110:113], v[232:235], v[216:219], v[110:113]
	ds_read_b128 v[166:169], v144 offset:4096
	v_mfma_f32_16x16x32_bf16 v[106:109], v[232:235], v[220:223], v[106:109]
	ds_read_b128 v[170:173], v144 offset:5120
	v_mfma_f32_16x16x32_bf16 v[102:105], v[232:235], v[224:227], v[102:105]
	ds_read_b128 v[176:179], v144 offset:6144
	v_mfma_f32_16x16x32_bf16 v[98:101], v[232:235], v[228:231], v[98:101]
	ds_read_b128 v[180:183], v144 offset:7168
	v_mfma_f32_16x16x32_bf16 v[94:97], v[236:239], v[200:203], v[94:97]
	v_add_u32_e64 v144, s40, v137
	v_mfma_f32_16x16x32_bf16 v[90:93], v[236:239], v[204:207], v[90:93]
	v_mfma_f32_16x16x32_bf16 v[86:89], v[236:239], v[208:211], v[86:89]
	ds_read_b128 v[184:187], v144 offset:16384
	v_mfma_f32_16x16x32_bf16 v[82:85], v[236:239], v[212:215], v[82:85]
	ds_read_b128 v[188:191], v144 offset:17408
	v_mfma_f32_16x16x32_bf16 v[78:81], v[236:239], v[216:219], v[78:81]
	ds_read_b128 v[192:195], v144 offset:18432
	s_setprio 2
	s_nop 0
	v_mfma_f32_16x16x32_bf16 v[74:77], v[236:239], v[220:223], v[74:77]
	ds_read_b128 v[196:199], v144 offset:19456
	v_mfma_f32_16x16x32_bf16 v[70:73], v[236:239], v[224:227], v[70:73]
	s_add_i32 s42, s46, s41
	s_mov_b32 m0, s42
	v_lshl_add_u64 v[142:143], v[132:133], 0, s[2:3]
	v_mfma_f32_16x16x32_bf16 v[66:69], v[236:239], v[228:231], v[66:69]
;     ...
;   for (int kt = 0; kt < nk; kt++) {
;     if (kt + 1 < nk) asm volatile("s_waitcnt vmcnt(6)" ::: "memory");
;     else asm volatile("s_waitcnt vmcnt(0)" ::: "memory");
;     __builtin_amdgcn_s_barrier();
;     asm volatile("" ::: "memory");
;     if (kt + 2 < nk) G2_STAGE(kt + 2);
;     const char* cS = smem + (kt % 3) * 24576;
;     bf16x8 xa[8], wb[4];
; #pragma unroll
;     for (int f = 0; f < 8; f++) xa[f] = *(const bf16x8*)(cS + aoff + f * 1024);
; #pragma unroll
;     for (int f = 0; f < 4; f++) wb[f] = *(const bf16x8*)(cS + boff + f * 1024);
; #pragma unroll
;     for (int nf = 0; nf < 4; nf++)
; #pragma unroll
;       for (int mf = 0; mf < 8; mf++)
;         acc[nf][mf] = __builtin_amdgcn_mfma_f32_16x16x32_bf16(wb[nf], xa[mf], acc[nf][mf], 0, 0, 0);
;   }
	global_load_lds_dwordx4 v[132:133], off
	s_add_i32 m0, m0, 0x1000
	v_mfma_f32_16x16x32_bf16 v[62:65], v[240:243], v[200:203], v[62:65]
	v_mfma_f32_16x16x32_bf16 v[58:61], v[240:243], v[204:207], v[58:61]
	v_mfma_f32_16x16x32_bf16 v[54:57], v[240:243], v[208:211], v[54:57]
	global_load_lds_dwordx4 v[142:143], off
	v_lshl_add_u64 v[142:143], v[142:143], 0, s[2:3]
	s_add_i32 m0, m0, 0x1000
	v_mfma_f32_16x16x32_bf16 v[50:53], v[240:243], v[212:215], v[50:53]
	v_mfma_f32_16x16x32_bf16 v[46:49], v[240:243], v[216:219], v[46:49]
	v_mfma_f32_16x16x32_bf16 v[42:45], v[240:243], v[220:223], v[42:45]
	global_load_lds_dwordx4 v[142:143], off
	v_lshl_add_u64 v[142:143], v[142:143], 0, s[2:3]
	s_add_i32 m0, m0, 0x1000
	v_mfma_f32_16x16x32_bf16 v[38:41], v[240:243], v[224:227], v[38:41]
	v_mfma_f32_16x16x32_bf16 v[34:37], v[240:243], v[228:231], v[34:37]
	s_setprio 0
	s_nop 0
	v_mfma_f32_16x16x32_bf16 v[30:33], v[244:247], v[200:203], v[30:33]
	global_load_lds_dwordx4 v[142:143], off
	s_add_i32 m0, m0, 0x1000
	v_lshl_add_u64 v[142:143], v[134:135], 0, s[2:3]
	v_mfma_f32_16x16x32_bf16 v[26:29], v[244:247], v[204:207], v[26:29]
	v_mfma_f32_16x16x32_bf16 v[22:25], v[244:247], v[208:211], v[22:25]
	v_mfma_f32_16x16x32_bf16 v[18:21], v[244:247], v[212:215], v[18:21]
	global_load_lds_dwordx4 v[134:135], off
	s_add_i32 m0, m0, 0x1000
	v_lshl_add_u64 v[132:133], v[132:133], 0, s[12:13]
	v_mfma_f32_16x16x32_bf16 v[14:17], v[244:247], v[216:219], v[14:17]
	v_mfma_f32_16x16x32_bf16 v[10:13], v[244:247], v[220:223], v[10:13]
	v_mfma_f32_16x16x32_bf16 v[6:9], v[244:247], v[224:227], v[6:9]
	global_load_lds_dwordx4 v[142:143], off
	v_lshl_add_u64 v[134:135], v[134:135], 0, s[4:5]
	v_mfma_f32_16x16x32_bf16 v[2:5], v[244:247], v[228:231], v[2:5]
	s_mov_b32 s41, s40
	s_nop 0
	s_add_i32 s40, s40, 0x6000
	s_cmp_eq_u32 s40, 0x12000
	s_cselect_b32 s40, 0, s40
	s_nop 0
	s_sub_i32 s39, s39, 1
	s_cmp_lg_u32 s39, 0
	s_cbranch_scc1 .Lt8_loop
	.p2align 3
	s_waitcnt vmcnt(6) lgkmcnt(0)
	s_barrier
	s_setprio 1
	v_add_u32_e32 v144, s40, v136
	v_mfma_f32_16x16x32_bf16 v[126:129], v[184:187], v[146:149], v[126:129]
	ds_read_b128 v[200:203], v144 offset:0
	v_mfma_f32_16x16x32_bf16 v[122:125], v[184:187], v[152:155], v[122:125]
	ds_read_b128 v[204:207], v144 offset:1024
	v_mfma_f32_16x16x32_bf16 v[118:121], v[184:187], v[156:159], v[118:121]
	ds_read_b128 v[208:211], v144 offset:2048
	v_mfma_f32_16x16x32_bf16 v[114:117], v[184:187], v[162:165], v[114:117]
	ds_read_b128 v[212:215], v144 offset:3072
	v_mfma_f32_16x16x32_bf16 v[110:113], v[184:187], v[166:169], v[110:113]
	ds_read_b128 v[216:219], v144 offset:4096
	v_mfma_f32_16x16x32_bf16 v[106:109], v[184:187], v[170:173], v[106:109]
	ds_read_b128 v[220:223], v144 offset:5120
	v_mfma_f32_16x16x32_bf16 v[102:105], v[184:187], v[176:179], v[102:105]
	ds_read_b128 v[224:227], v144 offset:6144
	v_mfma_f32_16x16x32_bf16 v[98:101], v[184:187], v[180:183], v[98:101]
	ds_read_b128 v[228:231], v144 offset:7168
	v_mfma_f32_16x16x32_bf16 v[94:97], v[188:191], v[146:149], v[94:97]
	v_add_u32_e64 v144, s40, v137
	v_mfma_f32_16x16x32_bf16 v[90:93], v[188:191], v[152:155], v[90:93]
	v_mfma_f32_16x16x32_bf16 v[86:89], v[188:191], v[156:159], v[86:89]
	ds_read_b128 v[232:235], v144 offset:16384
	v_mfma_f32_16x16x32_bf16 v[82:85], v[188:191], v[162:165], v[82:85]
	ds_read_b128 v[236:239], v144 offset:17408
	v_mfma_f32_16x16x32_bf16 v[78:81], v[188:191], v[166:169], v[78:81]
	ds_read_b128 v[240:243], v144 offset:18432
	s_setprio 2
	s_nop 0
	v_mfma_f32_16x16x32_bf16 v[74:77], v[188:191], v[170:173], v[74:77]
	ds_read_b128 v[244:247], v144 offset:19456
	v_mfma_f32_16x16x32_bf16 v[70:73], v[188:191], v[176:179], v[70:73]
	s_add_i32 s42, s46, s41
	s_mov_b32 m0, s42
	v_lshl_add_u64 v[142:143], v[132:133], 0, s[2:3]
	v_mfma_f32_16x16x32_bf16 v[66:69], v[188:191], v[180:183], v[66:69]
	global_load_lds_dwordx4 v[132:133], off
	s_add_i32 m0, m0, 0x1000
	v_mfma_f32_16x16x32_bf16 v[62:65], v[192:195], v[146:149], v[62:65]
	v_mfma_f32_16x16x32_bf16 v[58:61], v[192:195], v[152:155], v[58:61]
	v_mfma_f32_16x16x32_bf16 v[54:57], v[192:195], v[156:159], v[54:57]
	global_load_lds_dwordx4 v[142:143], off
	v_lshl_add_u64 v[142:143], v[142:143], 0, s[2:3]
	s_add_i32 m0, m0, 0x1000
	v_mfma_f32_16x16x32_bf16 v[50:53], v[192:195], v[162:165], v[50:53]
	v_mfma_f32_16x16x32_bf16 v[46:49], v[192:195], v[166:169], v[46:49]
	v_mfma_f32_16x16x32_bf16 v[42:45], v[192:195], v[170:173], v[42:45]
	global_load_lds_dwordx4 v[142:143], off
	v_lshl_add_u64 v[142:143], v[142:143], 0, s[2:3]
	s_add_i32 m0, m0, 0x1000
	v_mfma_f32_16x16x32_bf16 v[38:41], v[192:195], v[176:179], v[38:41]
	v_mfma_f32_16x16x32_bf16 v[34:37], v[192:195], v[180:183], v[34:37]
	s_setprio 0
	s_nop 0
	v_mfma_f32_16x16x32_bf16 v[30:33], v[196:199], v[146:149], v[30:33]
	global_load_lds_dwordx4 v[142:143], off
	s_add_i32 m0, m0, 0x1000
	v_lshl_add_u64 v[142:143], v[134:135], 0, s[2:3]
	v_mfma_f32_16x16x32_bf16 v[26:29], v[196:199], v[152:155], v[26:29]
	v_mfma_f32_16x16x32_bf16 v[22:25], v[196:199], v[156:159], v[22:25]
	v_mfma_f32_16x16x32_bf16 v[18:21], v[196:199], v[162:165], v[18:21]
	global_load_lds_dwordx4 v[134:135], off
	s_add_i32 m0, m0, 0x1000
	v_lshl_add_u64 v[132:133], v[132:133], 0, s[12:13]
	v_mfma_f32_16x16x32_bf16 v[14:17], v[196:199], v[166:169], v[14:17]
	v_mfma_f32_16x16x32_bf16 v[10:13], v[196:199], v[170:173], v[10:13]
	v_mfma_f32_16x16x32_bf16 v[6:9], v[196:199], v[176:179], v[6:9]
	global_load_lds_dwordx4 v[142:143], off
	v_lshl_add_u64 v[134:135], v[134:135], 0, s[4:5]
	v_mfma_f32_16x16x32_bf16 v[2:5], v[196:199], v[180:183], v[2:5]
	s_mov_b32 s41, s40
	s_nop 0
	s_add_i32 s40, s40, 0x6000
	s_cmp_eq_u32 s40, 0x12000
	s_cselect_b32 s40, 0, s40
	s_nop 0
	.p2align 3
	s_waitcnt vmcnt(6) lgkmcnt(0)
	s_barrier
;     ...
;   for (int kt = 0; kt < nk; kt++) {
;     if (kt + 1 < nk) asm volatile("s_waitcnt vmcnt(6)" ::: "memory");
;     else asm volatile("s_waitcnt vmcnt(0)" ::: "memory");
;     __builtin_amdgcn_s_barrier();
;     asm volatile("" ::: "memory");
;     if (kt + 2 < nk) G2_STAGE(kt + 2);
;     const char* cS = smem + (kt % 3) * 24576;
;     bf16x8 xa[8], wb[4];
; #pragma unroll
;     for (int f = 0; f < 8; f++) xa[f] = *(const bf16x8*)(cS + aoff + f * 1024);
; #pragma unroll
;     for (int f = 0; f < 4; f++) wb[f] = *(const bf16x8*)(cS + boff + f * 1024);
; #pragma unroll
;     for (int nf = 0; nf < 4; nf++)
; #pragma unroll
;       for (int mf = 0; mf < 8; mf++)
;         acc[nf][mf] = __builtin_amdgcn_mfma_f32_16x16x32_bf16(wb[nf], xa[mf], acc[nf][mf], 0, 0, 0);
;   }
	s_setprio 1
	v_add_u32_e32 v144, s40, v136
	v_mfma_f32_16x16x32_bf16 v[126:129], v[232:235], v[200:203], v[126:129]
	ds_read_b128 v[146:149], v144 offset:0
	v_mfma_f32_16x16x32_bf16 v[122:125], v[232:235], v[204:207], v[122:125]
	ds_read_b128 v[152:155], v144 offset:1024
	v_mfma_f32_16x16x32_bf16 v[118:121], v[232:235], v[208:211], v[118:121]
	ds_read_b128 v[156:159], v144 offset:2048
	v_mfma_f32_16x16x32_bf16 v[114:117], v[232:235], v[212:215], v[114:117]
	ds_read_b128 v[162:165], v144 offset:3072
	v_mfma_f32_16x16x32_bf16 v[110:113], v[232:235], v[216:219], v[110:113]
	ds_read_b128 v[166:169], v144 offset:4096
	v_mfma_f32_16x16x32_bf16 v[106:109], v[232:235], v[220:223], v[106:109]
	ds_read_b128 v[170:173], v144 offset:5120
	v_mfma_f32_16x16x32_bf16 v[102:105], v[232:235], v[224:227], v[102:105]
	ds_read_b128 v[176:179], v144 offset:6144
	v_mfma_f32_16x16x32_bf16 v[98:101], v[232:235], v[228:231], v[98:101]
	ds_read_b128 v[180:183], v144 offset:7168
	v_mfma_f32_16x16x32_bf16 v[94:97], v[236:239], v[200:203], v[94:97]
	v_add_u32_e64 v144, s40, v137
	v_mfma_f32_16x16x32_bf16 v[90:93], v[236:239], v[204:207], v[90:93]
	v_mfma_f32_16x16x32_bf16 v[86:89], v[236:239], v[208:211], v[86:89]
	ds_read_b128 v[184:187], v144 offset:16384
	v_mfma_f32_16x16x32_bf16 v[82:85], v[236:239], v[212:215], v[82:85]
	ds_read_b128 v[188:191], v144 offset:17408
	v_mfma_f32_16x16x32_bf16 v[78:81], v[236:239], v[216:219], v[78:81]
	ds_read_b128 v[192:195], v144 offset:18432
	v_mfma_f32_16x16x32_bf16 v[74:77], v[236:239], v[220:223], v[74:77]
	ds_read_b128 v[196:199], v144 offset:19456
	v_mfma_f32_16x16x32_bf16 v[70:73], v[236:239], v[224:227], v[70:73]
	v_mfma_f32_16x16x32_bf16 v[66:69], v[236:239], v[228:231], v[66:69]
	v_mfma_f32_16x16x32_bf16 v[62:65], v[240:243], v[200:203], v[62:65]
	v_mfma_f32_16x16x32_bf16 v[58:61], v[240:243], v[204:207], v[58:61]
	v_mfma_f32_16x16x32_bf16 v[54:57], v[240:243], v[208:211], v[54:57]
	v_mfma_f32_16x16x32_bf16 v[50:53], v[240:243], v[212:215], v[50:53]
	v_mfma_f32_16x16x32_bf16 v[46:49], v[240:243], v[216:219], v[46:49]
	v_mfma_f32_16x16x32_bf16 v[42:45], v[240:243], v[220:223], v[42:45]
	v_mfma_f32_16x16x32_bf16 v[38:41], v[240:243], v[224:227], v[38:41]
	v_mfma_f32_16x16x32_bf16 v[34:37], v[240:243], v[228:231], v[34:37]
	s_setprio 0
	s_nop 0
	v_mfma_f32_16x16x32_bf16 v[30:33], v[244:247], v[200:203], v[30:33]
	v_mfma_f32_16x16x32_bf16 v[26:29], v[244:247], v[204:207], v[26:29]
	v_mfma_f32_16x16x32_bf16 v[22:25], v[244:247], v[208:211], v[22:25]
	v_mfma_f32_16x16x32_bf16 v[18:21], v[244:247], v[212:215], v[18:21]
	v_mfma_f32_16x16x32_bf16 v[14:17], v[244:247], v[216:219], v[14:17]
	v_mfma_f32_16x16x32_bf16 v[10:13], v[244:247], v[220:223], v[10:13]
	v_mfma_f32_16x16x32_bf16 v[6:9], v[244:247], v[224:227], v[6:9]
	v_mfma_f32_16x16x32_bf16 v[2:5], v[244:247], v[228:231], v[2:5]
	s_mov_b32 s41, s40
	s_nop 0
	s_add_i32 s40, s40, 0x6000
	s_cmp_eq_u32 s40, 0x12000
	s_cselect_b32 s40, 0, s40
	s_nop 0
	.p2align 3
	s_waitcnt vmcnt(0) lgkmcnt(0)
	s_barrier
	s_setprio 1
	v_add_u32_e32 v144, s40, v136
	v_mfma_f32_16x16x32_bf16 v[126:129], v[184:187], v[146:149], v[126:129]
	ds_read_b128 v[200:203], v144 offset:0
	v_mfma_f32_16x16x32_bf16 v[122:125], v[184:187], v[152:155], v[122:125]
	ds_read_b128 v[204:207], v144 offset:1024
	v_mfma_f32_16x16x32_bf16 v[118:121], v[184:187], v[156:159], v[118:121]
	ds_read_b128 v[208:211], v144 offset:2048
	v_mfma_f32_16x16x32_bf16 v[114:117], v[184:187], v[162:165], v[114:117]
	ds_read_b128 v[212:215], v144 offset:3072
	v_mfma_f32_16x16x32_bf16 v[110:113], v[184:187], v[166:169], v[110:113]
	ds_read_b128 v[216:219], v144 offset:4096
	v_mfma_f32_16x16x32_bf16 v[106:109], v[184:187], v[170:173], v[106:109]
	ds_read_b128 v[220:223], v144 offset:5120
	v_mfma_f32_16x16x32_bf16 v[102:105], v[184:187], v[176:179], v[102:105]
	ds_read_b128 v[224:227], v144 offset:6144
	v_mfma_f32_16x16x32_bf16 v[98:101], v[184:187], v[180:183], v[98:101]
	ds_read_b128 v[228:231], v144 offset:7168
	v_mfma_f32_16x16x32_bf16 v[94:97], v[188:191], v[146:149], v[94:97]
	v_add_u32_e64 v144, s40, v137
	v_mfma_f32_16x16x32_bf16 v[90:93], v[188:191], v[152:155], v[90:93]
	v_mfma_f32_16x16x32_bf16 v[86:89], v[188:191], v[156:159], v[86:89]
	ds_read_b128 v[232:235], v144 offset:16384
	v_mfma_f32_16x16x32_bf16 v[82:85], v[188:191], v[162:165], v[82:85]
	ds_read_b128 v[236:239], v144 offset:17408
	v_mfma_f32_16x16x32_bf16 v[78:81], v[188:191], v[166:169], v[78:81]
	ds_read_b128 v[240:243], v144 offset:18432
	v_mfma_f32_16x16x32_bf16 v[74:77], v[188:191], v[170:173], v[74:77]
	ds_read_b128 v[244:247], v144 offset:19456
	v_mfma_f32_16x16x32_bf16 v[70:73], v[188:191], v[176:179], v[70:73]
	v_mfma_f32_16x16x32_bf16 v[66:69], v[188:191], v[180:183], v[66:69]
	v_mfma_f32_16x16x32_bf16 v[62:65], v[192:195], v[146:149], v[62:65]
	v_mfma_f32_16x16x32_bf16 v[58:61], v[192:195], v[152:155], v[58:61]
	v_mfma_f32_16x16x32_bf16 v[54:57], v[192:195], v[156:159], v[54:57]
	v_mfma_f32_16x16x32_bf16 v[50:53], v[192:195], v[162:165], v[50:53]
	v_mfma_f32_16x16x32_bf16 v[46:49], v[192:195], v[166:169], v[46:49]
	v_mfma_f32_16x16x32_bf16 v[42:45], v[192:195], v[170:173], v[42:45]
	v_mfma_f32_16x16x32_bf16 v[38:41], v[192:195], v[176:179], v[38:41]
	v_mfma_f32_16x16x32_bf16 v[34:37], v[192:195], v[180:183], v[34:37]
	s_setprio 0
	s_nop 0
	v_mfma_f32_16x16x32_bf16 v[30:33], v[196:199], v[146:149], v[30:33]
	v_mfma_f32_16x16x32_bf16 v[26:29], v[196:199], v[152:155], v[26:29]
	v_mfma_f32_16x16x32_bf16 v[22:25], v[196:199], v[156:159], v[22:25]
	v_mfma_f32_16x16x32_bf16 v[18:21], v[196:199], v[162:165], v[18:21]
	v_mfma_f32_16x16x32_bf16 v[14:17], v[196:199], v[166:169], v[14:17]
	v_mfma_f32_16x16x32_bf16 v[10:13], v[196:199], v[170:173], v[10:13]
	v_mfma_f32_16x16x32_bf16 v[6:9], v[196:199], v[176:179], v[6:9]
	v_mfma_f32_16x16x32_bf16 v[2:5], v[196:199], v[180:183], v[2:5]
	s_mov_b32 s41, s40
	s_nop 0
	s_add_i32 s40, s40, 0x6000
	s_cmp_eq_u32 s40, 0x12000
	s_cselect_b32 s40, 0, s40
	s_nop 0
	s_mov_b32 s4, 0x8000
	s_mov_b32 s5, 0
	s_mov_b32 s10, 0x10000
	s_mov_b32 s11, 0
	s_mov_b32 s44, 0x3fd744fd
	.p2align 3
	s_waitcnt lgkmcnt(0)
; DEVI float blo(unsigned u) { return __uint_as_float(u << 16); }
; DEVI float bhi(unsigned u) { return __uint_as_float(u & 0xffff0000u); }
;     ...
;         if (EPI == EPI_RESID || EPI == EPI_RESID_ATOMIC) {
;           f32x4 x = a;
;           if (EPI == EPI_RESID || kpart == 0) {
;             const u32x2 xr = *(const u32x2*)((const u16*)(p.ws + WS_XB) + (size_t)row * 1024 + col);
;             x[0] += ALPHA * blo(xr[0]); x[1] += ALPHA * bhi(xr[0]); x[2] += ALPHA * blo(xr[1]); x[3] += ALPHA * bhi(xr[1]);
;           }
;           if (EPI == EPI_RESID) *(f32x4*)((float*)(p.ws + WS_XF) + (size_t)row * 1024 + col) = x;
;           else *(f32x4*)((float*)(p.ws + WS_SLAB) + ((size_t)kpart * 512 + (row - T_P)) * 1024 + col) = x;
	s_nop 0
	v_mfma_f32_16x16x32_bf16 v[126:129], v[232:235], v[200:203], v[126:129]
	v_mfma_f32_16x16x32_bf16 v[122:125], v[232:235], v[204:207], v[122:125]
	v_mfma_f32_16x16x32_bf16 v[118:121], v[232:235], v[208:211], v[118:121]
	v_mfma_f32_16x16x32_bf16 v[114:117], v[232:235], v[212:215], v[114:117]
	v_mfma_f32_16x16x32_bf16 v[110:113], v[232:235], v[216:219], v[110:113]
	global_load_dwordx4 v[146:149], v[138:139], off offset:0
	v_mfma_f32_16x16x32_bf16 v[106:109], v[232:235], v[220:223], v[106:109]
	v_mfma_f32_16x16x32_bf16 v[102:105], v[232:235], v[224:227], v[102:105]
	global_load_dwordx4 v[152:155], v[138:139], off offset:64
	v_mfma_f32_16x16x32_bf16 v[98:101], v[232:235], v[228:231], v[98:101]
	v_lshl_add_u64 v[138:139], v[138:139], 0, s[4:5]
	v_mfma_f32_16x16x32_bf16 v[94:97], v[236:239], v[200:203], v[94:97]
	global_load_dwordx4 v[156:159], v[138:139], off offset:0
	v_mfma_f32_16x16x32_bf16 v[90:93], v[236:239], v[204:207], v[90:93]
	v_mfma_f32_16x16x32_bf16 v[86:89], v[236:239], v[208:211], v[86:89]
	global_load_dwordx4 v[162:165], v[138:139], off offset:64
	v_mfma_f32_16x16x32_bf16 v[82:85], v[236:239], v[212:215], v[82:85]
	v_lshl_add_u64 v[138:139], v[138:139], 0, s[4:5]
	v_mfma_f32_16x16x32_bf16 v[78:81], v[236:239], v[216:219], v[78:81]
	global_load_dwordx4 v[166:169], v[138:139], off offset:0
	v_mfma_f32_16x16x32_bf16 v[74:77], v[236:239], v[220:223], v[74:77]
	v_mfma_f32_16x16x32_bf16 v[70:73], v[236:239], v[224:227], v[70:73]
	global_load_dwordx4 v[170:173], v[138:139], off offset:64
	v_mfma_f32_16x16x32_bf16 v[66:69], v[236:239], v[228:231], v[66:69]
	v_lshl_add_u64 v[138:139], v[138:139], 0, s[4:5]
	v_mfma_f32_16x16x32_bf16 v[62:65], v[240:243], v[200:203], v[62:65]
	global_load_dwordx4 v[176:179], v[138:139], off offset:0
	v_mfma_f32_16x16x32_bf16 v[58:61], v[240:243], v[204:207], v[58:61]
	v_mfma_f32_16x16x32_bf16 v[54:57], v[240:243], v[208:211], v[54:57]
	global_load_dwordx4 v[180:183], v[138:139], off offset:64
	v_mfma_f32_16x16x32_bf16 v[50:53], v[240:243], v[212:215], v[50:53]
	v_lshl_add_u64 v[138:139], v[138:139], 0, s[4:5]
	v_mfma_f32_16x16x32_bf16 v[46:49], v[240:243], v[216:219], v[46:49]
	global_load_dwordx4 v[184:187], v[138:139], off offset:0
	v_mfma_f32_16x16x32_bf16 v[42:45], v[240:243], v[220:223], v[42:45]
	v_mfma_f32_16x16x32_bf16 v[38:41], v[240:243], v[224:227], v[38:41]
	global_load_dwordx4 v[188:191], v[138:139], off offset:64
	v_mfma_f32_16x16x32_bf16 v[34:37], v[240:243], v[228:231], v[34:37]
	v_lshl_add_u64 v[138:139], v[138:139], 0, s[4:5]
	v_mfma_f32_16x16x32_bf16 v[30:33], v[244:247], v[200:203], v[30:33]
	global_load_dwordx4 v[192:195], v[138:139], off offset:0
	v_mfma_f32_16x16x32_bf16 v[26:29], v[244:247], v[204:207], v[26:29]
	v_mfma_f32_16x16x32_bf16 v[22:25], v[244:247], v[208:211], v[22:25]
	global_load_dwordx4 v[196:199], v[138:139], off offset:64
	v_mfma_f32_16x16x32_bf16 v[18:21], v[244:247], v[212:215], v[18:21]
	v_lshl_add_u64 v[138:139], v[138:139], 0, s[4:5]
	v_mfma_f32_16x16x32_bf16 v[14:17], v[244:247], v[216:219], v[14:17]
	v_mfma_f32_16x16x32_bf16 v[10:13], v[244:247], v[220:223], v[10:13]
	v_mfma_f32_16x16x32_bf16 v[6:9], v[244:247], v[224:227], v[6:9]
	v_mfma_f32_16x16x32_bf16 v[2:5], v[244:247], v[228:231], v[2:5]
	s_mov_b32 m0, s43
	global_load_dwordx4 v[200:203], v[138:139], off offset:0
	global_load_dwordx4 v[204:207], v[138:139], off offset:64
	v_lshl_add_u64 v[138:139], v[138:139], 0, s[4:5]
	global_load_dwordx4 v[208:211], v[138:139], off offset:0
	global_load_dwordx4 v[212:215], v[138:139], off offset:64
	v_lshl_add_u64 v[138:139], v[138:139], 0, s[4:5]
	s_nop 7
	v_and_b32_e32 v228, 1, v145
	v_cmp_ne_u32_e32 vcc, 0, v228
	v_mov_b32_e32 v229, 0xfffff040
	v_cndmask_b32_e32 v230, 0, v229, vcc
	v_ashrrev_i32_e32 v231, 31, v230
	v_lshl_add_u64 v[140:141], v[140:141], 0, v[230:231]
	v_add_co_u32_e32 v142, vcc, 0x1000, v140
	s_nop 0
	v_addc_co_u32_e32 v143, vcc, 0, v141, vcc
	v_cmp_ne_u32_e32 vcc, 0, v228
	s_waitcnt vmcnt(15)
	v_permlane16_swap_b32_e32 v146, v148
	v_permlane16_swap_b32_e32 v147, v149
	v_lshlrev_b32_e32 v216, 16, v146
	v_and_b32_e32 v146, 0xffff0000, v146
	v_lshlrev_b32_e32 v217, 16, v147
	v_and_b32_e32 v147, 0xffff0000, v147
	v_fmac_f32_e32 v126, s44, v216
	v_fmac_f32_e32 v127, s44, v146
	v_fmac_f32_e32 v128, s44, v217
	v_fmac_f32_e32 v129, s44, v147
	v_lshlrev_b32_e32 v216, 16, v148
	v_and_b32_e32 v148, 0xffff0000, v148
	v_lshlrev_b32_e32 v217, 16, v149
	v_and_b32_e32 v149, 0xffff0000, v149
	v_fmac_f32_e32 v94, s44, v216
	v_fmac_f32_e32 v95, s44, v148
	v_fmac_f32_e32 v96, s44, v217
	v_fmac_f32_e32 v97, s44, v149
	v_mov_b32_dpp v220, v94 quad_perm:[1,0,3,2] row_mask:0xf bank_mask:0xf
	v_mov_b32_dpp v221, v95 quad_perm:[1,0,3,2] row_mask:0xf bank_mask:0xf
	v_mov_b32_dpp v222, v96 quad_perm:[1,0,3,2] row_mask:0xf bank_mask:0xf
	v_mov_b32_dpp v223, v97 quad_perm:[1,0,3,2] row_mask:0xf bank_mask:0xf
	v_mov_b32_dpp v224, v126 quad_perm:[1,0,3,2] row_mask:0xf bank_mask:0xf
	v_mov_b32_dpp v225, v127 quad_perm:[1,0,3,2] row_mask:0xf bank_mask:0xf
	v_mov_b32_dpp v226, v128 quad_perm:[1,0,3,2] row_mask:0xf bank_mask:0xf
	v_mov_b32_dpp v227, v129 quad_perm:[1,0,3,2] row_mask:0xf bank_mask:0xf
	v_cndmask_b32_e32 v94, v224, v94, vcc
	v_cndmask_b32_e32 v95, v225, v95, vcc
	v_cndmask_b32_e32 v96, v226, v96, vcc
	v_cndmask_b32_e32 v97, v227, v97, vcc
	v_cndmask_b32_e32 v126, v126, v220, vcc
	v_cndmask_b32_e32 v127, v127, v221, vcc
	v_cndmask_b32_e32 v128, v128, v222, vcc
	v_cndmask_b32_e32 v129, v129, v223, vcc
	global_store_dwordx4 v[140:141], v[126:129], off
	global_store_dwordx4 v[142:143], v[94:97], off
	s_waitcnt vmcnt(16)
; DEVI float blo(unsigned u) { return __uint_as_float(u << 16); }
; DEVI float bhi(unsigned u) { return __uint_as_float(u & 0xffff0000u); }
;     ...
;         if (EPI == EPI_RESID || EPI == EPI_RESID_ATOMIC) {
;           f32x4 x = a;
;           if (EPI == EPI_RESID || kpart == 0) {
;             const u32x2 xr = *(const u32x2*)((const u16*)(p.ws + WS_XB) + (size_t)row * 1024 + col);
;             x[0] += ALPHA * blo(xr[0]); x[1] += ALPHA * bhi(xr[0]); x[2] += ALPHA * blo(xr[1]); x[3] += ALPHA * bhi(xr[1]);
;           }
;           if (EPI == EPI_RESID) *(f32x4*)((float*)(p.ws + WS_XF) + (size_t)row * 1024 + col) = x;
;           else *(f32x4*)((float*)(p.ws + WS_SLAB) + ((size_t)kpart * 512 + (row - T_P)) * 1024 + col) = x;
	v_permlane16_swap_b32_e32 v152, v154
	v_permlane16_swap_b32_e32 v153, v155
	v_lshlrev_b32_e32 v216, 16, v152
	v_and_b32_e32 v152, 0xffff0000, v152
	v_lshlrev_b32_e32 v217, 16, v153
	v_and_b32_e32 v153, 0xffff0000, v153
	v_fmac_f32_e32 v62, s44, v216
	v_fmac_f32_e32 v63, s44, v152
	v_fmac_f32_e32 v64, s44, v217
	v_fmac_f32_e32 v65, s44, v153
	v_lshlrev_b32_e32 v216, 16, v154
	v_and_b32_e32 v154, 0xffff0000, v154
	v_lshlrev_b32_e32 v217, 16, v155
	v_and_b32_e32 v155, 0xffff0000, v155
	v_fmac_f32_e32 v30, s44, v216
	v_fmac_f32_e32 v31, s44, v154
	v_fmac_f32_e32 v32, s44, v217
	v_fmac_f32_e32 v33, s44, v155
	v_mov_b32_dpp v220, v30 quad_perm:[1,0,3,2] row_mask:0xf bank_mask:0xf
	v_mov_b32_dpp v221, v31 quad_perm:[1,0,3,2] row_mask:0xf bank_mask:0xf
	v_mov_b32_dpp v222, v32 quad_perm:[1,0,3,2] row_mask:0xf bank_mask:0xf
	v_mov_b32_dpp v223, v33 quad_perm:[1,0,3,2] row_mask:0xf bank_mask:0xf
	v_mov_b32_dpp v224, v62 quad_perm:[1,0,3,2] row_mask:0xf bank_mask:0xf
	v_mov_b32_dpp v225, v63 quad_perm:[1,0,3,2] row_mask:0xf bank_mask:0xf
	v_mov_b32_dpp v226, v64 quad_perm:[1,0,3,2] row_mask:0xf bank_mask:0xf
	v_mov_b32_dpp v227, v65 quad_perm:[1,0,3,2] row_mask:0xf bank_mask:0xf
	v_cndmask_b32_e32 v30, v224, v30, vcc
	v_cndmask_b32_e32 v31, v225, v31, vcc
	v_cndmask_b32_e32 v32, v226, v32, vcc
	v_cndmask_b32_e32 v33, v227, v33, vcc
	v_cndmask_b32_e32 v62, v62, v220, vcc
	v_cndmask_b32_e32 v63, v63, v221, vcc
	v_cndmask_b32_e32 v64, v64, v222, vcc
	v_cndmask_b32_e32 v65, v65, v223, vcc
	global_store_dwordx4 v[140:141], v[62:65], off offset:128
	global_store_dwordx4 v[142:143], v[30:33], off offset:128
	v_lshl_add_u64 v[140:141], v[140:141], 0, s[10:11]
	v_lshl_add_u64 v[142:143], v[142:143], 0, s[10:11]
	s_waitcnt vmcnt(17)
	v_permlane16_swap_b32_e32 v156, v158
	v_permlane16_swap_b32_e32 v157, v159
	v_lshlrev_b32_e32 v216, 16, v156
	v_and_b32_e32 v156, 0xffff0000, v156
	v_lshlrev_b32_e32 v217, 16, v157
	v_and_b32_e32 v157, 0xffff0000, v157
	v_fmac_f32_e32 v122, s44, v216
	v_fmac_f32_e32 v123, s44, v156
	v_fmac_f32_e32 v124, s44, v217
	v_fmac_f32_e32 v125, s44, v157
	v_lshlrev_b32_e32 v216, 16, v158
	v_and_b32_e32 v158, 0xffff0000, v158
	v_lshlrev_b32_e32 v217, 16, v159
	v_and_b32_e32 v159, 0xffff0000, v159
	v_fmac_f32_e32 v90, s44, v216
	v_fmac_f32_e32 v91, s44, v158
	v_fmac_f32_e32 v92, s44, v217
	v_fmac_f32_e32 v93, s44, v159
	v_mov_b32_dpp v220, v90 quad_perm:[1,0,3,2] row_mask:0xf bank_mask:0xf
	v_mov_b32_dpp v221, v91 quad_perm:[1,0,3,2] row_mask:0xf bank_mask:0xf
	v_mov_b32_dpp v222, v92 quad_perm:[1,0,3,2] row_mask:0xf bank_mask:0xf
	v_mov_b32_dpp v223, v93 quad_perm:[1,0,3,2] row_mask:0xf bank_mask:0xf
	v_mov_b32_dpp v224, v122 quad_perm:[1,0,3,2] row_mask:0xf bank_mask:0xf
	v_mov_b32_dpp v225, v123 quad_perm:[1,0,3,2] row_mask:0xf bank_mask:0xf
	v_mov_b32_dpp v226, v124 quad_perm:[1,0,3,2] row_mask:0xf bank_mask:0xf
	v_mov_b32_dpp v227, v125 quad_perm:[1,0,3,2] row_mask:0xf bank_mask:0xf
	v_cndmask_b32_e32 v90, v224, v90, vcc
	v_cndmask_b32_e32 v91, v225, v91, vcc
	v_cndmask_b32_e32 v92, v226, v92, vcc
	v_cndmask_b32_e32 v93, v227, v93, vcc
	v_cndmask_b32_e32 v122, v122, v220, vcc
	v_cndmask_b32_e32 v123, v123, v221, vcc
	v_cndmask_b32_e32 v124, v124, v222, vcc
	v_cndmask_b32_e32 v125, v125, v223, vcc
	global_store_dwordx4 v[140:141], v[122:125], off
	global_store_dwordx4 v[142:143], v[90:93], off
	s_waitcnt vmcnt(18)
	v_permlane16_swap_b32_e32 v162, v164
	v_permlane16_swap_b32_e32 v163, v165
	v_lshlrev_b32_e32 v216, 16, v162
	v_and_b32_e32 v162, 0xffff0000, v162
	v_lshlrev_b32_e32 v217, 16, v163
	v_and_b32_e32 v163, 0xffff0000, v163
	v_fmac_f32_e32 v58, s44, v216
	v_fmac_f32_e32 v59, s44, v162
	v_fmac_f32_e32 v60, s44, v217
	v_fmac_f32_e32 v61, s44, v163
	v_lshlrev_b32_e32 v216, 16, v164
	v_and_b32_e32 v164, 0xffff0000, v164
	v_lshlrev_b32_e32 v217, 16, v165
	v_and_b32_e32 v165, 0xffff0000, v165
	v_fmac_f32_e32 v26, s44, v216
	v_fmac_f32_e32 v27, s44, v164
	v_fmac_f32_e32 v28, s44, v217
	v_fmac_f32_e32 v29, s44, v165
	v_mov_b32_dpp v220, v26 quad_perm:[1,0,3,2] row_mask:0xf bank_mask:0xf
	v_mov_b32_dpp v221, v27 quad_perm:[1,0,3,2] row_mask:0xf bank_mask:0xf
	v_mov_b32_dpp v222, v28 quad_perm:[1,0,3,2] row_mask:0xf bank_mask:0xf
	v_mov_b32_dpp v223, v29 quad_perm:[1,0,3,2] row_mask:0xf bank_mask:0xf
	v_mov_b32_dpp v224, v58 quad_perm:[1,0,3,2] row_mask:0xf bank_mask:0xf
	v_mov_b32_dpp v225, v59 quad_perm:[1,0,3,2] row_mask:0xf bank_mask:0xf
	v_mov_b32_dpp v226, v60 quad_perm:[1,0,3,2] row_mask:0xf bank_mask:0xf
	v_mov_b32_dpp v227, v61 quad_perm:[1,0,3,2] row_mask:0xf bank_mask:0xf
	v_cndmask_b32_e32 v26, v224, v26, vcc
	v_cndmask_b32_e32 v27, v225, v27, vcc
	v_cndmask_b32_e32 v28, v226, v28, vcc
	v_cndmask_b32_e32 v29, v227, v29, vcc
	v_cndmask_b32_e32 v58, v58, v220, vcc
	v_cndmask_b32_e32 v59, v59, v221, vcc
	v_cndmask_b32_e32 v60, v60, v222, vcc
	v_cndmask_b32_e32 v61, v61, v223, vcc
	global_store_dwordx4 v[140:141], v[58:61], off offset:128
	global_store_dwordx4 v[142:143], v[26:29], off offset:128
	v_lshl_add_u64 v[140:141], v[140:141], 0, s[10:11]
	v_lshl_add_u64 v[142:143], v[142:143], 0, s[10:11]
	s_waitcnt vmcnt(19)
; DEVI float blo(unsigned u) { return __uint_as_float(u << 16); }
; DEVI float bhi(unsigned u) { return __uint_as_float(u & 0xffff0000u); }
;     ...
;         if (EPI == EPI_RESID || EPI == EPI_RESID_ATOMIC) {
;           f32x4 x = a;
;           if (EPI == EPI_RESID || kpart == 0) {
;             const u32x2 xr = *(const u32x2*)((const u16*)(p.ws + WS_XB) + (size_t)row * 1024 + col);
;             x[0] += ALPHA * blo(xr[0]); x[1] += ALPHA * bhi(xr[0]); x[2] += ALPHA * blo(xr[1]); x[3] += ALPHA * bhi(xr[1]);
;           }
;           if (EPI == EPI_RESID) *(f32x4*)((float*)(p.ws + WS_XF) + (size_t)row * 1024 + col) = x;
;           else *(f32x4*)((float*)(p.ws + WS_SLAB) + ((size_t)kpart * 512 + (row - T_P)) * 1024 + col) = x;
	v_permlane16_swap_b32_e32 v166, v168
	v_permlane16_swap_b32_e32 v167, v169
	v_lshlrev_b32_e32 v216, 16, v166
	v_and_b32_e32 v166, 0xffff0000, v166
	v_lshlrev_b32_e32 v217, 16, v167
	v_and_b32_e32 v167, 0xffff0000, v167
	v_fmac_f32_e32 v118, s44, v216
	v_fmac_f32_e32 v119, s44, v166
	v_fmac_f32_e32 v120, s44, v217
	v_fmac_f32_e32 v121, s44, v167
	v_lshlrev_b32_e32 v216, 16, v168
	v_and_b32_e32 v168, 0xffff0000, v168
	v_lshlrev_b32_e32 v217, 16, v169
	v_and_b32_e32 v169, 0xffff0000, v169
	v_fmac_f32_e32 v86, s44, v216
	v_fmac_f32_e32 v87, s44, v168
	v_fmac_f32_e32 v88, s44, v217
	v_fmac_f32_e32 v89, s44, v169
	v_mov_b32_dpp v220, v86 quad_perm:[1,0,3,2] row_mask:0xf bank_mask:0xf
	v_mov_b32_dpp v221, v87 quad_perm:[1,0,3,2] row_mask:0xf bank_mask:0xf
	v_mov_b32_dpp v222, v88 quad_perm:[1,0,3,2] row_mask:0xf bank_mask:0xf
	v_mov_b32_dpp v223, v89 quad_perm:[1,0,3,2] row_mask:0xf bank_mask:0xf
	v_mov_b32_dpp v224, v118 quad_perm:[1,0,3,2] row_mask:0xf bank_mask:0xf
	v_mov_b32_dpp v225, v119 quad_perm:[1,0,3,2] row_mask:0xf bank_mask:0xf
	v_mov_b32_dpp v226, v120 quad_perm:[1,0,3,2] row_mask:0xf bank_mask:0xf
	v_mov_b32_dpp v227, v121 quad_perm:[1,0,3,2] row_mask:0xf bank_mask:0xf
	v_cndmask_b32_e32 v86, v224, v86, vcc
	v_cndmask_b32_e32 v87, v225, v87, vcc
	v_cndmask_b32_e32 v88, v226, v88, vcc
	v_cndmask_b32_e32 v89, v227, v89, vcc
	v_cndmask_b32_e32 v118, v118, v220, vcc
	v_cndmask_b32_e32 v119, v119, v221, vcc
	v_cndmask_b32_e32 v120, v120, v222, vcc
	v_cndmask_b32_e32 v121, v121, v223, vcc
	global_store_dwordx4 v[140:141], v[118:121], off
	global_store_dwordx4 v[142:143], v[86:89], off
	s_waitcnt vmcnt(20)
	v_permlane16_swap_b32_e32 v170, v172
	v_permlane16_swap_b32_e32 v171, v173
	v_lshlrev_b32_e32 v216, 16, v170
	v_and_b32_e32 v170, 0xffff0000, v170
	v_lshlrev_b32_e32 v217, 16, v171
	v_and_b32_e32 v171, 0xffff0000, v171
	v_fmac_f32_e32 v54, s44, v216
	v_fmac_f32_e32 v55, s44, v170
	v_fmac_f32_e32 v56, s44, v217
	v_fmac_f32_e32 v57, s44, v171
	v_lshlrev_b32_e32 v216, 16, v172
	v_and_b32_e32 v172, 0xffff0000, v172
	v_lshlrev_b32_e32 v217, 16, v173
	v_and_b32_e32 v173, 0xffff0000, v173
	v_fmac_f32_e32 v22, s44, v216
	v_fmac_f32_e32 v23, s44, v172
	v_fmac_f32_e32 v24, s44, v217
	v_fmac_f32_e32 v25, s44, v173
	v_mov_b32_dpp v220, v22 quad_perm:[1,0,3,2] row_mask:0xf bank_mask:0xf
	v_mov_b32_dpp v221, v23 quad_perm:[1,0,3,2] row_mask:0xf bank_mask:0xf
	v_mov_b32_dpp v222, v24 quad_perm:[1,0,3,2] row_mask:0xf bank_mask:0xf
	v_mov_b32_dpp v223, v25 quad_perm:[1,0,3,2] row_mask:0xf bank_mask:0xf
	v_mov_b32_dpp v224, v54 quad_perm:[1,0,3,2] row_mask:0xf bank_mask:0xf
	v_mov_b32_dpp v225, v55 quad_perm:[1,0,3,2] row_mask:0xf bank_mask:0xf
	v_mov_b32_dpp v226, v56 quad_perm:[1,0,3,2] row_mask:0xf bank_mask:0xf
	v_mov_b32_dpp v227, v57 quad_perm:[1,0,3,2] row_mask:0xf bank_mask:0xf
	v_cndmask_b32_e32 v22, v224, v22, vcc
	v_cndmask_b32_e32 v23, v225, v23, vcc
	v_cndmask_b32_e32 v24, v226, v24, vcc
	v_cndmask_b32_e32 v25, v227, v25, vcc
	v_cndmask_b32_e32 v54, v54, v220, vcc
	v_cndmask_b32_e32 v55, v55, v221, vcc
	v_cndmask_b32_e32 v56, v56, v222, vcc
	v_cndmask_b32_e32 v57, v57, v223, vcc
	global_store_dwordx4 v[140:141], v[54:57], off offset:128
	global_store_dwordx4 v[142:143], v[22:25], off offset:128
	v_lshl_add_u64 v[140:141], v[140:141], 0, s[10:11]
	v_lshl_add_u64 v[142:143], v[142:143], 0, s[10:11]
	s_waitcnt vmcnt(21)
	v_permlane16_swap_b32_e32 v176, v178
	v_permlane16_swap_b32_e32 v177, v179
	v_lshlrev_b32_e32 v216, 16, v176
	v_and_b32_e32 v176, 0xffff0000, v176
	v_lshlrev_b32_e32 v217, 16, v177
	v_and_b32_e32 v177, 0xffff0000, v177
	v_fmac_f32_e32 v114, s44, v216
	v_fmac_f32_e32 v115, s44, v176
	v_fmac_f32_e32 v116, s44, v217
	v_fmac_f32_e32 v117, s44, v177
	v_lshlrev_b32_e32 v216, 16, v178
	v_and_b32_e32 v178, 0xffff0000, v178
	v_lshlrev_b32_e32 v217, 16, v179
	v_and_b32_e32 v179, 0xffff0000, v179
	v_fmac_f32_e32 v82, s44, v216
	v_fmac_f32_e32 v83, s44, v178
	v_fmac_f32_e32 v84, s44, v217
	v_fmac_f32_e32 v85, s44, v179
	v_mov_b32_dpp v220, v82 quad_perm:[1,0,3,2] row_mask:0xf bank_mask:0xf
	v_mov_b32_dpp v221, v83 quad_perm:[1,0,3,2] row_mask:0xf bank_mask:0xf
	v_mov_b32_dpp v222, v84 quad_perm:[1,0,3,2] row_mask:0xf bank_mask:0xf
	v_mov_b32_dpp v223, v85 quad_perm:[1,0,3,2] row_mask:0xf bank_mask:0xf
	v_mov_b32_dpp v224, v114 quad_perm:[1,0,3,2] row_mask:0xf bank_mask:0xf
	v_mov_b32_dpp v225, v115 quad_perm:[1,0,3,2] row_mask:0xf bank_mask:0xf
	v_mov_b32_dpp v226, v116 quad_perm:[1,0,3,2] row_mask:0xf bank_mask:0xf
	v_mov_b32_dpp v227, v117 quad_perm:[1,0,3,2] row_mask:0xf bank_mask:0xf
	v_cndmask_b32_e32 v82, v224, v82, vcc
	v_cndmask_b32_e32 v83, v225, v83, vcc
	v_cndmask_b32_e32 v84, v226, v84, vcc
	v_cndmask_b32_e32 v85, v227, v85, vcc
	v_cndmask_b32_e32 v114, v114, v220, vcc
	v_cndmask_b32_e32 v115, v115, v221, vcc
	v_cndmask_b32_e32 v116, v116, v222, vcc
	v_cndmask_b32_e32 v117, v117, v223, vcc
	global_store_dwordx4 v[140:141], v[114:117], off
	global_store_dwordx4 v[142:143], v[82:85], off
	s_waitcnt vmcnt(22)
; DEVI float blo(unsigned u) { return __uint_as_float(u << 16); }
; DEVI float bhi(unsigned u) { return __uint_as_float(u & 0xffff0000u); }
;     ...
;         if (EPI == EPI_RESID || EPI == EPI_RESID_ATOMIC) {
;           f32x4 x = a;
;           if (EPI == EPI_RESID || kpart == 0) {
;             const u32x2 xr = *(const u32x2*)((const u16*)(p.ws + WS_XB) + (size_t)row * 1024 + col);
;             x[0] += ALPHA * blo(xr[0]); x[1] += ALPHA * bhi(xr[0]); x[2] += ALPHA * blo(xr[1]); x[3] += ALPHA * bhi(xr[1]);
;           }
;           if (EPI == EPI_RESID) *(f32x4*)((float*)(p.ws + WS_XF) + (size_t)row * 1024 + col) = x;
;           else *(f32x4*)((float*)(p.ws + WS_SLAB) + ((size_t)kpart * 512 + (row - T_P)) * 1024 + col) = x;
	v_permlane16_swap_b32_e32 v180, v182
	v_permlane16_swap_b32_e32 v181, v183
	v_lshlrev_b32_e32 v216, 16, v180
	v_and_b32_e32 v180, 0xffff0000, v180
	v_lshlrev_b32_e32 v217, 16, v181
	v_and_b32_e32 v181, 0xffff0000, v181
	v_fmac_f32_e32 v50, s44, v216
	v_fmac_f32_e32 v51, s44, v180
	v_fmac_f32_e32 v52, s44, v217
	v_fmac_f32_e32 v53, s44, v181
	v_lshlrev_b32_e32 v216, 16, v182
	v_and_b32_e32 v182, 0xffff0000, v182
	v_lshlrev_b32_e32 v217, 16, v183
	v_and_b32_e32 v183, 0xffff0000, v183
	v_fmac_f32_e32 v18, s44, v216
	v_fmac_f32_e32 v19, s44, v182
	v_fmac_f32_e32 v20, s44, v217
	v_fmac_f32_e32 v21, s44, v183
	v_mov_b32_dpp v220, v18 quad_perm:[1,0,3,2] row_mask:0xf bank_mask:0xf
	v_mov_b32_dpp v221, v19 quad_perm:[1,0,3,2] row_mask:0xf bank_mask:0xf
	v_mov_b32_dpp v222, v20 quad_perm:[1,0,3,2] row_mask:0xf bank_mask:0xf
	v_mov_b32_dpp v223, v21 quad_perm:[1,0,3,2] row_mask:0xf bank_mask:0xf
	v_mov_b32_dpp v224, v50 quad_perm:[1,0,3,2] row_mask:0xf bank_mask:0xf
	v_mov_b32_dpp v225, v51 quad_perm:[1,0,3,2] row_mask:0xf bank_mask:0xf
	v_mov_b32_dpp v226, v52 quad_perm:[1,0,3,2] row_mask:0xf bank_mask:0xf
	v_mov_b32_dpp v227, v53 quad_perm:[1,0,3,2] row_mask:0xf bank_mask:0xf
	v_cndmask_b32_e32 v18, v224, v18, vcc
	v_cndmask_b32_e32 v19, v225, v19, vcc
	v_cndmask_b32_e32 v20, v226, v20, vcc
	v_cndmask_b32_e32 v21, v227, v21, vcc
	v_cndmask_b32_e32 v50, v50, v220, vcc
	v_cndmask_b32_e32 v51, v51, v221, vcc
	v_cndmask_b32_e32 v52, v52, v222, vcc
	v_cndmask_b32_e32 v53, v53, v223, vcc
	global_store_dwordx4 v[140:141], v[50:53], off offset:128
	global_store_dwordx4 v[142:143], v[18:21], off offset:128
	v_lshl_add_u64 v[140:141], v[140:141], 0, s[10:11]
	v_lshl_add_u64 v[142:143], v[142:143], 0, s[10:11]
	s_waitcnt vmcnt(23)
	v_permlane16_swap_b32_e32 v184, v186
	v_permlane16_swap_b32_e32 v185, v187
	v_lshlrev_b32_e32 v216, 16, v184
	v_and_b32_e32 v184, 0xffff0000, v184
	v_lshlrev_b32_e32 v217, 16, v185
	v_and_b32_e32 v185, 0xffff0000, v185
	v_fmac_f32_e32 v110, s44, v216
	v_fmac_f32_e32 v111, s44, v184
	v_fmac_f32_e32 v112, s44, v217
	v_fmac_f32_e32 v113, s44, v185
	v_lshlrev_b32_e32 v216, 16, v186
	v_and_b32_e32 v186, 0xffff0000, v186
	v_lshlrev_b32_e32 v217, 16, v187
	v_and_b32_e32 v187, 0xffff0000, v187
	v_fmac_f32_e32 v78, s44, v216
	v_fmac_f32_e32 v79, s44, v186
	v_fmac_f32_e32 v80, s44, v217
	v_fmac_f32_e32 v81, s44, v187
	v_mov_b32_dpp v220, v78 quad_perm:[1,0,3,2] row_mask:0xf bank_mask:0xf
	v_mov_b32_dpp v221, v79 quad_perm:[1,0,3,2] row_mask:0xf bank_mask:0xf
	v_mov_b32_dpp v222, v80 quad_perm:[1,0,3,2] row_mask:0xf bank_mask:0xf
	v_mov_b32_dpp v223, v81 quad_perm:[1,0,3,2] row_mask:0xf bank_mask:0xf
	v_mov_b32_dpp v224, v110 quad_perm:[1,0,3,2] row_mask:0xf bank_mask:0xf
	v_mov_b32_dpp v225, v111 quad_perm:[1,0,3,2] row_mask:0xf bank_mask:0xf
	v_mov_b32_dpp v226, v112 quad_perm:[1,0,3,2] row_mask:0xf bank_mask:0xf
	v_mov_b32_dpp v227, v113 quad_perm:[1,0,3,2] row_mask:0xf bank_mask:0xf
	v_cndmask_b32_e32 v78, v224, v78, vcc
	v_cndmask_b32_e32 v79, v225, v79, vcc
	v_cndmask_b32_e32 v80, v226, v80, vcc
	v_cndmask_b32_e32 v81, v227, v81, vcc
	v_cndmask_b32_e32 v110, v110, v220, vcc
	v_cndmask_b32_e32 v111, v111, v221, vcc
	v_cndmask_b32_e32 v112, v112, v222, vcc
	v_cndmask_b32_e32 v113, v113, v223, vcc
	global_store_dwordx4 v[140:141], v[110:113], off
	global_store_dwordx4 v[142:143], v[78:81], off
	s_waitcnt vmcnt(24)
	v_permlane16_swap_b32_e32 v188, v190
	v_permlane16_swap_b32_e32 v189, v191
	v_lshlrev_b32_e32 v216, 16, v188
	v_and_b32_e32 v188, 0xffff0000, v188
	v_lshlrev_b32_e32 v217, 16, v189
	v_and_b32_e32 v189, 0xffff0000, v189
	v_fmac_f32_e32 v46, s44, v216
	v_fmac_f32_e32 v47, s44, v188
	v_fmac_f32_e32 v48, s44, v217
	v_fmac_f32_e32 v49, s44, v189
	v_lshlrev_b32_e32 v216, 16, v190
	v_and_b32_e32 v190, 0xffff0000, v190
	v_lshlrev_b32_e32 v217, 16, v191
	v_and_b32_e32 v191, 0xffff0000, v191
	v_fmac_f32_e32 v14, s44, v216
	v_fmac_f32_e32 v15, s44, v190
	v_fmac_f32_e32 v16, s44, v217
	v_fmac_f32_e32 v17, s44, v191
	v_mov_b32_dpp v220, v14 quad_perm:[1,0,3,2] row_mask:0xf bank_mask:0xf
	v_mov_b32_dpp v221, v15 quad_perm:[1,0,3,2] row_mask:0xf bank_mask:0xf
	v_mov_b32_dpp v222, v16 quad_perm:[1,0,3,2] row_mask:0xf bank_mask:0xf
	v_mov_b32_dpp v223, v17 quad_perm:[1,0,3,2] row_mask:0xf bank_mask:0xf
	v_mov_b32_dpp v224, v46 quad_perm:[1,0,3,2] row_mask:0xf bank_mask:0xf
	v_mov_b32_dpp v225, v47 quad_perm:[1,0,3,2] row_mask:0xf bank_mask:0xf
	v_mov_b32_dpp v226, v48 quad_perm:[1,0,3,2] row_mask:0xf bank_mask:0xf
	v_mov_b32_dpp v227, v49 quad_perm:[1,0,3,2] row_mask:0xf bank_mask:0xf
	v_cndmask_b32_e32 v14, v224, v14, vcc
	v_cndmask_b32_e32 v15, v225, v15, vcc
	v_cndmask_b32_e32 v16, v226, v16, vcc
	v_cndmask_b32_e32 v17, v227, v17, vcc
	v_cndmask_b32_e32 v46, v46, v220, vcc
	v_cndmask_b32_e32 v47, v47, v221, vcc
	v_cndmask_b32_e32 v48, v48, v222, vcc
	v_cndmask_b32_e32 v49, v49, v223, vcc
	global_store_dwordx4 v[140:141], v[46:49], off offset:128
	global_store_dwordx4 v[142:143], v[14:17], off offset:128
	v_lshl_add_u64 v[140:141], v[140:141], 0, s[10:11]
	v_lshl_add_u64 v[142:143], v[142:143], 0, s[10:11]
	s_waitcnt vmcnt(25)
; DEVI float blo(unsigned u) { return __uint_as_float(u << 16); }
; DEVI float bhi(unsigned u) { return __uint_as_float(u & 0xffff0000u); }
;     ...
;         if (EPI == EPI_RESID || EPI == EPI_RESID_ATOMIC) {
;           f32x4 x = a;
;           if (EPI == EPI_RESID || kpart == 0) {
;             const u32x2 xr = *(const u32x2*)((const u16*)(p.ws + WS_XB) + (size_t)row * 1024 + col);
;             x[0] += ALPHA * blo(xr[0]); x[1] += ALPHA * bhi(xr[0]); x[2] += ALPHA * blo(xr[1]); x[3] += ALPHA * bhi(xr[1]);
;           }
;           if (EPI == EPI_RESID) *(f32x4*)((float*)(p.ws + WS_XF) + (size_t)row * 1024 + col) = x;
;           else *(f32x4*)((float*)(p.ws + WS_SLAB) + ((size_t)kpart * 512 + (row - T_P)) * 1024 + col) = x;
	v_permlane16_swap_b32_e32 v192, v194
	v_permlane16_swap_b32_e32 v193, v195
	v_lshlrev_b32_e32 v216, 16, v192
	v_and_b32_e32 v192, 0xffff0000, v192
	v_lshlrev_b32_e32 v217, 16, v193
	v_and_b32_e32 v193, 0xffff0000, v193
	v_fmac_f32_e32 v106, s44, v216
	v_fmac_f32_e32 v107, s44, v192
	v_fmac_f32_e32 v108, s44, v217
	v_fmac_f32_e32 v109, s44, v193
	v_lshlrev_b32_e32 v216, 16, v194
	v_and_b32_e32 v194, 0xffff0000, v194
	v_lshlrev_b32_e32 v217, 16, v195
	v_and_b32_e32 v195, 0xffff0000, v195
	v_fmac_f32_e32 v74, s44, v216
	v_fmac_f32_e32 v75, s44, v194
	v_fmac_f32_e32 v76, s44, v217
	v_fmac_f32_e32 v77, s44, v195
	v_mov_b32_dpp v220, v74 quad_perm:[1,0,3,2] row_mask:0xf bank_mask:0xf
	v_mov_b32_dpp v221, v75 quad_perm:[1,0,3,2] row_mask:0xf bank_mask:0xf
	v_mov_b32_dpp v222, v76 quad_perm:[1,0,3,2] row_mask:0xf bank_mask:0xf
	v_mov_b32_dpp v223, v77 quad_perm:[1,0,3,2] row_mask:0xf bank_mask:0xf
	v_mov_b32_dpp v224, v106 quad_perm:[1,0,3,2] row_mask:0xf bank_mask:0xf
	v_mov_b32_dpp v225, v107 quad_perm:[1,0,3,2] row_mask:0xf bank_mask:0xf
	v_mov_b32_dpp v226, v108 quad_perm:[1,0,3,2] row_mask:0xf bank_mask:0xf
	v_mov_b32_dpp v227, v109 quad_perm:[1,0,3,2] row_mask:0xf bank_mask:0xf
	v_cndmask_b32_e32 v74, v224, v74, vcc
	v_cndmask_b32_e32 v75, v225, v75, vcc
	v_cndmask_b32_e32 v76, v226, v76, vcc
	v_cndmask_b32_e32 v77, v227, v77, vcc
	v_cndmask_b32_e32 v106, v106, v220, vcc
	v_cndmask_b32_e32 v107, v107, v221, vcc
	v_cndmask_b32_e32 v108, v108, v222, vcc
	v_cndmask_b32_e32 v109, v109, v223, vcc
	global_store_dwordx4 v[140:141], v[106:109], off
	global_store_dwordx4 v[142:143], v[74:77], off
	s_waitcnt vmcnt(26)
	v_permlane16_swap_b32_e32 v196, v198
	v_permlane16_swap_b32_e32 v197, v199
	v_lshlrev_b32_e32 v216, 16, v196
	v_and_b32_e32 v196, 0xffff0000, v196
	v_lshlrev_b32_e32 v217, 16, v197
	v_and_b32_e32 v197, 0xffff0000, v197
	v_fmac_f32_e32 v42, s44, v216
	v_fmac_f32_e32 v43, s44, v196
	v_fmac_f32_e32 v44, s44, v217
	v_fmac_f32_e32 v45, s44, v197
	v_lshlrev_b32_e32 v216, 16, v198
	v_and_b32_e32 v198, 0xffff0000, v198
	v_lshlrev_b32_e32 v217, 16, v199
	v_and_b32_e32 v199, 0xffff0000, v199
	v_fmac_f32_e32 v10, s44, v216
	v_fmac_f32_e32 v11, s44, v198
	v_fmac_f32_e32 v12, s44, v217
	v_fmac_f32_e32 v13, s44, v199
	v_mov_b32_dpp v220, v10 quad_perm:[1,0,3,2] row_mask:0xf bank_mask:0xf
	v_mov_b32_dpp v221, v11 quad_perm:[1,0,3,2] row_mask:0xf bank_mask:0xf
	v_mov_b32_dpp v222, v12 quad_perm:[1,0,3,2] row_mask:0xf bank_mask:0xf
	v_mov_b32_dpp v223, v13 quad_perm:[1,0,3,2] row_mask:0xf bank_mask:0xf
	v_mov_b32_dpp v224, v42 quad_perm:[1,0,3,2] row_mask:0xf bank_mask:0xf
	v_mov_b32_dpp v225, v43 quad_perm:[1,0,3,2] row_mask:0xf bank_mask:0xf
	v_mov_b32_dpp v226, v44 quad_perm:[1,0,3,2] row_mask:0xf bank_mask:0xf
	v_mov_b32_dpp v227, v45 quad_perm:[1,0,3,2] row_mask:0xf bank_mask:0xf
	v_cndmask_b32_e32 v10, v224, v10, vcc
	v_cndmask_b32_e32 v11, v225, v11, vcc
	v_cndmask_b32_e32 v12, v226, v12, vcc
	v_cndmask_b32_e32 v13, v227, v13, vcc
	v_cndmask_b32_e32 v42, v42, v220, vcc
	v_cndmask_b32_e32 v43, v43, v221, vcc
	v_cndmask_b32_e32 v44, v44, v222, vcc
	v_cndmask_b32_e32 v45, v45, v223, vcc
	global_store_dwordx4 v[140:141], v[42:45], off offset:128
	global_store_dwordx4 v[142:143], v[10:13], off offset:128
	v_lshl_add_u64 v[140:141], v[140:141], 0, s[10:11]
	v_lshl_add_u64 v[142:143], v[142:143], 0, s[10:11]
	s_waitcnt vmcnt(27)
	v_permlane16_swap_b32_e32 v200, v202
	v_permlane16_swap_b32_e32 v201, v203
	v_lshlrev_b32_e32 v216, 16, v200
	v_and_b32_e32 v200, 0xffff0000, v200
	v_lshlrev_b32_e32 v217, 16, v201
	v_and_b32_e32 v201, 0xffff0000, v201
	v_fmac_f32_e32 v102, s44, v216
	v_fmac_f32_e32 v103, s44, v200
	v_fmac_f32_e32 v104, s44, v217
	v_fmac_f32_e32 v105, s44, v201
	v_lshlrev_b32_e32 v216, 16, v202
	v_and_b32_e32 v202, 0xffff0000, v202
	v_lshlrev_b32_e32 v217, 16, v203
	v_and_b32_e32 v203, 0xffff0000, v203
	v_fmac_f32_e32 v70, s44, v216
	v_fmac_f32_e32 v71, s44, v202
	v_fmac_f32_e32 v72, s44, v217
	v_fmac_f32_e32 v73, s44, v203
	v_mov_b32_dpp v220, v70 quad_perm:[1,0,3,2] row_mask:0xf bank_mask:0xf
	v_mov_b32_dpp v221, v71 quad_perm:[1,0,3,2] row_mask:0xf bank_mask:0xf
	v_mov_b32_dpp v222, v72 quad_perm:[1,0,3,2] row_mask:0xf bank_mask:0xf
	v_mov_b32_dpp v223, v73 quad_perm:[1,0,3,2] row_mask:0xf bank_mask:0xf
	v_mov_b32_dpp v224, v102 quad_perm:[1,0,3,2] row_mask:0xf bank_mask:0xf
	v_mov_b32_dpp v225, v103 quad_perm:[1,0,3,2] row_mask:0xf bank_mask:0xf
	v_mov_b32_dpp v226, v104 quad_perm:[1,0,3,2] row_mask:0xf bank_mask:0xf
	v_mov_b32_dpp v227, v105 quad_perm:[1,0,3,2] row_mask:0xf bank_mask:0xf
	v_cndmask_b32_e32 v70, v224, v70, vcc
	v_cndmask_b32_e32 v71, v225, v71, vcc
	v_cndmask_b32_e32 v72, v226, v72, vcc
	v_cndmask_b32_e32 v73, v227, v73, vcc
	v_cndmask_b32_e32 v102, v102, v220, vcc
	v_cndmask_b32_e32 v103, v103, v221, vcc
	v_cndmask_b32_e32 v104, v104, v222, vcc
	v_cndmask_b32_e32 v105, v105, v223, vcc
	global_store_dwordx4 v[140:141], v[102:105], off
	global_store_dwordx4 v[142:143], v[70:73], off
	s_waitcnt vmcnt(28)
; DEVI float blo(unsigned u) { return __uint_as_float(u << 16); }
; DEVI float bhi(unsigned u) { return __uint_as_float(u & 0xffff0000u); }
; DEVI int xcd_first_tile() { return (blockIdx.x & 7) * (gridDim.x >> 3) + (blockIdx.x >> 3); }
;     ...
;         if (EPI == EPI_RESID || EPI == EPI_RESID_ATOMIC) {
;           f32x4 x = a;
;           if (EPI == EPI_RESID || kpart == 0) {
;             const u32x2 xr = *(const u32x2*)((const u16*)(p.ws + WS_XB) + (size_t)row * 1024 + col);
;             x[0] += ALPHA * blo(xr[0]); x[1] += ALPHA * bhi(xr[0]); x[2] += ALPHA * blo(xr[1]); x[3] += ALPHA * bhi(xr[1]);
;           }
;           if (EPI == EPI_RESID) *(f32x4*)((float*)(p.ws + WS_XF) + (size_t)row * 1024 + col) = x;
;           else *(f32x4*)((float*)(p.ws + WS_SLAB) + ((size_t)kpart * 512 + (row - T_P)) * 1024 + col) = x;
; DEVI void run_phase(const Params& p, int ph, char* smem) {
;     ...
;       for (int t = xcd_first_tile(); t < 512 + 16 * 2; t += xcd_tile_step()) {
;         if (t < 512) {
;           int mt_, nt_; tile_coords(t, 64, 8, mt_, nt_);
;           gemm_tile256<EPI_RESID>(p, ox, 256, Bt, 256, mt_ * 256, nt_ * 128, nullptr, 0, smem);
;         } else {
;           const int u_ = t - 512, tl_ = u_ / 2, q_ = u_ - tl_ * 2;
;           gemm_tile256<EPI_RESID_ATOMIC>(p, ox, 256, Bt, 256, (64 + (tl_ & 1)) * 256, (tl_ >> 1) * 128, nullptr, 0, smem, q_ * 128, 4, q_);
;         }
	v_permlane16_swap_b32_e32 v204, v206
	v_permlane16_swap_b32_e32 v205, v207
	v_lshlrev_b32_e32 v216, 16, v204
	v_and_b32_e32 v204, 0xffff0000, v204
	v_lshlrev_b32_e32 v217, 16, v205
	v_and_b32_e32 v205, 0xffff0000, v205
	v_fmac_f32_e32 v38, s44, v216
	v_fmac_f32_e32 v39, s44, v204
	v_fmac_f32_e32 v40, s44, v217
	v_fmac_f32_e32 v41, s44, v205
	v_lshlrev_b32_e32 v216, 16, v206
	v_and_b32_e32 v206, 0xffff0000, v206
	v_lshlrev_b32_e32 v217, 16, v207
	v_and_b32_e32 v207, 0xffff0000, v207
	v_fmac_f32_e32 v6, s44, v216
	v_fmac_f32_e32 v7, s44, v206
	v_fmac_f32_e32 v8, s44, v217
	v_fmac_f32_e32 v9, s44, v207
	v_mov_b32_dpp v220, v6 quad_perm:[1,0,3,2] row_mask:0xf bank_mask:0xf
	v_mov_b32_dpp v221, v7 quad_perm:[1,0,3,2] row_mask:0xf bank_mask:0xf
	v_mov_b32_dpp v222, v8 quad_perm:[1,0,3,2] row_mask:0xf bank_mask:0xf
	v_mov_b32_dpp v223, v9 quad_perm:[1,0,3,2] row_mask:0xf bank_mask:0xf
	v_mov_b32_dpp v224, v38 quad_perm:[1,0,3,2] row_mask:0xf bank_mask:0xf
	v_mov_b32_dpp v225, v39 quad_perm:[1,0,3,2] row_mask:0xf bank_mask:0xf
	v_mov_b32_dpp v226, v40 quad_perm:[1,0,3,2] row_mask:0xf bank_mask:0xf
	v_mov_b32_dpp v227, v41 quad_perm:[1,0,3,2] row_mask:0xf bank_mask:0xf
	v_cndmask_b32_e32 v6, v224, v6, vcc
	v_cndmask_b32_e32 v7, v225, v7, vcc
	v_cndmask_b32_e32 v8, v226, v8, vcc
	v_cndmask_b32_e32 v9, v227, v9, vcc
	v_cndmask_b32_e32 v38, v38, v220, vcc
	v_cndmask_b32_e32 v39, v39, v221, vcc
	v_cndmask_b32_e32 v40, v40, v222, vcc
	v_cndmask_b32_e32 v41, v41, v223, vcc
	global_store_dwordx4 v[140:141], v[38:41], off offset:128
	global_store_dwordx4 v[142:143], v[6:9], off offset:128
	v_lshl_add_u64 v[140:141], v[140:141], 0, s[10:11]
	v_lshl_add_u64 v[142:143], v[142:143], 0, s[10:11]
	s_waitcnt vmcnt(29)
	v_permlane16_swap_b32_e32 v208, v210
	v_permlane16_swap_b32_e32 v209, v211
	v_lshlrev_b32_e32 v216, 16, v208
	v_and_b32_e32 v208, 0xffff0000, v208
	v_lshlrev_b32_e32 v217, 16, v209
	v_and_b32_e32 v209, 0xffff0000, v209
	v_fmac_f32_e32 v98, s44, v216
	v_fmac_f32_e32 v99, s44, v208
	v_fmac_f32_e32 v100, s44, v217
	v_fmac_f32_e32 v101, s44, v209
	v_lshlrev_b32_e32 v216, 16, v210
	v_and_b32_e32 v210, 0xffff0000, v210
	v_lshlrev_b32_e32 v217, 16, v211
	v_and_b32_e32 v211, 0xffff0000, v211
	v_fmac_f32_e32 v66, s44, v216
	v_fmac_f32_e32 v67, s44, v210
	v_fmac_f32_e32 v68, s44, v217
	v_fmac_f32_e32 v69, s44, v211
	v_mov_b32_dpp v220, v66 quad_perm:[1,0,3,2] row_mask:0xf bank_mask:0xf
	v_mov_b32_dpp v221, v67 quad_perm:[1,0,3,2] row_mask:0xf bank_mask:0xf
	v_mov_b32_dpp v222, v68 quad_perm:[1,0,3,2] row_mask:0xf bank_mask:0xf
	v_mov_b32_dpp v223, v69 quad_perm:[1,0,3,2] row_mask:0xf bank_mask:0xf
	v_mov_b32_dpp v224, v98 quad_perm:[1,0,3,2] row_mask:0xf bank_mask:0xf
	v_mov_b32_dpp v225, v99 quad_perm:[1,0,3,2] row_mask:0xf bank_mask:0xf
	v_mov_b32_dpp v226, v100 quad_perm:[1,0,3,2] row_mask:0xf bank_mask:0xf
	v_mov_b32_dpp v227, v101 quad_perm:[1,0,3,2] row_mask:0xf bank_mask:0xf
	v_cndmask_b32_e32 v66, v224, v66, vcc
	v_cndmask_b32_e32 v67, v225, v67, vcc
	v_cndmask_b32_e32 v68, v226, v68, vcc
	v_cndmask_b32_e32 v69, v227, v69, vcc
	v_cndmask_b32_e32 v98, v98, v220, vcc
	v_cndmask_b32_e32 v99, v99, v221, vcc
	v_cndmask_b32_e32 v100, v100, v222, vcc
	v_cndmask_b32_e32 v101, v101, v223, vcc
	global_store_dwordx4 v[140:141], v[98:101], off
	global_store_dwordx4 v[142:143], v[66:69], off
	s_waitcnt vmcnt(30)
	v_permlane16_swap_b32_e32 v212, v214
	v_permlane16_swap_b32_e32 v213, v215
	v_lshlrev_b32_e32 v216, 16, v212
	v_and_b32_e32 v212, 0xffff0000, v212
	v_lshlrev_b32_e32 v217, 16, v213
	v_and_b32_e32 v213, 0xffff0000, v213
	v_fmac_f32_e32 v34, s44, v216
	v_fmac_f32_e32 v35, s44, v212
	v_fmac_f32_e32 v36, s44, v217
	v_fmac_f32_e32 v37, s44, v213
	v_lshlrev_b32_e32 v216, 16, v214
	v_and_b32_e32 v214, 0xffff0000, v214
	v_lshlrev_b32_e32 v217, 16, v215
	v_and_b32_e32 v215, 0xffff0000, v215
	v_fmac_f32_e32 v2, s44, v216
	v_fmac_f32_e32 v3, s44, v214
	v_fmac_f32_e32 v4, s44, v217
	v_fmac_f32_e32 v5, s44, v215
	v_mov_b32_dpp v220, v2 quad_perm:[1,0,3,2] row_mask:0xf bank_mask:0xf
	v_mov_b32_dpp v221, v3 quad_perm:[1,0,3,2] row_mask:0xf bank_mask:0xf
	v_mov_b32_dpp v222, v4 quad_perm:[1,0,3,2] row_mask:0xf bank_mask:0xf
	v_mov_b32_dpp v223, v5 quad_perm:[1,0,3,2] row_mask:0xf bank_mask:0xf
	v_mov_b32_dpp v224, v34 quad_perm:[1,0,3,2] row_mask:0xf bank_mask:0xf
	v_mov_b32_dpp v225, v35 quad_perm:[1,0,3,2] row_mask:0xf bank_mask:0xf
	v_mov_b32_dpp v226, v36 quad_perm:[1,0,3,2] row_mask:0xf bank_mask:0xf
	v_mov_b32_dpp v227, v37 quad_perm:[1,0,3,2] row_mask:0xf bank_mask:0xf
	v_cndmask_b32_e32 v2, v224, v2, vcc
	v_cndmask_b32_e32 v3, v225, v3, vcc
	v_cndmask_b32_e32 v4, v226, v4, vcc
	v_cndmask_b32_e32 v5, v227, v5, vcc
	v_cndmask_b32_e32 v34, v34, v220, vcc
	v_cndmask_b32_e32 v35, v35, v221, vcc
	v_cndmask_b32_e32 v36, v36, v222, vcc
	v_cndmask_b32_e32 v37, v37, v223, vcc
	global_store_dwordx4 v[140:141], v[34:37], off offset:128
	global_store_dwordx4 v[142:143], v[2:5], off offset:128
	v_readlane_b32 s39, v250, 7
	s_cmpk_lg_u32 s39, 0x200
	s_cbranch_scc1 .LBB0_146
	v_readlane_b32 s40, v250, 0
	s_lshr_b32 s41, s40, 3
	s_and_b32 s40, s40, 7
	s_mul_i32 s40, s40, 4
	s_add_i32 s40, s40, s41
	s_cmp_lt_u32 s41, 4
	s_movk_i32 s38, 0x4000
	s_branch .LBB0_146

; #define LAS __attribute__((address_space(3)))
;     ...
;   const int lrow = tid >> 2, lpc = tid & 3;
;   const int lch = lpc ^ ((0x78 >> (((lrow >> 2) & 3) * 2)) & 3);
;   const u16* ga = A + (size_t)(m0 + lrow) * lda + kbeg + lch * 8;
;   const u16* gb = Bt + (size_t)(n0 + lrow) * K + kbeg + lch * 8;
;   const size_t ga1 = (size_t)64 * lda, gb1 = (size_t)64 * K;
;   const unsigned lds0 = (unsigned)(uintptr_t)(LAS char*)smem + (unsigned)__builtin_amdgcn_readfirstlane(wid) * 1024u;
;     ...
;   __syncthreads();
;   G2_STAGE(0); G2_STAGE(1);
; DEVI void run_phase(const Params& p, int ph, char* smem) {
;     ...
;         } else {
;           const int u_ = t - 512, tl_ = u_ / 8, q_ = u_ - tl_ * 8;
;           gemm_tile256<EPI_RESID_ATOMIC>(p, mix, 1024, Bt, 1024, (64 + (tl_ & 1)) * 256, (tl_ >> 1) * 128, nullptr, 0, smem, q_ * 128, 4, q_);
.LBB0_758:
	s_cmpk_gt_i32 s39, 0x1ff
	s_mov_b64 s[2:3], -1
	s_cbranch_scc0 .LBB0_812
	s_setprio 2
	s_sub_i32 s43, s39, 512
	s_lshr_b32 s42, s43, 3
	s_and_b32 s98, s43, 7
	s_lshr_b32 s15, s42, 1
	s_and_b32 s42, s42, 1
	s_add_i32 s42, s42, 64
	v_readlane_b32 s2, v250, 5
	v_readlane_b32 s3, v250, 6
	v_readlane_b32 s43, v254, 62
	s_mul_i32 s1, s42, 0x80000
	s_add_u32 s4, s2, s1
	s_addc_u32 s5, s3, 0
	s_add_u32 s4, s4, 0xb580000
	s_addc_u32 s5, s5, 0
	s_mul_i32 s1, s43, 0x200000
	s_mul_i32 s14, s15, 0x40000
	s_add_i32 s1, s1, s14
	s_add_u32 s10, s2, s1
	s_addc_u32 s11, s3, 0
	s_add_u32 s10, s10, 0x15e00000
	s_addc_u32 s11, s11, 0
	s_mul_i32 s1, s98, 256
	s_add_u32 s4, s4, s1
	s_addc_u32 s5, s5, 0
	s_mul_i32 s1, s98, 512
	s_add_u32 s10, s10, s1
	s_addc_u32 s11, s11, 0
	s_movk_i32 s0, 0x78
	v_lshrrev_b32_e32 v0, 2, v145
	v_and_b32_e32 v131, 3, v145
	v_bfe_u32 v136, v145, 4, 2
	v_lshlrev_b32_e32 v136, 1, v136
	v_lshrrev_b32_e64 v136, v136, s0
	v_and_b32_e32 v136, 3, v136
	v_xor_b32_e32 v131, v131, v136
	v_lshlrev_b32_e32 v131, 4, v131
	s_movk_i32 s14, 0x800
	v_mad_u32_u24 v0, v0, s14, v131
	v_bfe_u32 v137, v145, 2, 1
	s_movk_i32 s14, 0x7c0
	v_mul_u32_u24_e32 v136, s14, v137
	v_sub_u32_e32 v136, v0, v136
	v_mov_b32_e32 v137, 0
	v_lshl_add_u64 v[134:135], s[10:11], 0, v[136:137]
	v_bfe_u32 v137, v145, 2, 1
	s_mov_b32 s12, 64
	s_mov_b32 s13, 0
	v_lshl_add_u64 v[132:133], s[4:5], 0, v[0:1]
	v_bfe_u32 v136, v145, 2, 2
	v_lshlrev_b32_e32 v136, 1, v136
	v_lshrrev_b32_e64 v136, v136, s0
	v_and_b32_e32 v136, 3, v136
	v_bfe_u32 v137, v145, 4, 2
	v_xor_b32_e32 v136, v136, v137
	v_lshlrev_b32_e32 v136, 4, v136
	v_and_b32_e32 v131, 15, v145
	v_lshl_or_b32 v136, v131, 6, v136
	v_bfe_u32 v137, v145, 6, 1
	v_lshl_or_b32 v137, v137, 12, v136
	v_lshrrev_b32_e32 v0, 7, v145
	v_lshl_or_b32 v136, v0, 13, v136
	v_and_b32_e32 v140, 1, v131
	v_lshl_or_b32 v131, v0, 7, v131
	v_bfe_u32 v0, v145, 4, 2
	v_lshlrev_b32_e32 v0, 3, v0
	v_bfe_u32 v141, v145, 6, 1
	s_lshl_b32 s1, s42, 19
	s_lshl_b32 s14, s15, 8
	s_add_i32 s1, s1, s14
	s_add_u32 s4, s2, s1
	s_addc_u32 s5, s3, 0
	s_add_u32 s4, s4, 0x4200000
	s_addc_u32 s5, s5, 0
	v_lshlrev_b32_e32 v138, 11, v131
	v_lshl_add_u32 v138, v141, 7, v138
	v_bfe_u32 v139, v145, 4, 1
	v_lshl_add_u32 v138, v139, 5, v138
	v_bfe_u32 v139, v145, 5, 1
	v_lshl_add_u32 v138, v139, 4, v138
	v_mov_b32_e32 v139, 0
	v_lshl_add_u64 v[138:139], s[4:5], 0, v[138:139]
	s_and_b32 s1, s42, 1
	s_lshl_b32 s1, s1, 20
	s_lshl_b32 s14, s98, 21
	s_add_i32 s1, s1, s14
	s_lshl_b32 s14, s15, 9
	s_add_i32 s1, s1, s14
	s_add_u32 s10, s2, s1
	s_addc_u32 s11, s3, 0
	s_add_u32 s10, s10, 0x1dcc0000
	s_addc_u32 s11, s11, 0
	v_lshlrev_b32_e32 v140, 12, v131
	v_lshl_add_u32 v140, v141, 8, v140
	v_lshl_add_u32 v140, v0, 1, v140
	v_mov_b32_e32 v141, 0
	v_lshl_add_u64 v[140:141], s[10:11], 0, v[140:141]
	s_mov_b32 s2, 0x20000
	s_mov_b32 s3, 0
	v_lshrrev_b32_e32 v0, 6, v145
	v_lshlrev_b32_e32 v0, 10, v0
	s_nop 0
	v_readfirstlane_b32 s43, v0
	s_mov_b32 s40, m0
	s_mov_b32 s4, 128
	s_mov_b32 s5, 0
	s_barrier
	s_add_i32 s15, s43, 0x0
	s_mov_b32 m0, s15
	v_lshl_add_u64 v[142:143], v[132:133], 0, s[2:3]
	global_load_lds_dwordx4 v[132:133], off
	s_add_i32 m0, m0, 0x1000
	s_nop 0
	global_load_lds_dwordx4 v[142:143], off
	v_lshl_add_u64 v[142:143], v[142:143], 0, s[2:3]
	s_add_i32 m0, m0, 0x1000
	s_nop 0
	global_load_lds_dwordx4 v[142:143], off
	v_lshl_add_u64 v[142:143], v[142:143], 0, s[2:3]
	s_add_i32 m0, m0, 0x1000
	s_nop 0
	global_load_lds_dwordx4 v[142:143], off
	s_add_i32 m0, m0, 0x1000
	v_lshl_add_u64 v[142:143], v[134:135], 0, s[2:3]
	s_nop 0
	global_load_lds_dwordx4 v[134:135], off
	s_add_i32 m0, m0, 0x1000
	v_lshl_add_u64 v[132:133], v[132:133], 0, s[12:13]
	s_nop 0
	global_load_lds_dwordx4 v[142:143], off
	v_lshl_add_u64 v[134:135], v[134:135], 0, s[4:5]
	s_nop 0
	s_add_i32 s15, s43, 0x6000
	s_mov_b32 m0, s15
	v_lshl_add_u64 v[142:143], v[132:133], 0, s[2:3]
	global_load_lds_dwordx4 v[132:133], off
	s_add_i32 m0, m0, 0x1000
	s_nop 0
	global_load_lds_dwordx4 v[142:143], off
	v_lshl_add_u64 v[142:143], v[142:143], 0, s[2:3]
	s_add_i32 m0, m0, 0x1000
	s_nop 0
	global_load_lds_dwordx4 v[142:143], off
	v_lshl_add_u64 v[142:143], v[142:143], 0, s[2:3]
	s_add_i32 m0, m0, 0x1000
	s_nop 0
	global_load_lds_dwordx4 v[142:143], off
	s_add_i32 m0, m0, 0x1000
	v_lshl_add_u64 v[142:143], v[134:135], 0, s[2:3]
	s_nop 0
	global_load_lds_dwordx4 v[134:135], off
	s_add_i32 m0, m0, 0x1000
	v_lshl_add_u64 v[132:133], v[132:133], 0, s[12:13]
	s_nop 0
	global_load_lds_dwordx4 v[142:143], off
	v_lshl_add_u64 v[134:135], v[134:135], 0, s[4:5]
	s_nop 0
	s_add_i32 s15, s43, 0xc000
	s_mov_b32 m0, s15
	v_lshl_add_u64 v[142:143], v[132:133], 0, s[2:3]
	global_load_lds_dwordx4 v[132:133], off
	s_add_i32 m0, m0, 0x1000
	s_nop 0
	global_load_lds_dwordx4 v[142:143], off
	v_lshl_add_u64 v[142:143], v[142:143], 0, s[2:3]
	s_add_i32 m0, m0, 0x1000
	s_nop 0
	global_load_lds_dwordx4 v[142:143], off
	v_lshl_add_u64 v[142:143], v[142:143], 0, s[2:3]
	s_add_i32 m0, m0, 0x1000
	s_nop 0
	global_load_lds_dwordx4 v[142:143], off
	s_add_i32 m0, m0, 0x1000
	v_lshl_add_u64 v[142:143], v[134:135], 0, s[2:3]
	s_nop 0
	global_load_lds_dwordx4 v[134:135], off
	s_add_i32 m0, m0, 0x1000
	v_lshl_add_u64 v[132:133], v[132:133], 0, s[12:13]
	s_nop 0
	global_load_lds_dwordx4 v[142:143], off
	v_lshl_add_u64 v[134:135], v[134:135], 0, s[4:5]
	s_nop 0
	v_mov_b32_e32 v2, 0
	v_mov_b32_e32 v3, 0
	v_mov_b32_e32 v4, 0
	v_mov_b32_e32 v5, 0
	v_mov_b32_e32 v6, 0
	v_mov_b32_e32 v7, 0
	v_mov_b32_e32 v8, 0
	v_mov_b32_e32 v9, 0
	v_mov_b32_e32 v10, 0
	v_mov_b32_e32 v11, 0
	v_mov_b32_e32 v12, 0
	v_mov_b32_e32 v13, 0
	v_mov_b32_e32 v14, 0
; #define LAS __attribute__((address_space(3)))
;     ...
;   f32x4 acc[4][8];
; #pragma unroll
;   for (int i = 0; i < 4; i++)
; #pragma unroll
;     for (int j = 0; j < 8; j++) acc[i][j] = (f32x4){0.f, 0.f, 0.f, 0.f};
;   const int nk = (nk_part < 0) ? (K >> 5) : nk_part;
;   const int lrow = tid >> 2, lpc = tid & 3;
;   const int lch = lpc ^ ((0x78 >> (((lrow >> 2) & 3) * 2)) & 3);
;   const u16* ga = A + (size_t)(m0 + lrow) * lda + kbeg + lch * 8;
;   const u16* gb = Bt + (size_t)(n0 + lrow) * K + kbeg + lch * 8;
;   const size_t ga1 = (size_t)64 * lda, gb1 = (size_t)64 * K;
;   const unsigned lds0 = (unsigned)(uintptr_t)(LAS char*)smem + (unsigned)__builtin_amdgcn_readfirstlane(wid) * 1024u;
;     ...
;   __syncthreads();
;   G2_STAGE(0); G2_STAGE(1);
;   const int fsw = (0x78 >> (((r16 >> 2) & 3) * 2)) & 3;
;   const int aoff = (wm * 128 + r16) * 64 + ((quad ^ fsw) << 4);
;   const int boff = 16384 + (wn * 64 + r16) * 64 + ((quad ^ fsw) << 4);
;   for (int kt = 0; kt < nk; kt++) {
;     if (kt + 1 < nk) asm volatile("s_waitcnt vmcnt(6)" ::: "memory");
;     else asm volatile("s_waitcnt vmcnt(0)" ::: "memory");
;     __builtin_amdgcn_s_barrier();
;     asm volatile("" ::: "memory");
;     if (kt + 2 < nk) G2_STAGE(kt + 2);
;     const char* cS = smem + (kt % 3) * 24576;
;     bf16x8 xa[8], wb[4];
; #pragma unroll
;     for (int f = 0; f < 8; f++) xa[f] = *(const bf16x8*)(cS + aoff + f * 1024);
; #pragma unroll
;     for (int f = 0; f < 4; f++) wb[f] = *(const bf16x8*)(cS + boff + f * 1024);
	v_mov_b32_e32 v15, 0
	v_mov_b32_e32 v16, 0
	v_mov_b32_e32 v17, 0
	v_mov_b32_e32 v18, 0
	v_mov_b32_e32 v19, 0
	v_mov_b32_e32 v20, 0
	v_mov_b32_e32 v21, 0
	v_mov_b32_e32 v22, 0
	v_mov_b32_e32 v23, 0
	v_mov_b32_e32 v24, 0
	v_mov_b32_e32 v25, 0
	v_mov_b32_e32 v26, 0
	v_mov_b32_e32 v27, 0
	v_mov_b32_e32 v28, 0
	v_mov_b32_e32 v29, 0
	v_mov_b32_e32 v30, 0
	v_mov_b32_e32 v31, 0
	v_mov_b32_e32 v32, 0
	v_mov_b32_e32 v33, 0
	v_mov_b32_e32 v34, 0
	v_mov_b32_e32 v35, 0
	v_mov_b32_e32 v36, 0
	v_mov_b32_e32 v37, 0
	v_mov_b32_e32 v38, 0
	v_mov_b32_e32 v39, 0
	v_mov_b32_e32 v40, 0
	v_mov_b32_e32 v41, 0
	v_mov_b32_e32 v42, 0
	v_mov_b32_e32 v43, 0
	v_mov_b32_e32 v44, 0
	v_mov_b32_e32 v45, 0
	v_mov_b32_e32 v46, 0
	v_mov_b32_e32 v47, 0
	v_mov_b32_e32 v48, 0
	v_mov_b32_e32 v49, 0
	v_mov_b32_e32 v50, 0
	v_mov_b32_e32 v51, 0
	v_mov_b32_e32 v52, 0
	v_mov_b32_e32 v53, 0
	v_mov_b32_e32 v54, 0
	v_mov_b32_e32 v55, 0
	v_mov_b32_e32 v56, 0
	v_mov_b32_e32 v57, 0
	v_mov_b32_e32 v58, 0
	v_mov_b32_e32 v59, 0
	v_mov_b32_e32 v60, 0
	v_mov_b32_e32 v61, 0
	v_mov_b32_e32 v62, 0
	v_mov_b32_e32 v63, 0
	v_mov_b32_e32 v64, 0
	v_mov_b32_e32 v65, 0
	v_mov_b32_e32 v66, 0
	v_mov_b32_e32 v67, 0
	v_mov_b32_e32 v68, 0
	v_mov_b32_e32 v69, 0
	v_mov_b32_e32 v70, 0
	v_mov_b32_e32 v71, 0
	v_mov_b32_e32 v72, 0
	v_mov_b32_e32 v73, 0
	v_mov_b32_e32 v74, 0
	v_mov_b32_e32 v75, 0
	v_mov_b32_e32 v76, 0
	v_mov_b32_e32 v77, 0
	v_mov_b32_e32 v78, 0
	v_mov_b32_e32 v79, 0
	v_mov_b32_e32 v80, 0
	v_mov_b32_e32 v81, 0
	v_mov_b32_e32 v82, 0
	v_mov_b32_e32 v83, 0
	v_mov_b32_e32 v84, 0
	v_mov_b32_e32 v85, 0
	v_mov_b32_e32 v86, 0
	v_mov_b32_e32 v87, 0
	v_mov_b32_e32 v88, 0
	v_mov_b32_e32 v89, 0
	v_mov_b32_e32 v90, 0
	v_mov_b32_e32 v91, 0
	v_mov_b32_e32 v92, 0
	v_mov_b32_e32 v93, 0
	v_mov_b32_e32 v94, 0
	v_mov_b32_e32 v95, 0
	v_mov_b32_e32 v96, 0
	v_mov_b32_e32 v97, 0
	v_mov_b32_e32 v98, 0
	v_mov_b32_e32 v99, 0
	v_mov_b32_e32 v100, 0
	v_mov_b32_e32 v101, 0
	v_mov_b32_e32 v102, 0
	v_mov_b32_e32 v103, 0
	v_mov_b32_e32 v104, 0
	v_mov_b32_e32 v105, 0
	v_mov_b32_e32 v106, 0
	v_mov_b32_e32 v107, 0
	v_mov_b32_e32 v108, 0
	v_mov_b32_e32 v109, 0
	v_mov_b32_e32 v110, 0
	v_mov_b32_e32 v111, 0
	v_mov_b32_e32 v112, 0
	v_mov_b32_e32 v113, 0
	v_mov_b32_e32 v114, 0
	v_mov_b32_e32 v115, 0
	v_mov_b32_e32 v116, 0
	v_mov_b32_e32 v117, 0
	v_mov_b32_e32 v118, 0
	v_mov_b32_e32 v119, 0
	v_mov_b32_e32 v120, 0
	v_mov_b32_e32 v121, 0
	v_mov_b32_e32 v122, 0
	v_mov_b32_e32 v123, 0
	v_mov_b32_e32 v124, 0
	v_mov_b32_e32 v125, 0
	v_mov_b32_e32 v126, 0
	v_mov_b32_e32 v127, 0
	v_mov_b32_e32 v128, 0
	v_mov_b32_e32 v129, 0
	s_setprio 0
	s_waitcnt vmcnt(12)
	s_barrier
	ds_read_b128 v[146:149], v136 offset:0
	ds_read_b128 v[152:155], v136 offset:1024
	ds_read_b128 v[156:159], v136 offset:2048
	ds_read_b128 v[162:165], v136 offset:3072
	ds_read_b128 v[166:169], v136 offset:4096
	ds_read_b128 v[170:173], v136 offset:5120
	ds_read_b128 v[176:179], v136 offset:6144
	ds_read_b128 v[180:183], v136 offset:7168
	ds_read_b128 v[184:187], v137 offset:16384
	ds_read_b128 v[188:191], v137 offset:17408
	ds_read_b128 v[192:195], v137 offset:18432
	ds_read_b128 v[196:199], v137 offset:19456
	s_movk_i32 s1, 0x6000
	s_mov_b32 s14, 0
	.p2align 3
	s_waitcnt vmcnt(6) lgkmcnt(0)
	s_barrier
	s_setprio 1
	v_add_u32_e32 v144, s1, v136
	v_mfma_f32_16x16x32_bf16 v[126:129], v[184:187], v[146:149], v[126:129]
	ds_read_b128 v[200:203], v144 offset:0
	v_mfma_f32_16x16x32_bf16 v[122:125], v[184:187], v[152:155], v[122:125]
	ds_read_b128 v[204:207], v144 offset:1024
	v_mfma_f32_16x16x32_bf16 v[118:121], v[184:187], v[156:159], v[118:121]
	ds_read_b128 v[208:211], v144 offset:2048
	v_mfma_f32_16x16x32_bf16 v[114:117], v[184:187], v[162:165], v[114:117]
	ds_read_b128 v[212:215], v144 offset:3072
	v_mfma_f32_16x16x32_bf16 v[110:113], v[184:187], v[166:169], v[110:113]
	ds_read_b128 v[216:219], v144 offset:4096
	v_mfma_f32_16x16x32_bf16 v[106:109], v[184:187], v[170:173], v[106:109]
	ds_read_b128 v[220:223], v144 offset:5120
	v_mfma_f32_16x16x32_bf16 v[102:105], v[184:187], v[176:179], v[102:105]
	ds_read_b128 v[224:227], v144 offset:6144
	v_mfma_f32_16x16x32_bf16 v[98:101], v[184:187], v[180:183], v[98:101]
	ds_read_b128 v[228:231], v144 offset:7168
	v_mfma_f32_16x16x32_bf16 v[94:97], v[188:191], v[146:149], v[94:97]
	v_add_u32_e64 v144, s1, v137
	v_mfma_f32_16x16x32_bf16 v[90:93], v[188:191], v[152:155], v[90:93]
	v_mfma_f32_16x16x32_bf16 v[86:89], v[188:191], v[156:159], v[86:89]
	ds_read_b128 v[232:235], v144 offset:16384
	v_mfma_f32_16x16x32_bf16 v[82:85], v[188:191], v[162:165], v[82:85]
	ds_read_b128 v[236:239], v144 offset:17408
	v_mfma_f32_16x16x32_bf16 v[78:81], v[188:191], v[166:169], v[78:81]
	ds_read_b128 v[240:243], v144 offset:18432
	s_setprio 2
	s_nop 0
	v_mfma_f32_16x16x32_bf16 v[74:77], v[188:191], v[170:173], v[74:77]
	ds_read_b128 v[244:247], v144 offset:19456
	v_mfma_f32_16x16x32_bf16 v[70:73], v[188:191], v[176:179], v[70:73]
	s_add_i32 s15, s43, s14
	s_mov_b32 m0, s15
	v_lshl_add_u64 v[142:143], v[132:133], 0, s[2:3]
	v_mfma_f32_16x16x32_bf16 v[66:69], v[188:191], v[180:183], v[66:69]
	global_load_lds_dwordx4 v[132:133], off
	s_add_i32 m0, m0, 0x1000
	v_mfma_f32_16x16x32_bf16 v[62:65], v[192:195], v[146:149], v[62:65]
	v_mfma_f32_16x16x32_bf16 v[58:61], v[192:195], v[152:155], v[58:61]
	v_mfma_f32_16x16x32_bf16 v[54:57], v[192:195], v[156:159], v[54:57]
	global_load_lds_dwordx4 v[142:143], off
	v_lshl_add_u64 v[142:143], v[142:143], 0, s[2:3]
	s_add_i32 m0, m0, 0x1000
	v_mfma_f32_16x16x32_bf16 v[50:53], v[192:195], v[162:165], v[50:53]
	v_mfma_f32_16x16x32_bf16 v[46:49], v[192:195], v[166:169], v[46:49]
	v_mfma_f32_16x16x32_bf16 v[42:45], v[192:195], v[170:173], v[42:45]
	global_load_lds_dwordx4 v[142:143], off
	v_lshl_add_u64 v[142:143], v[142:143], 0, s[2:3]
	s_add_i32 m0, m0, 0x1000
	v_mfma_f32_16x16x32_bf16 v[38:41], v[192:195], v[176:179], v[38:41]
	v_mfma_f32_16x16x32_bf16 v[34:37], v[192:195], v[180:183], v[34:37]
	s_setprio 0
	s_nop 0
	v_mfma_f32_16x16x32_bf16 v[30:33], v[196:199], v[146:149], v[30:33]
	global_load_lds_dwordx4 v[142:143], off
	s_add_i32 m0, m0, 0x1000
	v_lshl_add_u64 v[142:143], v[134:135], 0, s[2:3]
	v_mfma_f32_16x16x32_bf16 v[26:29], v[196:199], v[152:155], v[26:29]
	v_mfma_f32_16x16x32_bf16 v[22:25], v[196:199], v[156:159], v[22:25]
	v_mfma_f32_16x16x32_bf16 v[18:21], v[196:199], v[162:165], v[18:21]
	global_load_lds_dwordx4 v[134:135], off
	s_add_i32 m0, m0, 0x1000
	v_lshl_add_u64 v[132:133], v[132:133], 0, s[12:13]
	v_mfma_f32_16x16x32_bf16 v[14:17], v[196:199], v[166:169], v[14:17]
	v_mfma_f32_16x16x32_bf16 v[10:13], v[196:199], v[170:173], v[10:13]
	v_mfma_f32_16x16x32_bf16 v[6:9], v[196:199], v[176:179], v[6:9]
	global_load_lds_dwordx4 v[142:143], off
	v_lshl_add_u64 v[134:135], v[134:135], 0, s[4:5]
	v_mfma_f32_16x16x32_bf16 v[2:5], v[196:199], v[180:183], v[2:5]
	s_mov_b32 s14, s1
	s_nop 0
	s_add_i32 s1, s1, 0x6000
	s_cmp_eq_u32 s1, 0x12000
	s_cselect_b32 s1, 0, s1
	s_nop 0
	.p2align 3
	s_waitcnt vmcnt(6) lgkmcnt(0)
	s_barrier
;     ...
;   for (int kt = 0; kt < nk; kt++) {
;     if (kt + 1 < nk) asm volatile("s_waitcnt vmcnt(6)" ::: "memory");
;     else asm volatile("s_waitcnt vmcnt(0)" ::: "memory");
;     __builtin_amdgcn_s_barrier();
;     asm volatile("" ::: "memory");
;     if (kt + 2 < nk) G2_STAGE(kt + 2);
;     const char* cS = smem + (kt % 3) * 24576;
;     bf16x8 xa[8], wb[4];
; #pragma unroll
;     for (int f = 0; f < 8; f++) xa[f] = *(const bf16x8*)(cS + aoff + f * 1024);
; #pragma unroll
;     for (int f = 0; f < 4; f++) wb[f] = *(const bf16x8*)(cS + boff + f * 1024);
; #pragma unroll
;     for (int nf = 0; nf < 4; nf++)
; #pragma unroll
;       for (int mf = 0; mf < 8; mf++)
;         acc[nf][mf] = __builtin_amdgcn_mfma_f32_16x16x32_bf16(wb[nf], xa[mf], acc[nf][mf], 0, 0, 0);
;   }
	s_setprio 1
	v_add_u32_e32 v144, s1, v136
	v_mfma_f32_16x16x32_bf16 v[126:129], v[232:235], v[200:203], v[126:129]
	ds_read_b128 v[146:149], v144 offset:0
	v_mfma_f32_16x16x32_bf16 v[122:125], v[232:235], v[204:207], v[122:125]
	ds_read_b128 v[152:155], v144 offset:1024
	v_mfma_f32_16x16x32_bf16 v[118:121], v[232:235], v[208:211], v[118:121]
	ds_read_b128 v[156:159], v144 offset:2048
	v_mfma_f32_16x16x32_bf16 v[114:117], v[232:235], v[212:215], v[114:117]
	ds_read_b128 v[162:165], v144 offset:3072
	v_mfma_f32_16x16x32_bf16 v[110:113], v[232:235], v[216:219], v[110:113]
	ds_read_b128 v[166:169], v144 offset:4096
	v_mfma_f32_16x16x32_bf16 v[106:109], v[232:235], v[220:223], v[106:109]
	ds_read_b128 v[170:173], v144 offset:5120
	v_mfma_f32_16x16x32_bf16 v[102:105], v[232:235], v[224:227], v[102:105]
	ds_read_b128 v[176:179], v144 offset:6144
	v_mfma_f32_16x16x32_bf16 v[98:101], v[232:235], v[228:231], v[98:101]
	ds_read_b128 v[180:183], v144 offset:7168
	v_mfma_f32_16x16x32_bf16 v[94:97], v[236:239], v[200:203], v[94:97]
	v_add_u32_e64 v144, s1, v137
	v_mfma_f32_16x16x32_bf16 v[90:93], v[236:239], v[204:207], v[90:93]
	v_mfma_f32_16x16x32_bf16 v[86:89], v[236:239], v[208:211], v[86:89]
	ds_read_b128 v[184:187], v144 offset:16384
	v_mfma_f32_16x16x32_bf16 v[82:85], v[236:239], v[212:215], v[82:85]
	ds_read_b128 v[188:191], v144 offset:17408
	v_mfma_f32_16x16x32_bf16 v[78:81], v[236:239], v[216:219], v[78:81]
	ds_read_b128 v[192:195], v144 offset:18432
	v_mfma_f32_16x16x32_bf16 v[74:77], v[236:239], v[220:223], v[74:77]
	ds_read_b128 v[196:199], v144 offset:19456
	v_mfma_f32_16x16x32_bf16 v[70:73], v[236:239], v[224:227], v[70:73]
	v_mfma_f32_16x16x32_bf16 v[66:69], v[236:239], v[228:231], v[66:69]
	v_mfma_f32_16x16x32_bf16 v[62:65], v[240:243], v[200:203], v[62:65]
	v_mfma_f32_16x16x32_bf16 v[58:61], v[240:243], v[204:207], v[58:61]
	v_mfma_f32_16x16x32_bf16 v[54:57], v[240:243], v[208:211], v[54:57]
	v_mfma_f32_16x16x32_bf16 v[50:53], v[240:243], v[212:215], v[50:53]
	v_mfma_f32_16x16x32_bf16 v[46:49], v[240:243], v[216:219], v[46:49]
	v_mfma_f32_16x16x32_bf16 v[42:45], v[240:243], v[220:223], v[42:45]
	v_mfma_f32_16x16x32_bf16 v[38:41], v[240:243], v[224:227], v[38:41]
	v_mfma_f32_16x16x32_bf16 v[34:37], v[240:243], v[228:231], v[34:37]
	s_setprio 0
	s_nop 0
	v_mfma_f32_16x16x32_bf16 v[30:33], v[244:247], v[200:203], v[30:33]
	v_mfma_f32_16x16x32_bf16 v[26:29], v[244:247], v[204:207], v[26:29]
	v_mfma_f32_16x16x32_bf16 v[22:25], v[244:247], v[208:211], v[22:25]
	v_mfma_f32_16x16x32_bf16 v[18:21], v[244:247], v[212:215], v[18:21]
	v_mfma_f32_16x16x32_bf16 v[14:17], v[244:247], v[216:219], v[14:17]
	v_mfma_f32_16x16x32_bf16 v[10:13], v[244:247], v[220:223], v[10:13]
	v_mfma_f32_16x16x32_bf16 v[6:9], v[244:247], v[224:227], v[6:9]
	v_mfma_f32_16x16x32_bf16 v[2:5], v[244:247], v[228:231], v[2:5]
	s_mov_b32 s14, s1
	s_nop 0
	s_add_i32 s1, s1, 0x6000
	s_cmp_eq_u32 s1, 0x12000
	s_cselect_b32 s1, 0, s1
	s_nop 0
	.p2align 3
	s_waitcnt vmcnt(0) lgkmcnt(0)
	s_barrier
	s_setprio 1
	v_add_u32_e32 v144, s1, v136
	v_mfma_f32_16x16x32_bf16 v[126:129], v[184:187], v[146:149], v[126:129]
	ds_read_b128 v[200:203], v144 offset:0
	v_mfma_f32_16x16x32_bf16 v[122:125], v[184:187], v[152:155], v[122:125]
	ds_read_b128 v[204:207], v144 offset:1024
	v_mfma_f32_16x16x32_bf16 v[118:121], v[184:187], v[156:159], v[118:121]
	ds_read_b128 v[208:211], v144 offset:2048
	v_mfma_f32_16x16x32_bf16 v[114:117], v[184:187], v[162:165], v[114:117]
	ds_read_b128 v[212:215], v144 offset:3072
	v_mfma_f32_16x16x32_bf16 v[110:113], v[184:187], v[166:169], v[110:113]
	ds_read_b128 v[216:219], v144 offset:4096
	v_mfma_f32_16x16x32_bf16 v[106:109], v[184:187], v[170:173], v[106:109]
	ds_read_b128 v[220:223], v144 offset:5120
	v_mfma_f32_16x16x32_bf16 v[102:105], v[184:187], v[176:179], v[102:105]
	ds_read_b128 v[224:227], v144 offset:6144
	v_mfma_f32_16x16x32_bf16 v[98:101], v[184:187], v[180:183], v[98:101]
	ds_read_b128 v[228:231], v144 offset:7168
	v_mfma_f32_16x16x32_bf16 v[94:97], v[188:191], v[146:149], v[94:97]
	v_add_u32_e64 v144, s1, v137
	v_mfma_f32_16x16x32_bf16 v[90:93], v[188:191], v[152:155], v[90:93]
	v_mfma_f32_16x16x32_bf16 v[86:89], v[188:191], v[156:159], v[86:89]
	ds_read_b128 v[232:235], v144 offset:16384
	v_mfma_f32_16x16x32_bf16 v[82:85], v[188:191], v[162:165], v[82:85]
	ds_read_b128 v[236:239], v144 offset:17408
	v_mfma_f32_16x16x32_bf16 v[78:81], v[188:191], v[166:169], v[78:81]
	ds_read_b128 v[240:243], v144 offset:18432
	v_mfma_f32_16x16x32_bf16 v[74:77], v[188:191], v[170:173], v[74:77]
	ds_read_b128 v[244:247], v144 offset:19456
	v_mfma_f32_16x16x32_bf16 v[70:73], v[188:191], v[176:179], v[70:73]
	v_mfma_f32_16x16x32_bf16 v[66:69], v[188:191], v[180:183], v[66:69]
	v_mfma_f32_16x16x32_bf16 v[62:65], v[192:195], v[146:149], v[62:65]
	v_mfma_f32_16x16x32_bf16 v[58:61], v[192:195], v[152:155], v[58:61]
	v_mfma_f32_16x16x32_bf16 v[54:57], v[192:195], v[156:159], v[54:57]
	v_mfma_f32_16x16x32_bf16 v[50:53], v[192:195], v[162:165], v[50:53]
	v_mfma_f32_16x16x32_bf16 v[46:49], v[192:195], v[166:169], v[46:49]
	v_mfma_f32_16x16x32_bf16 v[42:45], v[192:195], v[170:173], v[42:45]
	v_mfma_f32_16x16x32_bf16 v[38:41], v[192:195], v[176:179], v[38:41]
	v_mfma_f32_16x16x32_bf16 v[34:37], v[192:195], v[180:183], v[34:37]
	s_setprio 0
	s_nop 0
	v_mfma_f32_16x16x32_bf16 v[30:33], v[196:199], v[146:149], v[30:33]
	v_mfma_f32_16x16x32_bf16 v[26:29], v[196:199], v[152:155], v[26:29]
	v_mfma_f32_16x16x32_bf16 v[22:25], v[196:199], v[156:159], v[22:25]
	v_mfma_f32_16x16x32_bf16 v[18:21], v[196:199], v[162:165], v[18:21]
	v_mfma_f32_16x16x32_bf16 v[14:17], v[196:199], v[166:169], v[14:17]
	v_mfma_f32_16x16x32_bf16 v[10:13], v[196:199], v[170:173], v[10:13]
	v_mfma_f32_16x16x32_bf16 v[6:9], v[196:199], v[176:179], v[6:9]
	v_mfma_f32_16x16x32_bf16 v[2:5], v[196:199], v[180:183], v[2:5]
	s_mov_b32 s14, s1
	s_nop 0
	s_add_i32 s1, s1, 0x6000
	s_cmp_eq_u32 s1, 0x12000
	s_cselect_b32 s1, 0, s1
	s_nop 0
	s_mov_b32 s4, 0x8000
	s_mov_b32 s5, 0
	s_mov_b32 s10, 0x10000
	s_mov_b32 s11, 0
	s_mov_b32 s41, 0x3fd744fd
	.p2align 3
	s_waitcnt lgkmcnt(0)
; DEVI float blo(unsigned u) { return __uint_as_float(u << 16); }
; DEVI float bhi(unsigned u) { return __uint_as_float(u & 0xffff0000u); }
;     ...
;   for (int kt = 0; kt < nk; kt++) {
;     if (kt + 1 < nk) asm volatile("s_waitcnt vmcnt(6)" ::: "memory");
;     else asm volatile("s_waitcnt vmcnt(0)" ::: "memory");
;     __builtin_amdgcn_s_barrier();
;     asm volatile("" ::: "memory");
;     if (kt + 2 < nk) G2_STAGE(kt + 2);
;     const char* cS = smem + (kt % 3) * 24576;
;     bf16x8 xa[8], wb[4];
; #pragma unroll
;     for (int f = 0; f < 8; f++) xa[f] = *(const bf16x8*)(cS + aoff + f * 1024);
; #pragma unroll
;     for (int f = 0; f < 4; f++) wb[f] = *(const bf16x8*)(cS + boff + f * 1024);
; #pragma unroll
;     for (int nf = 0; nf < 4; nf++)
; #pragma unroll
;       for (int mf = 0; mf < 8; mf++)
;         acc[nf][mf] = __builtin_amdgcn_mfma_f32_16x16x32_bf16(wb[nf], xa[mf], acc[nf][mf], 0, 0, 0);
;   }
;     ...
;         if (EPI == EPI_RESID || EPI == EPI_RESID_ATOMIC) {
;           f32x4 x = a;
;           if (EPI == EPI_RESID || kpart == 0) {
;             const u32x2 xr = *(const u32x2*)((const u16*)(p.ws + WS_XB) + (size_t)row * 1024 + col);
;             x[0] += ALPHA * blo(xr[0]); x[1] += ALPHA * bhi(xr[0]); x[2] += ALPHA * blo(xr[1]); x[3] += ALPHA * bhi(xr[1]);
;           }
;           if (EPI == EPI_RESID) *(f32x4*)((float*)(p.ws + WS_XF) + (size_t)row * 1024 + col) = x;
;           else *(f32x4*)((float*)(p.ws + WS_SLAB) + ((size_t)kpart * 512 + (row - T_P)) * 1024 + col) = x;
	s_nop 0
	v_mfma_f32_16x16x32_bf16 v[126:129], v[232:235], v[200:203], v[126:129]
	v_mfma_f32_16x16x32_bf16 v[122:125], v[232:235], v[204:207], v[122:125]
	v_mfma_f32_16x16x32_bf16 v[118:121], v[232:235], v[208:211], v[118:121]
	v_mfma_f32_16x16x32_bf16 v[114:117], v[232:235], v[212:215], v[114:117]
	v_mfma_f32_16x16x32_bf16 v[110:113], v[232:235], v[216:219], v[110:113]
	v_mfma_f32_16x16x32_bf16 v[106:109], v[232:235], v[220:223], v[106:109]
	v_mfma_f32_16x16x32_bf16 v[102:105], v[232:235], v[224:227], v[102:105]
	v_mfma_f32_16x16x32_bf16 v[98:101], v[232:235], v[228:231], v[98:101]
	v_mfma_f32_16x16x32_bf16 v[94:97], v[236:239], v[200:203], v[94:97]
	v_mfma_f32_16x16x32_bf16 v[90:93], v[236:239], v[204:207], v[90:93]
	v_mfma_f32_16x16x32_bf16 v[86:89], v[236:239], v[208:211], v[86:89]
	v_mfma_f32_16x16x32_bf16 v[82:85], v[236:239], v[212:215], v[82:85]
	v_mfma_f32_16x16x32_bf16 v[78:81], v[236:239], v[216:219], v[78:81]
	v_mfma_f32_16x16x32_bf16 v[74:77], v[236:239], v[220:223], v[74:77]
	v_mfma_f32_16x16x32_bf16 v[70:73], v[236:239], v[224:227], v[70:73]
	v_mfma_f32_16x16x32_bf16 v[66:69], v[236:239], v[228:231], v[66:69]
	v_mfma_f32_16x16x32_bf16 v[62:65], v[240:243], v[200:203], v[62:65]
	v_mfma_f32_16x16x32_bf16 v[58:61], v[240:243], v[204:207], v[58:61]
	v_mfma_f32_16x16x32_bf16 v[54:57], v[240:243], v[208:211], v[54:57]
	v_mfma_f32_16x16x32_bf16 v[50:53], v[240:243], v[212:215], v[50:53]
	v_mfma_f32_16x16x32_bf16 v[46:49], v[240:243], v[216:219], v[46:49]
	v_mfma_f32_16x16x32_bf16 v[42:45], v[240:243], v[220:223], v[42:45]
	v_mfma_f32_16x16x32_bf16 v[38:41], v[240:243], v[224:227], v[38:41]
	v_mfma_f32_16x16x32_bf16 v[34:37], v[240:243], v[228:231], v[34:37]
	v_mfma_f32_16x16x32_bf16 v[30:33], v[244:247], v[200:203], v[30:33]
	v_mfma_f32_16x16x32_bf16 v[26:29], v[244:247], v[204:207], v[26:29]
	v_mfma_f32_16x16x32_bf16 v[22:25], v[244:247], v[208:211], v[22:25]
	v_mfma_f32_16x16x32_bf16 v[18:21], v[244:247], v[212:215], v[18:21]
	v_mfma_f32_16x16x32_bf16 v[14:17], v[244:247], v[216:219], v[14:17]
	v_mfma_f32_16x16x32_bf16 v[10:13], v[244:247], v[220:223], v[10:13]
	v_mfma_f32_16x16x32_bf16 v[6:9], v[244:247], v[224:227], v[6:9]
	v_mfma_f32_16x16x32_bf16 v[2:5], v[244:247], v[228:231], v[2:5]
	s_mov_b32 m0, s40
	s_cmp_eq_u32 s98, 0
	s_cbranch_scc1 .Lta4_first
	s_nop 7
	global_store_dwordx4 v[140:141], v[126:129], off offset:0
	global_store_dwordx4 v[140:141], v[94:97], off offset:64
	global_store_dwordx4 v[140:141], v[62:65], off offset:128
	global_store_dwordx4 v[140:141], v[30:33], off offset:192
	v_lshl_add_u64 v[140:141], v[140:141], 0, s[10:11]
	global_store_dwordx4 v[140:141], v[122:125], off offset:0
	global_store_dwordx4 v[140:141], v[90:93], off offset:64
	global_store_dwordx4 v[140:141], v[58:61], off offset:128
	global_store_dwordx4 v[140:141], v[26:29], off offset:192
	v_lshl_add_u64 v[140:141], v[140:141], 0, s[10:11]
	global_store_dwordx4 v[140:141], v[118:121], off offset:0
	global_store_dwordx4 v[140:141], v[86:89], off offset:64
	global_store_dwordx4 v[140:141], v[54:57], off offset:128
	global_store_dwordx4 v[140:141], v[22:25], off offset:192
	v_lshl_add_u64 v[140:141], v[140:141], 0, s[10:11]
	global_store_dwordx4 v[140:141], v[114:117], off offset:0
	global_store_dwordx4 v[140:141], v[82:85], off offset:64
	global_store_dwordx4 v[140:141], v[50:53], off offset:128
	global_store_dwordx4 v[140:141], v[18:21], off offset:192
	v_lshl_add_u64 v[140:141], v[140:141], 0, s[10:11]
	global_store_dwordx4 v[140:141], v[110:113], off offset:0
	global_store_dwordx4 v[140:141], v[78:81], off offset:64
	global_store_dwordx4 v[140:141], v[46:49], off offset:128
	global_store_dwordx4 v[140:141], v[14:17], off offset:192
	v_lshl_add_u64 v[140:141], v[140:141], 0, s[10:11]
	global_store_dwordx4 v[140:141], v[106:109], off offset:0
	global_store_dwordx4 v[140:141], v[74:77], off offset:64
	global_store_dwordx4 v[140:141], v[42:45], off offset:128
	global_store_dwordx4 v[140:141], v[10:13], off offset:192
	v_lshl_add_u64 v[140:141], v[140:141], 0, s[10:11]
	global_store_dwordx4 v[140:141], v[102:105], off offset:0
	global_store_dwordx4 v[140:141], v[70:73], off offset:64
	global_store_dwordx4 v[140:141], v[38:41], off offset:128
	global_store_dwordx4 v[140:141], v[6:9], off offset:192
	v_lshl_add_u64 v[140:141], v[140:141], 0, s[10:11]
	global_store_dwordx4 v[140:141], v[98:101], off offset:0
	global_store_dwordx4 v[140:141], v[66:69], off offset:64
	global_store_dwordx4 v[140:141], v[34:37], off offset:128
	global_store_dwordx4 v[140:141], v[2:5], off offset:192
	v_readlane_b32 s0, v250, 7
	s_cmpk_lg_u32 s0, 0x200
	s_cbranch_scc1 .Lta4_ar1
	s_mov_b32 s0, 1
	v_writelane_b32 v255, s0, 41
	v_readlane_b32 s1, v250, 0
	s_lshr_b32 s14, s1, 3
	s_and_b32 s1, s1, 7
	s_lshl_b32 s1, s1, 6
	s_add_i32 s1, s1, s14
	s_sub_i32 s39, s1, 0x200

;     ...
;   for (int kt = 0; kt < nk; kt++) {
;     if (kt + 1 < nk) asm volatile("s_waitcnt vmcnt(6)" ::: "memory");
;     else asm volatile("s_waitcnt vmcnt(0)" ::: "memory");
;     __builtin_amdgcn_s_barrier();
;     asm volatile("" ::: "memory");
;     if (kt + 2 < nk) G2_STAGE(kt + 2);
;     const char* cS = smem + (kt % 3) * 24576;
;     bf16x8 xa[8], wb[4];
; #pragma unroll
;     for (int f = 0; f < 8; f++) xa[f] = *(const bf16x8*)(cS + aoff + f * 1024);
; #pragma unroll
;     for (int f = 0; f < 4; f++) wb[f] = *(const bf16x8*)(cS + boff + f * 1024);
; #pragma unroll
;     for (int nf = 0; nf < 4; nf++)
; #pragma unroll
;       for (int mf = 0; mf < 8; mf++)
;         acc[nf][mf] = __builtin_amdgcn_mfma_f32_16x16x32_bf16(wb[nf], xa[mf], acc[nf][mf], 0, 0, 0);
;   }
.Lt4_loop:
	.p2align 3
	s_waitcnt vmcnt(6) lgkmcnt(0)
	s_barrier
	s_setprio 1
	v_add_u32_e32 v144, s41, v136
	v_mfma_f32_16x16x32_bf16 v[126:129], v[184:187], v[146:149], v[126:129]
	ds_read_b128 v[200:203], v144 offset:0
	v_mfma_f32_16x16x32_bf16 v[122:125], v[184:187], v[152:155], v[122:125]
	ds_read_b128 v[204:207], v144 offset:1024
	v_mfma_f32_16x16x32_bf16 v[118:121], v[184:187], v[156:159], v[118:121]
	ds_read_b128 v[208:211], v144 offset:2048
	v_mfma_f32_16x16x32_bf16 v[114:117], v[184:187], v[162:165], v[114:117]
	ds_read_b128 v[212:215], v144 offset:3072
	v_mfma_f32_16x16x32_bf16 v[110:113], v[184:187], v[166:169], v[110:113]
	ds_read_b128 v[216:219], v144 offset:4096
	v_mfma_f32_16x16x32_bf16 v[106:109], v[184:187], v[170:173], v[106:109]
	ds_read_b128 v[220:223], v144 offset:5120
	v_mfma_f32_16x16x32_bf16 v[102:105], v[184:187], v[176:179], v[102:105]
	ds_read_b128 v[224:227], v144 offset:6144
	v_mfma_f32_16x16x32_bf16 v[98:101], v[184:187], v[180:183], v[98:101]
	ds_read_b128 v[228:231], v144 offset:7168
	v_mfma_f32_16x16x32_bf16 v[94:97], v[188:191], v[146:149], v[94:97]
	v_add_u32_e64 v144, s41, v137
	v_mfma_f32_16x16x32_bf16 v[90:93], v[188:191], v[152:155], v[90:93]
	v_mfma_f32_16x16x32_bf16 v[86:89], v[188:191], v[156:159], v[86:89]
	ds_read_b128 v[232:235], v144 offset:16384
	v_mfma_f32_16x16x32_bf16 v[82:85], v[188:191], v[162:165], v[82:85]
	ds_read_b128 v[236:239], v144 offset:17408
	v_mfma_f32_16x16x32_bf16 v[78:81], v[188:191], v[166:169], v[78:81]
	ds_read_b128 v[240:243], v144 offset:18432
	s_setprio 2
	s_nop 0
	v_mfma_f32_16x16x32_bf16 v[74:77], v[188:191], v[170:173], v[74:77]
	ds_read_b128 v[244:247], v144 offset:19456
	v_mfma_f32_16x16x32_bf16 v[70:73], v[188:191], v[176:179], v[70:73]
	s_add_i32 s43, s47, s42
	s_mov_b32 m0, s43
	v_lshl_add_u64 v[142:143], v[132:133], 0, s[2:3]
	v_mfma_f32_16x16x32_bf16 v[66:69], v[188:191], v[180:183], v[66:69]
	global_load_lds_dwordx4 v[132:133], off
	s_add_i32 m0, m0, 0x1000
	v_mfma_f32_16x16x32_bf16 v[62:65], v[192:195], v[146:149], v[62:65]
	v_mfma_f32_16x16x32_bf16 v[58:61], v[192:195], v[152:155], v[58:61]
	v_mfma_f32_16x16x32_bf16 v[54:57], v[192:195], v[156:159], v[54:57]
	global_load_lds_dwordx4 v[142:143], off
	v_lshl_add_u64 v[142:143], v[142:143], 0, s[2:3]
	s_add_i32 m0, m0, 0x1000
	v_mfma_f32_16x16x32_bf16 v[50:53], v[192:195], v[162:165], v[50:53]
	v_mfma_f32_16x16x32_bf16 v[46:49], v[192:195], v[166:169], v[46:49]
	v_mfma_f32_16x16x32_bf16 v[42:45], v[192:195], v[170:173], v[42:45]
	global_load_lds_dwordx4 v[142:143], off
	v_lshl_add_u64 v[142:143], v[142:143], 0, s[2:3]
	s_add_i32 m0, m0, 0x1000
	v_mfma_f32_16x16x32_bf16 v[38:41], v[192:195], v[176:179], v[38:41]
	v_mfma_f32_16x16x32_bf16 v[34:37], v[192:195], v[180:183], v[34:37]
	s_setprio 0
	s_nop 0
	v_mfma_f32_16x16x32_bf16 v[30:33], v[196:199], v[146:149], v[30:33]
	global_load_lds_dwordx4 v[142:143], off
	s_add_i32 m0, m0, 0x1000
	v_lshl_add_u64 v[142:143], v[134:135], 0, s[2:3]
	v_mfma_f32_16x16x32_bf16 v[26:29], v[196:199], v[152:155], v[26:29]
	v_mfma_f32_16x16x32_bf16 v[22:25], v[196:199], v[156:159], v[22:25]
	v_mfma_f32_16x16x32_bf16 v[18:21], v[196:199], v[162:165], v[18:21]
	global_load_lds_dwordx4 v[134:135], off
	s_add_i32 m0, m0, 0x1000
	v_lshl_add_u64 v[132:133], v[132:133], 0, s[12:13]
	v_mfma_f32_16x16x32_bf16 v[14:17], v[196:199], v[166:169], v[14:17]
	v_mfma_f32_16x16x32_bf16 v[10:13], v[196:199], v[170:173], v[10:13]
	v_mfma_f32_16x16x32_bf16 v[6:9], v[196:199], v[176:179], v[6:9]
	global_load_lds_dwordx4 v[142:143], off
	v_lshl_add_u64 v[134:135], v[134:135], 0, s[4:5]
	v_mfma_f32_16x16x32_bf16 v[2:5], v[196:199], v[180:183], v[2:5]
	s_mov_b32 s42, s41
	s_nop 0
	s_add_i32 s41, s41, 0x6000
	s_cmp_eq_u32 s41, 0x12000
	s_cselect_b32 s41, 0, s41
	s_nop 0
	.p2align 3
	s_waitcnt vmcnt(6) lgkmcnt(0)
	s_barrier
	s_setprio 1
	v_add_u32_e32 v144, s41, v136
	v_mfma_f32_16x16x32_bf16 v[126:129], v[232:235], v[200:203], v[126:129]
	ds_read_b128 v[146:149], v144 offset:0
	v_mfma_f32_16x16x32_bf16 v[122:125], v[232:235], v[204:207], v[122:125]
	ds_read_b128 v[152:155], v144 offset:1024
	v_mfma_f32_16x16x32_bf16 v[118:121], v[232:235], v[208:211], v[118:121]
	ds_read_b128 v[156:159], v144 offset:2048
	v_mfma_f32_16x16x32_bf16 v[114:117], v[232:235], v[212:215], v[114:117]
	ds_read_b128 v[162:165], v144 offset:3072
	v_mfma_f32_16x16x32_bf16 v[110:113], v[232:235], v[216:219], v[110:113]
	ds_read_b128 v[166:169], v144 offset:4096
	v_mfma_f32_16x16x32_bf16 v[106:109], v[232:235], v[220:223], v[106:109]
	ds_read_b128 v[170:173], v144 offset:5120
	v_mfma_f32_16x16x32_bf16 v[102:105], v[232:235], v[224:227], v[102:105]
	ds_read_b128 v[176:179], v144 offset:6144
	v_mfma_f32_16x16x32_bf16 v[98:101], v[232:235], v[228:231], v[98:101]
	ds_read_b128 v[180:183], v144 offset:7168
	v_mfma_f32_16x16x32_bf16 v[94:97], v[236:239], v[200:203], v[94:97]
	v_add_u32_e64 v144, s41, v137
	v_mfma_f32_16x16x32_bf16 v[90:93], v[236:239], v[204:207], v[90:93]
	v_mfma_f32_16x16x32_bf16 v[86:89], v[236:239], v[208:211], v[86:89]
	ds_read_b128 v[184:187], v144 offset:16384
	v_mfma_f32_16x16x32_bf16 v[82:85], v[236:239], v[212:215], v[82:85]
	ds_read_b128 v[188:191], v144 offset:17408
	v_mfma_f32_16x16x32_bf16 v[78:81], v[236:239], v[216:219], v[78:81]
	ds_read_b128 v[192:195], v144 offset:18432
	s_setprio 2
	s_nop 0
	v_mfma_f32_16x16x32_bf16 v[74:77], v[236:239], v[220:223], v[74:77]
	ds_read_b128 v[196:199], v144 offset:19456
	v_mfma_f32_16x16x32_bf16 v[70:73], v[236:239], v[224:227], v[70:73]
	s_add_i32 s43, s47, s42
	s_mov_b32 m0, s43
	v_lshl_add_u64 v[142:143], v[132:133], 0, s[2:3]
	v_mfma_f32_16x16x32_bf16 v[66:69], v[236:239], v[228:231], v[66:69]
;     ...
;   for (int kt = 0; kt < nk; kt++) {
;     if (kt + 1 < nk) asm volatile("s_waitcnt vmcnt(6)" ::: "memory");
;     else asm volatile("s_waitcnt vmcnt(0)" ::: "memory");
;     __builtin_amdgcn_s_barrier();
;     asm volatile("" ::: "memory");
;     if (kt + 2 < nk) G2_STAGE(kt + 2);
;     const char* cS = smem + (kt % 3) * 24576;
;     bf16x8 xa[8], wb[4];
; #pragma unroll
;     for (int f = 0; f < 8; f++) xa[f] = *(const bf16x8*)(cS + aoff + f * 1024);
; #pragma unroll
;     for (int f = 0; f < 4; f++) wb[f] = *(const bf16x8*)(cS + boff + f * 1024);
; #pragma unroll
;     for (int nf = 0; nf < 4; nf++)
; #pragma unroll
;       for (int mf = 0; mf < 8; mf++)
;         acc[nf][mf] = __builtin_amdgcn_mfma_f32_16x16x32_bf16(wb[nf], xa[mf], acc[nf][mf], 0, 0, 0);
;   }
	global_load_lds_dwordx4 v[132:133], off
	s_add_i32 m0, m0, 0x1000
	v_mfma_f32_16x16x32_bf16 v[62:65], v[240:243], v[200:203], v[62:65]
	v_mfma_f32_16x16x32_bf16 v[58:61], v[240:243], v[204:207], v[58:61]
	v_mfma_f32_16x16x32_bf16 v[54:57], v[240:243], v[208:211], v[54:57]
	global_load_lds_dwordx4 v[142:143], off
	v_lshl_add_u64 v[142:143], v[142:143], 0, s[2:3]
	s_add_i32 m0, m0, 0x1000
	v_mfma_f32_16x16x32_bf16 v[50:53], v[240:243], v[212:215], v[50:53]
	v_mfma_f32_16x16x32_bf16 v[46:49], v[240:243], v[216:219], v[46:49]
	v_mfma_f32_16x16x32_bf16 v[42:45], v[240:243], v[220:223], v[42:45]
	global_load_lds_dwordx4 v[142:143], off
	v_lshl_add_u64 v[142:143], v[142:143], 0, s[2:3]
	s_add_i32 m0, m0, 0x1000
	v_mfma_f32_16x16x32_bf16 v[38:41], v[240:243], v[224:227], v[38:41]
	v_mfma_f32_16x16x32_bf16 v[34:37], v[240:243], v[228:231], v[34:37]
	s_setprio 0
	s_nop 0
	v_mfma_f32_16x16x32_bf16 v[30:33], v[244:247], v[200:203], v[30:33]
	global_load_lds_dwordx4 v[142:143], off
	s_add_i32 m0, m0, 0x1000
	v_lshl_add_u64 v[142:143], v[134:135], 0, s[2:3]
	v_mfma_f32_16x16x32_bf16 v[26:29], v[244:247], v[204:207], v[26:29]
	v_mfma_f32_16x16x32_bf16 v[22:25], v[244:247], v[208:211], v[22:25]
	v_mfma_f32_16x16x32_bf16 v[18:21], v[244:247], v[212:215], v[18:21]
	global_load_lds_dwordx4 v[134:135], off
	s_add_i32 m0, m0, 0x1000
	v_lshl_add_u64 v[132:133], v[132:133], 0, s[12:13]
	v_mfma_f32_16x16x32_bf16 v[14:17], v[244:247], v[216:219], v[14:17]
	v_mfma_f32_16x16x32_bf16 v[10:13], v[244:247], v[220:223], v[10:13]
	v_mfma_f32_16x16x32_bf16 v[6:9], v[244:247], v[224:227], v[6:9]
	global_load_lds_dwordx4 v[142:143], off
	v_lshl_add_u64 v[134:135], v[134:135], 0, s[4:5]
	v_mfma_f32_16x16x32_bf16 v[2:5], v[244:247], v[228:231], v[2:5]
	s_mov_b32 s42, s41
	s_nop 0
	s_add_i32 s41, s41, 0x6000
	s_cmp_eq_u32 s41, 0x12000
	s_cselect_b32 s41, 0, s41
	s_nop 0
	s_sub_i32 s40, s40, 1
	s_cmp_lg_u32 s40, 0
	s_cbranch_scc1 .Lt4_loop
	.p2align 3
	s_waitcnt vmcnt(6) lgkmcnt(0)
	s_barrier
	s_setprio 1
	v_add_u32_e32 v144, s41, v136
	v_mfma_f32_16x16x32_bf16 v[126:129], v[184:187], v[146:149], v[126:129]
	ds_read_b128 v[200:203], v144 offset:0
	v_mfma_f32_16x16x32_bf16 v[122:125], v[184:187], v[152:155], v[122:125]
	ds_read_b128 v[204:207], v144 offset:1024
	v_mfma_f32_16x16x32_bf16 v[118:121], v[184:187], v[156:159], v[118:121]
	ds_read_b128 v[208:211], v144 offset:2048
	v_mfma_f32_16x16x32_bf16 v[114:117], v[184:187], v[162:165], v[114:117]
	ds_read_b128 v[212:215], v144 offset:3072
	v_mfma_f32_16x16x32_bf16 v[110:113], v[184:187], v[166:169], v[110:113]
	ds_read_b128 v[216:219], v144 offset:4096
	v_mfma_f32_16x16x32_bf16 v[106:109], v[184:187], v[170:173], v[106:109]
	ds_read_b128 v[220:223], v144 offset:5120
	v_mfma_f32_16x16x32_bf16 v[102:105], v[184:187], v[176:179], v[102:105]
	ds_read_b128 v[224:227], v144 offset:6144
	v_mfma_f32_16x16x32_bf16 v[98:101], v[184:187], v[180:183], v[98:101]
	ds_read_b128 v[228:231], v144 offset:7168
	v_mfma_f32_16x16x32_bf16 v[94:97], v[188:191], v[146:149], v[94:97]
	v_add_u32_e64 v144, s41, v137
	v_mfma_f32_16x16x32_bf16 v[90:93], v[188:191], v[152:155], v[90:93]
	v_mfma_f32_16x16x32_bf16 v[86:89], v[188:191], v[156:159], v[86:89]
	ds_read_b128 v[232:235], v144 offset:16384
	v_mfma_f32_16x16x32_bf16 v[82:85], v[188:191], v[162:165], v[82:85]
	ds_read_b128 v[236:239], v144 offset:17408
	v_mfma_f32_16x16x32_bf16 v[78:81], v[188:191], v[166:169], v[78:81]
	ds_read_b128 v[240:243], v144 offset:18432
	s_setprio 2
	s_nop 0
	v_mfma_f32_16x16x32_bf16 v[74:77], v[188:191], v[170:173], v[74:77]
	ds_read_b128 v[244:247], v144 offset:19456
	v_mfma_f32_16x16x32_bf16 v[70:73], v[188:191], v[176:179], v[70:73]
	s_add_i32 s43, s47, s42
	s_mov_b32 m0, s43
	v_lshl_add_u64 v[142:143], v[132:133], 0, s[2:3]
	v_mfma_f32_16x16x32_bf16 v[66:69], v[188:191], v[180:183], v[66:69]
	global_load_lds_dwordx4 v[132:133], off
	s_add_i32 m0, m0, 0x1000
	v_mfma_f32_16x16x32_bf16 v[62:65], v[192:195], v[146:149], v[62:65]
	v_mfma_f32_16x16x32_bf16 v[58:61], v[192:195], v[152:155], v[58:61]
	v_mfma_f32_16x16x32_bf16 v[54:57], v[192:195], v[156:159], v[54:57]
	global_load_lds_dwordx4 v[142:143], off
	v_lshl_add_u64 v[142:143], v[142:143], 0, s[2:3]
	s_add_i32 m0, m0, 0x1000
	v_mfma_f32_16x16x32_bf16 v[50:53], v[192:195], v[162:165], v[50:53]
	v_mfma_f32_16x16x32_bf16 v[46:49], v[192:195], v[166:169], v[46:49]
	v_mfma_f32_16x16x32_bf16 v[42:45], v[192:195], v[170:173], v[42:45]
	global_load_lds_dwordx4 v[142:143], off
	v_lshl_add_u64 v[142:143], v[142:143], 0, s[2:3]
	s_add_i32 m0, m0, 0x1000
	v_mfma_f32_16x16x32_bf16 v[38:41], v[192:195], v[176:179], v[38:41]
	v_mfma_f32_16x16x32_bf16 v[34:37], v[192:195], v[180:183], v[34:37]
	s_setprio 0
	s_nop 0
	v_mfma_f32_16x16x32_bf16 v[30:33], v[196:199], v[146:149], v[30:33]
	global_load_lds_dwordx4 v[142:143], off
	s_add_i32 m0, m0, 0x1000
	v_lshl_add_u64 v[142:143], v[134:135], 0, s[2:3]
	v_mfma_f32_16x16x32_bf16 v[26:29], v[196:199], v[152:155], v[26:29]
	v_mfma_f32_16x16x32_bf16 v[22:25], v[196:199], v[156:159], v[22:25]
	v_mfma_f32_16x16x32_bf16 v[18:21], v[196:199], v[162:165], v[18:21]
	global_load_lds_dwordx4 v[134:135], off
	s_add_i32 m0, m0, 0x1000
	v_lshl_add_u64 v[132:133], v[132:133], 0, s[12:13]
	v_mfma_f32_16x16x32_bf16 v[14:17], v[196:199], v[166:169], v[14:17]
	v_mfma_f32_16x16x32_bf16 v[10:13], v[196:199], v[170:173], v[10:13]
	v_mfma_f32_16x16x32_bf16 v[6:9], v[196:199], v[176:179], v[6:9]
	global_load_lds_dwordx4 v[142:143], off
	v_lshl_add_u64 v[134:135], v[134:135], 0, s[4:5]
	v_mfma_f32_16x16x32_bf16 v[2:5], v[196:199], v[180:183], v[2:5]
	s_mov_b32 s42, s41
	s_nop 0
	s_add_i32 s41, s41, 0x6000
	s_cmp_eq_u32 s41, 0x12000
	s_cselect_b32 s41, 0, s41
	s_nop 0
	.p2align 3
	s_waitcnt vmcnt(6) lgkmcnt(0)
	s_barrier
;     ...
;   for (int kt = 0; kt < nk; kt++) {
;     if (kt + 1 < nk) asm volatile("s_waitcnt vmcnt(6)" ::: "memory");
;     else asm volatile("s_waitcnt vmcnt(0)" ::: "memory");
;     __builtin_amdgcn_s_barrier();
;     asm volatile("" ::: "memory");
;     if (kt + 2 < nk) G2_STAGE(kt + 2);
;     const char* cS = smem + (kt % 3) * 24576;
;     bf16x8 xa[8], wb[4];
; #pragma unroll
;     for (int f = 0; f < 8; f++) xa[f] = *(const bf16x8*)(cS + aoff + f * 1024);
; #pragma unroll
;     for (int f = 0; f < 4; f++) wb[f] = *(const bf16x8*)(cS + boff + f * 1024);
; #pragma unroll
;     for (int nf = 0; nf < 4; nf++)
; #pragma unroll
;       for (int mf = 0; mf < 8; mf++)
;         acc[nf][mf] = __builtin_amdgcn_mfma_f32_16x16x32_bf16(wb[nf], xa[mf], acc[nf][mf], 0, 0, 0);
;   }
	s_setprio 1
	v_add_u32_e32 v144, s41, v136
	v_mfma_f32_16x16x32_bf16 v[126:129], v[232:235], v[200:203], v[126:129]
	ds_read_b128 v[146:149], v144 offset:0
	v_mfma_f32_16x16x32_bf16 v[122:125], v[232:235], v[204:207], v[122:125]
	ds_read_b128 v[152:155], v144 offset:1024
	v_mfma_f32_16x16x32_bf16 v[118:121], v[232:235], v[208:211], v[118:121]
	ds_read_b128 v[156:159], v144 offset:2048
	v_mfma_f32_16x16x32_bf16 v[114:117], v[232:235], v[212:215], v[114:117]
	ds_read_b128 v[162:165], v144 offset:3072
	v_mfma_f32_16x16x32_bf16 v[110:113], v[232:235], v[216:219], v[110:113]
	ds_read_b128 v[166:169], v144 offset:4096
	v_mfma_f32_16x16x32_bf16 v[106:109], v[232:235], v[220:223], v[106:109]
	ds_read_b128 v[170:173], v144 offset:5120
	v_mfma_f32_16x16x32_bf16 v[102:105], v[232:235], v[224:227], v[102:105]
	ds_read_b128 v[176:179], v144 offset:6144
	v_mfma_f32_16x16x32_bf16 v[98:101], v[232:235], v[228:231], v[98:101]
	ds_read_b128 v[180:183], v144 offset:7168
	v_mfma_f32_16x16x32_bf16 v[94:97], v[236:239], v[200:203], v[94:97]
	v_add_u32_e64 v144, s41, v137
	v_mfma_f32_16x16x32_bf16 v[90:93], v[236:239], v[204:207], v[90:93]
	v_mfma_f32_16x16x32_bf16 v[86:89], v[236:239], v[208:211], v[86:89]
	ds_read_b128 v[184:187], v144 offset:16384
	v_mfma_f32_16x16x32_bf16 v[82:85], v[236:239], v[212:215], v[82:85]
	ds_read_b128 v[188:191], v144 offset:17408
	v_mfma_f32_16x16x32_bf16 v[78:81], v[236:239], v[216:219], v[78:81]
	ds_read_b128 v[192:195], v144 offset:18432
	v_mfma_f32_16x16x32_bf16 v[74:77], v[236:239], v[220:223], v[74:77]
	ds_read_b128 v[196:199], v144 offset:19456
	v_mfma_f32_16x16x32_bf16 v[70:73], v[236:239], v[224:227], v[70:73]
	v_mfma_f32_16x16x32_bf16 v[66:69], v[236:239], v[228:231], v[66:69]
	v_mfma_f32_16x16x32_bf16 v[62:65], v[240:243], v[200:203], v[62:65]
	v_mfma_f32_16x16x32_bf16 v[58:61], v[240:243], v[204:207], v[58:61]
	v_mfma_f32_16x16x32_bf16 v[54:57], v[240:243], v[208:211], v[54:57]
	v_mfma_f32_16x16x32_bf16 v[50:53], v[240:243], v[212:215], v[50:53]
	v_mfma_f32_16x16x32_bf16 v[46:49], v[240:243], v[216:219], v[46:49]
	v_mfma_f32_16x16x32_bf16 v[42:45], v[240:243], v[220:223], v[42:45]
	v_mfma_f32_16x16x32_bf16 v[38:41], v[240:243], v[224:227], v[38:41]
	v_mfma_f32_16x16x32_bf16 v[34:37], v[240:243], v[228:231], v[34:37]
	s_setprio 0
	s_nop 0
	v_mfma_f32_16x16x32_bf16 v[30:33], v[244:247], v[200:203], v[30:33]
	v_mfma_f32_16x16x32_bf16 v[26:29], v[244:247], v[204:207], v[26:29]
	v_mfma_f32_16x16x32_bf16 v[22:25], v[244:247], v[208:211], v[22:25]
	v_mfma_f32_16x16x32_bf16 v[18:21], v[244:247], v[212:215], v[18:21]
	v_mfma_f32_16x16x32_bf16 v[14:17], v[244:247], v[216:219], v[14:17]
	v_mfma_f32_16x16x32_bf16 v[10:13], v[244:247], v[220:223], v[10:13]
	v_mfma_f32_16x16x32_bf16 v[6:9], v[244:247], v[224:227], v[6:9]
	v_mfma_f32_16x16x32_bf16 v[2:5], v[244:247], v[228:231], v[2:5]
	s_mov_b32 s42, s41
	s_nop 0
	s_add_i32 s41, s41, 0x6000
	s_cmp_eq_u32 s41, 0x12000
	s_cselect_b32 s41, 0, s41
	s_nop 0
	.p2align 3
	s_waitcnt vmcnt(0) lgkmcnt(0)
	s_barrier
	s_setprio 1
	v_add_u32_e32 v144, s41, v136
	v_mfma_f32_16x16x32_bf16 v[126:129], v[184:187], v[146:149], v[126:129]
	ds_read_b128 v[200:203], v144 offset:0
	v_mfma_f32_16x16x32_bf16 v[122:125], v[184:187], v[152:155], v[122:125]
	ds_read_b128 v[204:207], v144 offset:1024
	v_mfma_f32_16x16x32_bf16 v[118:121], v[184:187], v[156:159], v[118:121]
	ds_read_b128 v[208:211], v144 offset:2048
	v_mfma_f32_16x16x32_bf16 v[114:117], v[184:187], v[162:165], v[114:117]
	ds_read_b128 v[212:215], v144 offset:3072
	v_mfma_f32_16x16x32_bf16 v[110:113], v[184:187], v[166:169], v[110:113]
	ds_read_b128 v[216:219], v144 offset:4096
	v_mfma_f32_16x16x32_bf16 v[106:109], v[184:187], v[170:173], v[106:109]
	ds_read_b128 v[220:223], v144 offset:5120
	v_mfma_f32_16x16x32_bf16 v[102:105], v[184:187], v[176:179], v[102:105]
	ds_read_b128 v[224:227], v144 offset:6144
	v_mfma_f32_16x16x32_bf16 v[98:101], v[184:187], v[180:183], v[98:101]
	ds_read_b128 v[228:231], v144 offset:7168
	v_mfma_f32_16x16x32_bf16 v[94:97], v[188:191], v[146:149], v[94:97]
	v_add_u32_e64 v144, s41, v137
	v_mfma_f32_16x16x32_bf16 v[90:93], v[188:191], v[152:155], v[90:93]
	v_mfma_f32_16x16x32_bf16 v[86:89], v[188:191], v[156:159], v[86:89]
	ds_read_b128 v[232:235], v144 offset:16384
	v_mfma_f32_16x16x32_bf16 v[82:85], v[188:191], v[162:165], v[82:85]
	ds_read_b128 v[236:239], v144 offset:17408
	v_mfma_f32_16x16x32_bf16 v[78:81], v[188:191], v[166:169], v[78:81]
	ds_read_b128 v[240:243], v144 offset:18432
	v_mfma_f32_16x16x32_bf16 v[74:77], v[188:191], v[170:173], v[74:77]
	ds_read_b128 v[244:247], v144 offset:19456
	v_mfma_f32_16x16x32_bf16 v[70:73], v[188:191], v[176:179], v[70:73]
	v_mfma_f32_16x16x32_bf16 v[66:69], v[188:191], v[180:183], v[66:69]
	v_mfma_f32_16x16x32_bf16 v[62:65], v[192:195], v[146:149], v[62:65]
	v_mfma_f32_16x16x32_bf16 v[58:61], v[192:195], v[152:155], v[58:61]
	v_mfma_f32_16x16x32_bf16 v[54:57], v[192:195], v[156:159], v[54:57]
	v_mfma_f32_16x16x32_bf16 v[50:53], v[192:195], v[162:165], v[50:53]
	v_mfma_f32_16x16x32_bf16 v[46:49], v[192:195], v[166:169], v[46:49]
	v_mfma_f32_16x16x32_bf16 v[42:45], v[192:195], v[170:173], v[42:45]
	v_mfma_f32_16x16x32_bf16 v[38:41], v[192:195], v[176:179], v[38:41]
	v_mfma_f32_16x16x32_bf16 v[34:37], v[192:195], v[180:183], v[34:37]
	s_setprio 0
	s_nop 0
	v_mfma_f32_16x16x32_bf16 v[30:33], v[196:199], v[146:149], v[30:33]
	v_mfma_f32_16x16x32_bf16 v[26:29], v[196:199], v[152:155], v[26:29]
	v_mfma_f32_16x16x32_bf16 v[22:25], v[196:199], v[156:159], v[22:25]
	v_mfma_f32_16x16x32_bf16 v[18:21], v[196:199], v[162:165], v[18:21]
	v_mfma_f32_16x16x32_bf16 v[14:17], v[196:199], v[166:169], v[14:17]
	v_mfma_f32_16x16x32_bf16 v[10:13], v[196:199], v[170:173], v[10:13]
	v_mfma_f32_16x16x32_bf16 v[6:9], v[196:199], v[176:179], v[6:9]
	v_mfma_f32_16x16x32_bf16 v[2:5], v[196:199], v[180:183], v[2:5]
	s_mov_b32 s42, s41
	s_nop 0
	s_add_i32 s41, s41, 0x6000
	s_cmp_eq_u32 s41, 0x12000
	s_cselect_b32 s41, 0, s41
	s_nop 0
	s_mov_b32 s4, 0x8000
	s_mov_b32 s5, 0
	s_mov_b32 s10, 0x10000
	s_mov_b32 s11, 0
	s_mov_b32 s45, 0x3fd744fd
	.p2align 3
	s_waitcnt lgkmcnt(0)
; DEVI float blo(unsigned u) { return __uint_as_float(u << 16); }
; DEVI float bhi(unsigned u) { return __uint_as_float(u & 0xffff0000u); }
;     ...
;         if (EPI == EPI_RESID || EPI == EPI_RESID_ATOMIC) {
;           f32x4 x = a;
;           if (EPI == EPI_RESID || kpart == 0) {
;             const u32x2 xr = *(const u32x2*)((const u16*)(p.ws + WS_XB) + (size_t)row * 1024 + col);
;             x[0] += ALPHA * blo(xr[0]); x[1] += ALPHA * bhi(xr[0]); x[2] += ALPHA * blo(xr[1]); x[3] += ALPHA * bhi(xr[1]);
;           }
;           if (EPI == EPI_RESID) *(f32x4*)((float*)(p.ws + WS_XF) + (size_t)row * 1024 + col) = x;
;           else *(f32x4*)((float*)(p.ws + WS_SLAB) + ((size_t)kpart * 512 + (row - T_P)) * 1024 + col) = x;
	s_nop 0
	v_mfma_f32_16x16x32_bf16 v[126:129], v[232:235], v[200:203], v[126:129]
	v_mfma_f32_16x16x32_bf16 v[122:125], v[232:235], v[204:207], v[122:125]
	v_mfma_f32_16x16x32_bf16 v[118:121], v[232:235], v[208:211], v[118:121]
	v_mfma_f32_16x16x32_bf16 v[114:117], v[232:235], v[212:215], v[114:117]
	v_mfma_f32_16x16x32_bf16 v[110:113], v[232:235], v[216:219], v[110:113]
	global_load_dwordx4 v[146:149], v[138:139], off offset:0
	v_mfma_f32_16x16x32_bf16 v[106:109], v[232:235], v[220:223], v[106:109]
	v_mfma_f32_16x16x32_bf16 v[102:105], v[232:235], v[224:227], v[102:105]
	global_load_dwordx4 v[152:155], v[138:139], off offset:128
	v_mfma_f32_16x16x32_bf16 v[98:101], v[232:235], v[228:231], v[98:101]
	v_lshl_add_u64 v[138:139], v[138:139], 0, s[4:5]
	v_mfma_f32_16x16x32_bf16 v[94:97], v[236:239], v[200:203], v[94:97]
	global_load_dwordx4 v[156:159], v[138:139], off offset:0
	v_mfma_f32_16x16x32_bf16 v[90:93], v[236:239], v[204:207], v[90:93]
	v_mfma_f32_16x16x32_bf16 v[86:89], v[236:239], v[208:211], v[86:89]
	global_load_dwordx4 v[162:165], v[138:139], off offset:128
	v_mfma_f32_16x16x32_bf16 v[82:85], v[236:239], v[212:215], v[82:85]
	v_lshl_add_u64 v[138:139], v[138:139], 0, s[4:5]
	v_mfma_f32_16x16x32_bf16 v[78:81], v[236:239], v[216:219], v[78:81]
	global_load_dwordx4 v[166:169], v[138:139], off offset:0
	v_mfma_f32_16x16x32_bf16 v[74:77], v[236:239], v[220:223], v[74:77]
	v_mfma_f32_16x16x32_bf16 v[70:73], v[236:239], v[224:227], v[70:73]
	global_load_dwordx4 v[170:173], v[138:139], off offset:128
	v_mfma_f32_16x16x32_bf16 v[66:69], v[236:239], v[228:231], v[66:69]
	v_lshl_add_u64 v[138:139], v[138:139], 0, s[4:5]
	v_mfma_f32_16x16x32_bf16 v[62:65], v[240:243], v[200:203], v[62:65]
	global_load_dwordx4 v[176:179], v[138:139], off offset:0
	v_mfma_f32_16x16x32_bf16 v[58:61], v[240:243], v[204:207], v[58:61]
	v_mfma_f32_16x16x32_bf16 v[54:57], v[240:243], v[208:211], v[54:57]
	global_load_dwordx4 v[180:183], v[138:139], off offset:128
	v_mfma_f32_16x16x32_bf16 v[50:53], v[240:243], v[212:215], v[50:53]
	v_lshl_add_u64 v[138:139], v[138:139], 0, s[4:5]
	v_mfma_f32_16x16x32_bf16 v[46:49], v[240:243], v[216:219], v[46:49]
	global_load_dwordx4 v[184:187], v[138:139], off offset:0
	v_mfma_f32_16x16x32_bf16 v[42:45], v[240:243], v[220:223], v[42:45]
	v_mfma_f32_16x16x32_bf16 v[38:41], v[240:243], v[224:227], v[38:41]
	global_load_dwordx4 v[188:191], v[138:139], off offset:128
	v_mfma_f32_16x16x32_bf16 v[34:37], v[240:243], v[228:231], v[34:37]
	v_lshl_add_u64 v[138:139], v[138:139], 0, s[4:5]
	v_mfma_f32_16x16x32_bf16 v[30:33], v[244:247], v[200:203], v[30:33]
	global_load_dwordx4 v[192:195], v[138:139], off offset:0
	v_mfma_f32_16x16x32_bf16 v[26:29], v[244:247], v[204:207], v[26:29]
	v_mfma_f32_16x16x32_bf16 v[22:25], v[244:247], v[208:211], v[22:25]
	global_load_dwordx4 v[196:199], v[138:139], off offset:128
	v_mfma_f32_16x16x32_bf16 v[18:21], v[244:247], v[212:215], v[18:21]
	v_lshl_add_u64 v[138:139], v[138:139], 0, s[4:5]
	v_mfma_f32_16x16x32_bf16 v[14:17], v[244:247], v[216:219], v[14:17]
	v_mfma_f32_16x16x32_bf16 v[10:13], v[244:247], v[220:223], v[10:13]
	v_mfma_f32_16x16x32_bf16 v[6:9], v[244:247], v[224:227], v[6:9]
	v_mfma_f32_16x16x32_bf16 v[2:5], v[244:247], v[228:231], v[2:5]
	s_mov_b32 m0, s44
	global_load_dwordx4 v[200:203], v[138:139], off offset:0
	global_load_dwordx4 v[204:207], v[138:139], off offset:128
	v_lshl_add_u64 v[138:139], v[138:139], 0, s[4:5]
	global_load_dwordx4 v[208:211], v[138:139], off offset:0
	global_load_dwordx4 v[212:215], v[138:139], off offset:128
	v_lshl_add_u64 v[138:139], v[138:139], 0, s[4:5]
	s_nop 7
	v_and_b32_e32 v228, 1, v145
	v_cmp_ne_u32_e32 vcc, 0, v228
	v_mov_b32_e32 v229, 0xfffff040
	v_cndmask_b32_e32 v230, 0, v229, vcc
	v_ashrrev_i32_e32 v231, 31, v230
	v_lshl_add_u64 v[140:141], v[140:141], 0, v[230:231]
	v_add_co_u32_e32 v142, vcc, 0x1000, v140
	s_nop 0
	v_addc_co_u32_e32 v143, vcc, 0, v141, vcc
	v_cmp_ne_u32_e32 vcc, 0, v228
	s_waitcnt vmcnt(15)
	v_permlane16_swap_b32_e32 v146, v148
	v_permlane16_swap_b32_e32 v147, v149
	v_lshlrev_b32_e32 v216, 16, v146
	v_and_b32_e32 v146, 0xffff0000, v146
	v_lshlrev_b32_e32 v217, 16, v147
	v_and_b32_e32 v147, 0xffff0000, v147
	v_fmac_f32_e32 v126, s45, v216
	v_fmac_f32_e32 v127, s45, v146
	v_fmac_f32_e32 v128, s45, v217
	v_fmac_f32_e32 v129, s45, v147
	v_lshlrev_b32_e32 v216, 16, v148
	v_and_b32_e32 v148, 0xffff0000, v148
	v_lshlrev_b32_e32 v217, 16, v149
	v_and_b32_e32 v149, 0xffff0000, v149
	v_fmac_f32_e32 v94, s45, v216
	v_fmac_f32_e32 v95, s45, v148
	v_fmac_f32_e32 v96, s45, v217
	v_fmac_f32_e32 v97, s45, v149
	v_mov_b32_dpp v220, v94 quad_perm:[1,0,3,2] row_mask:0xf bank_mask:0xf
	v_mov_b32_dpp v221, v95 quad_perm:[1,0,3,2] row_mask:0xf bank_mask:0xf
	v_mov_b32_dpp v222, v96 quad_perm:[1,0,3,2] row_mask:0xf bank_mask:0xf
	v_mov_b32_dpp v223, v97 quad_perm:[1,0,3,2] row_mask:0xf bank_mask:0xf
	v_mov_b32_dpp v224, v126 quad_perm:[1,0,3,2] row_mask:0xf bank_mask:0xf
	v_mov_b32_dpp v225, v127 quad_perm:[1,0,3,2] row_mask:0xf bank_mask:0xf
	v_mov_b32_dpp v226, v128 quad_perm:[1,0,3,2] row_mask:0xf bank_mask:0xf
	v_mov_b32_dpp v227, v129 quad_perm:[1,0,3,2] row_mask:0xf bank_mask:0xf
	v_cndmask_b32_e32 v94, v224, v94, vcc
	v_cndmask_b32_e32 v95, v225, v95, vcc
	v_cndmask_b32_e32 v96, v226, v96, vcc
	v_cndmask_b32_e32 v97, v227, v97, vcc
	v_cndmask_b32_e32 v126, v126, v220, vcc
	v_cndmask_b32_e32 v127, v127, v221, vcc
	v_cndmask_b32_e32 v128, v128, v222, vcc
	v_cndmask_b32_e32 v129, v129, v223, vcc
	global_store_dwordx4 v[140:141], v[126:129], off
	global_store_dwordx4 v[142:143], v[94:97], off
	s_waitcnt vmcnt(16)
; DEVI float blo(unsigned u) { return __uint_as_float(u << 16); }
; DEVI float bhi(unsigned u) { return __uint_as_float(u & 0xffff0000u); }
;     ...
;         if (EPI == EPI_RESID || EPI == EPI_RESID_ATOMIC) {
;           f32x4 x = a;
;           if (EPI == EPI_RESID || kpart == 0) {
;             const u32x2 xr = *(const u32x2*)((const u16*)(p.ws + WS_XB) + (size_t)row * 1024 + col);
;             x[0] += ALPHA * blo(xr[0]); x[1] += ALPHA * bhi(xr[0]); x[2] += ALPHA * blo(xr[1]); x[3] += ALPHA * bhi(xr[1]);
;           }
;           if (EPI == EPI_RESID) *(f32x4*)((float*)(p.ws + WS_XF) + (size_t)row * 1024 + col) = x;
;           else *(f32x4*)((float*)(p.ws + WS_SLAB) + ((size_t)kpart * 512 + (row - T_P)) * 1024 + col) = x;
	v_permlane16_swap_b32_e32 v152, v154
	v_permlane16_swap_b32_e32 v153, v155
	v_lshlrev_b32_e32 v216, 16, v152
	v_and_b32_e32 v152, 0xffff0000, v152
	v_lshlrev_b32_e32 v217, 16, v153
	v_and_b32_e32 v153, 0xffff0000, v153
	v_fmac_f32_e32 v62, s45, v216
	v_fmac_f32_e32 v63, s45, v152
	v_fmac_f32_e32 v64, s45, v217
	v_fmac_f32_e32 v65, s45, v153
	v_lshlrev_b32_e32 v216, 16, v154
	v_and_b32_e32 v154, 0xffff0000, v154
	v_lshlrev_b32_e32 v217, 16, v155
	v_and_b32_e32 v155, 0xffff0000, v155
	v_fmac_f32_e32 v30, s45, v216
	v_fmac_f32_e32 v31, s45, v154
	v_fmac_f32_e32 v32, s45, v217
	v_fmac_f32_e32 v33, s45, v155
	v_mov_b32_dpp v220, v30 quad_perm:[1,0,3,2] row_mask:0xf bank_mask:0xf
	v_mov_b32_dpp v221, v31 quad_perm:[1,0,3,2] row_mask:0xf bank_mask:0xf
	v_mov_b32_dpp v222, v32 quad_perm:[1,0,3,2] row_mask:0xf bank_mask:0xf
	v_mov_b32_dpp v223, v33 quad_perm:[1,0,3,2] row_mask:0xf bank_mask:0xf
	v_mov_b32_dpp v224, v62 quad_perm:[1,0,3,2] row_mask:0xf bank_mask:0xf
	v_mov_b32_dpp v225, v63 quad_perm:[1,0,3,2] row_mask:0xf bank_mask:0xf
	v_mov_b32_dpp v226, v64 quad_perm:[1,0,3,2] row_mask:0xf bank_mask:0xf
	v_mov_b32_dpp v227, v65 quad_perm:[1,0,3,2] row_mask:0xf bank_mask:0xf
	v_cndmask_b32_e32 v30, v224, v30, vcc
	v_cndmask_b32_e32 v31, v225, v31, vcc
	v_cndmask_b32_e32 v32, v226, v32, vcc
	v_cndmask_b32_e32 v33, v227, v33, vcc
	v_cndmask_b32_e32 v62, v62, v220, vcc
	v_cndmask_b32_e32 v63, v63, v221, vcc
	v_cndmask_b32_e32 v64, v64, v222, vcc
	v_cndmask_b32_e32 v65, v65, v223, vcc
	global_store_dwordx4 v[140:141], v[62:65], off offset:128
	global_store_dwordx4 v[142:143], v[30:33], off offset:128
	v_lshl_add_u64 v[140:141], v[140:141], 0, s[10:11]
	v_lshl_add_u64 v[142:143], v[142:143], 0, s[10:11]
	s_waitcnt vmcnt(17)
	v_permlane16_swap_b32_e32 v156, v158
	v_permlane16_swap_b32_e32 v157, v159
	v_lshlrev_b32_e32 v216, 16, v156
	v_and_b32_e32 v156, 0xffff0000, v156
	v_lshlrev_b32_e32 v217, 16, v157
	v_and_b32_e32 v157, 0xffff0000, v157
	v_fmac_f32_e32 v122, s45, v216
	v_fmac_f32_e32 v123, s45, v156
	v_fmac_f32_e32 v124, s45, v217
	v_fmac_f32_e32 v125, s45, v157
	v_lshlrev_b32_e32 v216, 16, v158
	v_and_b32_e32 v158, 0xffff0000, v158
	v_lshlrev_b32_e32 v217, 16, v159
	v_and_b32_e32 v159, 0xffff0000, v159
	v_fmac_f32_e32 v90, s45, v216
	v_fmac_f32_e32 v91, s45, v158
	v_fmac_f32_e32 v92, s45, v217
	v_fmac_f32_e32 v93, s45, v159
	v_mov_b32_dpp v220, v90 quad_perm:[1,0,3,2] row_mask:0xf bank_mask:0xf
	v_mov_b32_dpp v221, v91 quad_perm:[1,0,3,2] row_mask:0xf bank_mask:0xf
	v_mov_b32_dpp v222, v92 quad_perm:[1,0,3,2] row_mask:0xf bank_mask:0xf
	v_mov_b32_dpp v223, v93 quad_perm:[1,0,3,2] row_mask:0xf bank_mask:0xf
	v_mov_b32_dpp v224, v122 quad_perm:[1,0,3,2] row_mask:0xf bank_mask:0xf
	v_mov_b32_dpp v225, v123 quad_perm:[1,0,3,2] row_mask:0xf bank_mask:0xf
	v_mov_b32_dpp v226, v124 quad_perm:[1,0,3,2] row_mask:0xf bank_mask:0xf
	v_mov_b32_dpp v227, v125 quad_perm:[1,0,3,2] row_mask:0xf bank_mask:0xf
	v_cndmask_b32_e32 v90, v224, v90, vcc
	v_cndmask_b32_e32 v91, v225, v91, vcc
	v_cndmask_b32_e32 v92, v226, v92, vcc
	v_cndmask_b32_e32 v93, v227, v93, vcc
	v_cndmask_b32_e32 v122, v122, v220, vcc
	v_cndmask_b32_e32 v123, v123, v221, vcc
	v_cndmask_b32_e32 v124, v124, v222, vcc
	v_cndmask_b32_e32 v125, v125, v223, vcc
	global_store_dwordx4 v[140:141], v[122:125], off
	global_store_dwordx4 v[142:143], v[90:93], off
	s_waitcnt vmcnt(18)
	v_permlane16_swap_b32_e32 v162, v164
	v_permlane16_swap_b32_e32 v163, v165
	v_lshlrev_b32_e32 v216, 16, v162
	v_and_b32_e32 v162, 0xffff0000, v162
	v_lshlrev_b32_e32 v217, 16, v163
	v_and_b32_e32 v163, 0xffff0000, v163
	v_fmac_f32_e32 v58, s45, v216
	v_fmac_f32_e32 v59, s45, v162
	v_fmac_f32_e32 v60, s45, v217
	v_fmac_f32_e32 v61, s45, v163
	v_lshlrev_b32_e32 v216, 16, v164
	v_and_b32_e32 v164, 0xffff0000, v164
	v_lshlrev_b32_e32 v217, 16, v165
	v_and_b32_e32 v165, 0xffff0000, v165
	v_fmac_f32_e32 v26, s45, v216
	v_fmac_f32_e32 v27, s45, v164
	v_fmac_f32_e32 v28, s45, v217
	v_fmac_f32_e32 v29, s45, v165
	v_mov_b32_dpp v220, v26 quad_perm:[1,0,3,2] row_mask:0xf bank_mask:0xf
	v_mov_b32_dpp v221, v27 quad_perm:[1,0,3,2] row_mask:0xf bank_mask:0xf
	v_mov_b32_dpp v222, v28 quad_perm:[1,0,3,2] row_mask:0xf bank_mask:0xf
	v_mov_b32_dpp v223, v29 quad_perm:[1,0,3,2] row_mask:0xf bank_mask:0xf
	v_mov_b32_dpp v224, v58 quad_perm:[1,0,3,2] row_mask:0xf bank_mask:0xf
	v_mov_b32_dpp v225, v59 quad_perm:[1,0,3,2] row_mask:0xf bank_mask:0xf
	v_mov_b32_dpp v226, v60 quad_perm:[1,0,3,2] row_mask:0xf bank_mask:0xf
	v_mov_b32_dpp v227, v61 quad_perm:[1,0,3,2] row_mask:0xf bank_mask:0xf
	v_cndmask_b32_e32 v26, v224, v26, vcc
	v_cndmask_b32_e32 v27, v225, v27, vcc
	v_cndmask_b32_e32 v28, v226, v28, vcc
	v_cndmask_b32_e32 v29, v227, v29, vcc
	v_cndmask_b32_e32 v58, v58, v220, vcc
	v_cndmask_b32_e32 v59, v59, v221, vcc
	v_cndmask_b32_e32 v60, v60, v222, vcc
	v_cndmask_b32_e32 v61, v61, v223, vcc
	global_store_dwordx4 v[140:141], v[58:61], off offset:128
	global_store_dwordx4 v[142:143], v[26:29], off offset:128
	v_lshl_add_u64 v[140:141], v[140:141], 0, s[10:11]
	v_lshl_add_u64 v[142:143], v[142:143], 0, s[10:11]
	s_waitcnt vmcnt(19)
; DEVI float blo(unsigned u) { return __uint_as_float(u << 16); }
; DEVI float bhi(unsigned u) { return __uint_as_float(u & 0xffff0000u); }
;     ...
;         if (EPI == EPI_RESID || EPI == EPI_RESID_ATOMIC) {
;           f32x4 x = a;
;           if (EPI == EPI_RESID || kpart == 0) {
;             const u32x2 xr = *(const u32x2*)((const u16*)(p.ws + WS_XB) + (size_t)row * 1024 + col);
;             x[0] += ALPHA * blo(xr[0]); x[1] += ALPHA * bhi(xr[0]); x[2] += ALPHA * blo(xr[1]); x[3] += ALPHA * bhi(xr[1]);
;           }
;           if (EPI == EPI_RESID) *(f32x4*)((float*)(p.ws + WS_XF) + (size_t)row * 1024 + col) = x;
;           else *(f32x4*)((float*)(p.ws + WS_SLAB) + ((size_t)kpart * 512 + (row - T_P)) * 1024 + col) = x;
	v_permlane16_swap_b32_e32 v166, v168
	v_permlane16_swap_b32_e32 v167, v169
	v_lshlrev_b32_e32 v216, 16, v166
	v_and_b32_e32 v166, 0xffff0000, v166
	v_lshlrev_b32_e32 v217, 16, v167
	v_and_b32_e32 v167, 0xffff0000, v167
	v_fmac_f32_e32 v118, s45, v216
	v_fmac_f32_e32 v119, s45, v166
	v_fmac_f32_e32 v120, s45, v217
	v_fmac_f32_e32 v121, s45, v167
	v_lshlrev_b32_e32 v216, 16, v168
	v_and_b32_e32 v168, 0xffff0000, v168
	v_lshlrev_b32_e32 v217, 16, v169
	v_and_b32_e32 v169, 0xffff0000, v169
	v_fmac_f32_e32 v86, s45, v216
	v_fmac_f32_e32 v87, s45, v168
	v_fmac_f32_e32 v88, s45, v217
	v_fmac_f32_e32 v89, s45, v169
	v_mov_b32_dpp v220, v86 quad_perm:[1,0,3,2] row_mask:0xf bank_mask:0xf
	v_mov_b32_dpp v221, v87 quad_perm:[1,0,3,2] row_mask:0xf bank_mask:0xf
	v_mov_b32_dpp v222, v88 quad_perm:[1,0,3,2] row_mask:0xf bank_mask:0xf
	v_mov_b32_dpp v223, v89 quad_perm:[1,0,3,2] row_mask:0xf bank_mask:0xf
	v_mov_b32_dpp v224, v118 quad_perm:[1,0,3,2] row_mask:0xf bank_mask:0xf
	v_mov_b32_dpp v225, v119 quad_perm:[1,0,3,2] row_mask:0xf bank_mask:0xf
	v_mov_b32_dpp v226, v120 quad_perm:[1,0,3,2] row_mask:0xf bank_mask:0xf
	v_mov_b32_dpp v227, v121 quad_perm:[1,0,3,2] row_mask:0xf bank_mask:0xf
	v_cndmask_b32_e32 v86, v224, v86, vcc
	v_cndmask_b32_e32 v87, v225, v87, vcc
	v_cndmask_b32_e32 v88, v226, v88, vcc
	v_cndmask_b32_e32 v89, v227, v89, vcc
	v_cndmask_b32_e32 v118, v118, v220, vcc
	v_cndmask_b32_e32 v119, v119, v221, vcc
	v_cndmask_b32_e32 v120, v120, v222, vcc
	v_cndmask_b32_e32 v121, v121, v223, vcc
	global_store_dwordx4 v[140:141], v[118:121], off
	global_store_dwordx4 v[142:143], v[86:89], off
	s_waitcnt vmcnt(20)
	v_permlane16_swap_b32_e32 v170, v172
	v_permlane16_swap_b32_e32 v171, v173
	v_lshlrev_b32_e32 v216, 16, v170
	v_and_b32_e32 v170, 0xffff0000, v170
	v_lshlrev_b32_e32 v217, 16, v171
	v_and_b32_e32 v171, 0xffff0000, v171
	v_fmac_f32_e32 v54, s45, v216
	v_fmac_f32_e32 v55, s45, v170
	v_fmac_f32_e32 v56, s45, v217
	v_fmac_f32_e32 v57, s45, v171
	v_lshlrev_b32_e32 v216, 16, v172
	v_and_b32_e32 v172, 0xffff0000, v172
	v_lshlrev_b32_e32 v217, 16, v173
	v_and_b32_e32 v173, 0xffff0000, v173
	v_fmac_f32_e32 v22, s45, v216
	v_fmac_f32_e32 v23, s45, v172
	v_fmac_f32_e32 v24, s45, v217
	v_fmac_f32_e32 v25, s45, v173
	v_mov_b32_dpp v220, v22 quad_perm:[1,0,3,2] row_mask:0xf bank_mask:0xf
	v_mov_b32_dpp v221, v23 quad_perm:[1,0,3,2] row_mask:0xf bank_mask:0xf
	v_mov_b32_dpp v222, v24 quad_perm:[1,0,3,2] row_mask:0xf bank_mask:0xf
	v_mov_b32_dpp v223, v25 quad_perm:[1,0,3,2] row_mask:0xf bank_mask:0xf
	v_mov_b32_dpp v224, v54 quad_perm:[1,0,3,2] row_mask:0xf bank_mask:0xf
	v_mov_b32_dpp v225, v55 quad_perm:[1,0,3,2] row_mask:0xf bank_mask:0xf
	v_mov_b32_dpp v226, v56 quad_perm:[1,0,3,2] row_mask:0xf bank_mask:0xf
	v_mov_b32_dpp v227, v57 quad_perm:[1,0,3,2] row_mask:0xf bank_mask:0xf
	v_cndmask_b32_e32 v22, v224, v22, vcc
	v_cndmask_b32_e32 v23, v225, v23, vcc
	v_cndmask_b32_e32 v24, v226, v24, vcc
	v_cndmask_b32_e32 v25, v227, v25, vcc
	v_cndmask_b32_e32 v54, v54, v220, vcc
	v_cndmask_b32_e32 v55, v55, v221, vcc
	v_cndmask_b32_e32 v56, v56, v222, vcc
	v_cndmask_b32_e32 v57, v57, v223, vcc
	global_store_dwordx4 v[140:141], v[54:57], off offset:128
	global_store_dwordx4 v[142:143], v[22:25], off offset:128
	v_lshl_add_u64 v[140:141], v[140:141], 0, s[10:11]
	v_lshl_add_u64 v[142:143], v[142:143], 0, s[10:11]
	s_waitcnt vmcnt(21)
	v_permlane16_swap_b32_e32 v176, v178
	v_permlane16_swap_b32_e32 v177, v179
	v_lshlrev_b32_e32 v216, 16, v176
	v_and_b32_e32 v176, 0xffff0000, v176
	v_lshlrev_b32_e32 v217, 16, v177
	v_and_b32_e32 v177, 0xffff0000, v177
	v_fmac_f32_e32 v114, s45, v216
	v_fmac_f32_e32 v115, s45, v176
	v_fmac_f32_e32 v116, s45, v217
	v_fmac_f32_e32 v117, s45, v177
	v_lshlrev_b32_e32 v216, 16, v178
	v_and_b32_e32 v178, 0xffff0000, v178
	v_lshlrev_b32_e32 v217, 16, v179
	v_and_b32_e32 v179, 0xffff0000, v179
	v_fmac_f32_e32 v82, s45, v216
	v_fmac_f32_e32 v83, s45, v178
	v_fmac_f32_e32 v84, s45, v217
	v_fmac_f32_e32 v85, s45, v179
	v_mov_b32_dpp v220, v82 quad_perm:[1,0,3,2] row_mask:0xf bank_mask:0xf
	v_mov_b32_dpp v221, v83 quad_perm:[1,0,3,2] row_mask:0xf bank_mask:0xf
	v_mov_b32_dpp v222, v84 quad_perm:[1,0,3,2] row_mask:0xf bank_mask:0xf
	v_mov_b32_dpp v223, v85 quad_perm:[1,0,3,2] row_mask:0xf bank_mask:0xf
	v_mov_b32_dpp v224, v114 quad_perm:[1,0,3,2] row_mask:0xf bank_mask:0xf
	v_mov_b32_dpp v225, v115 quad_perm:[1,0,3,2] row_mask:0xf bank_mask:0xf
	v_mov_b32_dpp v226, v116 quad_perm:[1,0,3,2] row_mask:0xf bank_mask:0xf
	v_mov_b32_dpp v227, v117 quad_perm:[1,0,3,2] row_mask:0xf bank_mask:0xf
	v_cndmask_b32_e32 v82, v224, v82, vcc
	v_cndmask_b32_e32 v83, v225, v83, vcc
	v_cndmask_b32_e32 v84, v226, v84, vcc
	v_cndmask_b32_e32 v85, v227, v85, vcc
	v_cndmask_b32_e32 v114, v114, v220, vcc
	v_cndmask_b32_e32 v115, v115, v221, vcc
	v_cndmask_b32_e32 v116, v116, v222, vcc
	v_cndmask_b32_e32 v117, v117, v223, vcc
	global_store_dwordx4 v[140:141], v[114:117], off
	global_store_dwordx4 v[142:143], v[82:85], off
	s_waitcnt vmcnt(22)
; DEVI float blo(unsigned u) { return __uint_as_float(u << 16); }
; DEVI float bhi(unsigned u) { return __uint_as_float(u & 0xffff0000u); }
;     ...
; #pragma unroll
;       for (int nf = 0; nf < 4; nf++) {
;         const int col = n0 + wn * 64 + nf * 16 + quad * 4;
;         f32x4 a = acc[nf][mf];
;         if (EPI == EPI_RESID || EPI == EPI_RESID_ATOMIC) {
;           f32x4 x = a;
;           if (EPI == EPI_RESID || kpart == 0) {
;             const u32x2 xr = *(const u32x2*)((const u16*)(p.ws + WS_XB) + (size_t)row * 1024 + col);
;             x[0] += ALPHA * blo(xr[0]); x[1] += ALPHA * bhi(xr[0]); x[2] += ALPHA * blo(xr[1]); x[3] += ALPHA * bhi(xr[1]);
;           }
;           if (EPI == EPI_RESID) *(f32x4*)((float*)(p.ws + WS_XF) + (size_t)row * 1024 + col) = x;
;           else *(f32x4*)((float*)(p.ws + WS_SLAB) + ((size_t)kpart * 512 + (row - T_P)) * 1024 + col) = x;
	v_permlane16_swap_b32_e32 v180, v182
	v_permlane16_swap_b32_e32 v181, v183
	v_lshlrev_b32_e32 v216, 16, v180
	v_and_b32_e32 v180, 0xffff0000, v180
	v_lshlrev_b32_e32 v217, 16, v181
	v_and_b32_e32 v181, 0xffff0000, v181
	v_fmac_f32_e32 v50, s45, v216
	v_fmac_f32_e32 v51, s45, v180
	v_fmac_f32_e32 v52, s45, v217
	v_fmac_f32_e32 v53, s45, v181
	v_lshlrev_b32_e32 v216, 16, v182
	v_and_b32_e32 v182, 0xffff0000, v182
	v_lshlrev_b32_e32 v217, 16, v183
	v_and_b32_e32 v183, 0xffff0000, v183
	v_fmac_f32_e32 v18, s45, v216
	v_fmac_f32_e32 v19, s45, v182
	v_fmac_f32_e32 v20, s45, v217
	v_fmac_f32_e32 v21, s45, v183
	v_mov_b32_dpp v220, v18 quad_perm:[1,0,3,2] row_mask:0xf bank_mask:0xf
	v_mov_b32_dpp v221, v19 quad_perm:[1,0,3,2] row_mask:0xf bank_mask:0xf
	v_mov_b32_dpp v222, v20 quad_perm:[1,0,3,2] row_mask:0xf bank_mask:0xf
	v_mov_b32_dpp v223, v21 quad_perm:[1,0,3,2] row_mask:0xf bank_mask:0xf
	v_mov_b32_dpp v224, v50 quad_perm:[1,0,3,2] row_mask:0xf bank_mask:0xf
	v_mov_b32_dpp v225, v51 quad_perm:[1,0,3,2] row_mask:0xf bank_mask:0xf
	v_mov_b32_dpp v226, v52 quad_perm:[1,0,3,2] row_mask:0xf bank_mask:0xf
	v_mov_b32_dpp v227, v53 quad_perm:[1,0,3,2] row_mask:0xf bank_mask:0xf
	v_cndmask_b32_e32 v18, v224, v18, vcc
	v_cndmask_b32_e32 v19, v225, v19, vcc
	v_cndmask_b32_e32 v20, v226, v20, vcc
	v_cndmask_b32_e32 v21, v227, v21, vcc
	v_cndmask_b32_e32 v50, v50, v220, vcc
	v_cndmask_b32_e32 v51, v51, v221, vcc
	v_cndmask_b32_e32 v52, v52, v222, vcc
	v_cndmask_b32_e32 v53, v53, v223, vcc
	global_store_dwordx4 v[140:141], v[50:53], off offset:128
	global_store_dwordx4 v[142:143], v[18:21], off offset:128
	v_lshl_add_u64 v[140:141], v[140:141], 0, s[10:11]
	v_lshl_add_u64 v[142:143], v[142:143], 0, s[10:11]
	s_waitcnt vmcnt(23)
	v_permlane16_swap_b32_e32 v184, v186
	v_permlane16_swap_b32_e32 v185, v187
	v_lshlrev_b32_e32 v216, 16, v184
	v_and_b32_e32 v184, 0xffff0000, v184
	v_lshlrev_b32_e32 v217, 16, v185
	v_and_b32_e32 v185, 0xffff0000, v185
	v_fmac_f32_e32 v110, s45, v216
	v_fmac_f32_e32 v111, s45, v184
	v_fmac_f32_e32 v112, s45, v217
	v_fmac_f32_e32 v113, s45, v185
	v_lshlrev_b32_e32 v216, 16, v186
	v_and_b32_e32 v186, 0xffff0000, v186
	v_lshlrev_b32_e32 v217, 16, v187
	v_and_b32_e32 v187, 0xffff0000, v187
	v_fmac_f32_e32 v78, s45, v216
	v_fmac_f32_e32 v79, s45, v186
	v_fmac_f32_e32 v80, s45, v217
	v_fmac_f32_e32 v81, s45, v187
	v_mov_b32_dpp v220, v78 quad_perm:[1,0,3,2] row_mask:0xf bank_mask:0xf
	v_mov_b32_dpp v221, v79 quad_perm:[1,0,3,2] row_mask:0xf bank_mask:0xf
	v_mov_b32_dpp v222, v80 quad_perm:[1,0,3,2] row_mask:0xf bank_mask:0xf
	v_mov_b32_dpp v223, v81 quad_perm:[1,0,3,2] row_mask:0xf bank_mask:0xf
	v_mov_b32_dpp v224, v110 quad_perm:[1,0,3,2] row_mask:0xf bank_mask:0xf
	v_mov_b32_dpp v225, v111 quad_perm:[1,0,3,2] row_mask:0xf bank_mask:0xf
	v_mov_b32_dpp v226, v112 quad_perm:[1,0,3,2] row_mask:0xf bank_mask:0xf
	v_mov_b32_dpp v227, v113 quad_perm:[1,0,3,2] row_mask:0xf bank_mask:0xf
	v_cndmask_b32_e32 v78, v224, v78, vcc
	v_cndmask_b32_e32 v79, v225, v79, vcc
	v_cndmask_b32_e32 v80, v226, v80, vcc
	v_cndmask_b32_e32 v81, v227, v81, vcc
	v_cndmask_b32_e32 v110, v110, v220, vcc
	v_cndmask_b32_e32 v111, v111, v221, vcc
	v_cndmask_b32_e32 v112, v112, v222, vcc
	v_cndmask_b32_e32 v113, v113, v223, vcc
	global_store_dwordx4 v[140:141], v[110:113], off
	global_store_dwordx4 v[142:143], v[78:81], off
	s_waitcnt vmcnt(24)
	v_permlane16_swap_b32_e32 v188, v190
	v_permlane16_swap_b32_e32 v189, v191
	v_lshlrev_b32_e32 v216, 16, v188
	v_and_b32_e32 v188, 0xffff0000, v188
	v_lshlrev_b32_e32 v217, 16, v189
	v_and_b32_e32 v189, 0xffff0000, v189
	v_fmac_f32_e32 v46, s45, v216
	v_fmac_f32_e32 v47, s45, v188
	v_fmac_f32_e32 v48, s45, v217
	v_fmac_f32_e32 v49, s45, v189
	v_lshlrev_b32_e32 v216, 16, v190
	v_and_b32_e32 v190, 0xffff0000, v190
	v_lshlrev_b32_e32 v217, 16, v191
	v_and_b32_e32 v191, 0xffff0000, v191
	v_fmac_f32_e32 v14, s45, v216
	v_fmac_f32_e32 v15, s45, v190
	v_fmac_f32_e32 v16, s45, v217
	v_fmac_f32_e32 v17, s45, v191
	v_mov_b32_dpp v220, v14 quad_perm:[1,0,3,2] row_mask:0xf bank_mask:0xf
	v_mov_b32_dpp v221, v15 quad_perm:[1,0,3,2] row_mask:0xf bank_mask:0xf
	v_mov_b32_dpp v222, v16 quad_perm:[1,0,3,2] row_mask:0xf bank_mask:0xf
	v_mov_b32_dpp v223, v17 quad_perm:[1,0,3,2] row_mask:0xf bank_mask:0xf
	v_mov_b32_dpp v224, v46 quad_perm:[1,0,3,2] row_mask:0xf bank_mask:0xf
	v_mov_b32_dpp v225, v47 quad_perm:[1,0,3,2] row_mask:0xf bank_mask:0xf
	v_mov_b32_dpp v226, v48 quad_perm:[1,0,3,2] row_mask:0xf bank_mask:0xf
	v_mov_b32_dpp v227, v49 quad_perm:[1,0,3,2] row_mask:0xf bank_mask:0xf
	v_cndmask_b32_e32 v14, v224, v14, vcc
	v_cndmask_b32_e32 v15, v225, v15, vcc
	v_cndmask_b32_e32 v16, v226, v16, vcc
	v_cndmask_b32_e32 v17, v227, v17, vcc
	v_cndmask_b32_e32 v46, v46, v220, vcc
	v_cndmask_b32_e32 v47, v47, v221, vcc
	v_cndmask_b32_e32 v48, v48, v222, vcc
	v_cndmask_b32_e32 v49, v49, v223, vcc
	global_store_dwordx4 v[140:141], v[46:49], off offset:128
	global_store_dwordx4 v[142:143], v[14:17], off offset:128
	v_lshl_add_u64 v[140:141], v[140:141], 0, s[10:11]
	v_lshl_add_u64 v[142:143], v[142:143], 0, s[10:11]
	s_waitcnt vmcnt(25)
; DEVI float blo(unsigned u) { return __uint_as_float(u << 16); }
; DEVI float bhi(unsigned u) { return __uint_as_float(u & 0xffff0000u); }
;     ...
; #pragma unroll
;       for (int nf = 0; nf < 4; nf++) {
;         const int col = n0 + wn * 64 + nf * 16 + quad * 4;
;         f32x4 a = acc[nf][mf];
;         if (EPI == EPI_RESID || EPI == EPI_RESID_ATOMIC) {
;           f32x4 x = a;
;           if (EPI == EPI_RESID || kpart == 0) {
;             const u32x2 xr = *(const u32x2*)((const u16*)(p.ws + WS_XB) + (size_t)row * 1024 + col);
;             x[0] += ALPHA * blo(xr[0]); x[1] += ALPHA * bhi(xr[0]); x[2] += ALPHA * blo(xr[1]); x[3] += ALPHA * bhi(xr[1]);
;           }
;           if (EPI == EPI_RESID) *(f32x4*)((float*)(p.ws + WS_XF) + (size_t)row * 1024 + col) = x;
;           else *(f32x4*)((float*)(p.ws + WS_SLAB) + ((size_t)kpart * 512 + (row - T_P)) * 1024 + col) = x;
	v_permlane16_swap_b32_e32 v192, v194
	v_permlane16_swap_b32_e32 v193, v195
	v_lshlrev_b32_e32 v216, 16, v192
	v_and_b32_e32 v192, 0xffff0000, v192
	v_lshlrev_b32_e32 v217, 16, v193
	v_and_b32_e32 v193, 0xffff0000, v193
	v_fmac_f32_e32 v106, s45, v216
	v_fmac_f32_e32 v107, s45, v192
	v_fmac_f32_e32 v108, s45, v217
	v_fmac_f32_e32 v109, s45, v193
	v_lshlrev_b32_e32 v216, 16, v194
	v_and_b32_e32 v194, 0xffff0000, v194
	v_lshlrev_b32_e32 v217, 16, v195
	v_and_b32_e32 v195, 0xffff0000, v195
	v_fmac_f32_e32 v74, s45, v216
	v_fmac_f32_e32 v75, s45, v194
	v_fmac_f32_e32 v76, s45, v217
	v_fmac_f32_e32 v77, s45, v195
	v_mov_b32_dpp v220, v74 quad_perm:[1,0,3,2] row_mask:0xf bank_mask:0xf
	v_mov_b32_dpp v221, v75 quad_perm:[1,0,3,2] row_mask:0xf bank_mask:0xf
	v_mov_b32_dpp v222, v76 quad_perm:[1,0,3,2] row_mask:0xf bank_mask:0xf
	v_mov_b32_dpp v223, v77 quad_perm:[1,0,3,2] row_mask:0xf bank_mask:0xf
	v_mov_b32_dpp v224, v106 quad_perm:[1,0,3,2] row_mask:0xf bank_mask:0xf
	v_mov_b32_dpp v225, v107 quad_perm:[1,0,3,2] row_mask:0xf bank_mask:0xf
	v_mov_b32_dpp v226, v108 quad_perm:[1,0,3,2] row_mask:0xf bank_mask:0xf
	v_mov_b32_dpp v227, v109 quad_perm:[1,0,3,2] row_mask:0xf bank_mask:0xf
	v_cndmask_b32_e32 v74, v224, v74, vcc
	v_cndmask_b32_e32 v75, v225, v75, vcc
	v_cndmask_b32_e32 v76, v226, v76, vcc
	v_cndmask_b32_e32 v77, v227, v77, vcc
	v_cndmask_b32_e32 v106, v106, v220, vcc
	v_cndmask_b32_e32 v107, v107, v221, vcc
	v_cndmask_b32_e32 v108, v108, v222, vcc
	v_cndmask_b32_e32 v109, v109, v223, vcc
	global_store_dwordx4 v[140:141], v[106:109], off
	global_store_dwordx4 v[142:143], v[74:77], off
	s_waitcnt vmcnt(26)
	v_permlane16_swap_b32_e32 v196, v198
	v_permlane16_swap_b32_e32 v197, v199
	v_lshlrev_b32_e32 v216, 16, v196
	v_and_b32_e32 v196, 0xffff0000, v196
	v_lshlrev_b32_e32 v217, 16, v197
	v_and_b32_e32 v197, 0xffff0000, v197
	v_fmac_f32_e32 v42, s45, v216
	v_fmac_f32_e32 v43, s45, v196
	v_fmac_f32_e32 v44, s45, v217
	v_fmac_f32_e32 v45, s45, v197
	v_lshlrev_b32_e32 v216, 16, v198
	v_and_b32_e32 v198, 0xffff0000, v198
	v_lshlrev_b32_e32 v217, 16, v199
	v_and_b32_e32 v199, 0xffff0000, v199
	v_fmac_f32_e32 v10, s45, v216
	v_fmac_f32_e32 v11, s45, v198
	v_fmac_f32_e32 v12, s45, v217
	v_fmac_f32_e32 v13, s45, v199
	v_mov_b32_dpp v220, v10 quad_perm:[1,0,3,2] row_mask:0xf bank_mask:0xf
	v_mov_b32_dpp v221, v11 quad_perm:[1,0,3,2] row_mask:0xf bank_mask:0xf
	v_mov_b32_dpp v222, v12 quad_perm:[1,0,3,2] row_mask:0xf bank_mask:0xf
	v_mov_b32_dpp v223, v13 quad_perm:[1,0,3,2] row_mask:0xf bank_mask:0xf
	v_mov_b32_dpp v224, v42 quad_perm:[1,0,3,2] row_mask:0xf bank_mask:0xf
	v_mov_b32_dpp v225, v43 quad_perm:[1,0,3,2] row_mask:0xf bank_mask:0xf
	v_mov_b32_dpp v226, v44 quad_perm:[1,0,3,2] row_mask:0xf bank_mask:0xf
	v_mov_b32_dpp v227, v45 quad_perm:[1,0,3,2] row_mask:0xf bank_mask:0xf
	v_cndmask_b32_e32 v10, v224, v10, vcc
	v_cndmask_b32_e32 v11, v225, v11, vcc
	v_cndmask_b32_e32 v12, v226, v12, vcc
	v_cndmask_b32_e32 v13, v227, v13, vcc
	v_cndmask_b32_e32 v42, v42, v220, vcc
	v_cndmask_b32_e32 v43, v43, v221, vcc
	v_cndmask_b32_e32 v44, v44, v222, vcc
	v_cndmask_b32_e32 v45, v45, v223, vcc
	global_store_dwordx4 v[140:141], v[42:45], off offset:128
	global_store_dwordx4 v[142:143], v[10:13], off offset:128
	v_lshl_add_u64 v[140:141], v[140:141], 0, s[10:11]
	v_lshl_add_u64 v[142:143], v[142:143], 0, s[10:11]
	s_waitcnt vmcnt(27)
	v_permlane16_swap_b32_e32 v200, v202
	v_permlane16_swap_b32_e32 v201, v203
	v_lshlrev_b32_e32 v216, 16, v200
	v_and_b32_e32 v200, 0xffff0000, v200
	v_lshlrev_b32_e32 v217, 16, v201
	v_and_b32_e32 v201, 0xffff0000, v201
	v_fmac_f32_e32 v102, s45, v216
	v_fmac_f32_e32 v103, s45, v200
	v_fmac_f32_e32 v104, s45, v217
	v_fmac_f32_e32 v105, s45, v201
	v_lshlrev_b32_e32 v216, 16, v202
	v_and_b32_e32 v202, 0xffff0000, v202
	v_lshlrev_b32_e32 v217, 16, v203
	v_and_b32_e32 v203, 0xffff0000, v203
	v_fmac_f32_e32 v70, s45, v216
	v_fmac_f32_e32 v71, s45, v202
	v_fmac_f32_e32 v72, s45, v217
	v_fmac_f32_e32 v73, s45, v203
	v_mov_b32_dpp v220, v70 quad_perm:[1,0,3,2] row_mask:0xf bank_mask:0xf
	v_mov_b32_dpp v221, v71 quad_perm:[1,0,3,2] row_mask:0xf bank_mask:0xf
	v_mov_b32_dpp v222, v72 quad_perm:[1,0,3,2] row_mask:0xf bank_mask:0xf
	v_mov_b32_dpp v223, v73 quad_perm:[1,0,3,2] row_mask:0xf bank_mask:0xf
	v_mov_b32_dpp v224, v102 quad_perm:[1,0,3,2] row_mask:0xf bank_mask:0xf
	v_mov_b32_dpp v225, v103 quad_perm:[1,0,3,2] row_mask:0xf bank_mask:0xf
	v_mov_b32_dpp v226, v104 quad_perm:[1,0,3,2] row_mask:0xf bank_mask:0xf
	v_mov_b32_dpp v227, v105 quad_perm:[1,0,3,2] row_mask:0xf bank_mask:0xf
	v_cndmask_b32_e32 v70, v224, v70, vcc
	v_cndmask_b32_e32 v71, v225, v71, vcc
	v_cndmask_b32_e32 v72, v226, v72, vcc
	v_cndmask_b32_e32 v73, v227, v73, vcc
	v_cndmask_b32_e32 v102, v102, v220, vcc
	v_cndmask_b32_e32 v103, v103, v221, vcc
	v_cndmask_b32_e32 v104, v104, v222, vcc
	v_cndmask_b32_e32 v105, v105, v223, vcc
	global_store_dwordx4 v[140:141], v[102:105], off
	global_store_dwordx4 v[142:143], v[70:73], off
	s_waitcnt vmcnt(28)
; DEVI float blo(unsigned u) { return __uint_as_float(u << 16); }
; DEVI float bhi(unsigned u) { return __uint_as_float(u & 0xffff0000u); }
;     ...
; #pragma unroll
;       for (int nf = 0; nf < 4; nf++) {
;         const int col = n0 + wn * 64 + nf * 16 + quad * 4;
;         f32x4 a = acc[nf][mf];
;         if (EPI == EPI_RESID || EPI == EPI_RESID_ATOMIC) {
;           f32x4 x = a;
;           if (EPI == EPI_RESID || kpart == 0) {
;             const u32x2 xr = *(const u32x2*)((const u16*)(p.ws + WS_XB) + (size_t)row * 1024 + col);
;             x[0] += ALPHA * blo(xr[0]); x[1] += ALPHA * bhi(xr[0]); x[2] += ALPHA * blo(xr[1]); x[3] += ALPHA * bhi(xr[1]);
;           }
;           if (EPI == EPI_RESID) *(f32x4*)((float*)(p.ws + WS_XF) + (size_t)row * 1024 + col) = x;
;           else *(f32x4*)((float*)(p.ws + WS_SLAB) + ((size_t)kpart * 512 + (row - T_P)) * 1024 + col) = x;
	v_permlane16_swap_b32_e32 v204, v206
	v_permlane16_swap_b32_e32 v205, v207
	v_lshlrev_b32_e32 v216, 16, v204
	v_and_b32_e32 v204, 0xffff0000, v204
	v_lshlrev_b32_e32 v217, 16, v205
	v_and_b32_e32 v205, 0xffff0000, v205
	v_fmac_f32_e32 v38, s45, v216
	v_fmac_f32_e32 v39, s45, v204
	v_fmac_f32_e32 v40, s45, v217
	v_fmac_f32_e32 v41, s45, v205
	v_lshlrev_b32_e32 v216, 16, v206
	v_and_b32_e32 v206, 0xffff0000, v206
	v_lshlrev_b32_e32 v217, 16, v207
	v_and_b32_e32 v207, 0xffff0000, v207
	v_fmac_f32_e32 v6, s45, v216
	v_fmac_f32_e32 v7, s45, v206
	v_fmac_f32_e32 v8, s45, v217
	v_fmac_f32_e32 v9, s45, v207
	v_mov_b32_dpp v220, v6 quad_perm:[1,0,3,2] row_mask:0xf bank_mask:0xf
	v_mov_b32_dpp v221, v7 quad_perm:[1,0,3,2] row_mask:0xf bank_mask:0xf
	v_mov_b32_dpp v222, v8 quad_perm:[1,0,3,2] row_mask:0xf bank_mask:0xf
	v_mov_b32_dpp v223, v9 quad_perm:[1,0,3,2] row_mask:0xf bank_mask:0xf
	v_mov_b32_dpp v224, v38 quad_perm:[1,0,3,2] row_mask:0xf bank_mask:0xf
	v_mov_b32_dpp v225, v39 quad_perm:[1,0,3,2] row_mask:0xf bank_mask:0xf
	v_mov_b32_dpp v226, v40 quad_perm:[1,0,3,2] row_mask:0xf bank_mask:0xf
	v_mov_b32_dpp v227, v41 quad_perm:[1,0,3,2] row_mask:0xf bank_mask:0xf
	v_cndmask_b32_e32 v6, v224, v6, vcc
	v_cndmask_b32_e32 v7, v225, v7, vcc
	v_cndmask_b32_e32 v8, v226, v8, vcc
	v_cndmask_b32_e32 v9, v227, v9, vcc
	v_cndmask_b32_e32 v38, v38, v220, vcc
	v_cndmask_b32_e32 v39, v39, v221, vcc
	v_cndmask_b32_e32 v40, v40, v222, vcc
	v_cndmask_b32_e32 v41, v41, v223, vcc
	global_store_dwordx4 v[140:141], v[38:41], off offset:128
	global_store_dwordx4 v[142:143], v[6:9], off offset:128
	v_lshl_add_u64 v[140:141], v[140:141], 0, s[10:11]
	v_lshl_add_u64 v[142:143], v[142:143], 0, s[10:11]
	s_waitcnt vmcnt(29)
	v_permlane16_swap_b32_e32 v208, v210
	v_permlane16_swap_b32_e32 v209, v211
	v_lshlrev_b32_e32 v216, 16, v208
	v_and_b32_e32 v208, 0xffff0000, v208
	v_lshlrev_b32_e32 v217, 16, v209
	v_and_b32_e32 v209, 0xffff0000, v209
	v_fmac_f32_e32 v98, s45, v216
	v_fmac_f32_e32 v99, s45, v208
	v_fmac_f32_e32 v100, s45, v217
	v_fmac_f32_e32 v101, s45, v209
	v_lshlrev_b32_e32 v216, 16, v210
	v_and_b32_e32 v210, 0xffff0000, v210
	v_lshlrev_b32_e32 v217, 16, v211
	v_and_b32_e32 v211, 0xffff0000, v211
	v_fmac_f32_e32 v66, s45, v216
	v_fmac_f32_e32 v67, s45, v210
	v_fmac_f32_e32 v68, s45, v217
	v_fmac_f32_e32 v69, s45, v211
	v_mov_b32_dpp v220, v66 quad_perm:[1,0,3,2] row_mask:0xf bank_mask:0xf
	v_mov_b32_dpp v221, v67 quad_perm:[1,0,3,2] row_mask:0xf bank_mask:0xf
	v_mov_b32_dpp v222, v68 quad_perm:[1,0,3,2] row_mask:0xf bank_mask:0xf
	v_mov_b32_dpp v223, v69 quad_perm:[1,0,3,2] row_mask:0xf bank_mask:0xf
	v_mov_b32_dpp v224, v98 quad_perm:[1,0,3,2] row_mask:0xf bank_mask:0xf
	v_mov_b32_dpp v225, v99 quad_perm:[1,0,3,2] row_mask:0xf bank_mask:0xf
	v_mov_b32_dpp v226, v100 quad_perm:[1,0,3,2] row_mask:0xf bank_mask:0xf
	v_mov_b32_dpp v227, v101 quad_perm:[1,0,3,2] row_mask:0xf bank_mask:0xf
	v_cndmask_b32_e32 v66, v224, v66, vcc
	v_cndmask_b32_e32 v67, v225, v67, vcc
	v_cndmask_b32_e32 v68, v226, v68, vcc
	v_cndmask_b32_e32 v69, v227, v69, vcc
	v_cndmask_b32_e32 v98, v98, v220, vcc
	v_cndmask_b32_e32 v99, v99, v221, vcc
	v_cndmask_b32_e32 v100, v100, v222, vcc
	v_cndmask_b32_e32 v101, v101, v223, vcc
	global_store_dwordx4 v[140:141], v[98:101], off
	global_store_dwordx4 v[142:143], v[66:69], off
	s_waitcnt vmcnt(30)
	v_permlane16_swap_b32_e32 v212, v214
	v_permlane16_swap_b32_e32 v213, v215
	v_lshlrev_b32_e32 v216, 16, v212
	v_and_b32_e32 v212, 0xffff0000, v212
	v_lshlrev_b32_e32 v217, 16, v213
	v_and_b32_e32 v213, 0xffff0000, v213
	v_fmac_f32_e32 v34, s45, v216
	v_fmac_f32_e32 v35, s45, v212
	v_fmac_f32_e32 v36, s45, v217
	v_fmac_f32_e32 v37, s45, v213
	v_lshlrev_b32_e32 v216, 16, v214
	v_and_b32_e32 v214, 0xffff0000, v214
	v_lshlrev_b32_e32 v217, 16, v215
	v_and_b32_e32 v215, 0xffff0000, v215
	v_fmac_f32_e32 v2, s45, v216
	v_fmac_f32_e32 v3, s45, v214
	v_fmac_f32_e32 v4, s45, v217
	v_fmac_f32_e32 v5, s45, v215
	v_mov_b32_dpp v220, v2 quad_perm:[1,0,3,2] row_mask:0xf bank_mask:0xf
	v_mov_b32_dpp v221, v3 quad_perm:[1,0,3,2] row_mask:0xf bank_mask:0xf
	v_mov_b32_dpp v222, v4 quad_perm:[1,0,3,2] row_mask:0xf bank_mask:0xf
	v_mov_b32_dpp v223, v5 quad_perm:[1,0,3,2] row_mask:0xf bank_mask:0xf
	v_mov_b32_dpp v224, v34 quad_perm:[1,0,3,2] row_mask:0xf bank_mask:0xf
	v_mov_b32_dpp v225, v35 quad_perm:[1,0,3,2] row_mask:0xf bank_mask:0xf
	v_mov_b32_dpp v226, v36 quad_perm:[1,0,3,2] row_mask:0xf bank_mask:0xf
	v_mov_b32_dpp v227, v37 quad_perm:[1,0,3,2] row_mask:0xf bank_mask:0xf
	v_cndmask_b32_e32 v2, v224, v2, vcc
	v_cndmask_b32_e32 v3, v225, v3, vcc
	v_cndmask_b32_e32 v4, v226, v4, vcc
	v_cndmask_b32_e32 v5, v227, v5, vcc
	v_cndmask_b32_e32 v34, v34, v220, vcc
	v_cndmask_b32_e32 v35, v35, v221, vcc
	v_cndmask_b32_e32 v36, v36, v222, vcc
	v_cndmask_b32_e32 v37, v37, v223, vcc
	global_store_dwordx4 v[140:141], v[34:37], off offset:128
	global_store_dwordx4 v[142:143], v[2:5], off offset:128
	v_readlane_b32 s40, v250, 7
	s_cmpk_lg_u32 s40, 0x200
	s_cbranch_scc1 .LBB0_757
	v_readlane_b32 s41, v250, 0
	s_lshr_b32 s42, s41, 3
	s_and_b32 s41, s41, 7
	s_mul_i32 s41, s41, 16
	s_add_i32 s41, s41, s42
	s_cmp_lt_u32 s42, 16
	s_movk_i32 s39, 0x4000
	s_branch .LBB0_757

;     ...
;   __syncthreads();
;   G2_STAGE(0); G2_STAGE(1);
;   const int fsw = (0x78 >> (((r16 >> 2) & 3) * 2)) & 3;
;   const int aoff = (wm * 128 + r16) * 64 + ((quad ^ fsw) << 4);
;   const int boff = 16384 + (wn * 64 + r16) * 64 + ((quad ^ fsw) << 4);
;   for (int kt = 0; kt < nk; kt++) {
;     if (kt + 1 < nk) asm volatile("s_waitcnt vmcnt(6)" ::: "memory");
;     else asm volatile("s_waitcnt vmcnt(0)" ::: "memory");
;     __builtin_amdgcn_s_barrier();
;     asm volatile("" ::: "memory");
;     if (kt + 2 < nk) G2_STAGE(kt + 2);
;     const char* cS = smem + (kt % 3) * 24576;
;     bf16x8 xa[8], wb[4];
; #pragma unroll
;     for (int f = 0; f < 8; f++) xa[f] = *(const bf16x8*)(cS + aoff + f * 1024);
; #pragma unroll
;     for (int f = 0; f < 4; f++) wb[f] = *(const bf16x8*)(cS + boff + f * 1024);
; #pragma unroll
;     for (int nf = 0; nf < 4; nf++)
; #pragma unroll
;       for (int mf = 0; mf < 8; mf++)
;         acc[nf][mf] = __builtin_amdgcn_mfma_f32_16x16x32_bf16(wb[nf], xa[mf], acc[nf][mf], 0, 0, 0);
;   }
.Lt0_loop:
	.p2align 3
	s_waitcnt vmcnt(6) lgkmcnt(0)
	s_barrier
	s_setprio 1
	v_add_u32_e32 v144, s38, v136
	v_mfma_f32_16x16x32_bf16 v[126:129], v[184:187], v[146:149], v[126:129]
	ds_read_b128 v[200:203], v144 offset:0
	v_mfma_f32_16x16x32_bf16 v[122:125], v[184:187], v[152:155], v[122:125]
	ds_read_b128 v[204:207], v144 offset:1024
	v_mfma_f32_16x16x32_bf16 v[118:121], v[184:187], v[156:159], v[118:121]
	ds_read_b128 v[208:211], v144 offset:2048
	v_mfma_f32_16x16x32_bf16 v[114:117], v[184:187], v[162:165], v[114:117]
	ds_read_b128 v[212:215], v144 offset:3072
	v_mfma_f32_16x16x32_bf16 v[110:113], v[184:187], v[166:169], v[110:113]
	ds_read_b128 v[216:219], v144 offset:4096
	v_mfma_f32_16x16x32_bf16 v[106:109], v[184:187], v[170:173], v[106:109]
	ds_read_b128 v[220:223], v144 offset:5120
	v_mfma_f32_16x16x32_bf16 v[102:105], v[184:187], v[176:179], v[102:105]
	ds_read_b128 v[224:227], v144 offset:6144
	v_mfma_f32_16x16x32_bf16 v[98:101], v[184:187], v[180:183], v[98:101]
	ds_read_b128 v[228:231], v144 offset:7168
	v_mfma_f32_16x16x32_bf16 v[94:97], v[188:191], v[146:149], v[94:97]
	v_add_u32_e64 v144, s38, v137
	v_mfma_f32_16x16x32_bf16 v[90:93], v[188:191], v[152:155], v[90:93]
	v_mfma_f32_16x16x32_bf16 v[86:89], v[188:191], v[156:159], v[86:89]
	ds_read_b128 v[232:235], v144 offset:16384
	v_mfma_f32_16x16x32_bf16 v[82:85], v[188:191], v[162:165], v[82:85]
	ds_read_b128 v[236:239], v144 offset:17408
	v_mfma_f32_16x16x32_bf16 v[78:81], v[188:191], v[166:169], v[78:81]
	ds_read_b128 v[240:243], v144 offset:18432
	s_setprio 2
	s_nop 0
	v_mfma_f32_16x16x32_bf16 v[74:77], v[188:191], v[170:173], v[74:77]
	ds_read_b128 v[244:247], v144 offset:19456
	v_mfma_f32_16x16x32_bf16 v[70:73], v[188:191], v[176:179], v[70:73]
	s_add_i32 s40, s44, s39
	s_mov_b32 m0, s40
	v_lshl_add_u64 v[142:143], v[132:133], 0, s[2:3]
	v_mfma_f32_16x16x32_bf16 v[66:69], v[188:191], v[180:183], v[66:69]
	global_load_lds_dwordx4 v[132:133], off
	s_add_i32 m0, m0, 0x1000
	v_mfma_f32_16x16x32_bf16 v[62:65], v[192:195], v[146:149], v[62:65]
	v_mfma_f32_16x16x32_bf16 v[58:61], v[192:195], v[152:155], v[58:61]
	v_mfma_f32_16x16x32_bf16 v[54:57], v[192:195], v[156:159], v[54:57]
	global_load_lds_dwordx4 v[142:143], off
	v_lshl_add_u64 v[142:143], v[142:143], 0, s[2:3]
	s_add_i32 m0, m0, 0x1000
	v_mfma_f32_16x16x32_bf16 v[50:53], v[192:195], v[162:165], v[50:53]
	v_mfma_f32_16x16x32_bf16 v[46:49], v[192:195], v[166:169], v[46:49]
	v_mfma_f32_16x16x32_bf16 v[42:45], v[192:195], v[170:173], v[42:45]
	global_load_lds_dwordx4 v[142:143], off
	v_lshl_add_u64 v[142:143], v[142:143], 0, s[2:3]
	s_add_i32 m0, m0, 0x1000
	v_mfma_f32_16x16x32_bf16 v[38:41], v[192:195], v[176:179], v[38:41]
	v_mfma_f32_16x16x32_bf16 v[34:37], v[192:195], v[180:183], v[34:37]
	s_setprio 0
	s_nop 0
	v_mfma_f32_16x16x32_bf16 v[30:33], v[196:199], v[146:149], v[30:33]
	global_load_lds_dwordx4 v[142:143], off
	s_add_i32 m0, m0, 0x1000
	v_lshl_add_u64 v[142:143], v[134:135], 0, s[2:3]
	v_mfma_f32_16x16x32_bf16 v[26:29], v[196:199], v[152:155], v[26:29]
	v_mfma_f32_16x16x32_bf16 v[22:25], v[196:199], v[156:159], v[22:25]
	v_mfma_f32_16x16x32_bf16 v[18:21], v[196:199], v[162:165], v[18:21]
	global_load_lds_dwordx4 v[134:135], off
	s_add_i32 m0, m0, 0x1000
	v_lshl_add_u64 v[132:133], v[132:133], 0, s[36:37]
	v_mfma_f32_16x16x32_bf16 v[14:17], v[196:199], v[166:169], v[14:17]
	v_mfma_f32_16x16x32_bf16 v[10:13], v[196:199], v[170:173], v[10:13]
	v_mfma_f32_16x16x32_bf16 v[6:9], v[196:199], v[176:179], v[6:9]
	global_load_lds_dwordx4 v[142:143], off
	v_lshl_add_u64 v[134:135], v[134:135], 0, s[8:9]
	v_mfma_f32_16x16x32_bf16 v[2:5], v[196:199], v[180:183], v[2:5]
	s_mov_b32 s39, s38
	s_nop 0
	s_add_i32 s38, s38, 0x6000
	s_cmp_eq_u32 s38, 0x12000
	s_cselect_b32 s38, 0, s38
	s_nop 0
	.p2align 3
	s_waitcnt vmcnt(6) lgkmcnt(0)
	s_barrier
	s_setprio 1
	v_add_u32_e32 v144, s38, v136
	v_mfma_f32_16x16x32_bf16 v[126:129], v[232:235], v[200:203], v[126:129]
	ds_read_b128 v[146:149], v144 offset:0
	v_mfma_f32_16x16x32_bf16 v[122:125], v[232:235], v[204:207], v[122:125]
	ds_read_b128 v[152:155], v144 offset:1024
	v_mfma_f32_16x16x32_bf16 v[118:121], v[232:235], v[208:211], v[118:121]
	ds_read_b128 v[156:159], v144 offset:2048
	v_mfma_f32_16x16x32_bf16 v[114:117], v[232:235], v[212:215], v[114:117]
	ds_read_b128 v[162:165], v144 offset:3072
	v_mfma_f32_16x16x32_bf16 v[110:113], v[232:235], v[216:219], v[110:113]
	ds_read_b128 v[166:169], v144 offset:4096
	v_mfma_f32_16x16x32_bf16 v[106:109], v[232:235], v[220:223], v[106:109]
	ds_read_b128 v[170:173], v144 offset:5120
	v_mfma_f32_16x16x32_bf16 v[102:105], v[232:235], v[224:227], v[102:105]
	ds_read_b128 v[176:179], v144 offset:6144
	v_mfma_f32_16x16x32_bf16 v[98:101], v[232:235], v[228:231], v[98:101]
	ds_read_b128 v[180:183], v144 offset:7168
	v_mfma_f32_16x16x32_bf16 v[94:97], v[236:239], v[200:203], v[94:97]
	v_add_u32_e64 v144, s38, v137
	v_mfma_f32_16x16x32_bf16 v[90:93], v[236:239], v[204:207], v[90:93]
	v_mfma_f32_16x16x32_bf16 v[86:89], v[236:239], v[208:211], v[86:89]
	ds_read_b128 v[184:187], v144 offset:16384
	v_mfma_f32_16x16x32_bf16 v[82:85], v[236:239], v[212:215], v[82:85]
	ds_read_b128 v[188:191], v144 offset:17408
	v_mfma_f32_16x16x32_bf16 v[78:81], v[236:239], v[216:219], v[78:81]
	ds_read_b128 v[192:195], v144 offset:18432
	s_setprio 2
	s_nop 0
	v_mfma_f32_16x16x32_bf16 v[74:77], v[236:239], v[220:223], v[74:77]
	ds_read_b128 v[196:199], v144 offset:19456
	v_mfma_f32_16x16x32_bf16 v[70:73], v[236:239], v[224:227], v[70:73]
	s_add_i32 s40, s44, s39
	s_mov_b32 m0, s40
	v_lshl_add_u64 v[142:143], v[132:133], 0, s[2:3]
	v_mfma_f32_16x16x32_bf16 v[66:69], v[236:239], v[228:231], v[66:69]
;     ...
;   __syncthreads();
;   G2_STAGE(0); G2_STAGE(1);
;   const int fsw = (0x78 >> (((r16 >> 2) & 3) * 2)) & 3;
;   const int aoff = (wm * 128 + r16) * 64 + ((quad ^ fsw) << 4);
;   const int boff = 16384 + (wn * 64 + r16) * 64 + ((quad ^ fsw) << 4);
;   for (int kt = 0; kt < nk; kt++) {
;     if (kt + 1 < nk) asm volatile("s_waitcnt vmcnt(6)" ::: "memory");
;     else asm volatile("s_waitcnt vmcnt(0)" ::: "memory");
;     __builtin_amdgcn_s_barrier();
;     asm volatile("" ::: "memory");
;     if (kt + 2 < nk) G2_STAGE(kt + 2);
;     const char* cS = smem + (kt % 3) * 24576;
;     bf16x8 xa[8], wb[4];
; #pragma unroll
;     for (int f = 0; f < 8; f++) xa[f] = *(const bf16x8*)(cS + aoff + f * 1024);
; #pragma unroll
;     for (int f = 0; f < 4; f++) wb[f] = *(const bf16x8*)(cS + boff + f * 1024);
; #pragma unroll
;     for (int nf = 0; nf < 4; nf++)
; #pragma unroll
;       for (int mf = 0; mf < 8; mf++)
;         acc[nf][mf] = __builtin_amdgcn_mfma_f32_16x16x32_bf16(wb[nf], xa[mf], acc[nf][mf], 0, 0, 0);
;   }
	global_load_lds_dwordx4 v[132:133], off
	s_add_i32 m0, m0, 0x1000
	v_mfma_f32_16x16x32_bf16 v[62:65], v[240:243], v[200:203], v[62:65]
	v_mfma_f32_16x16x32_bf16 v[58:61], v[240:243], v[204:207], v[58:61]
	v_mfma_f32_16x16x32_bf16 v[54:57], v[240:243], v[208:211], v[54:57]
	global_load_lds_dwordx4 v[142:143], off
	v_lshl_add_u64 v[142:143], v[142:143], 0, s[2:3]
	s_add_i32 m0, m0, 0x1000
	v_mfma_f32_16x16x32_bf16 v[50:53], v[240:243], v[212:215], v[50:53]
	v_mfma_f32_16x16x32_bf16 v[46:49], v[240:243], v[216:219], v[46:49]
	v_mfma_f32_16x16x32_bf16 v[42:45], v[240:243], v[220:223], v[42:45]
	global_load_lds_dwordx4 v[142:143], off
	v_lshl_add_u64 v[142:143], v[142:143], 0, s[2:3]
	s_add_i32 m0, m0, 0x1000
	v_mfma_f32_16x16x32_bf16 v[38:41], v[240:243], v[224:227], v[38:41]
	v_mfma_f32_16x16x32_bf16 v[34:37], v[240:243], v[228:231], v[34:37]
	s_setprio 0
	s_nop 0
	v_mfma_f32_16x16x32_bf16 v[30:33], v[244:247], v[200:203], v[30:33]
	global_load_lds_dwordx4 v[142:143], off
	s_add_i32 m0, m0, 0x1000
	v_lshl_add_u64 v[142:143], v[134:135], 0, s[2:3]
	v_mfma_f32_16x16x32_bf16 v[26:29], v[244:247], v[204:207], v[26:29]
	v_mfma_f32_16x16x32_bf16 v[22:25], v[244:247], v[208:211], v[22:25]
	v_mfma_f32_16x16x32_bf16 v[18:21], v[244:247], v[212:215], v[18:21]
	global_load_lds_dwordx4 v[134:135], off
	s_add_i32 m0, m0, 0x1000
	v_lshl_add_u64 v[132:133], v[132:133], 0, s[36:37]
	v_mfma_f32_16x16x32_bf16 v[14:17], v[244:247], v[216:219], v[14:17]
	v_mfma_f32_16x16x32_bf16 v[10:13], v[244:247], v[220:223], v[10:13]
	v_mfma_f32_16x16x32_bf16 v[6:9], v[244:247], v[224:227], v[6:9]
	global_load_lds_dwordx4 v[142:143], off
	v_lshl_add_u64 v[134:135], v[134:135], 0, s[8:9]
	v_mfma_f32_16x16x32_bf16 v[2:5], v[244:247], v[228:231], v[2:5]
	s_mov_b32 s39, s38
	s_nop 0
	s_add_i32 s38, s38, 0x6000
	s_cmp_eq_u32 s38, 0x12000
	s_cselect_b32 s38, 0, s38
	s_nop 0
	s_sub_i32 s15, s15, 1
	s_cmp_lg_u32 s15, 0
	s_cbranch_scc1 .Lt0_loop
	.p2align 3
	s_waitcnt vmcnt(6) lgkmcnt(0)
	s_barrier
	s_setprio 1
	v_add_u32_e32 v144, s38, v136
	v_mfma_f32_16x16x32_bf16 v[126:129], v[184:187], v[146:149], v[126:129]
	ds_read_b128 v[200:203], v144 offset:0
	v_mfma_f32_16x16x32_bf16 v[122:125], v[184:187], v[152:155], v[122:125]
	ds_read_b128 v[204:207], v144 offset:1024
	v_mfma_f32_16x16x32_bf16 v[118:121], v[184:187], v[156:159], v[118:121]
	ds_read_b128 v[208:211], v144 offset:2048
	v_mfma_f32_16x16x32_bf16 v[114:117], v[184:187], v[162:165], v[114:117]
	ds_read_b128 v[212:215], v144 offset:3072
	v_mfma_f32_16x16x32_bf16 v[110:113], v[184:187], v[166:169], v[110:113]
	ds_read_b128 v[216:219], v144 offset:4096
	v_mfma_f32_16x16x32_bf16 v[106:109], v[184:187], v[170:173], v[106:109]
	ds_read_b128 v[220:223], v144 offset:5120
	v_mfma_f32_16x16x32_bf16 v[102:105], v[184:187], v[176:179], v[102:105]
	ds_read_b128 v[224:227], v144 offset:6144
	v_mfma_f32_16x16x32_bf16 v[98:101], v[184:187], v[180:183], v[98:101]
	ds_read_b128 v[228:231], v144 offset:7168
	v_mfma_f32_16x16x32_bf16 v[94:97], v[188:191], v[146:149], v[94:97]
	v_add_u32_e64 v144, s38, v137
	v_mfma_f32_16x16x32_bf16 v[90:93], v[188:191], v[152:155], v[90:93]
	v_mfma_f32_16x16x32_bf16 v[86:89], v[188:191], v[156:159], v[86:89]
	ds_read_b128 v[232:235], v144 offset:16384
	v_mfma_f32_16x16x32_bf16 v[82:85], v[188:191], v[162:165], v[82:85]
	ds_read_b128 v[236:239], v144 offset:17408
	v_mfma_f32_16x16x32_bf16 v[78:81], v[188:191], v[166:169], v[78:81]
	ds_read_b128 v[240:243], v144 offset:18432
	s_setprio 2
	s_nop 0
	v_mfma_f32_16x16x32_bf16 v[74:77], v[188:191], v[170:173], v[74:77]
	ds_read_b128 v[244:247], v144 offset:19456
	v_mfma_f32_16x16x32_bf16 v[70:73], v[188:191], v[176:179], v[70:73]
	s_add_i32 s40, s44, s39
	s_mov_b32 m0, s40
	v_lshl_add_u64 v[142:143], v[132:133], 0, s[2:3]
	v_mfma_f32_16x16x32_bf16 v[66:69], v[188:191], v[180:183], v[66:69]
	global_load_lds_dwordx4 v[132:133], off
	s_add_i32 m0, m0, 0x1000
	v_mfma_f32_16x16x32_bf16 v[62:65], v[192:195], v[146:149], v[62:65]
	v_mfma_f32_16x16x32_bf16 v[58:61], v[192:195], v[152:155], v[58:61]
	v_mfma_f32_16x16x32_bf16 v[54:57], v[192:195], v[156:159], v[54:57]
	global_load_lds_dwordx4 v[142:143], off
	v_lshl_add_u64 v[142:143], v[142:143], 0, s[2:3]
	s_add_i32 m0, m0, 0x1000
	v_mfma_f32_16x16x32_bf16 v[50:53], v[192:195], v[162:165], v[50:53]
	v_mfma_f32_16x16x32_bf16 v[46:49], v[192:195], v[166:169], v[46:49]
	v_mfma_f32_16x16x32_bf16 v[42:45], v[192:195], v[170:173], v[42:45]
	global_load_lds_dwordx4 v[142:143], off
	v_lshl_add_u64 v[142:143], v[142:143], 0, s[2:3]
	s_add_i32 m0, m0, 0x1000
	v_mfma_f32_16x16x32_bf16 v[38:41], v[192:195], v[176:179], v[38:41]
	v_mfma_f32_16x16x32_bf16 v[34:37], v[192:195], v[180:183], v[34:37]
	s_setprio 0
	s_nop 0
	v_mfma_f32_16x16x32_bf16 v[30:33], v[196:199], v[146:149], v[30:33]
	global_load_lds_dwordx4 v[142:143], off
	s_add_i32 m0, m0, 0x1000
	v_lshl_add_u64 v[142:143], v[134:135], 0, s[2:3]
	v_mfma_f32_16x16x32_bf16 v[26:29], v[196:199], v[152:155], v[26:29]
	v_mfma_f32_16x16x32_bf16 v[22:25], v[196:199], v[156:159], v[22:25]
	v_mfma_f32_16x16x32_bf16 v[18:21], v[196:199], v[162:165], v[18:21]
	global_load_lds_dwordx4 v[134:135], off
	s_add_i32 m0, m0, 0x1000
	v_lshl_add_u64 v[132:133], v[132:133], 0, s[36:37]
	v_mfma_f32_16x16x32_bf16 v[14:17], v[196:199], v[166:169], v[14:17]
	v_mfma_f32_16x16x32_bf16 v[10:13], v[196:199], v[170:173], v[10:13]
	v_mfma_f32_16x16x32_bf16 v[6:9], v[196:199], v[176:179], v[6:9]
	global_load_lds_dwordx4 v[142:143], off
	v_lshl_add_u64 v[134:135], v[134:135], 0, s[8:9]
	v_mfma_f32_16x16x32_bf16 v[2:5], v[196:199], v[180:183], v[2:5]
	s_mov_b32 s39, s38
	s_nop 0
	s_add_i32 s38, s38, 0x6000
	s_cmp_eq_u32 s38, 0x12000
	s_cselect_b32 s38, 0, s38
	s_nop 0
	.p2align 3
	s_waitcnt vmcnt(6) lgkmcnt(0)
	s_barrier
;     ...
;   for (int kt = 0; kt < nk; kt++) {
;     if (kt + 1 < nk) asm volatile("s_waitcnt vmcnt(6)" ::: "memory");
;     else asm volatile("s_waitcnt vmcnt(0)" ::: "memory");
;     __builtin_amdgcn_s_barrier();
;     asm volatile("" ::: "memory");
;     if (kt + 2 < nk) G2_STAGE(kt + 2);
;     const char* cS = smem + (kt % 3) * 24576;
;     bf16x8 xa[8], wb[4];
; #pragma unroll
;     for (int f = 0; f < 8; f++) xa[f] = *(const bf16x8*)(cS + aoff + f * 1024);
; #pragma unroll
;     for (int f = 0; f < 4; f++) wb[f] = *(const bf16x8*)(cS + boff + f * 1024);
; #pragma unroll
;     for (int nf = 0; nf < 4; nf++)
; #pragma unroll
;       for (int mf = 0; mf < 8; mf++)
;         acc[nf][mf] = __builtin_amdgcn_mfma_f32_16x16x32_bf16(wb[nf], xa[mf], acc[nf][mf], 0, 0, 0);
;   }
	s_setprio 1
	v_add_u32_e32 v144, s38, v136
	v_mfma_f32_16x16x32_bf16 v[126:129], v[232:235], v[200:203], v[126:129]
	ds_read_b128 v[146:149], v144 offset:0
	v_mfma_f32_16x16x32_bf16 v[122:125], v[232:235], v[204:207], v[122:125]
	ds_read_b128 v[152:155], v144 offset:1024
	v_mfma_f32_16x16x32_bf16 v[118:121], v[232:235], v[208:211], v[118:121]
	ds_read_b128 v[156:159], v144 offset:2048
	v_mfma_f32_16x16x32_bf16 v[114:117], v[232:235], v[212:215], v[114:117]
	ds_read_b128 v[162:165], v144 offset:3072
	v_mfma_f32_16x16x32_bf16 v[110:113], v[232:235], v[216:219], v[110:113]
	ds_read_b128 v[166:169], v144 offset:4096
	v_mfma_f32_16x16x32_bf16 v[106:109], v[232:235], v[220:223], v[106:109]
	ds_read_b128 v[170:173], v144 offset:5120
	v_mfma_f32_16x16x32_bf16 v[102:105], v[232:235], v[224:227], v[102:105]
	ds_read_b128 v[176:179], v144 offset:6144
	v_mfma_f32_16x16x32_bf16 v[98:101], v[232:235], v[228:231], v[98:101]
	ds_read_b128 v[180:183], v144 offset:7168
	v_mfma_f32_16x16x32_bf16 v[94:97], v[236:239], v[200:203], v[94:97]
	v_add_u32_e64 v144, s38, v137
	v_mfma_f32_16x16x32_bf16 v[90:93], v[236:239], v[204:207], v[90:93]
	v_mfma_f32_16x16x32_bf16 v[86:89], v[236:239], v[208:211], v[86:89]
	ds_read_b128 v[184:187], v144 offset:16384
	v_mfma_f32_16x16x32_bf16 v[82:85], v[236:239], v[212:215], v[82:85]
	ds_read_b128 v[188:191], v144 offset:17408
	v_mfma_f32_16x16x32_bf16 v[78:81], v[236:239], v[216:219], v[78:81]
	ds_read_b128 v[192:195], v144 offset:18432
	v_mfma_f32_16x16x32_bf16 v[74:77], v[236:239], v[220:223], v[74:77]
	ds_read_b128 v[196:199], v144 offset:19456
	v_mfma_f32_16x16x32_bf16 v[70:73], v[236:239], v[224:227], v[70:73]
	v_mfma_f32_16x16x32_bf16 v[66:69], v[236:239], v[228:231], v[66:69]
	v_mfma_f32_16x16x32_bf16 v[62:65], v[240:243], v[200:203], v[62:65]
	v_mfma_f32_16x16x32_bf16 v[58:61], v[240:243], v[204:207], v[58:61]
	v_mfma_f32_16x16x32_bf16 v[54:57], v[240:243], v[208:211], v[54:57]
	v_mfma_f32_16x16x32_bf16 v[50:53], v[240:243], v[212:215], v[50:53]
	v_mfma_f32_16x16x32_bf16 v[46:49], v[240:243], v[216:219], v[46:49]
	v_mfma_f32_16x16x32_bf16 v[42:45], v[240:243], v[220:223], v[42:45]
	v_mfma_f32_16x16x32_bf16 v[38:41], v[240:243], v[224:227], v[38:41]
	v_mfma_f32_16x16x32_bf16 v[34:37], v[240:243], v[228:231], v[34:37]
	s_setprio 0
	s_nop 0
	v_mfma_f32_16x16x32_bf16 v[30:33], v[244:247], v[200:203], v[30:33]
	v_mfma_f32_16x16x32_bf16 v[26:29], v[244:247], v[204:207], v[26:29]
	v_mfma_f32_16x16x32_bf16 v[22:25], v[244:247], v[208:211], v[22:25]
	v_mfma_f32_16x16x32_bf16 v[18:21], v[244:247], v[212:215], v[18:21]
	v_mfma_f32_16x16x32_bf16 v[14:17], v[244:247], v[216:219], v[14:17]
	v_mfma_f32_16x16x32_bf16 v[10:13], v[244:247], v[220:223], v[10:13]
	v_mfma_f32_16x16x32_bf16 v[6:9], v[244:247], v[224:227], v[6:9]
	v_mfma_f32_16x16x32_bf16 v[2:5], v[244:247], v[228:231], v[2:5]
	s_mov_b32 s39, s38
	s_nop 0
	s_add_i32 s38, s38, 0x6000
	s_cmp_eq_u32 s38, 0x12000
	s_cselect_b32 s38, 0, s38
	s_nop 0
	.p2align 3
	s_waitcnt vmcnt(0) lgkmcnt(0)
	s_barrier
	s_setprio 1
	v_add_u32_e32 v144, s38, v136
	v_mfma_f32_16x16x32_bf16 v[126:129], v[184:187], v[146:149], v[126:129]
	ds_read_b128 v[200:203], v144 offset:0
	v_mfma_f32_16x16x32_bf16 v[122:125], v[184:187], v[152:155], v[122:125]
	ds_read_b128 v[204:207], v144 offset:1024
	v_mfma_f32_16x16x32_bf16 v[118:121], v[184:187], v[156:159], v[118:121]
	ds_read_b128 v[208:211], v144 offset:2048
	v_mfma_f32_16x16x32_bf16 v[114:117], v[184:187], v[162:165], v[114:117]
	ds_read_b128 v[212:215], v144 offset:3072
	v_mfma_f32_16x16x32_bf16 v[110:113], v[184:187], v[166:169], v[110:113]
	ds_read_b128 v[216:219], v144 offset:4096
	v_mfma_f32_16x16x32_bf16 v[106:109], v[184:187], v[170:173], v[106:109]
	ds_read_b128 v[220:223], v144 offset:5120
	v_mfma_f32_16x16x32_bf16 v[102:105], v[184:187], v[176:179], v[102:105]
	ds_read_b128 v[224:227], v144 offset:6144
	v_mfma_f32_16x16x32_bf16 v[98:101], v[184:187], v[180:183], v[98:101]
	ds_read_b128 v[228:231], v144 offset:7168
	v_mfma_f32_16x16x32_bf16 v[94:97], v[188:191], v[146:149], v[94:97]
	v_add_u32_e64 v144, s38, v137
	v_mfma_f32_16x16x32_bf16 v[90:93], v[188:191], v[152:155], v[90:93]
	v_mfma_f32_16x16x32_bf16 v[86:89], v[188:191], v[156:159], v[86:89]
	ds_read_b128 v[232:235], v144 offset:16384
	v_mfma_f32_16x16x32_bf16 v[82:85], v[188:191], v[162:165], v[82:85]
	ds_read_b128 v[236:239], v144 offset:17408
	v_mfma_f32_16x16x32_bf16 v[78:81], v[188:191], v[166:169], v[78:81]
	ds_read_b128 v[240:243], v144 offset:18432
	v_mfma_f32_16x16x32_bf16 v[74:77], v[188:191], v[170:173], v[74:77]
	ds_read_b128 v[244:247], v144 offset:19456
	v_mfma_f32_16x16x32_bf16 v[70:73], v[188:191], v[176:179], v[70:73]
	v_mfma_f32_16x16x32_bf16 v[66:69], v[188:191], v[180:183], v[66:69]
	v_mfma_f32_16x16x32_bf16 v[62:65], v[192:195], v[146:149], v[62:65]
	v_mfma_f32_16x16x32_bf16 v[58:61], v[192:195], v[152:155], v[58:61]
	v_mfma_f32_16x16x32_bf16 v[54:57], v[192:195], v[156:159], v[54:57]
	v_mfma_f32_16x16x32_bf16 v[50:53], v[192:195], v[162:165], v[50:53]
	v_mfma_f32_16x16x32_bf16 v[46:49], v[192:195], v[166:169], v[46:49]
	v_mfma_f32_16x16x32_bf16 v[42:45], v[192:195], v[170:173], v[42:45]
	v_mfma_f32_16x16x32_bf16 v[38:41], v[192:195], v[176:179], v[38:41]
	v_mfma_f32_16x16x32_bf16 v[34:37], v[192:195], v[180:183], v[34:37]
	s_setprio 0
	s_nop 0
	v_mfma_f32_16x16x32_bf16 v[30:33], v[196:199], v[146:149], v[30:33]
	v_mfma_f32_16x16x32_bf16 v[26:29], v[196:199], v[152:155], v[26:29]
	v_mfma_f32_16x16x32_bf16 v[22:25], v[196:199], v[156:159], v[22:25]
	v_mfma_f32_16x16x32_bf16 v[18:21], v[196:199], v[162:165], v[18:21]
	v_mfma_f32_16x16x32_bf16 v[14:17], v[196:199], v[166:169], v[14:17]
	v_mfma_f32_16x16x32_bf16 v[10:13], v[196:199], v[170:173], v[10:13]
	v_mfma_f32_16x16x32_bf16 v[6:9], v[196:199], v[176:179], v[6:9]
	v_mfma_f32_16x16x32_bf16 v[2:5], v[196:199], v[180:183], v[2:5]
	s_mov_b32 s39, s38
	s_nop 0
	s_add_i32 s38, s38, 0x6000
	s_cmp_eq_u32 s38, 0x12000
	s_cselect_b32 s38, 0, s38
	s_nop 0
	.p2align 3
	s_waitcnt lgkmcnt(0)
; DEVI unsigned pack2(float a, float b) { return __builtin_bit_cast(unsigned, __builtin_convertvector((f32x2_t){a, b}, bf16x2_t)); }
; DEVI float blo(unsigned u) { return __uint_as_float(u << 16); }
; DEVI float bhi(unsigned u) { return __uint_as_float(u & 0xffff0000u); }
; DEVI float siluf_(float x) { return x * __builtin_amdgcn_rcpf(1.f + __expf(-x)); }
;     ...
;     for (int f = 0; f < 8; f++) xa[f] = *(const bf16x8*)(cS + aoff + f * 1024);
; #pragma unroll
;     for (int f = 0; f < 4; f++) wb[f] = *(const bf16x8*)(cS + boff + f * 1024);
; #pragma unroll
;     for (int nf = 0; nf < 4; nf++)
; #pragma unroll
;       for (int mf = 0; mf < 8; mf++)
;         acc[nf][mf] = __builtin_amdgcn_mfma_f32_16x16x32_bf16(wb[nf], xa[mf], acc[nf][mf], 0, 0, 0);
;     ...
; #pragma unroll
;   for (int mf = 0; mf < 8; mf++) {
;     const int row = m0 + wm * 128 + mf * 16 + r16;
;     if (EPI == EPI_SWIGLU) {
; #pragma unroll
;       for (int nf = 0; nf < 2; nf++) {
;         const int hcol = (n0 >> 1) + wn * 32 + nf * 16 + quad * 4;
;         f32x4 g = acc[nf][mf], u = acc[nf + 2][mf];
;         u32x2 pk;
;         pk[0] = pack2(siluf_(g[0]) * u[0], siluf_(g[1]) * u[1]);
;         pk[1] = pack2(siluf_(g[2]) * u[2], siluf_(g[3]) * u[3]);
;         *(u32x2*)(outb + (size_t)row * DFF + hcol) = pk;
;       }
;     } else {
; #pragma unroll
;       for (int nf = 0; nf < 4; nf++) {
;         const int col = n0 + wn * 64 + nf * 16 + quad * 4;
;         f32x4 a = acc[nf][mf];
;         if (EPI == EPI_RESID || EPI == EPI_RESID_ATOMIC) {
;           f32x4 x = a;
;           if (EPI == EPI_RESID || kpart == 0) {
;             const u32x2 xr = *(const u32x2*)((const u16*)(p.ws + WS_XB) + (size_t)row * 1024 + col);
;             x[0] += ALPHA * blo(xr[0]); x[1] += ALPHA * bhi(xr[0]); x[2] += ALPHA * blo(xr[1]); x[3] += ALPHA * bhi(xr[1]);
;           }
;           if (EPI == EPI_RESID) *(f32x4*)((float*)(p.ws + WS_XF) + (size_t)row * 1024 + col) = x;
;           else *(f32x4*)((float*)(p.ws + WS_SLAB) + ((size_t)kpart * 512 + (row - T_P)) * 1024 + col) = x;
;         } else {
;           u32x2 pk; pk[0] = pack2(a[0], a[1]); pk[1] = pack2(a[2], a[3]);
;           *(u32x2*)(outb + (size_t)row * ldc + col) = pk;
;         }
	s_nop 0
	v_mfma_f32_16x16x32_bf16 v[126:129], v[232:235], v[200:203], v[126:129]
	v_mfma_f32_16x16x32_bf16 v[122:125], v[232:235], v[204:207], v[122:125]
	v_mfma_f32_16x16x32_bf16 v[118:121], v[232:235], v[208:211], v[118:121]
	v_mfma_f32_16x16x32_bf16 v[114:117], v[232:235], v[212:215], v[114:117]
	v_mfma_f32_16x16x32_bf16 v[110:113], v[232:235], v[216:219], v[110:113]
	v_mfma_f32_16x16x32_bf16 v[106:109], v[232:235], v[220:223], v[106:109]
	v_mfma_f32_16x16x32_bf16 v[102:105], v[232:235], v[224:227], v[102:105]
	v_mfma_f32_16x16x32_bf16 v[98:101], v[232:235], v[228:231], v[98:101]
	v_mfma_f32_16x16x32_bf16 v[94:97], v[236:239], v[200:203], v[94:97]
	v_mfma_f32_16x16x32_bf16 v[90:93], v[236:239], v[204:207], v[90:93]
	v_mfma_f32_16x16x32_bf16 v[86:89], v[236:239], v[208:211], v[86:89]
	v_mfma_f32_16x16x32_bf16 v[82:85], v[236:239], v[212:215], v[82:85]
	v_mfma_f32_16x16x32_bf16 v[78:81], v[236:239], v[216:219], v[78:81]
	v_mfma_f32_16x16x32_bf16 v[74:77], v[236:239], v[220:223], v[74:77]
	v_mfma_f32_16x16x32_bf16 v[70:73], v[236:239], v[224:227], v[70:73]
	v_mfma_f32_16x16x32_bf16 v[66:69], v[236:239], v[228:231], v[66:69]
	v_mfma_f32_16x16x32_bf16 v[62:65], v[240:243], v[200:203], v[62:65]
	v_mfma_f32_16x16x32_bf16 v[58:61], v[240:243], v[204:207], v[58:61]
	v_mfma_f32_16x16x32_bf16 v[54:57], v[240:243], v[208:211], v[54:57]
	v_mfma_f32_16x16x32_bf16 v[50:53], v[240:243], v[212:215], v[50:53]
	v_mfma_f32_16x16x32_bf16 v[46:49], v[240:243], v[216:219], v[46:49]
	v_mfma_f32_16x16x32_bf16 v[42:45], v[240:243], v[220:223], v[42:45]
	v_mfma_f32_16x16x32_bf16 v[38:41], v[240:243], v[224:227], v[38:41]
	v_mfma_f32_16x16x32_bf16 v[34:37], v[240:243], v[228:231], v[34:37]
	v_mfma_f32_16x16x32_bf16 v[30:33], v[244:247], v[200:203], v[30:33]
	v_mfma_f32_16x16x32_bf16 v[26:29], v[244:247], v[204:207], v[26:29]
	v_mfma_f32_16x16x32_bf16 v[22:25], v[244:247], v[208:211], v[22:25]
	v_mfma_f32_16x16x32_bf16 v[18:21], v[244:247], v[212:215], v[18:21]
	v_mfma_f32_16x16x32_bf16 v[14:17], v[244:247], v[216:219], v[14:17]
	v_mfma_f32_16x16x32_bf16 v[10:13], v[244:247], v[220:223], v[10:13]
	v_mfma_f32_16x16x32_bf16 v[6:9], v[244:247], v[224:227], v[6:9]
	v_mfma_f32_16x16x32_bf16 v[2:5], v[244:247], v[228:231], v[2:5]
	s_mov_b32 m0, s41
	s_mov_b32 s8, 0x14000
	s_mov_b32 s9, 0
	s_nop 7
	v_and_b32_e32 v228, 1, v145
	v_cmp_ne_u32_e32 vcc, 0, v228
	v_mov_b32_e32 v229, 0xffffec40
	v_cndmask_b32_e32 v230, 0, v229, vcc
	v_ashrrev_i32_e32 v231, 31, v230
	v_lshl_add_u64 v[140:141], v[140:141], 0, v[230:231]
	v_add_co_u32_e32 v142, vcc, 0x1400, v140
	s_nop 0
	v_addc_co_u32_e32 v143, vcc, 0, v141, vcc
	v_cmp_ne_u32_e32 vcc, 0, v228
	v_cvt_pk_bf16_f32 v126, v126, v127
	v_cvt_pk_bf16_f32 v127, v128, v129
	v_cvt_pk_bf16_f32 v128, v94, v95
	v_cvt_pk_bf16_f32 v129, v96, v97
	v_cvt_pk_bf16_f32 v62, v62, v63
	v_cvt_pk_bf16_f32 v63, v64, v65
	v_cvt_pk_bf16_f32 v64, v30, v31
	v_cvt_pk_bf16_f32 v65, v32, v33
	v_permlane16_swap_b32_e32 v126, v128
	v_permlane16_swap_b32_e32 v127, v129
	v_permlane16_swap_b32_e32 v62, v64
	v_permlane16_swap_b32_e32 v63, v65
	v_mov_b32_dpp v224, v126 quad_perm:[1,0,3,2] row_mask:0xf bank_mask:0xf
	v_mov_b32_dpp v225, v127 quad_perm:[1,0,3,2] row_mask:0xf bank_mask:0xf
	v_mov_b32_dpp v226, v128 quad_perm:[1,0,3,2] row_mask:0xf bank_mask:0xf
	v_mov_b32_dpp v227, v129 quad_perm:[1,0,3,2] row_mask:0xf bank_mask:0xf
	v_mov_b32_dpp v220, v62 quad_perm:[1,0,3,2] row_mask:0xf bank_mask:0xf
	v_mov_b32_dpp v221, v63 quad_perm:[1,0,3,2] row_mask:0xf bank_mask:0xf
	v_mov_b32_dpp v222, v64 quad_perm:[1,0,3,2] row_mask:0xf bank_mask:0xf
	v_mov_b32_dpp v223, v65 quad_perm:[1,0,3,2] row_mask:0xf bank_mask:0xf
	v_cndmask_b32_e32 v62, v224, v62, vcc
	v_cndmask_b32_e32 v63, v225, v63, vcc
	v_cndmask_b32_e32 v64, v226, v64, vcc
	v_cndmask_b32_e32 v65, v227, v65, vcc
	v_cndmask_b32_e32 v126, v126, v220, vcc
	v_cndmask_b32_e32 v127, v127, v221, vcc
	v_cndmask_b32_e32 v128, v128, v222, vcc
	v_cndmask_b32_e32 v129, v129, v223, vcc
	global_store_dwordx4 v[140:141], v[126:129], off
	global_store_dwordx4 v[142:143], v[62:65], off
	v_lshl_add_u64 v[140:141], v[140:141], 0, s[8:9]
	v_lshl_add_u64 v[142:143], v[142:143], 0, s[8:9]
	v_cvt_pk_bf16_f32 v122, v122, v123
	v_cvt_pk_bf16_f32 v123, v124, v125
	v_cvt_pk_bf16_f32 v124, v90, v91
	v_cvt_pk_bf16_f32 v125, v92, v93
	v_cvt_pk_bf16_f32 v58, v58, v59
	v_cvt_pk_bf16_f32 v59, v60, v61
	v_cvt_pk_bf16_f32 v60, v26, v27
	v_cvt_pk_bf16_f32 v61, v28, v29
	v_permlane16_swap_b32_e32 v122, v124
	v_permlane16_swap_b32_e32 v123, v125
	v_permlane16_swap_b32_e32 v58, v60
	v_permlane16_swap_b32_e32 v59, v61
	v_mov_b32_dpp v224, v122 quad_perm:[1,0,3,2] row_mask:0xf bank_mask:0xf
	v_mov_b32_dpp v225, v123 quad_perm:[1,0,3,2] row_mask:0xf bank_mask:0xf
	v_mov_b32_dpp v226, v124 quad_perm:[1,0,3,2] row_mask:0xf bank_mask:0xf
	v_mov_b32_dpp v227, v125 quad_perm:[1,0,3,2] row_mask:0xf bank_mask:0xf
	v_mov_b32_dpp v220, v58 quad_perm:[1,0,3,2] row_mask:0xf bank_mask:0xf
	v_mov_b32_dpp v221, v59 quad_perm:[1,0,3,2] row_mask:0xf bank_mask:0xf
	v_mov_b32_dpp v222, v60 quad_perm:[1,0,3,2] row_mask:0xf bank_mask:0xf
	v_mov_b32_dpp v223, v61 quad_perm:[1,0,3,2] row_mask:0xf bank_mask:0xf
	v_cndmask_b32_e32 v58, v224, v58, vcc
	v_cndmask_b32_e32 v59, v225, v59, vcc
	v_cndmask_b32_e32 v60, v226, v60, vcc
	v_cndmask_b32_e32 v61, v227, v61, vcc
	v_cndmask_b32_e32 v122, v122, v220, vcc
	v_cndmask_b32_e32 v123, v123, v221, vcc
	v_cndmask_b32_e32 v124, v124, v222, vcc
	v_cndmask_b32_e32 v125, v125, v223, vcc
	global_store_dwordx4 v[140:141], v[122:125], off
	global_store_dwordx4 v[142:143], v[58:61], off
	v_lshl_add_u64 v[140:141], v[140:141], 0, s[8:9]
; DEVI unsigned pack2(float a, float b) { return __builtin_bit_cast(unsigned, __builtin_convertvector((f32x2_t){a, b}, bf16x2_t)); }
; DEVI float blo(unsigned u) { return __uint_as_float(u << 16); }
; DEVI float bhi(unsigned u) { return __uint_as_float(u & 0xffff0000u); }
; DEVI float siluf_(float x) { return x * __builtin_amdgcn_rcpf(1.f + __expf(-x)); }
;     ...
;   for (int mf = 0; mf < 8; mf++) {
;     const int row = m0 + wm * 128 + mf * 16 + r16;
;     if (EPI == EPI_SWIGLU) {
; #pragma unroll
;       for (int nf = 0; nf < 2; nf++) {
;         const int hcol = (n0 >> 1) + wn * 32 + nf * 16 + quad * 4;
;         f32x4 g = acc[nf][mf], u = acc[nf + 2][mf];
;         u32x2 pk;
;         pk[0] = pack2(siluf_(g[0]) * u[0], siluf_(g[1]) * u[1]);
;         pk[1] = pack2(siluf_(g[2]) * u[2], siluf_(g[3]) * u[3]);
;         *(u32x2*)(outb + (size_t)row * DFF + hcol) = pk;
;       }
;     } else {
; #pragma unroll
;       for (int nf = 0; nf < 4; nf++) {
;         const int col = n0 + wn * 64 + nf * 16 + quad * 4;
;         f32x4 a = acc[nf][mf];
;         if (EPI == EPI_RESID || EPI == EPI_RESID_ATOMIC) {
;           f32x4 x = a;
;           if (EPI == EPI_RESID || kpart == 0) {
;             const u32x2 xr = *(const u32x2*)((const u16*)(p.ws + WS_XB) + (size_t)row * 1024 + col);
;             x[0] += ALPHA * blo(xr[0]); x[1] += ALPHA * bhi(xr[0]); x[2] += ALPHA * blo(xr[1]); x[3] += ALPHA * bhi(xr[1]);
;           }
;           if (EPI == EPI_RESID) *(f32x4*)((float*)(p.ws + WS_XF) + (size_t)row * 1024 + col) = x;
;           else *(f32x4*)((float*)(p.ws + WS_SLAB) + ((size_t)kpart * 512 + (row - T_P)) * 1024 + col) = x;
;         } else {
;           u32x2 pk; pk[0] = pack2(a[0], a[1]); pk[1] = pack2(a[2], a[3]);
;           *(u32x2*)(outb + (size_t)row * ldc + col) = pk;
;         }
	v_lshl_add_u64 v[142:143], v[142:143], 0, s[8:9]
	v_cvt_pk_bf16_f32 v118, v118, v119
	v_cvt_pk_bf16_f32 v119, v120, v121
	v_cvt_pk_bf16_f32 v120, v86, v87
	v_cvt_pk_bf16_f32 v121, v88, v89
	v_cvt_pk_bf16_f32 v54, v54, v55
	v_cvt_pk_bf16_f32 v55, v56, v57
	v_cvt_pk_bf16_f32 v56, v22, v23
	v_cvt_pk_bf16_f32 v57, v24, v25
	v_permlane16_swap_b32_e32 v118, v120
	v_permlane16_swap_b32_e32 v119, v121
	v_permlane16_swap_b32_e32 v54, v56
	v_permlane16_swap_b32_e32 v55, v57
	v_mov_b32_dpp v224, v118 quad_perm:[1,0,3,2] row_mask:0xf bank_mask:0xf
	v_mov_b32_dpp v225, v119 quad_perm:[1,0,3,2] row_mask:0xf bank_mask:0xf
	v_mov_b32_dpp v226, v120 quad_perm:[1,0,3,2] row_mask:0xf bank_mask:0xf
	v_mov_b32_dpp v227, v121 quad_perm:[1,0,3,2] row_mask:0xf bank_mask:0xf
	v_mov_b32_dpp v220, v54 quad_perm:[1,0,3,2] row_mask:0xf bank_mask:0xf
	v_mov_b32_dpp v221, v55 quad_perm:[1,0,3,2] row_mask:0xf bank_mask:0xf
	v_mov_b32_dpp v222, v56 quad_perm:[1,0,3,2] row_mask:0xf bank_mask:0xf
	v_mov_b32_dpp v223, v57 quad_perm:[1,0,3,2] row_mask:0xf bank_mask:0xf
	v_cndmask_b32_e32 v54, v224, v54, vcc
	v_cndmask_b32_e32 v55, v225, v55, vcc
	v_cndmask_b32_e32 v56, v226, v56, vcc
	v_cndmask_b32_e32 v57, v227, v57, vcc
	v_cndmask_b32_e32 v118, v118, v220, vcc
	v_cndmask_b32_e32 v119, v119, v221, vcc
	v_cndmask_b32_e32 v120, v120, v222, vcc
	v_cndmask_b32_e32 v121, v121, v223, vcc
	global_store_dwordx4 v[140:141], v[118:121], off
	global_store_dwordx4 v[142:143], v[54:57], off
	v_lshl_add_u64 v[140:141], v[140:141], 0, s[8:9]
	v_lshl_add_u64 v[142:143], v[142:143], 0, s[8:9]
	v_cvt_pk_bf16_f32 v114, v114, v115
	v_cvt_pk_bf16_f32 v115, v116, v117
	v_cvt_pk_bf16_f32 v116, v82, v83
	v_cvt_pk_bf16_f32 v117, v84, v85
	v_cvt_pk_bf16_f32 v50, v50, v51
	v_cvt_pk_bf16_f32 v51, v52, v53
	v_cvt_pk_bf16_f32 v52, v18, v19
	v_cvt_pk_bf16_f32 v53, v20, v21
	v_permlane16_swap_b32_e32 v114, v116
	v_permlane16_swap_b32_e32 v115, v117
	v_permlane16_swap_b32_e32 v50, v52
	v_permlane16_swap_b32_e32 v51, v53
	v_mov_b32_dpp v224, v114 quad_perm:[1,0,3,2] row_mask:0xf bank_mask:0xf
	v_mov_b32_dpp v225, v115 quad_perm:[1,0,3,2] row_mask:0xf bank_mask:0xf
	v_mov_b32_dpp v226, v116 quad_perm:[1,0,3,2] row_mask:0xf bank_mask:0xf
	v_mov_b32_dpp v227, v117 quad_perm:[1,0,3,2] row_mask:0xf bank_mask:0xf
	v_mov_b32_dpp v220, v50 quad_perm:[1,0,3,2] row_mask:0xf bank_mask:0xf
	v_mov_b32_dpp v221, v51 quad_perm:[1,0,3,2] row_mask:0xf bank_mask:0xf
	v_mov_b32_dpp v222, v52 quad_perm:[1,0,3,2] row_mask:0xf bank_mask:0xf
	v_mov_b32_dpp v223, v53 quad_perm:[1,0,3,2] row_mask:0xf bank_mask:0xf
	v_cndmask_b32_e32 v50, v224, v50, vcc
	v_cndmask_b32_e32 v51, v225, v51, vcc
	v_cndmask_b32_e32 v52, v226, v52, vcc
	v_cndmask_b32_e32 v53, v227, v53, vcc
	v_cndmask_b32_e32 v114, v114, v220, vcc
	v_cndmask_b32_e32 v115, v115, v221, vcc
	v_cndmask_b32_e32 v116, v116, v222, vcc
	v_cndmask_b32_e32 v117, v117, v223, vcc
	global_store_dwordx4 v[140:141], v[114:117], off
	global_store_dwordx4 v[142:143], v[50:53], off
	v_lshl_add_u64 v[140:141], v[140:141], 0, s[8:9]
	v_lshl_add_u64 v[142:143], v[142:143], 0, s[8:9]
	v_cvt_pk_bf16_f32 v110, v110, v111
	v_cvt_pk_bf16_f32 v111, v112, v113
	v_cvt_pk_bf16_f32 v112, v78, v79
	v_cvt_pk_bf16_f32 v113, v80, v81
	v_cvt_pk_bf16_f32 v46, v46, v47
	v_cvt_pk_bf16_f32 v47, v48, v49
	v_cvt_pk_bf16_f32 v48, v14, v15
	v_cvt_pk_bf16_f32 v49, v16, v17
	v_permlane16_swap_b32_e32 v110, v112
	v_permlane16_swap_b32_e32 v111, v113
	v_permlane16_swap_b32_e32 v46, v48
	v_permlane16_swap_b32_e32 v47, v49
	v_mov_b32_dpp v224, v110 quad_perm:[1,0,3,2] row_mask:0xf bank_mask:0xf
	v_mov_b32_dpp v225, v111 quad_perm:[1,0,3,2] row_mask:0xf bank_mask:0xf
	v_mov_b32_dpp v226, v112 quad_perm:[1,0,3,2] row_mask:0xf bank_mask:0xf
	v_mov_b32_dpp v227, v113 quad_perm:[1,0,3,2] row_mask:0xf bank_mask:0xf
	v_mov_b32_dpp v220, v46 quad_perm:[1,0,3,2] row_mask:0xf bank_mask:0xf
	v_mov_b32_dpp v221, v47 quad_perm:[1,0,3,2] row_mask:0xf bank_mask:0xf
	v_mov_b32_dpp v222, v48 quad_perm:[1,0,3,2] row_mask:0xf bank_mask:0xf
	v_mov_b32_dpp v223, v49 quad_perm:[1,0,3,2] row_mask:0xf bank_mask:0xf
	v_cndmask_b32_e32 v46, v224, v46, vcc
	v_cndmask_b32_e32 v47, v225, v47, vcc
	v_cndmask_b32_e32 v48, v226, v48, vcc
	v_cndmask_b32_e32 v49, v227, v49, vcc
	v_cndmask_b32_e32 v110, v110, v220, vcc
	v_cndmask_b32_e32 v111, v111, v221, vcc
	v_cndmask_b32_e32 v112, v112, v222, vcc
	v_cndmask_b32_e32 v113, v113, v223, vcc
	global_store_dwordx4 v[140:141], v[110:113], off
	global_store_dwordx4 v[142:143], v[46:49], off
; DEVI unsigned pack2(float a, float b) { return __builtin_bit_cast(unsigned, __builtin_convertvector((f32x2_t){a, b}, bf16x2_t)); }
; DEVI float blo(unsigned u) { return __uint_as_float(u << 16); }
; DEVI float bhi(unsigned u) { return __uint_as_float(u & 0xffff0000u); }
; DEVI float siluf_(float x) { return x * __builtin_amdgcn_rcpf(1.f + __expf(-x)); }
;     ...
;   for (int mf = 0; mf < 8; mf++) {
;     const int row = m0 + wm * 128 + mf * 16 + r16;
;     if (EPI == EPI_SWIGLU) {
; #pragma unroll
;       for (int nf = 0; nf < 2; nf++) {
;         const int hcol = (n0 >> 1) + wn * 32 + nf * 16 + quad * 4;
;         f32x4 g = acc[nf][mf], u = acc[nf + 2][mf];
;         u32x2 pk;
;         pk[0] = pack2(siluf_(g[0]) * u[0], siluf_(g[1]) * u[1]);
;         pk[1] = pack2(siluf_(g[2]) * u[2], siluf_(g[3]) * u[3]);
;         *(u32x2*)(outb + (size_t)row * DFF + hcol) = pk;
;       }
;     } else {
; #pragma unroll
;       for (int nf = 0; nf < 4; nf++) {
;         const int col = n0 + wn * 64 + nf * 16 + quad * 4;
;         f32x4 a = acc[nf][mf];
;         if (EPI == EPI_RESID || EPI == EPI_RESID_ATOMIC) {
;           f32x4 x = a;
;           if (EPI == EPI_RESID || kpart == 0) {
;             const u32x2 xr = *(const u32x2*)((const u16*)(p.ws + WS_XB) + (size_t)row * 1024 + col);
;             x[0] += ALPHA * blo(xr[0]); x[1] += ALPHA * bhi(xr[0]); x[2] += ALPHA * blo(xr[1]); x[3] += ALPHA * bhi(xr[1]);
;           }
;           if (EPI == EPI_RESID) *(f32x4*)((float*)(p.ws + WS_XF) + (size_t)row * 1024 + col) = x;
;           else *(f32x4*)((float*)(p.ws + WS_SLAB) + ((size_t)kpart * 512 + (row - T_P)) * 1024 + col) = x;
;         } else {
;           u32x2 pk; pk[0] = pack2(a[0], a[1]); pk[1] = pack2(a[2], a[3]);
;           *(u32x2*)(outb + (size_t)row * ldc + col) = pk;
;         }
	v_lshl_add_u64 v[140:141], v[140:141], 0, s[8:9]
	v_lshl_add_u64 v[142:143], v[142:143], 0, s[8:9]
	v_cvt_pk_bf16_f32 v106, v106, v107
	v_cvt_pk_bf16_f32 v107, v108, v109
	v_cvt_pk_bf16_f32 v108, v74, v75
	v_cvt_pk_bf16_f32 v109, v76, v77
	v_cvt_pk_bf16_f32 v42, v42, v43
	v_cvt_pk_bf16_f32 v43, v44, v45
	v_cvt_pk_bf16_f32 v44, v10, v11
	v_cvt_pk_bf16_f32 v45, v12, v13
	v_permlane16_swap_b32_e32 v106, v108
	v_permlane16_swap_b32_e32 v107, v109
	v_permlane16_swap_b32_e32 v42, v44
	v_permlane16_swap_b32_e32 v43, v45
	v_mov_b32_dpp v224, v106 quad_perm:[1,0,3,2] row_mask:0xf bank_mask:0xf
	v_mov_b32_dpp v225, v107 quad_perm:[1,0,3,2] row_mask:0xf bank_mask:0xf
	v_mov_b32_dpp v226, v108 quad_perm:[1,0,3,2] row_mask:0xf bank_mask:0xf
	v_mov_b32_dpp v227, v109 quad_perm:[1,0,3,2] row_mask:0xf bank_mask:0xf
	v_mov_b32_dpp v220, v42 quad_perm:[1,0,3,2] row_mask:0xf bank_mask:0xf
	v_mov_b32_dpp v221, v43 quad_perm:[1,0,3,2] row_mask:0xf bank_mask:0xf
	v_mov_b32_dpp v222, v44 quad_perm:[1,0,3,2] row_mask:0xf bank_mask:0xf
	v_mov_b32_dpp v223, v45 quad_perm:[1,0,3,2] row_mask:0xf bank_mask:0xf
	v_cndmask_b32_e32 v42, v224, v42, vcc
	v_cndmask_b32_e32 v43, v225, v43, vcc
	v_cndmask_b32_e32 v44, v226, v44, vcc
	v_cndmask_b32_e32 v45, v227, v45, vcc
	v_cndmask_b32_e32 v106, v106, v220, vcc
	v_cndmask_b32_e32 v107, v107, v221, vcc
	v_cndmask_b32_e32 v108, v108, v222, vcc
	v_cndmask_b32_e32 v109, v109, v223, vcc
	global_store_dwordx4 v[140:141], v[106:109], off
	global_store_dwordx4 v[142:143], v[42:45], off
	v_lshl_add_u64 v[140:141], v[140:141], 0, s[8:9]
	v_lshl_add_u64 v[142:143], v[142:143], 0, s[8:9]
	v_cvt_pk_bf16_f32 v102, v102, v103
	v_cvt_pk_bf16_f32 v103, v104, v105
	v_cvt_pk_bf16_f32 v104, v70, v71
	v_cvt_pk_bf16_f32 v105, v72, v73
	v_cvt_pk_bf16_f32 v38, v38, v39
	v_cvt_pk_bf16_f32 v39, v40, v41
	v_cvt_pk_bf16_f32 v40, v6, v7
	v_cvt_pk_bf16_f32 v41, v8, v9
	v_permlane16_swap_b32_e32 v102, v104
	v_permlane16_swap_b32_e32 v103, v105
	v_permlane16_swap_b32_e32 v38, v40
	v_permlane16_swap_b32_e32 v39, v41
	v_mov_b32_dpp v224, v102 quad_perm:[1,0,3,2] row_mask:0xf bank_mask:0xf
	v_mov_b32_dpp v225, v103 quad_perm:[1,0,3,2] row_mask:0xf bank_mask:0xf
	v_mov_b32_dpp v226, v104 quad_perm:[1,0,3,2] row_mask:0xf bank_mask:0xf
	v_mov_b32_dpp v227, v105 quad_perm:[1,0,3,2] row_mask:0xf bank_mask:0xf
	v_mov_b32_dpp v220, v38 quad_perm:[1,0,3,2] row_mask:0xf bank_mask:0xf
	v_mov_b32_dpp v221, v39 quad_perm:[1,0,3,2] row_mask:0xf bank_mask:0xf
	v_mov_b32_dpp v222, v40 quad_perm:[1,0,3,2] row_mask:0xf bank_mask:0xf
	v_mov_b32_dpp v223, v41 quad_perm:[1,0,3,2] row_mask:0xf bank_mask:0xf
	v_cndmask_b32_e32 v38, v224, v38, vcc
	v_cndmask_b32_e32 v39, v225, v39, vcc
	v_cndmask_b32_e32 v40, v226, v40, vcc
	v_cndmask_b32_e32 v41, v227, v41, vcc
	v_cndmask_b32_e32 v102, v102, v220, vcc
	v_cndmask_b32_e32 v103, v103, v221, vcc
	v_cndmask_b32_e32 v104, v104, v222, vcc
	v_cndmask_b32_e32 v105, v105, v223, vcc
	global_store_dwordx4 v[140:141], v[102:105], off
	global_store_dwordx4 v[142:143], v[38:41], off
	v_lshl_add_u64 v[140:141], v[140:141], 0, s[8:9]
	v_lshl_add_u64 v[142:143], v[142:143], 0, s[8:9]
	v_cvt_pk_bf16_f32 v98, v98, v99
	v_cvt_pk_bf16_f32 v99, v100, v101
	v_cvt_pk_bf16_f32 v100, v66, v67
	v_cvt_pk_bf16_f32 v101, v68, v69
	v_cvt_pk_bf16_f32 v34, v34, v35
	v_cvt_pk_bf16_f32 v35, v36, v37
	v_cvt_pk_bf16_f32 v36, v2, v3
	v_cvt_pk_bf16_f32 v37, v4, v5
	v_permlane16_swap_b32_e32 v98, v100
	v_permlane16_swap_b32_e32 v99, v101
	v_permlane16_swap_b32_e32 v34, v36
	v_permlane16_swap_b32_e32 v35, v37
	v_mov_b32_dpp v224, v98 quad_perm:[1,0,3,2] row_mask:0xf bank_mask:0xf
	v_mov_b32_dpp v225, v99 quad_perm:[1,0,3,2] row_mask:0xf bank_mask:0xf
	v_mov_b32_dpp v226, v100 quad_perm:[1,0,3,2] row_mask:0xf bank_mask:0xf
	v_mov_b32_dpp v227, v101 quad_perm:[1,0,3,2] row_mask:0xf bank_mask:0xf
	v_mov_b32_dpp v220, v34 quad_perm:[1,0,3,2] row_mask:0xf bank_mask:0xf
	v_mov_b32_dpp v221, v35 quad_perm:[1,0,3,2] row_mask:0xf bank_mask:0xf
	v_mov_b32_dpp v222, v36 quad_perm:[1,0,3,2] row_mask:0xf bank_mask:0xf
	v_mov_b32_dpp v223, v37 quad_perm:[1,0,3,2] row_mask:0xf bank_mask:0xf
	v_cndmask_b32_e32 v34, v224, v34, vcc
	v_cndmask_b32_e32 v35, v225, v35, vcc
	v_cndmask_b32_e32 v36, v226, v36, vcc
	v_cndmask_b32_e32 v37, v227, v37, vcc
	v_cndmask_b32_e32 v98, v98, v220, vcc
	v_cndmask_b32_e32 v99, v99, v221, vcc
	v_cndmask_b32_e32 v100, v100, v222, vcc
	v_cndmask_b32_e32 v101, v101, v223, vcc
	global_store_dwordx4 v[140:141], v[98:101], off
	global_store_dwordx4 v[142:143], v[34:37], off
	s_branch .LBB0_886
